# H (norm output) stored K-tile-blocked in LDS-image order; in/up GEMMs stage A linearly (on top of U/w_up/w_down layouts)
# speedup vs baseline: 1.5235x; 1.5235x over previous
.LBB0_173:
	v_add_u32_e32 v18, s6, v153
	v_add_u32_e32 v20, 0x10000, v18
	ds_read_b128 v[38:41], v20
	v_add_u32_e32 v20, 0x10400, v18
	s_addk_i32 s6, 0x2000
	s_cmpk_lg_u32 s6, 0xe000
	s_waitcnt vmcnt(0) lgkmcnt(0)
	v_pk_add_f32 v[12:13], v[12:13], v[40:41]
	v_pk_add_f32 v[10:11], v[10:11], v[38:39]
	ds_read_b128 v[38:41], v20
	v_add_u32_e32 v20, 0x10800, v18
	s_waitcnt lgkmcnt(0)
	v_pk_add_f32 v[8:9], v[8:9], v[40:41]
	v_pk_add_f32 v[6:7], v[6:7], v[38:39]
	ds_read_b128 v[38:41], v20
	v_add_u32_e32 v20, 0x10c00, v18
	s_waitcnt lgkmcnt(0)
	v_pk_add_f32 v[4:5], v[4:5], v[40:41]
	v_pk_add_f32 v[2:3], v[2:3], v[38:39]
	ds_read_b128 v[38:41], v20
	v_add_u32_e32 v20, 0x11000, v18
	s_waitcnt lgkmcnt(0)
	v_pk_add_f32 v[16:17], v[16:17], v[40:41]
	v_pk_add_f32 v[14:15], v[14:15], v[38:39]
	ds_read_b128 v[38:41], v20
	v_add_u32_e32 v20, 0x11400, v18
	s_waitcnt lgkmcnt(0)
	v_pk_add_f32 v[24:25], v[24:25], v[40:41]
	v_pk_add_f32 v[22:23], v[22:23], v[38:39]
	ds_read_b128 v[38:41], v20
	v_add_u32_e32 v20, 0x11800, v18
	v_add_u32_e32 v18, 0x11c00, v18
	s_waitcnt lgkmcnt(0)
	v_pk_add_f32 v[28:29], v[28:29], v[40:41]
	v_pk_add_f32 v[26:27], v[26:27], v[38:39]
	ds_read_b128 v[38:41], v20
	s_waitcnt lgkmcnt(0)
	v_pk_add_f32 v[36:37], v[36:37], v[40:41]
	v_pk_add_f32 v[34:35], v[34:35], v[38:39]
	ds_read_b128 v[38:41], v18
	s_waitcnt lgkmcnt(0)
	v_pk_add_f32 v[32:33], v[32:33], v[40:41]
	v_pk_add_f32 v[30:31], v[30:31], v[38:39]
	s_cbranch_scc1 .LBB0_173
	s_lshr_b32 s7, s45, 3
	s_ashr_i32 s6, s22, 12
	s_add_i32 s7, s7, 2
	s_cmp_lt_i32 s45, 0
	s_cselect_b32 s6, s6, s7
	s_ashr_i32 s7, s6, 31
	s_add_u32 s6, s43, s6
	s_addc_u32 s7, s42, s7
	v_lshl_add_u64 v[20:21], s[24:25], 0, v[78:79]
	s_mul_i32 s7, s7, 0xc000
	s_mul_hi_u32 s24, s6, 0xc000
	s_add_i32 s24, s24, s7
	s_mul_i32 s6, s6, 0xc000
	s_add_u32 s6, s38, s6
	global_store_dwordx4 v[20:21], v[10:13], off
	global_store_dwordx4 v[20:21], v[6:9], off offset:1024
	global_store_dwordx4 v[20:21], v[2:5], off offset:2048
	global_store_dwordx4 v[20:21], v[14:17], off offset:3072
	v_add_co_u32_e32 v20, vcc, 0x1000, v20
	s_addc_u32 s7, s39, s24
	s_nop 0
	v_addc_co_u32_e32 v21, vcc, 0, v21, vcc
	v_lshl_add_u64 v[66:67], s[6:7], 0, v[78:79]
	v_add_co_u32_e32 v94, vcc, s78, v66
	global_store_dwordx4 v[20:21], v[22:25], off
	global_store_dwordx4 v[20:21], v[26:29], off offset:1024
	global_store_dwordx4 v[20:21], v[34:37], off offset:2048
	global_store_dwordx4 v[20:21], v[30:33], off offset:3072
	v_addc_co_u32_e32 v95, vcc, 0, v67, vcc
	global_load_dwordx4 v[38:41], v[80:81], off
	global_load_dwordx4 v[46:49], v[94:95], off offset:-4096
	global_load_dwordx4 v[42:45], v[66:67], off
	s_mov_b64 s[6:7], 0x2000
	v_lshl_add_u64 v[58:59], v[66:67], 0, s[6:7]
	v_add_co_u32_e32 v98, vcc, s3, v66
	v_mul_f32_e32 v18, v22, v22
	s_nop 0
	v_addc_co_u32_e32 v99, vcc, 0, v67, vcc
	s_lshl_b64 s[6:7], s[22:23], 12
	v_lshl_add_u64 v[160:161], v[90:91], 0, s[6:7]
	s_waitcnt vmcnt(1)
	v_pk_add_f32 v[20:21], v[48:49], 1.0 op_sel_hi:[1,0]
	v_pk_add_f32 v[46:47], v[46:47], 1.0 op_sel_hi:[1,0]
	v_pk_mul_f32 v[20:21], v[40:41], v[20:21]
	v_pk_mul_f32 v[114:115], v[38:39], v[46:47]
	global_load_dwordx4 v[38:41], v[80:81], off offset:1024
	global_load_dwordx4 v[50:53], v[58:59], off offset:1024
	global_load_dwordx4 v[46:49], v[66:67], off offset:1024
	s_waitcnt vmcnt(1)
	v_pk_add_f32 v[52:53], v[52:53], 1.0 op_sel_hi:[1,0]
	v_pk_add_f32 v[50:51], v[50:51], 1.0 op_sel_hi:[1,0]
	v_pk_mul_f32 v[116:117], v[40:41], v[52:53]
	v_pk_mul_f32 v[118:119], v[38:39], v[50:51]
	global_load_dwordx4 v[38:41], v[80:81], off offset:2048
	global_load_dwordx4 v[54:57], v[58:59], off offset:2048
	global_load_dwordx4 v[50:53], v[66:67], off offset:2048
	s_waitcnt vmcnt(1)
	v_pk_add_f32 v[56:57], v[56:57], 1.0 op_sel_hi:[1,0]
	v_pk_add_f32 v[54:55], v[54:55], 1.0 op_sel_hi:[1,0]
	v_pk_mul_f32 v[128:129], v[40:41], v[56:57]
	v_pk_mul_f32 v[130:131], v[38:39], v[54:55]
	global_load_dwordx4 v[38:41], v[80:81], off offset:3072
	s_nop 0
	global_load_dwordx4 v[58:61], v[58:59], off offset:3072
	s_nop 0
	global_load_dwordx4 v[54:57], v[66:67], off offset:3072
	s_waitcnt vmcnt(1)
	v_pk_add_f32 v[60:61], v[60:61], 1.0 op_sel_hi:[1,0]
	v_pk_add_f32 v[58:59], v[58:59], 1.0 op_sel_hi:[1,0]
	v_pk_mul_f32 v[108:109], v[40:41], v[60:61]
	v_pk_mul_f32 v[110:111], v[38:39], v[58:59]
	global_load_dwordx4 v[38:41], v[82:83], off
	global_load_dwordx4 v[62:65], v[94:95], off
	global_load_dwordx4 v[58:61], v[98:99], off
	s_waitcnt vmcnt(1)
	v_pk_add_f32 v[64:65], v[64:65], 1.0 op_sel_hi:[1,0]
	v_pk_add_f32 v[62:63], v[62:63], 1.0 op_sel_hi:[1,0]
	v_pk_mul_f32 v[104:105], v[40:41], v[64:65]
	v_pk_mul_f32 v[106:107], v[38:39], v[62:63]
	global_load_dwordx4 v[38:41], v[84:85], off
	global_load_dwordx4 v[66:69], v[94:95], off offset:1024
	global_load_dwordx4 v[62:65], v[98:99], off offset:1024
	s_waitcnt vmcnt(1)
	v_pk_add_f32 v[68:69], v[68:69], 1.0 op_sel_hi:[1,0]
	v_pk_add_f32 v[66:67], v[66:67], 1.0 op_sel_hi:[1,0]
	v_pk_mul_f32 v[120:121], v[40:41], v[68:69]
	v_pk_mul_f32 v[102:103], v[38:39], v[66:67]
	global_load_dwordx4 v[66:69], v[86:87], off
	global_load_dwordx4 v[70:73], v[94:95], off offset:2048
	global_load_dwordx4 v[38:41], v[98:99], off offset:2048
	s_waitcnt vmcnt(1)
	v_pk_add_f32 v[72:73], v[72:73], 1.0 op_sel_hi:[1,0]
	v_pk_add_f32 v[74:75], v[70:71], 1.0 op_sel_hi:[1,0]
	v_pk_mul_f32 v[70:71], v[68:69], v[72:73]
	v_pk_mul_f32 v[72:73], v[66:67], v[74:75]
	global_load_dwordx4 v[74:77], v[88:89], off
	s_nop 0
	global_load_dwordx4 v[94:97], v[94:95], off offset:3072
	s_nop 0
	global_load_dwordx4 v[66:69], v[98:99], off offset:3072
	s_waitcnt vmcnt(1)
	v_pk_add_f32 v[96:97], v[96:97], 1.0 op_sel_hi:[1,0]
	v_pk_add_f32 v[94:95], v[94:95], 1.0 op_sel_hi:[1,0]
	v_pk_mul_f32 v[98:99], v[76:77], v[96:97]
	v_mov_b32_e32 v76, v11
	v_mov_b32_e32 v77, v7
	v_pk_mul_f32 v[100:101], v[74:75], v[94:95]
	v_mov_b32_e32 v74, v10
	v_mov_b32_e32 v75, v6
	v_pk_mul_f32 v[76:77], v[76:77], v[76:77]
	v_mov_b32_e32 v94, v13
	v_mov_b32_e32 v95, v9
	v_pk_fma_f32 v[74:75], v[74:75], v[74:75], v[76:77]
	v_mov_b32_e32 v76, v12
	v_mov_b32_e32 v77, v8
	v_pk_mul_f32 v[94:95], v[94:95], v[94:95]
	s_nop 0
	v_pk_fma_f32 v[76:77], v[76:77], v[76:77], v[94:95]
	v_pk_mul_f32 v[94:95], v[2:3], v[2:3]
	v_pk_add_f32 v[74:75], v[74:75], v[76:77]
	v_pk_mul_f32 v[76:77], v[4:5], v[4:5]
	v_pk_add_f32 v[74:75], v[74:75], v[74:75] op_sel:[0,1] op_sel_hi:[1,0]
	v_pk_mov_b32 v[96:97], v[94:95], v[76:77] op_sel:[1,0]
	v_mov_b32_e32 v95, v77
	v_pk_add_f32 v[76:77], v[96:97], v[94:95]
	v_mul_f32_e32 v94, v23, v23
	v_pk_add_f32 v[76:77], v[76:77], v[76:77] op_sel:[0,1] op_sel_hi:[1,0]
	v_mov_b32_e32 v75, v18
	v_mov_b32_e32 v77, v94
	v_mul_f32_e32 v18, v15, v15
	v_mul_f32_e32 v95, v24, v24
	v_pk_add_f32 v[74:75], v[74:75], v[76:77]
	v_pk_fma_f32 v[76:77], v[14:15], v[14:15], v[18:19] op_sel_hi:[1,1,0]
	v_mul_f32_e32 v18, v17, v17
	v_mul_f32_e32 v96, v25, v25
	v_mov_b32_e32 v77, v95
	v_pk_fma_f32 v[94:95], v[16:17], v[16:17], v[18:19] op_sel_hi:[1,1,0]
	v_mul_f32_e32 v18, v30, v30
	v_mov_b32_e32 v95, v96
	v_pk_add_f32 v[76:77], v[76:77], v[94:95]
	v_pk_mul_f32 v[94:95], v[26:27], v[26:27]
	v_pk_add_f32 v[74:75], v[74:75], v[76:77]
	v_pk_mul_f32 v[76:77], v[28:29], v[28:29]
	v_pk_add_f32 v[74:75], v[74:75], v[74:75] op_sel:[0,1] op_sel_hi:[1,0]
	v_pk_mov_b32 v[96:97], v[94:95], v[76:77] op_sel:[1,0]
	v_mov_b32_e32 v95, v77
	v_pk_add_f32 v[76:77], v[96:97], v[94:95]
	v_mul_f32_e32 v94, v31, v31
	v_pk_add_f32 v[76:77], v[76:77], v[76:77] op_sel:[0,1] op_sel_hi:[1,0]
	v_mov_b32_e32 v75, v18
	v_mov_b32_e32 v77, v94
	v_mul_f32_e32 v18, v35, v35
	v_mul_f32_e32 v95, v32, v32
	v_pk_add_f32 v[74:75], v[74:75], v[76:77]
	v_pk_fma_f32 v[76:77], v[34:35], v[34:35], v[18:19] op_sel_hi:[1,1,0]
	v_mul_f32_e32 v18, v37, v37
	v_mul_f32_e32 v96, v33, v33
	v_mov_b32_e32 v77, v95
	v_pk_fma_f32 v[94:95], v[36:37], v[36:37], v[18:19] op_sel_hi:[1,1,0]
	v_and_b32_e32 v18, 64, v213
	v_mov_b32_e32 v95, v96
	v_pk_add_f32 v[76:77], v[76:77], v[94:95]
	s_nop 0
	v_pk_add_f32 v[74:75], v[74:75], v[76:77]
	s_nop 0
	v_add_f32_e32 v74, v74, v75
	v_add_u32_e32 v75, 64, v18
	v_xor_b32_e32 v18, 1, v213
	v_cmp_lt_i32_e32 vcc, v18, v75
	s_nop 1
	v_cndmask_b32_e32 v18, v213, v18, vcc
	v_lshlrev_b32_e32 v18, 2, v18
	ds_bpermute_b32 v76, v18, v74
	s_waitcnt lgkmcnt(0)
	v_add_f32_e32 v74, v74, v76
	v_xor_b32_e32 v76, 2, v213
	v_cmp_lt_i32_e32 vcc, v76, v75
	s_nop 1
	v_cndmask_b32_e32 v76, v213, v76, vcc
	v_lshlrev_b32_e32 v155, 2, v76
	ds_bpermute_b32 v76, v155, v74
	s_waitcnt lgkmcnt(0)
	v_add_f32_e32 v74, v74, v76
	v_xor_b32_e32 v76, 4, v213
	v_cmp_lt_i32_e32 vcc, v76, v75
	s_nop 1
	v_cndmask_b32_e32 v76, v213, v76, vcc
	v_lshlrev_b32_e32 v156, 2, v76
	ds_bpermute_b32 v76, v156, v74
	s_waitcnt lgkmcnt(0)
	v_add_f32_e32 v74, v74, v76
	v_xor_b32_e32 v76, 8, v213
	v_cmp_lt_i32_e32 vcc, v76, v75
	s_nop 1
	v_cndmask_b32_e32 v76, v213, v76, vcc
	v_lshlrev_b32_e32 v157, 2, v76
	ds_bpermute_b32 v76, v157, v74
	s_waitcnt lgkmcnt(0)
	v_add_f32_e32 v74, v74, v76
	v_xor_b32_e32 v76, 16, v213
	v_cmp_lt_i32_e32 vcc, v76, v75
	s_nop 1
	v_cndmask_b32_e32 v76, v213, v76, vcc
	v_lshlrev_b32_e32 v158, 2, v76
	ds_bpermute_b32 v76, v158, v74
	s_waitcnt lgkmcnt(0)
	v_add_f32_e32 v74, v74, v76
	v_xor_b32_e32 v76, 32, v213
	v_cmp_lt_i32_e32 vcc, v76, v75
	s_nop 1
	v_cndmask_b32_e32 v75, v213, v76, vcc
	v_lshlrev_b32_e32 v159, 2, v75
	ds_bpermute_b32 v75, v159, v74
	s_waitcnt lgkmcnt(0)
	v_add_f32_e32 v74, v74, v75
	v_fmamk_f32 v74, v74, 0x3a000000, v165
	v_rsq_f32_e32 v144, v74
	s_nop 0
	v_pk_mul_f32 v[34:35], v[34:35], v[144:145] op_sel_hi:[1,0]
	s_nop 0
	v_pk_fma_f32 v[96:97], v[72:73], v[34:35], v[38:39]
	v_pk_mul_f32 v[34:35], v[36:37], v[144:145] op_sel_hi:[1,0]
	v_pk_mul_f32 v[122:123], v[30:31], v[144:145] op_sel_hi:[1,0]
	v_pk_fma_f32 v[94:95], v[70:71], v[34:35], v[40:41]
	v_bfe_u32 v34, v96, 16, 1
	v_add3_u32 v34, v96, v34, s79
	v_bfe_u32 v35, v97, 16, 1
	v_lshrrev_b32_e32 v34, 16, v34
	v_add3_u32 v35, v97, v35, s79
	v_and_or_b32 v34, v35, s80, v34
	v_bfe_u32 v35, v94, 16, 1
	v_add3_u32 v35, v94, v35, s79
	v_bfe_u32 v36, v95, 16, 1
	v_lshrrev_b32_e32 v35, 16, v35
	v_add3_u32 v36, v95, v36, s79
	v_and_or_b32 v35, v36, s80, v35
	v_subrev_u32_e32 v248, s30, v160
	v_add_u32_e32 v248, 0xe8400000, v248
	v_and_b32_e32 v249, 0xfff00000, v248
	v_lshrrev_b32_e32 v218, 5, v248
	v_and_b32_e32 v218, 0x7800, v218
	v_or_b32_e32 v249, v249, v218
	v_lshrrev_b32_e32 v218, 6, v248
	v_and_b32_e32 v218, 0x3c0, v218
	v_or_b32_e32 v249, v249, v218
	v_and_b32_e32 v218, 0x180, v248
	v_lshlrev_b32_e32 v218, 8, v218
	v_or_b32_e32 v249, v249, v218
	v_and_b32_e32 v218, 64, v248
	v_lshlrev_b32_e32 v218, 4, v218
	v_or_b32_e32 v249, v249, v218
	v_and_b32_e32 v218, 56, v248
	v_or_b32_e32 v249, v249, v218
	v_lshrrev_b32_e32 v218, 10, v248
	v_and_b32_e32 v218, 32, v218
	v_xor_b32_e32 v249, v249, v218
	v_sub_u32_e32 v218, v249, v248
	v_ashrrev_i32_e32 v219, 31, v218
	v_lshl_add_u64 v[160:161], v[160:161], 0, v[218:219]
	s_mov_b64 s[100:101], 0xc0000
	v_lshl_add_u64 v[248:249], v[160:161], 0, s[100:101]
	global_store_dwordx2 v[248:249], v[34:35], off
	v_pk_mul_f32 v[124:125], v[32:33], v[144:145] op_sel_hi:[1,0]
	ds_read_b128 v[132:135], v153
	ds_read_b128 v[136:139], v153 offset:1024
	ds_read_b128 v[140:143], v153 offset:2048
	ds_read_b128 v[74:77], v153 offset:3072
	ds_read_b128 v[70:73], v153 offset:4096
	ds_read_b128 v[38:41], v153 offset:5120
	ds_read_b128 v[34:37], v153 offset:6144
	ds_read_b128 v[30:33], v153 offset:7168
	v_pk_mul_f32 v[14:15], v[14:15], v[144:145] op_sel_hi:[1,0]
	v_pk_mul_f32 v[10:11], v[10:11], v[144:145] op_sel_hi:[1,0]
	v_pk_mul_f32 v[6:7], v[6:7], v[144:145] op_sel_hi:[1,0]
	v_pk_mul_f32 v[2:3], v[2:3], v[144:145] op_sel_hi:[1,0]
	s_waitcnt vmcnt(1)
	v_pk_fma_f32 v[100:101], v[100:101], v[122:123], v[66:67]
	v_pk_fma_f32 v[98:99], v[98:99], v[124:125], v[68:69]
	v_pk_mul_f32 v[28:29], v[28:29], v[144:145] op_sel_hi:[1,0]
	v_pk_fma_f32 v[110:111], v[110:111], v[14:15], v[54:55]
	v_pk_mul_f32 v[14:15], v[16:17], v[144:145] op_sel_hi:[1,0]
	v_pk_fma_f32 v[124:125], v[114:115], v[10:11], v[42:43]
	v_pk_mul_f32 v[10:11], v[12:13], v[144:145] op_sel_hi:[1,0]
	v_pk_fma_f32 v[126:127], v[118:119], v[6:7], v[46:47]
	v_pk_mul_f32 v[6:7], v[8:9], v[144:145] op_sel_hi:[1,0]
	v_pk_fma_f32 v[118:119], v[130:131], v[2:3], v[50:51]
	v_pk_mul_f32 v[2:3], v[4:5], v[144:145] op_sel_hi:[1,0]
	v_bfe_u32 v66, v100, 16, 1
	v_pk_fma_f32 v[28:29], v[120:121], v[28:29], v[64:65]
	v_pk_fma_f32 v[108:109], v[108:109], v[14:15], v[56:57]
	v_bfe_u32 v14, v110, 16, 1
	v_pk_fma_f32 v[120:121], v[20:21], v[10:11], v[44:45]
	v_bfe_u32 v10, v124, 16, 1
	v_pk_fma_f32 v[122:123], v[116:117], v[6:7], v[48:49]
	v_bfe_u32 v6, v126, 16, 1
	v_pk_fma_f32 v[114:115], v[128:129], v[2:3], v[52:53]
	v_bfe_u32 v2, v118, 16, 1
	v_add3_u32 v66, v100, v66, s79
	v_bfe_u32 v67, v101, 16, 1
	v_pk_mul_f32 v[26:27], v[26:27], v[144:145] op_sel_hi:[1,0]
	v_pk_mul_f32 v[24:25], v[24:25], v[144:145] op_sel_hi:[1,0]
	v_pk_mul_f32 v[22:23], v[22:23], v[144:145] op_sel_hi:[1,0]
	v_add3_u32 v14, v110, v14, s79
	v_bfe_u32 v15, v111, 16, 1
	v_add3_u32 v10, v124, v10, s79
	v_bfe_u32 v11, v125, 16, 1
	v_add3_u32 v6, v126, v6, s79
	v_bfe_u32 v7, v127, 16, 1
	v_add3_u32 v2, v118, v2, s79
	v_bfe_u32 v3, v119, 16, 1
	v_lshrrev_b32_e32 v66, 16, v66
	v_add3_u32 v67, v101, v67, s79
	v_pk_fma_f32 v[102:103], v[102:103], v[26:27], v[62:63]
	v_pk_fma_f32 v[104:105], v[104:105], v[24:25], v[60:61]
	v_pk_fma_f32 v[106:107], v[106:107], v[22:23], v[58:59]
	v_lshrrev_b32_e32 v14, 16, v14
	v_add3_u32 v15, v111, v15, s79
	v_lshrrev_b32_e32 v10, 16, v10
	v_add3_u32 v11, v125, v11, s79
	v_lshrrev_b32_e32 v6, 16, v6
	v_add3_u32 v7, v127, v7, s79
	v_lshrrev_b32_e32 v2, 16, v2
	v_add3_u32 v3, v119, v3, s79
	v_and_or_b32 v66, v67, s80, v66
	v_bfe_u32 v67, v98, 16, 1
	v_bfe_u32 v64, v28, 16, 1
	v_bfe_u32 v26, v102, 16, 1
	v_bfe_u32 v24, v104, 16, 1
	v_bfe_u32 v22, v106, 16, 1
	v_and_or_b32 v14, v15, s80, v14
	v_bfe_u32 v15, v108, 16, 1
	v_and_or_b32 v10, v11, s80, v10
	v_bfe_u32 v11, v120, 16, 1
	v_and_or_b32 v6, v7, s80, v6
	v_bfe_u32 v7, v122, 16, 1
	v_and_or_b32 v2, v3, s80, v2
	v_bfe_u32 v3, v114, 16, 1
	v_add3_u32 v67, v98, v67, s79
	v_bfe_u32 v68, v99, 16, 1
	v_add3_u32 v64, v28, v64, s79
	v_bfe_u32 v65, v29, 16, 1
	v_add3_u32 v26, v102, v26, s79
	v_bfe_u32 v27, v103, 16, 1
	v_add3_u32 v24, v104, v24, s79
	v_bfe_u32 v25, v105, 16, 1
	v_add3_u32 v22, v106, v22, s79
	v_bfe_u32 v23, v107, 16, 1
	v_add3_u32 v15, v108, v15, s79
	v_bfe_u32 v16, v109, 16, 1
	v_add3_u32 v11, v120, v11, s79
	v_bfe_u32 v12, v121, 16, 1
	v_add3_u32 v7, v122, v7, s79
	v_bfe_u32 v8, v123, 16, 1
	v_add3_u32 v3, v114, v3, s79
	v_bfe_u32 v4, v115, 16, 1
	v_lshrrev_b32_e32 v67, 16, v67
	v_add3_u32 v68, v99, v68, s79
	v_lshrrev_b32_e32 v64, 16, v64
	v_add3_u32 v65, v29, v65, s79
	v_lshrrev_b32_e32 v26, 16, v26
	v_add3_u32 v27, v103, v27, s79
	v_lshrrev_b32_e32 v24, 16, v24
	v_add3_u32 v25, v105, v25, s79
	v_lshrrev_b32_e32 v22, 16, v22
	v_add3_u32 v23, v107, v23, s79
	v_lshrrev_b32_e32 v15, 16, v15
	v_add3_u32 v16, v109, v16, s79
	v_lshrrev_b32_e32 v11, 16, v11
	v_add3_u32 v12, v121, v12, s79
	v_lshrrev_b32_e32 v7, 16, v7
	v_add3_u32 v8, v123, v8, s79
	v_lshrrev_b32_e32 v3, 16, v3
	v_add3_u32 v4, v115, v4, s79
	v_and_or_b32 v67, v68, s80, v67
	v_and_or_b32 v65, v65, s80, v64
	v_and_or_b32 v64, v27, s80, v26
	v_and_or_b32 v25, v25, s80, v24
	v_and_or_b32 v24, v23, s80, v22
	v_and_or_b32 v15, v16, s80, v15
	v_and_or_b32 v11, v12, s80, v11
	v_and_or_b32 v7, v8, s80, v7
	v_and_or_b32 v3, v4, s80, v3
	s_mov_b64 s[100:101], 0xe0000
	v_lshl_add_u64 v[248:249], v[160:161], 0, s[100:101]
	global_store_dwordx2 v[248:249], v[66:67], off
	s_mov_b64 s[100:101], 0xa0000
	v_lshl_add_u64 v[248:249], v[160:161], 0, s[100:101]
	global_store_dwordx2 v[248:249], v[64:65], off
	s_mov_b64 s[100:101], 0x80000
	v_lshl_add_u64 v[248:249], v[160:161], 0, s[100:101]
	global_store_dwordx2 v[248:249], v[24:25], off
	s_mov_b64 s[100:101], 0x60000
	v_lshl_add_u64 v[248:249], v[160:161], 0, s[100:101]
	global_store_dwordx2 v[248:249], v[14:15], off
	global_store_dwordx2 v[160:161], v[10:11], off
	s_mov_b64 s[100:101], 0x20000
	v_lshl_add_u64 v[248:249], v[160:161], 0, s[100:101]
	global_store_dwordx2 v[248:249], v[6:7], off
	s_mov_b64 s[100:101], 0x40000
	v_lshl_add_u64 v[248:249], v[160:161], 0, s[100:101]
	global_store_dwordx2 v[248:249], v[2:3], off
	ds_read_b128 v[2:5], v153 offset:8192
	ds_read_b128 v[6:9], v153 offset:9216
	ds_read_b128 v[10:13], v153 offset:10240
	s_waitcnt lgkmcnt(10)
	v_mov_b32_e32 v15, v133
	s_waitcnt lgkmcnt(5)
	v_mov_b32_e32 v131, v41
	s_waitcnt lgkmcnt(2)
	v_mov_b32_e32 v14, v2
	v_pk_mov_b32 v[2:3], v[2:3], v[132:133] op_sel:[1,0]
	v_pk_mul_f32 v[14:15], v[124:125], v[14:15]
	v_mov_b32_e32 v133, v39
	v_pk_fma_f32 v[2:3], v[124:125], v[2:3], v[14:15] op_sel:[1,0,0] op_sel_hi:[0,1,1]
	v_mov_b32_e32 v14, v4
	v_mov_b32_e32 v15, v135
	v_pk_mul_f32 v[14:15], v[120:121], v[14:15]
	v_pk_mov_b32 v[4:5], v[4:5], v[134:135] op_sel:[1,0]
	ds_read_b128 v[20:23], v153 offset:13312
	v_pk_fma_f32 v[4:5], v[120:121], v[4:5], v[14:15] op_sel:[1,0,0] op_sel_hi:[0,1,1]
	v_pk_add_f32 v[2:3], v[2:3], v[4:5]
	s_waitcnt lgkmcnt(2)
	v_mov_b32_e32 v4, v6
	v_mov_b32_e32 v5, v137
	v_pk_mul_f32 v[4:5], v[126:127], v[4:5]
	v_pk_mov_b32 v[6:7], v[6:7], v[136:137] op_sel:[1,0]
	v_pk_add_f32 v[2:3], v[2:3], 0 op_sel_hi:[1,0]
	v_pk_fma_f32 v[4:5], v[126:127], v[6:7], v[4:5] op_sel:[1,0,0] op_sel_hi:[0,1,1]
	v_mov_b32_e32 v6, v8
	v_mov_b32_e32 v7, v139
	v_pk_mul_f32 v[6:7], v[122:123], v[6:7]
	v_pk_mov_b32 v[8:9], v[8:9], v[138:139] op_sel:[1,0]
	s_waitcnt lgkmcnt(0)
	v_mov_b32_e32 v132, v20
	v_pk_fma_f32 v[6:7], v[122:123], v[8:9], v[6:7] op_sel:[1,0,0] op_sel_hi:[0,1,1]
	v_pk_add_f32 v[4:5], v[4:5], v[6:7]
	v_mov_b32_e32 v8, v10
	v_mov_b32_e32 v9, v141
	v_pk_add_f32 v[6:7], v[2:3], v[4:5]
	ds_read_b128 v[2:5], v153 offset:11264
	v_pk_mul_f32 v[8:9], v[118:119], v[8:9]
	v_pk_mov_b32 v[10:11], v[10:11], v[140:141] op_sel:[1,0]
	v_mov_b32_e32 v130, v22
	v_pk_fma_f32 v[8:9], v[118:119], v[10:11], v[8:9] op_sel:[1,0,0] op_sel_hi:[0,1,1]
	v_mov_b32_e32 v10, v12
	v_mov_b32_e32 v11, v143
	v_pk_mul_f32 v[10:11], v[114:115], v[10:11]
	v_pk_mov_b32 v[12:13], v[12:13], v[142:143] op_sel:[1,0]
	s_nop 0
	v_pk_fma_f32 v[10:11], v[114:115], v[12:13], v[10:11] op_sel:[1,0,0] op_sel_hi:[0,1,1]
	v_pk_add_f32 v[8:9], v[8:9], v[10:11]
	s_nop 0
	v_pk_add_f32 v[116:117], v[6:7], v[8:9]
	s_waitcnt lgkmcnt(0)
	v_mov_b32_e32 v6, v2
	v_mov_b32_e32 v7, v75
	v_pk_mul_f32 v[6:7], v[110:111], v[6:7]
	v_pk_mov_b32 v[2:3], v[2:3], v[74:75] op_sel:[1,0]
	s_nop 0
	v_pk_fma_f32 v[2:3], v[110:111], v[2:3], v[6:7] op_sel:[1,0,0] op_sel_hi:[0,1,1]
	v_mov_b32_e32 v6, v4
	v_mov_b32_e32 v7, v77
	v_pk_mul_f32 v[10:11], v[108:109], v[6:7]
	ds_read_b128 v[6:9], v153 offset:12288
	v_pk_mov_b32 v[4:5], v[4:5], v[76:77] op_sel:[1,0]
	ds_read_b128 v[24:27], v153 offset:14336
	ds_read_b128 v[14:17], v153 offset:15360
	v_pk_fma_f32 v[4:5], v[108:109], v[4:5], v[10:11] op_sel:[1,0,0] op_sel_hi:[0,1,1]
	v_pk_add_f32 v[74:75], v[2:3], v[4:5]
	s_waitcnt lgkmcnt(2)
	v_mov_b32_e32 v2, v6
	v_mov_b32_e32 v3, v71
	v_pk_mul_f32 v[2:3], v[106:107], v[2:3]
	v_pk_mov_b32 v[4:5], v[6:7], v[70:71] op_sel:[1,0]
	s_nop 0
	v_pk_fma_f32 v[76:77], v[106:107], v[4:5], v[2:3] op_sel:[1,0,0] op_sel_hi:[0,1,1]
	v_mov_b32_e32 v2, v8
	v_mov_b32_e32 v3, v73
	v_pk_mul_f32 v[2:3], v[104:105], v[2:3]
	v_pk_mov_b32 v[4:5], v[8:9], v[72:73] op_sel:[1,0]
	s_nop 0
	v_pk_fma_f32 v[128:129], v[104:105], v[4:5], v[2:3] op_sel:[1,0,0] op_sel_hi:[0,1,1]
	ds_read_b128 v[42:45], v153 offset:16384
	ds_read_b128 v[46:49], v153 offset:17408
	ds_read_b128 v[50:53], v153 offset:18432
	ds_read_b128 v[54:57], v153 offset:19456
	ds_read_b128 v[58:61], v153 offset:20480
	ds_read_b128 v[10:13], v153 offset:21504
	ds_read_b128 v[6:9], v153 offset:22528
	ds_read_b128 v[2:5], v153 offset:23552
	ds_read_b128 v[62:65], v153 offset:24576
	ds_read_b128 v[66:69], v153 offset:25600
	ds_read_b128 v[70:73], v153 offset:26624
	s_waitcnt lgkmcnt(10)
	v_mov_b32_e32 v135, v43
	s_waitcnt lgkmcnt(5)
	v_mov_b32_e32 v145, v11
	s_waitcnt lgkmcnt(2)
	v_mov_b32_e32 v134, v62
	v_pk_mov_b32 v[42:43], v[62:63], v[42:43] op_sel:[1,0]
	v_pk_mul_f32 v[62:63], v[124:125], v[134:135]
	v_mov_b32_e32 v143, v13
	v_pk_fma_f32 v[42:43], v[124:125], v[42:43], v[62:63] op_sel:[1,0,0] op_sel_hi:[0,1,1]
	v_mov_b32_e32 v62, v64
	v_mov_b32_e32 v63, v45
	v_pk_mul_f32 v[62:63], v[120:121], v[62:63]
	v_pk_mov_b32 v[44:45], v[64:65], v[44:45] op_sel:[1,0]
	s_nop 0
	v_pk_fma_f32 v[44:45], v[120:121], v[44:45], v[62:63] op_sel:[1,0,0] op_sel_hi:[0,1,1]
	v_pk_add_f32 v[42:43], v[42:43], v[44:45]
	s_waitcnt lgkmcnt(1)
	v_mov_b32_e32 v44, v66
	v_mov_b32_e32 v45, v47
	v_pk_mul_f32 v[44:45], v[126:127], v[44:45]
	v_pk_mov_b32 v[46:47], v[66:67], v[46:47] op_sel:[1,0]
	v_pk_add_f32 v[42:43], v[42:43], 0 op_sel_hi:[1,0]
	v_pk_fma_f32 v[44:45], v[126:127], v[46:47], v[44:45] op_sel:[1,0,0] op_sel_hi:[0,1,1]
	v_mov_b32_e32 v46, v68
	v_mov_b32_e32 v47, v49
	v_pk_mul_f32 v[46:47], v[122:123], v[46:47]
	v_pk_mov_b32 v[48:49], v[68:69], v[48:49] op_sel:[1,0]
	s_nop 0
	v_pk_fma_f32 v[46:47], v[122:123], v[48:49], v[46:47] op_sel:[1,0,0] op_sel_hi:[0,1,1]
	v_pk_add_f32 v[44:45], v[44:45], v[46:47]
	s_waitcnt lgkmcnt(0)
	v_mov_b32_e32 v48, v70
	v_mov_b32_e32 v49, v51
	v_pk_add_f32 v[46:47], v[42:43], v[44:45]
	ds_read_b128 v[42:45], v153 offset:27648
	v_pk_mul_f32 v[48:49], v[118:119], v[48:49]
	v_pk_mov_b32 v[50:51], v[70:71], v[50:51] op_sel:[1,0]
	s_nop 0
	v_pk_fma_f32 v[48:49], v[118:119], v[50:51], v[48:49] op_sel:[1,0,0] op_sel_hi:[0,1,1]
	v_mov_b32_e32 v50, v72
	v_mov_b32_e32 v51, v53
	v_pk_mul_f32 v[50:51], v[114:115], v[50:51]
	v_pk_mov_b32 v[52:53], v[72:73], v[52:53] op_sel:[1,0]
	s_nop 0
	v_pk_fma_f32 v[50:51], v[114:115], v[52:53], v[50:51] op_sel:[1,0,0] op_sel_hi:[0,1,1]
	v_pk_add_f32 v[48:49], v[48:49], v[50:51]
	ds_read_b128 v[50:53], v153 offset:28672
	v_pk_add_f32 v[134:135], v[46:47], v[48:49]
	s_waitcnt lgkmcnt(1)
	v_mov_b32_e32 v46, v42
	v_mov_b32_e32 v47, v55
	v_pk_mul_f32 v[46:47], v[110:111], v[46:47]
	v_pk_mov_b32 v[42:43], v[42:43], v[54:55] op_sel:[1,0]
	s_nop 0
	v_pk_fma_f32 v[42:43], v[110:111], v[42:43], v[46:47] op_sel:[1,0,0] op_sel_hi:[0,1,1]
	v_mov_b32_e32 v46, v44
	v_mov_b32_e32 v47, v57
	v_pk_mul_f32 v[46:47], v[108:109], v[46:47]
	v_pk_mov_b32 v[44:45], v[44:45], v[56:57] op_sel:[1,0]
	s_nop 0
	v_pk_fma_f32 v[44:45], v[108:109], v[44:45], v[46:47] op_sel:[1,0,0] op_sel_hi:[0,1,1]
	v_pk_add_f32 v[136:137], v[42:43], v[44:45]
	s_waitcnt lgkmcnt(0)
	v_mov_b32_e32 v42, v50
	v_mov_b32_e32 v43, v59
	v_pk_mul_f32 v[42:43], v[106:107], v[42:43]
	v_pk_mov_b32 v[44:45], v[50:51], v[58:59] op_sel:[1,0]
	ds_read_b128 v[46:49], v153 offset:29696
	v_pk_fma_f32 v[138:139], v[106:107], v[44:45], v[42:43] op_sel:[1,0,0] op_sel_hi:[0,1,1]
	v_mov_b32_e32 v42, v52
	v_mov_b32_e32 v43, v61
	v_pk_mul_f32 v[42:43], v[104:105], v[42:43]
	v_pk_mov_b32 v[44:45], v[52:53], v[60:61] op_sel:[1,0]
	s_waitcnt lgkmcnt(0)
	v_mov_b32_e32 v144, v46
	v_pk_fma_f32 v[140:141], v[104:105], v[44:45], v[42:43] op_sel:[1,0,0] op_sel_hi:[0,1,1]
	ds_read_b128 v[50:53], v153 offset:30720
	ds_read_b128 v[42:45], v153 offset:31744
	v_mov_b32_e32 v142, v48
	ds_read_b128 v[160:163], v153 offset:32768
	ds_read_b128 v[170:173], v153 offset:33792
	ds_read_b128 v[174:177], v153 offset:34816
	ds_read_b128 v[70:73], v153 offset:35840
	ds_read_b128 v[66:69], v153 offset:36864
	ds_read_b128 v[62:65], v153 offset:37888
	ds_read_b128 v[58:61], v153 offset:38912
	ds_read_b128 v[54:57], v153 offset:39936
	ds_read_b128 v[178:181], v153 offset:40960
	s_waitcnt lgkmcnt(0)
	v_pk_mov_b32 v[182:183], v[160:161], v[178:179] op_sel:[1,0]
	v_mov_b32_e32 v161, v179
	v_pk_mov_b32 v[178:179], v[162:163], v[180:181] op_sel:[1,0]
	v_pk_mul_f32 v[182:183], v[124:125], v[182:183] op_sel:[1,0] op_sel_hi:[0,1]
	v_pk_mul_f32 v[178:179], v[120:121], v[178:179] op_sel:[1,0] op_sel_hi:[0,1]
	v_mov_b32_e32 v163, v181
	v_pk_fma_f32 v[160:161], v[124:125], v[160:161], v[182:183]
	v_pk_fma_f32 v[162:163], v[120:121], v[162:163], v[178:179]
	s_nop 0
	v_pk_add_f32 v[160:161], v[160:161], v[162:163]
	s_nop 0
	v_pk_add_f32 v[178:179], v[160:161], 0 op_sel_hi:[1,0]
	ds_read_b128 v[160:163], v153 offset:41984
	s_waitcnt lgkmcnt(0)
	v_pk_mov_b32 v[180:181], v[170:171], v[160:161] op_sel:[1,0]
	s_nop 0
	v_pk_mul_f32 v[180:181], v[126:127], v[180:181] op_sel:[1,0] op_sel_hi:[0,1]
	v_mov_b32_e32 v171, v161
	v_pk_fma_f32 v[160:161], v[126:127], v[170:171], v[180:181]
	v_pk_mov_b32 v[170:171], v[172:173], v[162:163] op_sel:[1,0]
	v_mov_b32_e32 v173, v163
	v_pk_mul_f32 v[170:171], v[122:123], v[170:171] op_sel:[1,0] op_sel_hi:[0,1]
	v_pk_fma_f32 v[162:163], v[122:123], v[172:173], v[170:171]
	s_nop 0
	v_pk_add_f32 v[160:161], v[160:161], v[162:163]
	s_nop 0
	v_pk_add_f32 v[170:171], v[178:179], v[160:161]
	ds_read_b128 v[160:163], v153 offset:43008
	s_waitcnt lgkmcnt(0)
	v_pk_mov_b32 v[172:173], v[174:175], v[160:161] op_sel:[1,0]
	s_nop 0
	v_pk_mul_f32 v[172:173], v[118:119], v[172:173] op_sel:[1,0] op_sel_hi:[0,1]
	v_mov_b32_e32 v175, v161
	v_pk_fma_f32 v[160:161], v[118:119], v[174:175], v[172:173]
	v_pk_mov_b32 v[172:173], v[176:177], v[162:163] op_sel:[1,0]
	v_mov_b32_e32 v177, v163
	v_pk_mul_f32 v[172:173], v[114:115], v[172:173] op_sel:[1,0] op_sel_hi:[0,1]
	v_pk_fma_f32 v[162:163], v[114:115], v[176:177], v[172:173]
	s_nop 0
	v_pk_add_f32 v[160:161], v[160:161], v[162:163]
	s_nop 0
	v_pk_add_f32 v[170:171], v[170:171], v[160:161]
	ds_read_b128 v[160:163], v153 offset:44032
	s_waitcnt lgkmcnt(0)
	v_pk_mov_b32 v[172:173], v[70:71], v[160:161] op_sel:[1,0]
	v_mov_b32_e32 v71, v161
	v_pk_mov_b32 v[160:161], v[72:73], v[162:163] op_sel:[1,0]
	v_pk_mul_f32 v[172:173], v[110:111], v[172:173] op_sel:[1,0] op_sel_hi:[0,1]
	v_pk_mul_f32 v[160:161], v[108:109], v[160:161] op_sel:[1,0] op_sel_hi:[0,1]
	v_mov_b32_e32 v73, v163
	v_pk_fma_f32 v[70:71], v[110:111], v[70:71], v[172:173]
	v_pk_fma_f32 v[72:73], v[108:109], v[72:73], v[160:161]
	s_nop 0
	v_pk_add_f32 v[70:71], v[70:71], v[72:73]
	s_nop 0
	v_pk_add_f32 v[160:161], v[170:171], v[70:71]
	ds_read_b128 v[70:73], v153 offset:45056
	s_waitcnt lgkmcnt(0)
	v_pk_mov_b32 v[162:163], v[66:67], v[70:71] op_sel:[1,0]
	v_mov_b32_e32 v67, v71
	v_pk_mov_b32 v[70:71], v[68:69], v[72:73] op_sel:[1,0]
	v_pk_mul_f32 v[162:163], v[106:107], v[162:163] op_sel:[1,0] op_sel_hi:[0,1]
	v_pk_mul_f32 v[70:71], v[104:105], v[70:71] op_sel:[1,0] op_sel_hi:[0,1]
	v_mov_b32_e32 v69, v73
	v_pk_fma_f32 v[66:67], v[106:107], v[66:67], v[162:163]
	v_pk_fma_f32 v[68:69], v[104:105], v[68:69], v[70:71]
	v_mov_b32_e32 v73, v63
	v_pk_add_f32 v[66:67], v[66:67], v[68:69]
	s_nop 0
	v_pk_add_f32 v[70:71], v[160:161], v[66:67]
	ds_read_b128 v[66:69], v153 offset:46080
	s_waitcnt lgkmcnt(0)
	v_pk_mov_b32 v[62:63], v[66:67], v[62:63] op_sel:[1,0]
	v_mov_b32_e32 v67, v65
	v_pk_mov_b32 v[64:65], v[68:69], v[64:65] op_sel:[1,0]
	v_mov_b32_e32 v72, v66
	v_pk_mul_f32 v[62:63], v[102:103], v[62:63] op_sel:[1,0] op_sel_hi:[0,1]
	v_mov_b32_e32 v66, v68
	v_pk_mul_f32 v[64:65], v[28:29], v[64:65] op_sel:[1,0] op_sel_hi:[0,1]
	v_pk_fma_f32 v[62:63], v[102:103], v[72:73], v[62:63]
	v_pk_fma_f32 v[64:65], v[28:29], v[66:67], v[64:65]
	v_mov_b32_e32 v69, v59
	v_pk_add_f32 v[62:63], v[62:63], v[64:65]
	s_nop 0
	v_pk_add_f32 v[66:67], v[70:71], v[62:63] op_sel:[1,0] op_sel_hi:[0,1]
	ds_read_b128 v[62:65], v153 offset:47104
	s_waitcnt lgkmcnt(0)
	v_pk_mov_b32 v[58:59], v[62:63], v[58:59] op_sel:[1,0]
	v_mov_b32_e32 v63, v61
	v_pk_mov_b32 v[60:61], v[64:65], v[60:61] op_sel:[1,0]
	v_mov_b32_e32 v68, v62
	v_pk_mul_f32 v[58:59], v[96:97], v[58:59] op_sel:[1,0] op_sel_hi:[0,1]
	v_mov_b32_e32 v62, v64
	v_pk_mul_f32 v[60:61], v[94:95], v[60:61] op_sel:[1,0] op_sel_hi:[0,1]
	v_pk_fma_f32 v[58:59], v[96:97], v[68:69], v[58:59]
	v_pk_fma_f32 v[60:61], v[94:95], v[62:63], v[60:61]
	v_mov_b32_e32 v65, v55
	v_pk_add_f32 v[58:59], v[58:59], v[60:61]
	s_nop 0
	v_pk_add_f32 v[62:63], v[66:67], v[58:59]
	ds_read_b128 v[58:61], v153 offset:48128
	s_waitcnt lgkmcnt(0)
	v_pk_mov_b32 v[54:55], v[58:59], v[54:55] op_sel:[1,0]
	v_mov_b32_e32 v59, v57
	v_pk_mov_b32 v[56:57], v[60:61], v[56:57] op_sel:[1,0]
	v_mov_b32_e32 v64, v58
	v_pk_mul_f32 v[54:55], v[100:101], v[54:55] op_sel:[1,0] op_sel_hi:[0,1]
	v_mov_b32_e32 v58, v60
	v_pk_mul_f32 v[56:57], v[98:99], v[56:57] op_sel:[1,0] op_sel_hi:[0,1]
	v_pk_fma_f32 v[54:55], v[100:101], v[64:65], v[54:55]
	v_pk_fma_f32 v[56:57], v[98:99], v[58:59], v[56:57]
	s_nop 0
	v_pk_add_f32 v[54:55], v[54:55], v[56:57]
	s_nop 0
	v_pk_add_f32 v[190:191], v[62:63], v[54:55]
	ds_read_b128 v[66:69], v153 offset:49152
	ds_read_b128 v[70:73], v153 offset:50176
	ds_read_b128 v[160:163], v153 offset:51200
	ds_read_b128 v[170:173], v153 offset:52224
	ds_read_b128 v[174:177], v153 offset:53248
	ds_read_b128 v[62:65], v153 offset:54272
	ds_read_b128 v[58:61], v153 offset:55296
	ds_read_b128 v[54:57], v153 offset:56320
	ds_read_b128 v[178:181], v153 offset:57344
	ds_read_b128 v[182:185], v153 offset:58368
	ds_read_b128 v[186:189], v153 offset:59392
	s_waitcnt lgkmcnt(10)
	v_mov_b32_e32 v193, v67
	s_waitcnt lgkmcnt(2)
	v_mov_b32_e32 v192, v178
	v_pk_mov_b32 v[66:67], v[178:179], v[66:67] op_sel:[1,0]
	v_pk_mul_f32 v[178:179], v[124:125], v[192:193]
	s_nop 0
	v_pk_fma_f32 v[66:67], v[124:125], v[66:67], v[178:179] op_sel:[1,0,0] op_sel_hi:[0,1,1]
	v_mov_b32_e32 v124, v180
	v_mov_b32_e32 v125, v69
	v_pk_mul_f32 v[124:125], v[120:121], v[124:125]
	v_pk_mov_b32 v[68:69], v[180:181], v[68:69] op_sel:[1,0]
	s_nop 0
	v_pk_fma_f32 v[68:69], v[120:121], v[68:69], v[124:125] op_sel:[1,0,0] op_sel_hi:[0,1,1]
	v_pk_add_f32 v[66:67], v[66:67], v[68:69]
	s_waitcnt lgkmcnt(1)
	v_mov_b32_e32 v68, v182
	v_mov_b32_e32 v69, v71
	v_pk_mul_f32 v[68:69], v[126:127], v[68:69]
	v_pk_mov_b32 v[70:71], v[182:183], v[70:71] op_sel:[1,0]
	v_pk_add_f32 v[66:67], v[66:67], 0 op_sel_hi:[1,0]
	v_pk_fma_f32 v[68:69], v[126:127], v[70:71], v[68:69] op_sel:[1,0,0] op_sel_hi:[0,1,1]
	v_mov_b32_e32 v70, v184
	v_mov_b32_e32 v71, v73
	v_pk_mul_f32 v[70:71], v[122:123], v[70:71]
	v_pk_mov_b32 v[72:73], v[184:185], v[72:73] op_sel:[1,0]
	s_waitcnt lgkmcnt(0)
	v_pk_mov_b32 v[120:121], v[186:187], v[160:161] op_sel:[1,0]
	v_pk_fma_f32 v[70:71], v[122:123], v[72:73], v[70:71] op_sel:[1,0,0] op_sel_hi:[0,1,1]
	v_pk_add_f32 v[68:69], v[68:69], v[70:71]
	v_mov_b32_e32 v72, v186
	v_mov_b32_e32 v73, v161
	v_pk_add_f32 v[66:67], v[66:67], v[68:69]
	ds_read_b128 v[68:71], v153 offset:60416
	v_pk_mul_f32 v[72:73], v[118:119], v[72:73]
	v_mov_b32_e32 v123, v65
	v_pk_fma_f32 v[72:73], v[118:119], v[120:121], v[72:73] op_sel:[1,0,0] op_sel_hi:[0,1,1]
	v_mov_b32_e32 v118, v188
	v_mov_b32_e32 v119, v163
	v_pk_mul_f32 v[118:119], v[114:115], v[118:119]
	v_pk_mov_b32 v[120:121], v[188:189], v[162:163] op_sel:[1,0]
	s_nop 0
	v_pk_fma_f32 v[114:115], v[114:115], v[120:121], v[118:119] op_sel:[1,0,0] op_sel_hi:[0,1,1]
	v_pk_add_f32 v[72:73], v[72:73], v[114:115]
	ds_read_b128 v[118:121], v153 offset:61440
	v_pk_add_f32 v[66:67], v[66:67], v[72:73]
	s_waitcnt lgkmcnt(1)
	v_mov_b32_e32 v72, v68
	v_mov_b32_e32 v73, v171
	v_pk_mul_f32 v[72:73], v[110:111], v[72:73]
	v_pk_mov_b32 v[68:69], v[68:69], v[170:171] op_sel:[1,0]
	s_nop 0
	v_pk_fma_f32 v[68:69], v[110:111], v[68:69], v[72:73] op_sel:[1,0,0] op_sel_hi:[0,1,1]
	v_mov_b32_e32 v72, v70
	v_mov_b32_e32 v73, v173
	v_pk_mul_f32 v[72:73], v[108:109], v[72:73]
	v_pk_mov_b32 v[70:71], v[70:71], v[172:173] op_sel:[1,0]
	s_waitcnt lgkmcnt(0)
	v_pk_mov_b32 v[110:111], v[118:119], v[174:175] op_sel:[1,0]
	v_pk_fma_f32 v[70:71], v[108:109], v[70:71], v[72:73] op_sel:[1,0,0] op_sel_hi:[0,1,1]
	v_mov_b32_e32 v108, v118
	v_mov_b32_e32 v109, v175
	v_pk_mul_f32 v[108:109], v[106:107], v[108:109]
	v_pk_add_f32 v[72:73], v[68:69], v[70:71]
	v_pk_fma_f32 v[114:115], v[106:107], v[110:111], v[108:109] op_sel:[1,0,0] op_sel_hi:[0,1,1]
	v_mov_b32_e32 v106, v120
	v_mov_b32_e32 v107, v177
	v_pk_mul_f32 v[106:107], v[104:105], v[106:107]
	v_pk_mov_b32 v[108:109], v[120:121], v[176:177] op_sel:[1,0]
	ds_read_b128 v[68:71], v153 offset:62464
	v_pk_fma_f32 v[118:119], v[104:105], v[108:109], v[106:107] op_sel:[1,0,0] op_sel_hi:[0,1,1]
	ds_read_b128 v[104:107], v153 offset:63488
	ds_read_b128 v[108:111], v153 offset:64512
	v_mov_b32_e32 v121, v63
	s_waitcnt lgkmcnt(2)
	v_mov_b32_e32 v120, v68
	v_mov_b32_e32 v122, v70
	v_pk_mov_b32 v[20:21], v[20:21], v[38:39] op_sel:[1,0]
	v_pk_mov_b32 v[22:23], v[22:23], v[40:41] op_sel:[1,0]
	v_pk_mul_f32 v[20:21], v[102:103], v[20:21] op_sel:[1,0] op_sel_hi:[0,1]
	v_pk_mul_f32 v[22:23], v[28:29], v[22:23] op_sel:[1,0] op_sel_hi:[0,1]
	v_pk_fma_f32 v[20:21], v[102:103], v[132:133], v[20:21]
	v_pk_fma_f32 v[22:23], v[28:29], v[130:131], v[22:23]
	v_pk_add_f32 v[74:75], v[116:117], v[74:75]
	v_pk_add_f32 v[20:21], v[20:21], v[22:23]
	v_mov_b32_e32 v22, v24
	v_pk_mov_b32 v[24:25], v[24:25], v[34:35] op_sel:[1,0]
	v_mov_b32_e32 v23, v35
	v_pk_mul_f32 v[24:25], v[96:97], v[24:25] op_sel:[1,0] op_sel_hi:[0,1]
	v_pk_fma_f32 v[22:23], v[96:97], v[22:23], v[24:25]
	v_mov_b32_e32 v24, v26
	v_pk_mov_b32 v[26:27], v[26:27], v[36:37] op_sel:[1,0]
	v_pk_add_f32 v[76:77], v[76:77], v[128:129]
	v_mov_b32_e32 v25, v37
	v_pk_mul_f32 v[26:27], v[94:95], v[26:27] op_sel:[1,0] op_sel_hi:[0,1]
	v_pk_add_f32 v[74:75], v[74:75], v[76:77]
	v_pk_fma_f32 v[24:25], v[94:95], v[24:25], v[26:27]
	v_pk_add_f32 v[20:21], v[74:75], v[20:21]
	v_pk_add_f32 v[22:23], v[22:23], v[24:25]
	v_pk_mov_b32 v[10:11], v[46:47], v[10:11] op_sel:[1,0]
	v_pk_add_f32 v[20:21], v[20:21], v[22:23]
	v_mov_b32_e32 v22, v14
	v_pk_mov_b32 v[14:15], v[14:15], v[30:31] op_sel:[1,0]
	v_mov_b32_e32 v23, v31
	v_pk_mul_f32 v[14:15], v[100:101], v[14:15] op_sel:[1,0] op_sel_hi:[0,1]
	v_pk_fma_f32 v[14:15], v[100:101], v[22:23], v[14:15]
	v_mov_b32_e32 v22, v16
	v_pk_mov_b32 v[16:17], v[16:17], v[32:33] op_sel:[1,0]
	v_mov_b32_e32 v23, v33
	v_pk_mul_f32 v[16:17], v[98:99], v[16:17] op_sel:[1,0] op_sel_hi:[0,1]
	v_pk_fma_f32 v[16:17], v[98:99], v[22:23], v[16:17]
	v_pk_mov_b32 v[12:13], v[48:49], v[12:13] op_sel:[1,0]
	v_pk_add_f32 v[14:15], v[14:15], v[16:17]
	v_pk_mul_f32 v[10:11], v[102:103], v[10:11] op_sel:[1,0] op_sel_hi:[0,1]
	v_pk_add_f32 v[14:15], v[20:21], v[14:15]
	ds_bpermute_b32 v17, v18, v15
	ds_bpermute_b32 v16, v18, v14
	v_pk_mul_f32 v[12:13], v[28:29], v[12:13] op_sel:[1,0] op_sel_hi:[0,1]
	v_pk_fma_f32 v[10:11], v[102:103], v[144:145], v[10:11]
	v_pk_fma_f32 v[12:13], v[28:29], v[142:143], v[12:13]
	v_pk_add_f32 v[24:25], v[134:135], v[136:137]
	s_waitcnt lgkmcnt(0)
	v_pk_add_f32 v[14:15], v[14:15], v[16:17]
	ds_bpermute_b32 v17, v155, v15
	ds_bpermute_b32 v16, v155, v14
	v_pk_add_f32 v[10:11], v[10:11], v[12:13]
	v_mov_b32_e32 v13, v7
	v_pk_mov_b32 v[6:7], v[50:51], v[6:7] op_sel:[1,0]
	v_mov_b32_e32 v12, v50
	v_pk_mul_f32 v[6:7], v[96:97], v[6:7] op_sel:[1,0] op_sel_hi:[0,1]
	v_pk_fma_f32 v[6:7], v[96:97], v[12:13], v[6:7]
	v_mov_b32_e32 v13, v9
	v_pk_mov_b32 v[8:9], v[52:53], v[8:9] op_sel:[1,0]
	v_mov_b32_e32 v12, v52
	v_pk_mul_f32 v[8:9], v[94:95], v[8:9] op_sel:[1,0] op_sel_hi:[0,1]
	v_pk_fma_f32 v[8:9], v[94:95], v[12:13], v[8:9]
	s_waitcnt lgkmcnt(0)
	v_pk_add_f32 v[14:15], v[14:15], v[16:17]
	v_pk_add_f32 v[6:7], v[6:7], v[8:9]
	v_mov_b32_e32 v9, v3
	v_pk_mov_b32 v[2:3], v[42:43], v[2:3] op_sel:[1,0]
	ds_bpermute_b32 v17, v156, v15
	ds_bpermute_b32 v16, v156, v14
	v_mov_b32_e32 v8, v42
	v_pk_mul_f32 v[2:3], v[100:101], v[2:3] op_sel:[1,0] op_sel_hi:[0,1]
	v_pk_add_f32 v[26:27], v[138:139], v[140:141]
	v_pk_fma_f32 v[2:3], v[100:101], v[8:9], v[2:3]
	v_mov_b32_e32 v9, v5
	v_pk_mov_b32 v[4:5], v[44:45], v[4:5] op_sel:[1,0]
	v_pk_add_f32 v[24:25], v[24:25], v[26:27]
	v_mov_b32_e32 v8, v44
	v_pk_mul_f32 v[4:5], v[98:99], v[4:5] op_sel:[1,0] op_sel_hi:[0,1]
	v_pk_add_f32 v[10:11], v[24:25], v[10:11]
	v_pk_fma_f32 v[4:5], v[98:99], v[8:9], v[4:5]
	v_pk_add_f32 v[6:7], v[10:11], v[6:7]
	v_pk_add_f32 v[2:3], v[2:3], v[4:5]
	v_pk_add_f32 v[8:9], v[66:67], v[72:73]
	v_pk_add_f32 v[12:13], v[114:115], v[118:119]
	v_pk_add_f32 v[2:3], v[6:7], v[2:3]
	s_waitcnt lgkmcnt(0)
	v_pk_add_f32 v[6:7], v[14:15], v[16:17]
	v_pk_add_f32 v[8:9], v[8:9], v[12:13]
	v_pk_mov_b32 v[12:13], v[68:69], v[62:63] op_sel:[1,0]
	v_pk_mov_b32 v[14:15], v[70:71], v[64:65] op_sel:[1,0]
	v_pk_mul_f32 v[12:13], v[102:103], v[12:13] op_sel:[1,0] op_sel_hi:[0,1]
	v_pk_mul_f32 v[14:15], v[28:29], v[14:15] op_sel:[1,0] op_sel_hi:[0,1]
	v_pk_fma_f32 v[12:13], v[102:103], v[120:121], v[12:13]
	v_pk_fma_f32 v[14:15], v[28:29], v[122:123], v[14:15]
	v_pk_mov_b32 v[16:17], v[106:107], v[60:61] op_sel:[1,0]
	v_pk_add_f32 v[12:13], v[12:13], v[14:15]
	v_pk_mov_b32 v[14:15], v[104:105], v[58:59] op_sel:[1,0]
	v_pk_add_f32 v[8:9], v[8:9], v[12:13]
	v_mov_b32_e32 v12, v104
	v_mov_b32_e32 v13, v59
	v_pk_mul_f32 v[14:15], v[96:97], v[14:15] op_sel:[1,0] op_sel_hi:[0,1]
	v_pk_fma_f32 v[12:13], v[96:97], v[12:13], v[14:15]
	v_mov_b32_e32 v14, v106
	v_mov_b32_e32 v15, v61
	v_pk_mul_f32 v[16:17], v[94:95], v[16:17] op_sel:[1,0] op_sel_hi:[0,1]
	v_pk_fma_f32 v[14:15], v[94:95], v[14:15], v[16:17]
	ds_bpermute_b32 v5, v18, v3
	ds_bpermute_b32 v4, v18, v2
	v_pk_add_f32 v[12:13], v[12:13], v[14:15]
	v_pk_mov_b32 v[14:15], v[108:109], v[54:55] op_sel:[1,0]
	v_pk_add_f32 v[8:9], v[8:9], v[12:13]
	v_mov_b32_e32 v12, v108
	v_mov_b32_e32 v13, v55
	v_pk_mul_f32 v[14:15], v[100:101], v[14:15] op_sel:[1,0] op_sel_hi:[0,1]
	v_pk_mov_b32 v[16:17], v[110:111], v[56:57] op_sel:[1,0]
	v_pk_fma_f32 v[12:13], v[100:101], v[12:13], v[14:15]
	v_mov_b32_e32 v14, v110
	v_mov_b32_e32 v15, v57
	v_pk_mul_f32 v[16:17], v[98:99], v[16:17] op_sel:[1,0] op_sel_hi:[0,1]
	v_pk_fma_f32 v[14:15], v[98:99], v[14:15], v[16:17]
	s_waitcnt lgkmcnt(0)
	v_pk_add_f32 v[2:3], v[2:3], v[4:5]
	v_pk_add_f32 v[12:13], v[12:13], v[14:15]
	ds_bpermute_b32 v125, v18, v191
	v_pk_add_f32 v[8:9], v[8:9], v[12:13]
	ds_bpermute_b32 v124, v18, v190
	ds_bpermute_b32 v5, v155, v3
	ds_bpermute_b32 v4, v155, v2
	ds_bpermute_b32 v13, v18, v9
	ds_bpermute_b32 v12, v18, v8
	s_waitcnt lgkmcnt(4)
	v_pk_add_f32 v[116:117], v[190:191], v[124:125]
	ds_bpermute_b32 v125, v155, v117
	s_waitcnt lgkmcnt(3)
	v_pk_add_f32 v[2:3], v[2:3], v[4:5]
	ds_bpermute_b32 v124, v155, v116
	s_waitcnt lgkmcnt(2)
	v_pk_add_f32 v[8:9], v[8:9], v[12:13]
	ds_bpermute_b32 v5, v156, v3
	ds_bpermute_b32 v4, v156, v2
	ds_bpermute_b32 v13, v155, v9
	ds_bpermute_b32 v12, v155, v8
	s_waitcnt lgkmcnt(4)
	v_pk_add_f32 v[20:21], v[116:117], v[124:125]
	ds_bpermute_b32 v23, v156, v21
	s_waitcnt lgkmcnt(3)
	v_pk_add_f32 v[2:3], v[2:3], v[4:5]
	ds_bpermute_b32 v22, v156, v20
	s_waitcnt lgkmcnt(2)
	v_pk_add_f32 v[8:9], v[8:9], v[12:13]
	ds_bpermute_b32 v5, v157, v3
	ds_bpermute_b32 v4, v157, v2
	ds_bpermute_b32 v13, v156, v9
	ds_bpermute_b32 v12, v156, v8
	s_waitcnt lgkmcnt(4)
	v_pk_add_f32 v[20:21], v[20:21], v[22:23]
	ds_bpermute_b32 v23, v157, v21
	s_waitcnt lgkmcnt(3)
	v_pk_add_f32 v[2:3], v[2:3], v[4:5]
	ds_bpermute_b32 v22, v157, v20
	s_waitcnt lgkmcnt(2)
	v_pk_add_f32 v[4:5], v[8:9], v[12:13]
	ds_bpermute_b32 v15, v157, v7
	ds_bpermute_b32 v14, v157, v6
	ds_bpermute_b32 v9, v157, v5
	ds_bpermute_b32 v8, v157, v4
	s_waitcnt lgkmcnt(4)
	v_pk_add_f32 v[10:11], v[20:21], v[22:23]
	ds_bpermute_b32 v13, v158, v3
	s_waitcnt lgkmcnt(3)
	v_pk_add_f32 v[6:7], v[6:7], v[14:15]
	ds_bpermute_b32 v15, v158, v7
	s_waitcnt lgkmcnt(2)
	v_pk_add_f32 v[4:5], v[4:5], v[8:9]
	ds_bpermute_b32 v14, v158, v6
	ds_bpermute_b32 v12, v158, v2
	ds_bpermute_b32 v17, v158, v11
	ds_bpermute_b32 v16, v158, v10
	ds_bpermute_b32 v21, v158, v5
	ds_bpermute_b32 v20, v158, v4
	s_waitcnt lgkmcnt(5)
	v_pk_add_f32 v[8:9], v[6:7], v[14:15]
	s_waitcnt lgkmcnt(4)
	v_pk_add_f32 v[6:7], v[2:3], v[12:13]
	s_waitcnt lgkmcnt(2)
	v_pk_add_f32 v[2:3], v[10:11], v[16:17]
	ds_bpermute_b32 v17, v159, v9
	s_waitcnt lgkmcnt(1)
	v_pk_add_f32 v[4:5], v[4:5], v[20:21]
	ds_bpermute_b32 v16, v159, v8
	ds_bpermute_b32 v15, v159, v7
	ds_bpermute_b32 v14, v159, v6
	ds_bpermute_b32 v11, v159, v3
	ds_bpermute_b32 v10, v159, v2
	ds_bpermute_b32 v13, v159, v5
	ds_bpermute_b32 v12, v159, v4
	s_and_saveexec_b64 s[6:7], s[0:1]
	s_cbranch_execz .LBB0_146
	s_lshl_b64 s[22:23], s[22:23], 5
	s_waitcnt lgkmcnt(6)
	v_pk_add_f32 v[8:9], v[8:9], v[16:17]
	s_waitcnt lgkmcnt(4)
	v_pk_add_f32 v[6:7], v[6:7], v[14:15]
	s_add_u32 s22, s40, s22
	s_waitcnt lgkmcnt(2)
	v_pk_add_f32 v[10:11], v[2:3], v[10:11]
	s_waitcnt lgkmcnt(0)
	v_pk_add_f32 v[12:13], v[4:5], v[12:13]
	s_addc_u32 s23, s41, s23
	v_mov_b32_e32 v2, v9
	v_mov_b32_e32 v3, v8
	v_mov_b32_e32 v4, v7
	v_mov_b32_e32 v5, v6
	global_store_dwordx4 v19, v[2:5], s[22:23]
	s_nop 1
	v_mov_b32_e32 v2, v11
	v_mov_b32_e32 v3, v10
	v_mov_b32_e32 v4, v13
	v_mov_b32_e32 v5, v12
	global_store_dwordx4 v19, v[2:5], s[22:23] offset:16
	s_branch .LBB0_146

.LBB0_193:
	s_add_i32 s17, s8, 0xffffe000
	s_lshr_b32 s17, s17, 3
	s_ashr_i32 s9, s8, 12
	s_add_i32 s17, s17, 2
	s_cmpk_lt_i32 s8, 0x2000
	s_cselect_b32 s9, s9, s17
	s_ashr_i32 s17, s9, 31
	s_add_u32 s9, s43, s9
	s_addc_u32 s17, s42, s17
	s_mul_i32 s17, s17, 0xc000
	s_mul_hi_u32 s18, s9, 0xc000
	s_add_i32 s17, s18, s17
	s_mul_i32 s9, s9, 0xc000
	s_add_u32 s18, s38, s9
	s_addc_u32 s19, s39, s17
	v_lshl_add_u64 v[66:67], v[112:113], 4, s[18:19]
	v_add_co_u32_e32 v64, vcc, s78, v66
	global_load_dwordx4 v[10:13], v[118:119], off
	s_nop 0
	v_addc_co_u32_e32 v65, vcc, 0, v67, vcc
	global_load_dwordx4 v[44:47], v[64:65], off offset:-4096
	global_load_dwordx4 v[40:43], v[66:67], off
	s_mov_b64 s[18:19], 0x2000
	v_lshl_add_u64 v[56:57], v[66:67], 0, s[18:19]
	v_add_co_u32_e32 v80, vcc, s3, v66
	s_waitcnt vmcnt(6)
	v_mul_f32_e32 v18, v32, v32
	v_addc_co_u32_e32 v81, vcc, 0, v67, vcc
	s_ashr_i32 s9, s8, 31
	s_lshl_b64 s[18:19], s[8:9], 12
	v_lshl_add_u64 v[152:153], v[128:129], 0, s[18:19]
	s_waitcnt vmcnt(1)
	v_pk_add_f32 v[46:47], v[46:47], 1.0 op_sel_hi:[1,0]
	v_pk_add_f32 v[44:45], v[44:45], 1.0 op_sel_hi:[1,0]
	v_pk_mul_f32 v[96:97], v[12:13], v[46:47]
	v_pk_mul_f32 v[98:99], v[10:11], v[44:45]
	global_load_dwordx4 v[10:13], v[118:119], off offset:1024
	global_load_dwordx4 v[48:51], v[56:57], off offset:1024
	global_load_dwordx4 v[44:47], v[66:67], off offset:1024
	s_waitcnt vmcnt(1)
	v_pk_add_f32 v[50:51], v[50:51], 1.0 op_sel_hi:[1,0]
	v_pk_add_f32 v[48:49], v[48:49], 1.0 op_sel_hi:[1,0]
	v_pk_mul_f32 v[100:101], v[12:13], v[50:51]
	v_pk_mul_f32 v[104:105], v[10:11], v[48:49]
	global_load_dwordx4 v[10:13], v[118:119], off offset:2048
	global_load_dwordx4 v[52:55], v[56:57], off offset:2048
	global_load_dwordx4 v[48:51], v[66:67], off offset:2048
	s_waitcnt vmcnt(1)
	v_pk_add_f32 v[54:55], v[54:55], 1.0 op_sel_hi:[1,0]
	v_pk_add_f32 v[52:53], v[52:53], 1.0 op_sel_hi:[1,0]
	v_pk_mul_f32 v[110:111], v[12:13], v[54:55]
	v_pk_mul_f32 v[130:131], v[10:11], v[52:53]
	global_load_dwordx4 v[10:13], v[118:119], off offset:3072
	s_nop 0
	global_load_dwordx4 v[56:59], v[56:57], off offset:3072
	s_nop 0
	global_load_dwordx4 v[52:55], v[66:67], off offset:3072
	s_waitcnt vmcnt(1)
	v_pk_add_f32 v[58:59], v[58:59], 1.0 op_sel_hi:[1,0]
	v_pk_add_f32 v[56:57], v[56:57], 1.0 op_sel_hi:[1,0]
	v_pk_mul_f32 v[92:93], v[12:13], v[58:59]
	v_pk_mul_f32 v[94:95], v[10:11], v[56:57]
	global_load_dwordx4 v[10:13], v[120:121], off
	global_load_dwordx4 v[60:63], v[64:65], off
	global_load_dwordx4 v[56:59], v[80:81], off
	s_waitcnt vmcnt(1)
	v_pk_add_f32 v[62:63], v[62:63], 1.0 op_sel_hi:[1,0]
	v_pk_add_f32 v[60:61], v[60:61], 1.0 op_sel_hi:[1,0]
	v_pk_mul_f32 v[88:89], v[12:13], v[62:63]
	v_pk_mul_f32 v[90:91], v[10:11], v[60:61]
	global_load_dwordx4 v[10:13], v[122:123], off
	global_load_dwordx4 v[66:69], v[64:65], off offset:1024
	global_load_dwordx4 v[60:63], v[80:81], off offset:1024
	s_waitcnt vmcnt(1)
	v_pk_add_f32 v[68:69], v[68:69], 1.0 op_sel_hi:[1,0]
	v_pk_add_f32 v[66:67], v[66:67], 1.0 op_sel_hi:[1,0]
	v_pk_mul_f32 v[84:85], v[12:13], v[68:69]
	v_pk_mul_f32 v[86:87], v[10:11], v[66:67]
	global_load_dwordx4 v[66:69], v[124:125], off
	global_load_dwordx4 v[70:73], v[64:65], off offset:2048
	global_load_dwordx4 v[10:13], v[80:81], off offset:2048
	s_waitcnt vmcnt(1)
	v_pk_add_f32 v[72:73], v[72:73], 1.0 op_sel_hi:[1,0]
	v_pk_add_f32 v[70:71], v[70:71], 1.0 op_sel_hi:[1,0]
	v_pk_mul_f32 v[68:69], v[68:69], v[72:73]
	v_pk_mul_f32 v[70:71], v[66:67], v[70:71]
	global_load_dwordx4 v[72:75], v[126:127], off
	global_load_dwordx4 v[76:79], v[64:65], off offset:3072
	s_nop 0
	global_load_dwordx4 v[64:67], v[80:81], off offset:3072
	s_waitcnt vmcnt(1)
	v_pk_add_f32 v[78:79], v[78:79], 1.0 op_sel_hi:[1,0]
	v_pk_add_f32 v[76:77], v[76:77], 1.0 op_sel_hi:[1,0]
	v_pk_mul_f32 v[80:81], v[74:75], v[78:79]
	v_mov_b32_e32 v74, v25
	v_mov_b32_e32 v75, v21
	v_pk_mul_f32 v[82:83], v[72:73], v[76:77]
	v_mov_b32_e32 v72, v24
	v_mov_b32_e32 v73, v20
	v_pk_mul_f32 v[74:75], v[74:75], v[74:75]
	v_mov_b32_e32 v76, v27
	v_mov_b32_e32 v77, v23
	v_pk_fma_f32 v[72:73], v[72:73], v[72:73], v[74:75]
	v_mov_b32_e32 v74, v26
	v_mov_b32_e32 v75, v22
	v_pk_mul_f32 v[76:77], v[76:77], v[76:77]
	s_nop 0
	v_pk_fma_f32 v[74:75], v[74:75], v[74:75], v[76:77]
	v_pk_mul_f32 v[76:77], v[14:15], v[14:15]
	v_pk_add_f32 v[72:73], v[72:73], v[74:75]
	v_pk_mul_f32 v[74:75], v[16:17], v[16:17]
	v_pk_add_f32 v[72:73], v[72:73], v[72:73] op_sel:[0,1] op_sel_hi:[1,0]
	v_pk_mov_b32 v[78:79], v[76:77], v[74:75] op_sel:[1,0]
	v_mov_b32_e32 v77, v75
	v_pk_add_f32 v[74:75], v[78:79], v[76:77]
	v_mul_f32_e32 v76, v33, v33
	v_pk_add_f32 v[74:75], v[74:75], v[74:75] op_sel:[0,1] op_sel_hi:[1,0]
	v_mov_b32_e32 v73, v18
	v_mov_b32_e32 v75, v76
	v_mul_f32_e32 v18, v29, v29
	v_mul_f32_e32 v77, v34, v34
	v_pk_add_f32 v[72:73], v[72:73], v[74:75]
	v_pk_fma_f32 v[74:75], v[28:29], v[28:29], v[18:19] op_sel_hi:[1,1,0]
	v_mul_f32_e32 v18, v31, v31
	v_mul_f32_e32 v78, v35, v35
	v_mov_b32_e32 v75, v77
	v_pk_fma_f32 v[76:77], v[30:31], v[30:31], v[18:19] op_sel_hi:[1,1,0]
	v_mul_f32_e32 v18, v2, v2
	v_mov_b32_e32 v77, v78
	v_pk_add_f32 v[74:75], v[74:75], v[76:77]
	v_pk_mul_f32 v[76:77], v[36:37], v[36:37]
	v_pk_add_f32 v[72:73], v[72:73], v[74:75]
	v_pk_mul_f32 v[74:75], v[38:39], v[38:39]
	v_pk_add_f32 v[72:73], v[72:73], v[72:73] op_sel:[0,1] op_sel_hi:[1,0]
	v_pk_mov_b32 v[78:79], v[76:77], v[74:75] op_sel:[1,0]
	v_mov_b32_e32 v77, v75
	v_pk_add_f32 v[74:75], v[78:79], v[76:77]
	v_mul_f32_e32 v76, v3, v3
	v_pk_add_f32 v[74:75], v[74:75], v[74:75] op_sel:[0,1] op_sel_hi:[1,0]
	v_mov_b32_e32 v73, v18
	v_mov_b32_e32 v75, v76
	v_mul_f32_e32 v18, v7, v7
	v_mul_f32_e32 v77, v4, v4
	v_pk_add_f32 v[72:73], v[72:73], v[74:75]
	v_pk_fma_f32 v[74:75], v[6:7], v[6:7], v[18:19] op_sel_hi:[1,1,0]
	v_mul_f32_e32 v18, v9, v9
	v_mul_f32_e32 v78, v5, v5
	v_mov_b32_e32 v75, v77
	v_pk_fma_f32 v[76:77], v[8:9], v[8:9], v[18:19] op_sel_hi:[1,1,0]
	v_and_b32_e32 v18, 64, v213
	v_mov_b32_e32 v77, v78
	v_pk_add_f32 v[74:75], v[74:75], v[76:77]
	s_nop 0
	v_pk_add_f32 v[72:73], v[72:73], v[74:75]
	s_nop 0
	v_add_f32_e32 v72, v72, v73
	v_add_u32_e32 v73, 64, v18
	v_xor_b32_e32 v18, 1, v213
	v_cmp_lt_i32_e32 vcc, v18, v73
	s_nop 1
	v_cndmask_b32_e32 v18, v213, v18, vcc
	v_lshlrev_b32_e32 v18, 2, v18
	ds_bpermute_b32 v74, v18, v72
	s_waitcnt lgkmcnt(0)
	v_add_f32_e32 v72, v72, v74
	v_xor_b32_e32 v74, 2, v213
	v_cmp_lt_i32_e32 vcc, v74, v73
	s_nop 1
	v_cndmask_b32_e32 v74, v213, v74, vcc
	v_lshlrev_b32_e32 v146, 2, v74
	ds_bpermute_b32 v74, v146, v72
	s_waitcnt lgkmcnt(0)
	v_add_f32_e32 v72, v72, v74
	v_xor_b32_e32 v74, 4, v213
	v_cmp_lt_i32_e32 vcc, v74, v73
	s_nop 1
	v_cndmask_b32_e32 v74, v213, v74, vcc
	v_lshlrev_b32_e32 v147, 2, v74
	ds_bpermute_b32 v74, v147, v72
	s_waitcnt lgkmcnt(0)
	v_add_f32_e32 v72, v72, v74
	v_xor_b32_e32 v74, 8, v213
	v_cmp_lt_i32_e32 vcc, v74, v73
	s_nop 1
	v_cndmask_b32_e32 v74, v213, v74, vcc
	v_lshlrev_b32_e32 v148, 2, v74
	ds_bpermute_b32 v74, v148, v72
	s_waitcnt lgkmcnt(0)
	v_add_f32_e32 v72, v72, v74
	v_xor_b32_e32 v74, 16, v213
	v_cmp_lt_i32_e32 vcc, v74, v73
	s_nop 1
	v_cndmask_b32_e32 v74, v213, v74, vcc
	v_lshlrev_b32_e32 v149, 2, v74
	ds_bpermute_b32 v74, v149, v72
	s_waitcnt lgkmcnt(0)
	v_add_f32_e32 v72, v72, v74
	v_xor_b32_e32 v74, 32, v213
	v_cmp_lt_i32_e32 vcc, v74, v73
	s_nop 1
	v_cndmask_b32_e32 v73, v213, v74, vcc
	v_lshlrev_b32_e32 v150, 2, v73
	ds_bpermute_b32 v73, v150, v72
	s_waitcnt lgkmcnt(0)
	v_add_f32_e32 v72, v72, v73
	v_fmamk_f32 v72, v72, 0x3a000000, v165
	v_rsq_f32_e32 v144, v72
	s_nop 0
	v_pk_mul_f32 v[6:7], v[6:7], v[144:145] op_sel_hi:[1,0]
	s_nop 0
	v_pk_fma_f32 v[78:79], v[70:71], v[6:7], v[10:11]
	v_pk_mul_f32 v[6:7], v[8:9], v[144:145] op_sel_hi:[1,0]
	v_pk_mul_f32 v[102:103], v[2:3], v[144:145] op_sel_hi:[1,0]
	v_pk_fma_f32 v[76:77], v[68:69], v[6:7], v[12:13]
	v_bfe_u32 v6, v78, 16, 1
	v_add3_u32 v6, v78, v6, s79
	v_bfe_u32 v7, v79, 16, 1
	v_lshrrev_b32_e32 v6, 16, v6
	v_add3_u32 v7, v79, v7, s79
	v_and_or_b32 v6, v7, s80, v6
	v_bfe_u32 v7, v76, 16, 1
	v_add3_u32 v7, v76, v7, s79
	v_bfe_u32 v8, v77, 16, 1
	v_lshrrev_b32_e32 v7, 16, v7
	v_add3_u32 v8, v77, v8, s79
	v_and_or_b32 v7, v8, s80, v7
	v_subrev_u32_e32 v248, s30, v152
	v_add_u32_e32 v248, 0xe8400000, v248
	v_and_b32_e32 v249, 0xfff00000, v248
	v_lshrrev_b32_e32 v218, 5, v248
	v_and_b32_e32 v218, 0x7800, v218
	v_or_b32_e32 v249, v249, v218
	v_lshrrev_b32_e32 v218, 6, v248
	v_and_b32_e32 v218, 0x3c0, v218
	v_or_b32_e32 v249, v249, v218
	v_and_b32_e32 v218, 0x180, v248
	v_lshlrev_b32_e32 v218, 8, v218
	v_or_b32_e32 v249, v249, v218
	v_and_b32_e32 v218, 64, v248
	v_lshlrev_b32_e32 v218, 4, v218
	v_or_b32_e32 v249, v249, v218
	v_and_b32_e32 v218, 56, v248
	v_or_b32_e32 v249, v249, v218
	v_lshrrev_b32_e32 v218, 10, v248
	v_and_b32_e32 v218, 32, v218
	v_xor_b32_e32 v249, v249, v218
	v_sub_u32_e32 v218, v249, v248
	v_ashrrev_i32_e32 v219, 31, v218
	v_lshl_add_u64 v[152:153], v[152:153], 0, v[218:219]
	s_mov_b64 s[100:101], 0xc0000
	v_lshl_add_u64 v[248:249], v[152:153], 0, s[100:101]
	global_store_dwordx2 v[248:249], v[6:7], off
	v_pk_mul_f32 v[106:107], v[4:5], v[144:145] op_sel_hi:[1,0]
	ds_read_b128 v[132:135], v1
	ds_read_b128 v[136:139], v1 offset:1024
	ds_read_b128 v[140:143], v1 offset:2048
	ds_read_b128 v[72:75], v1 offset:3072
	ds_read_b128 v[68:71], v1 offset:4096
	ds_read_b128 v[10:13], v1 offset:5120
	ds_read_b128 v[6:9], v1 offset:6144
	ds_read_b128 v[2:5], v1 offset:7168
	v_pk_mul_f32 v[20:21], v[20:21], v[144:145] op_sel_hi:[1,0]
	v_pk_mul_f32 v[28:29], v[28:29], v[144:145] op_sel_hi:[1,0]
	v_pk_mul_f32 v[24:25], v[24:25], v[144:145] op_sel_hi:[1,0]
	v_pk_fma_f32 v[108:109], v[104:105], v[20:21], v[44:45]
	v_pk_mul_f32 v[20:21], v[22:23], v[144:145] op_sel_hi:[1,0]
	v_pk_mul_f32 v[14:15], v[14:15], v[144:145] op_sel_hi:[1,0]
	s_waitcnt vmcnt(1)
	v_pk_fma_f32 v[82:83], v[82:83], v[102:103], v[64:65]
	v_pk_fma_f32 v[80:81], v[80:81], v[106:107], v[66:67]
	v_pk_fma_f32 v[94:95], v[94:95], v[28:29], v[52:53]
	v_pk_mul_f32 v[28:29], v[30:31], v[144:145] op_sel_hi:[1,0]
	v_pk_fma_f32 v[106:107], v[98:99], v[24:25], v[40:41]
	v_pk_mul_f32 v[24:25], v[26:27], v[144:145] op_sel_hi:[1,0]
	v_pk_fma_f32 v[104:105], v[100:101], v[20:21], v[46:47]
	v_pk_fma_f32 v[100:101], v[130:131], v[14:15], v[48:49]
	v_pk_mul_f32 v[14:15], v[16:17], v[144:145] op_sel_hi:[1,0]
	v_bfe_u32 v64, v82, 16, 1
	v_pk_fma_f32 v[92:93], v[92:93], v[28:29], v[54:55]
	v_bfe_u32 v28, v94, 16, 1
	v_pk_fma_f32 v[102:103], v[96:97], v[24:25], v[42:43]
	v_bfe_u32 v24, v106, 16, 1
	v_bfe_u32 v20, v108, 16, 1
	v_pk_fma_f32 v[96:97], v[110:111], v[14:15], v[50:51]
	v_bfe_u32 v14, v100, 16, 1
	v_add3_u32 v64, v82, v64, s79
	v_bfe_u32 v65, v83, 16, 1
	v_pk_mul_f32 v[38:39], v[38:39], v[144:145] op_sel_hi:[1,0]
	v_pk_mul_f32 v[36:37], v[36:37], v[144:145] op_sel_hi:[1,0]
	v_pk_mul_f32 v[34:35], v[34:35], v[144:145] op_sel_hi:[1,0]
	v_pk_mul_f32 v[32:33], v[32:33], v[144:145] op_sel_hi:[1,0]
	v_add3_u32 v28, v94, v28, s79
	v_bfe_u32 v29, v95, 16, 1
	v_add3_u32 v24, v106, v24, s79
	v_bfe_u32 v25, v107, 16, 1
	v_add3_u32 v20, v108, v20, s79
	v_bfe_u32 v21, v109, 16, 1
	v_add3_u32 v14, v100, v14, s79
	v_bfe_u32 v15, v101, 16, 1
	v_lshrrev_b32_e32 v64, 16, v64
	v_add3_u32 v65, v83, v65, s79
	v_pk_fma_f32 v[84:85], v[84:85], v[38:39], v[62:63]
	v_pk_fma_f32 v[86:87], v[86:87], v[36:37], v[60:61]
	v_pk_fma_f32 v[88:89], v[88:89], v[34:35], v[58:59]
	v_pk_fma_f32 v[90:91], v[90:91], v[32:33], v[56:57]
	v_lshrrev_b32_e32 v28, 16, v28
	v_add3_u32 v29, v95, v29, s79
	v_lshrrev_b32_e32 v24, 16, v24
	v_add3_u32 v25, v107, v25, s79
	v_lshrrev_b32_e32 v20, 16, v20
	v_add3_u32 v21, v109, v21, s79
	v_lshrrev_b32_e32 v14, 16, v14
	v_add3_u32 v15, v101, v15, s79
	v_and_or_b32 v64, v65, s80, v64
	v_bfe_u32 v65, v80, 16, 1
	v_bfe_u32 v38, v84, 16, 1
	v_bfe_u32 v36, v86, 16, 1
	v_bfe_u32 v34, v88, 16, 1
	v_bfe_u32 v32, v90, 16, 1
	v_and_or_b32 v28, v29, s80, v28
	v_bfe_u32 v29, v92, 16, 1
	v_and_or_b32 v24, v25, s80, v24
	v_bfe_u32 v25, v102, 16, 1
	v_and_or_b32 v20, v21, s80, v20
	v_bfe_u32 v21, v104, 16, 1
	v_and_or_b32 v14, v15, s80, v14
	v_bfe_u32 v15, v96, 16, 1
	v_add3_u32 v65, v80, v65, s79
	v_bfe_u32 v66, v81, 16, 1
	v_add3_u32 v38, v84, v38, s79
	v_bfe_u32 v39, v85, 16, 1
	v_add3_u32 v36, v86, v36, s79
	v_bfe_u32 v37, v87, 16, 1
	v_add3_u32 v34, v88, v34, s79
	v_bfe_u32 v35, v89, 16, 1
	v_add3_u32 v32, v90, v32, s79
	v_bfe_u32 v33, v91, 16, 1
	v_add3_u32 v29, v92, v29, s79
	v_bfe_u32 v30, v93, 16, 1
	v_add3_u32 v25, v102, v25, s79
	v_bfe_u32 v26, v103, 16, 1
	v_add3_u32 v21, v104, v21, s79
	v_bfe_u32 v22, v105, 16, 1
	v_add3_u32 v15, v96, v15, s79
	v_bfe_u32 v16, v97, 16, 1
	v_lshrrev_b32_e32 v65, 16, v65
	v_add3_u32 v66, v81, v66, s79
	v_lshrrev_b32_e32 v38, 16, v38
	v_add3_u32 v39, v85, v39, s79
	v_lshrrev_b32_e32 v36, 16, v36
	v_add3_u32 v37, v87, v37, s79
	v_lshrrev_b32_e32 v34, 16, v34
	v_add3_u32 v35, v89, v35, s79
	v_lshrrev_b32_e32 v32, 16, v32
	v_add3_u32 v33, v91, v33, s79
	v_lshrrev_b32_e32 v29, 16, v29
	v_add3_u32 v30, v93, v30, s79
	v_lshrrev_b32_e32 v25, 16, v25
	v_add3_u32 v26, v103, v26, s79
	v_lshrrev_b32_e32 v21, 16, v21
	v_add3_u32 v22, v105, v22, s79
	v_lshrrev_b32_e32 v15, 16, v15
	v_add3_u32 v16, v97, v16, s79
	v_and_or_b32 v65, v66, s80, v65
	v_and_or_b32 v39, v39, s80, v38
	v_and_or_b32 v38, v37, s80, v36
	v_and_or_b32 v35, v35, s80, v34
	v_and_or_b32 v34, v33, s80, v32
	v_and_or_b32 v29, v30, s80, v29
	v_and_or_b32 v25, v26, s80, v25
	v_and_or_b32 v21, v22, s80, v21
	v_and_or_b32 v15, v16, s80, v15
	s_mov_b64 s[100:101], 0xe0000
	v_lshl_add_u64 v[248:249], v[152:153], 0, s[100:101]
	global_store_dwordx2 v[248:249], v[64:65], off
	s_mov_b64 s[100:101], 0xa0000
	v_lshl_add_u64 v[248:249], v[152:153], 0, s[100:101]
	global_store_dwordx2 v[248:249], v[38:39], off
	s_mov_b64 s[100:101], 0x80000
	v_lshl_add_u64 v[248:249], v[152:153], 0, s[100:101]
	global_store_dwordx2 v[248:249], v[34:35], off
	s_mov_b64 s[100:101], 0x60000
	v_lshl_add_u64 v[248:249], v[152:153], 0, s[100:101]
	global_store_dwordx2 v[248:249], v[28:29], off
	global_store_dwordx2 v[152:153], v[24:25], off
	s_mov_b64 s[100:101], 0x20000
	v_lshl_add_u64 v[248:249], v[152:153], 0, s[100:101]
	global_store_dwordx2 v[248:249], v[20:21], off
	s_mov_b64 s[100:101], 0x40000
	v_lshl_add_u64 v[248:249], v[152:153], 0, s[100:101]
	global_store_dwordx2 v[248:249], v[14:15], off
	ds_read_b128 v[14:17], v1 offset:8192
	ds_read_b128 v[20:23], v1 offset:9216
	ds_read_b128 v[24:27], v1 offset:10240
	s_waitcnt lgkmcnt(10)
	v_mov_b32_e32 v29, v133
	s_waitcnt lgkmcnt(5)
	v_mov_b32_e32 v131, v13
	s_waitcnt lgkmcnt(2)
	v_mov_b32_e32 v28, v14
	v_pk_mov_b32 v[14:15], v[14:15], v[132:133] op_sel:[1,0]
	v_pk_mul_f32 v[28:29], v[106:107], v[28:29]
	v_mov_b32_e32 v133, v11
	v_pk_fma_f32 v[14:15], v[106:107], v[14:15], v[28:29] op_sel:[1,0,0] op_sel_hi:[0,1,1]
	v_mov_b32_e32 v28, v16
	v_mov_b32_e32 v29, v135
	v_pk_mul_f32 v[28:29], v[102:103], v[28:29]
	v_pk_mov_b32 v[16:17], v[16:17], v[134:135] op_sel:[1,0]
	ds_read_b128 v[32:35], v1 offset:13312
	v_pk_fma_f32 v[16:17], v[102:103], v[16:17], v[28:29] op_sel:[1,0,0] op_sel_hi:[0,1,1]
	v_pk_add_f32 v[14:15], v[14:15], v[16:17]
	s_waitcnt lgkmcnt(2)
	v_mov_b32_e32 v16, v20
	v_mov_b32_e32 v17, v137
	v_pk_mul_f32 v[16:17], v[108:109], v[16:17]
	v_pk_mov_b32 v[20:21], v[20:21], v[136:137] op_sel:[1,0]
	v_pk_add_f32 v[14:15], v[14:15], 0 op_sel_hi:[1,0]
	v_pk_fma_f32 v[16:17], v[108:109], v[20:21], v[16:17] op_sel:[1,0,0] op_sel_hi:[0,1,1]
	v_mov_b32_e32 v20, v22
	v_mov_b32_e32 v21, v139
	v_pk_mul_f32 v[20:21], v[104:105], v[20:21]
	v_pk_mov_b32 v[22:23], v[22:23], v[138:139] op_sel:[1,0]
	s_waitcnt lgkmcnt(0)
	v_mov_b32_e32 v132, v32
	v_pk_fma_f32 v[20:21], v[104:105], v[22:23], v[20:21] op_sel:[1,0,0] op_sel_hi:[0,1,1]
	v_pk_add_f32 v[16:17], v[16:17], v[20:21]
	v_mov_b32_e32 v22, v24
	v_mov_b32_e32 v23, v141
	v_pk_add_f32 v[20:21], v[14:15], v[16:17]
	ds_read_b128 v[14:17], v1 offset:11264
	v_pk_mul_f32 v[22:23], v[100:101], v[22:23]
	v_pk_mov_b32 v[24:25], v[24:25], v[140:141] op_sel:[1,0]
	v_mov_b32_e32 v130, v34
	v_pk_fma_f32 v[22:23], v[100:101], v[24:25], v[22:23] op_sel:[1,0,0] op_sel_hi:[0,1,1]
	v_mov_b32_e32 v24, v26
	v_mov_b32_e32 v25, v143
	v_pk_mul_f32 v[24:25], v[96:97], v[24:25]
	v_pk_mov_b32 v[26:27], v[26:27], v[142:143] op_sel:[1,0]
	s_nop 0
	v_pk_fma_f32 v[24:25], v[96:97], v[26:27], v[24:25] op_sel:[1,0,0] op_sel_hi:[0,1,1]
	v_pk_add_f32 v[22:23], v[22:23], v[24:25]
	s_nop 0
	v_pk_add_f32 v[98:99], v[20:21], v[22:23]
	s_waitcnt lgkmcnt(0)
	v_mov_b32_e32 v20, v14
	v_mov_b32_e32 v21, v73
	v_pk_mul_f32 v[20:21], v[94:95], v[20:21]
	v_pk_mov_b32 v[14:15], v[14:15], v[72:73] op_sel:[1,0]
	s_nop 0
	v_pk_fma_f32 v[14:15], v[94:95], v[14:15], v[20:21] op_sel:[1,0,0] op_sel_hi:[0,1,1]
	v_mov_b32_e32 v20, v16
	v_mov_b32_e32 v21, v75
	v_pk_mul_f32 v[24:25], v[92:93], v[20:21]
	ds_read_b128 v[20:23], v1 offset:12288
	v_pk_mov_b32 v[16:17], v[16:17], v[74:75] op_sel:[1,0]
	ds_read_b128 v[36:39], v1 offset:14336
	ds_read_b128 v[28:31], v1 offset:15360
	v_pk_fma_f32 v[16:17], v[92:93], v[16:17], v[24:25] op_sel:[1,0,0] op_sel_hi:[0,1,1]
	v_pk_add_f32 v[72:73], v[14:15], v[16:17]
	s_waitcnt lgkmcnt(2)
	v_mov_b32_e32 v14, v20
	v_mov_b32_e32 v15, v69
	v_pk_mul_f32 v[14:15], v[90:91], v[14:15]
	v_pk_mov_b32 v[16:17], v[20:21], v[68:69] op_sel:[1,0]
	s_nop 0
	v_pk_fma_f32 v[74:75], v[90:91], v[16:17], v[14:15] op_sel:[1,0,0] op_sel_hi:[0,1,1]
	v_mov_b32_e32 v14, v22
	v_mov_b32_e32 v15, v71
	v_pk_mul_f32 v[14:15], v[88:89], v[14:15]
	v_pk_mov_b32 v[16:17], v[22:23], v[70:71] op_sel:[1,0]
	s_nop 0
	v_pk_fma_f32 v[110:111], v[88:89], v[16:17], v[14:15] op_sel:[1,0,0] op_sel_hi:[0,1,1]
	ds_read_b128 v[40:43], v1 offset:16384
	ds_read_b128 v[44:47], v1 offset:17408
	ds_read_b128 v[48:51], v1 offset:18432
	ds_read_b128 v[52:55], v1 offset:19456
	ds_read_b128 v[56:59], v1 offset:20480
	ds_read_b128 v[24:27], v1 offset:21504
	ds_read_b128 v[20:23], v1 offset:22528
	ds_read_b128 v[14:17], v1 offset:23552
	ds_read_b128 v[60:63], v1 offset:24576
	ds_read_b128 v[64:67], v1 offset:25600
	ds_read_b128 v[68:71], v1 offset:26624
	s_waitcnt lgkmcnt(10)
	v_mov_b32_e32 v135, v41
	s_waitcnt lgkmcnt(5)
	v_mov_b32_e32 v145, v25
	s_waitcnt lgkmcnt(2)
	v_mov_b32_e32 v134, v60
	v_pk_mov_b32 v[40:41], v[60:61], v[40:41] op_sel:[1,0]
	v_pk_mul_f32 v[60:61], v[106:107], v[134:135]
	v_mov_b32_e32 v143, v27
	v_pk_fma_f32 v[40:41], v[106:107], v[40:41], v[60:61] op_sel:[1,0,0] op_sel_hi:[0,1,1]
	v_mov_b32_e32 v60, v62
	v_mov_b32_e32 v61, v43
	v_pk_mul_f32 v[60:61], v[102:103], v[60:61]
	v_pk_mov_b32 v[42:43], v[62:63], v[42:43] op_sel:[1,0]
	s_nop 0
	v_pk_fma_f32 v[42:43], v[102:103], v[42:43], v[60:61] op_sel:[1,0,0] op_sel_hi:[0,1,1]
	v_pk_add_f32 v[40:41], v[40:41], v[42:43]
	s_waitcnt lgkmcnt(1)
	v_mov_b32_e32 v42, v64
	v_mov_b32_e32 v43, v45
	v_pk_mul_f32 v[42:43], v[108:109], v[42:43]
	v_pk_mov_b32 v[44:45], v[64:65], v[44:45] op_sel:[1,0]
	v_pk_add_f32 v[40:41], v[40:41], 0 op_sel_hi:[1,0]
	v_pk_fma_f32 v[42:43], v[108:109], v[44:45], v[42:43] op_sel:[1,0,0] op_sel_hi:[0,1,1]
	v_mov_b32_e32 v44, v66
	v_mov_b32_e32 v45, v47
	v_pk_mul_f32 v[44:45], v[104:105], v[44:45]
	v_pk_mov_b32 v[46:47], v[66:67], v[46:47] op_sel:[1,0]
	s_nop 0
	v_pk_fma_f32 v[44:45], v[104:105], v[46:47], v[44:45] op_sel:[1,0,0] op_sel_hi:[0,1,1]
	v_pk_add_f32 v[42:43], v[42:43], v[44:45]
	s_waitcnt lgkmcnt(0)
	v_mov_b32_e32 v46, v68
	v_mov_b32_e32 v47, v49
	v_pk_add_f32 v[44:45], v[40:41], v[42:43]
	ds_read_b128 v[40:43], v1 offset:27648
	v_pk_mul_f32 v[46:47], v[100:101], v[46:47]
	v_pk_mov_b32 v[48:49], v[68:69], v[48:49] op_sel:[1,0]
	s_nop 0
	v_pk_fma_f32 v[46:47], v[100:101], v[48:49], v[46:47] op_sel:[1,0,0] op_sel_hi:[0,1,1]
	v_mov_b32_e32 v48, v70
	v_mov_b32_e32 v49, v51
	v_pk_mul_f32 v[48:49], v[96:97], v[48:49]
	v_pk_mov_b32 v[50:51], v[70:71], v[50:51] op_sel:[1,0]
	s_nop 0
	v_pk_fma_f32 v[48:49], v[96:97], v[50:51], v[48:49] op_sel:[1,0,0] op_sel_hi:[0,1,1]
	v_pk_add_f32 v[46:47], v[46:47], v[48:49]
	ds_read_b128 v[48:51], v1 offset:28672
	v_pk_add_f32 v[134:135], v[44:45], v[46:47]
	s_waitcnt lgkmcnt(1)
	v_mov_b32_e32 v44, v40
	v_mov_b32_e32 v45, v53
	v_pk_mul_f32 v[44:45], v[94:95], v[44:45]
	v_pk_mov_b32 v[40:41], v[40:41], v[52:53] op_sel:[1,0]
	s_nop 0
	v_pk_fma_f32 v[40:41], v[94:95], v[40:41], v[44:45] op_sel:[1,0,0] op_sel_hi:[0,1,1]
	v_mov_b32_e32 v44, v42
	v_mov_b32_e32 v45, v55
	v_pk_mul_f32 v[44:45], v[92:93], v[44:45]
	v_pk_mov_b32 v[42:43], v[42:43], v[54:55] op_sel:[1,0]
	s_nop 0
	v_pk_fma_f32 v[42:43], v[92:93], v[42:43], v[44:45] op_sel:[1,0,0] op_sel_hi:[0,1,1]
	v_pk_add_f32 v[136:137], v[40:41], v[42:43]
	s_waitcnt lgkmcnt(0)
	v_mov_b32_e32 v40, v48
	v_mov_b32_e32 v41, v57
	v_pk_mul_f32 v[40:41], v[90:91], v[40:41]
	v_pk_mov_b32 v[42:43], v[48:49], v[56:57] op_sel:[1,0]
	ds_read_b128 v[44:47], v1 offset:29696
	v_pk_fma_f32 v[138:139], v[90:91], v[42:43], v[40:41] op_sel:[1,0,0] op_sel_hi:[0,1,1]
	v_mov_b32_e32 v40, v50
	v_mov_b32_e32 v41, v59
	v_pk_mul_f32 v[40:41], v[88:89], v[40:41]
	v_pk_mov_b32 v[42:43], v[50:51], v[58:59] op_sel:[1,0]
	s_waitcnt lgkmcnt(0)
	v_mov_b32_e32 v144, v44
	v_pk_fma_f32 v[140:141], v[88:89], v[42:43], v[40:41] op_sel:[1,0,0] op_sel_hi:[0,1,1]
	ds_read_b128 v[48:51], v1 offset:30720
	ds_read_b128 v[40:43], v1 offset:31744
	v_mov_b32_e32 v142, v46
	ds_read_b128 v[152:155], v1 offset:32768
	ds_read_b128 v[156:159], v1 offset:33792
	ds_read_b128 v[160:163], v1 offset:34816
	ds_read_b128 v[68:71], v1 offset:35840
	ds_read_b128 v[64:67], v1 offset:36864
	ds_read_b128 v[60:63], v1 offset:37888
	ds_read_b128 v[56:59], v1 offset:38912
	ds_read_b128 v[52:55], v1 offset:39936
	ds_read_b128 v[170:173], v1 offset:40960
	s_waitcnt lgkmcnt(0)
	v_pk_mov_b32 v[174:175], v[152:153], v[170:171] op_sel:[1,0]
	v_mov_b32_e32 v153, v171
	v_pk_mov_b32 v[170:171], v[154:155], v[172:173] op_sel:[1,0]
	v_pk_mul_f32 v[174:175], v[106:107], v[174:175] op_sel:[1,0] op_sel_hi:[0,1]
	v_pk_mul_f32 v[170:171], v[102:103], v[170:171] op_sel:[1,0] op_sel_hi:[0,1]
	v_mov_b32_e32 v155, v173
	v_pk_fma_f32 v[152:153], v[106:107], v[152:153], v[174:175]
	v_pk_fma_f32 v[154:155], v[102:103], v[154:155], v[170:171]
	s_nop 0
	v_pk_add_f32 v[152:153], v[152:153], v[154:155]
	s_nop 0
	v_pk_add_f32 v[170:171], v[152:153], 0 op_sel_hi:[1,0]
	ds_read_b128 v[152:155], v1 offset:41984
	s_waitcnt lgkmcnt(0)
	v_pk_mov_b32 v[172:173], v[156:157], v[152:153] op_sel:[1,0]
	s_nop 0
	v_pk_mul_f32 v[172:173], v[108:109], v[172:173] op_sel:[1,0] op_sel_hi:[0,1]
	v_mov_b32_e32 v157, v153
	v_pk_fma_f32 v[152:153], v[108:109], v[156:157], v[172:173]
	v_pk_mov_b32 v[156:157], v[158:159], v[154:155] op_sel:[1,0]
	v_mov_b32_e32 v159, v155
	v_pk_mul_f32 v[156:157], v[104:105], v[156:157] op_sel:[1,0] op_sel_hi:[0,1]
	v_pk_fma_f32 v[154:155], v[104:105], v[158:159], v[156:157]
	s_nop 0
	v_pk_add_f32 v[152:153], v[152:153], v[154:155]
	s_nop 0
	v_pk_add_f32 v[156:157], v[170:171], v[152:153]
	ds_read_b128 v[152:155], v1 offset:43008
	s_waitcnt lgkmcnt(0)
	v_pk_mov_b32 v[158:159], v[160:161], v[152:153] op_sel:[1,0]
	s_nop 0
	v_pk_mul_f32 v[158:159], v[100:101], v[158:159] op_sel:[1,0] op_sel_hi:[0,1]
	v_mov_b32_e32 v161, v153
	v_pk_fma_f32 v[152:153], v[100:101], v[160:161], v[158:159]
	v_pk_mov_b32 v[158:159], v[162:163], v[154:155] op_sel:[1,0]
	v_mov_b32_e32 v163, v155
	v_pk_mul_f32 v[158:159], v[96:97], v[158:159] op_sel:[1,0] op_sel_hi:[0,1]
	v_pk_fma_f32 v[154:155], v[96:97], v[162:163], v[158:159]
	s_nop 0
	v_pk_add_f32 v[152:153], v[152:153], v[154:155]
	s_nop 0
	v_pk_add_f32 v[156:157], v[156:157], v[152:153]
	ds_read_b128 v[152:155], v1 offset:44032
	s_waitcnt lgkmcnt(0)
	v_pk_mov_b32 v[158:159], v[68:69], v[152:153] op_sel:[1,0]
	v_mov_b32_e32 v69, v153
	v_pk_mov_b32 v[152:153], v[70:71], v[154:155] op_sel:[1,0]
	v_pk_mul_f32 v[158:159], v[94:95], v[158:159] op_sel:[1,0] op_sel_hi:[0,1]
	v_pk_mul_f32 v[152:153], v[92:93], v[152:153] op_sel:[1,0] op_sel_hi:[0,1]
	v_mov_b32_e32 v71, v155
	v_pk_fma_f32 v[68:69], v[94:95], v[68:69], v[158:159]
	v_pk_fma_f32 v[70:71], v[92:93], v[70:71], v[152:153]
	s_nop 0
	v_pk_add_f32 v[68:69], v[68:69], v[70:71]
	s_nop 0
	v_pk_add_f32 v[152:153], v[156:157], v[68:69]
	ds_read_b128 v[68:71], v1 offset:45056
	s_waitcnt lgkmcnt(0)
	v_pk_mov_b32 v[154:155], v[64:65], v[68:69] op_sel:[1,0]
	v_mov_b32_e32 v65, v69
	v_pk_mov_b32 v[68:69], v[66:67], v[70:71] op_sel:[1,0]
	v_pk_mul_f32 v[154:155], v[90:91], v[154:155] op_sel:[1,0] op_sel_hi:[0,1]
	v_pk_mul_f32 v[68:69], v[88:89], v[68:69] op_sel:[1,0] op_sel_hi:[0,1]
	v_mov_b32_e32 v67, v71
	v_pk_fma_f32 v[64:65], v[90:91], v[64:65], v[154:155]
	v_pk_fma_f32 v[66:67], v[88:89], v[66:67], v[68:69]
	v_mov_b32_e32 v71, v61
	v_pk_add_f32 v[64:65], v[64:65], v[66:67]
	s_nop 0
	v_pk_add_f32 v[68:69], v[152:153], v[64:65]
	ds_read_b128 v[64:67], v1 offset:46080
	s_waitcnt lgkmcnt(0)
	v_pk_mov_b32 v[60:61], v[64:65], v[60:61] op_sel:[1,0]
	v_mov_b32_e32 v65, v63
	v_pk_mov_b32 v[62:63], v[66:67], v[62:63] op_sel:[1,0]
	v_mov_b32_e32 v70, v64
	v_pk_mul_f32 v[60:61], v[86:87], v[60:61] op_sel:[1,0] op_sel_hi:[0,1]
	v_mov_b32_e32 v64, v66
	v_pk_mul_f32 v[62:63], v[84:85], v[62:63] op_sel:[1,0] op_sel_hi:[0,1]
	v_pk_fma_f32 v[60:61], v[86:87], v[70:71], v[60:61]
	v_pk_fma_f32 v[62:63], v[84:85], v[64:65], v[62:63]
	v_mov_b32_e32 v67, v57
	v_pk_add_f32 v[60:61], v[60:61], v[62:63]
	s_nop 0
	v_pk_add_f32 v[64:65], v[68:69], v[60:61] op_sel:[1,0] op_sel_hi:[0,1]
	ds_read_b128 v[60:63], v1 offset:47104
	s_waitcnt lgkmcnt(0)
	v_pk_mov_b32 v[56:57], v[60:61], v[56:57] op_sel:[1,0]
	v_mov_b32_e32 v61, v59
	v_pk_mov_b32 v[58:59], v[62:63], v[58:59] op_sel:[1,0]
	v_mov_b32_e32 v66, v60
	v_pk_mul_f32 v[56:57], v[78:79], v[56:57] op_sel:[1,0] op_sel_hi:[0,1]
	v_mov_b32_e32 v60, v62
	v_pk_mul_f32 v[58:59], v[76:77], v[58:59] op_sel:[1,0] op_sel_hi:[0,1]
	v_pk_fma_f32 v[56:57], v[78:79], v[66:67], v[56:57]
	v_pk_fma_f32 v[58:59], v[76:77], v[60:61], v[58:59]
	v_mov_b32_e32 v63, v53
	v_pk_add_f32 v[56:57], v[56:57], v[58:59]
	s_nop 0
	v_pk_add_f32 v[60:61], v[64:65], v[56:57]
	ds_read_b128 v[56:59], v1 offset:48128
	s_waitcnt lgkmcnt(0)
	v_pk_mov_b32 v[52:53], v[56:57], v[52:53] op_sel:[1,0]
	v_mov_b32_e32 v57, v55
	v_pk_mov_b32 v[54:55], v[58:59], v[54:55] op_sel:[1,0]
	v_mov_b32_e32 v62, v56
	v_pk_mul_f32 v[52:53], v[82:83], v[52:53] op_sel:[1,0] op_sel_hi:[0,1]
	v_mov_b32_e32 v56, v58
	v_pk_mul_f32 v[54:55], v[80:81], v[54:55] op_sel:[1,0] op_sel_hi:[0,1]
	v_pk_fma_f32 v[52:53], v[82:83], v[62:63], v[52:53]
	v_pk_fma_f32 v[54:55], v[80:81], v[56:57], v[54:55]
	s_nop 0
	v_pk_add_f32 v[52:53], v[52:53], v[54:55]
	s_nop 0
	v_pk_add_f32 v[182:183], v[60:61], v[52:53]
	ds_read_b128 v[64:67], v1 offset:49152
	ds_read_b128 v[68:71], v1 offset:50176
	ds_read_b128 v[152:155], v1 offset:51200
	ds_read_b128 v[156:159], v1 offset:52224
	ds_read_b128 v[160:163], v1 offset:53248
	ds_read_b128 v[60:63], v1 offset:54272
	ds_read_b128 v[56:59], v1 offset:55296
	ds_read_b128 v[52:55], v1 offset:56320
	ds_read_b128 v[170:173], v1 offset:57344
	ds_read_b128 v[174:177], v1 offset:58368
	ds_read_b128 v[178:181], v1 offset:59392
	s_waitcnt lgkmcnt(10)
	v_mov_b32_e32 v185, v65
	s_waitcnt lgkmcnt(2)
	v_mov_b32_e32 v184, v170
	v_pk_mov_b32 v[64:65], v[170:171], v[64:65] op_sel:[1,0]
	v_pk_mul_f32 v[170:171], v[106:107], v[184:185]
	s_nop 0
	v_pk_fma_f32 v[64:65], v[106:107], v[64:65], v[170:171] op_sel:[1,0,0] op_sel_hi:[0,1,1]
	v_mov_b32_e32 v106, v172
	v_mov_b32_e32 v107, v67
	v_pk_mul_f32 v[106:107], v[102:103], v[106:107]
	v_pk_mov_b32 v[66:67], v[172:173], v[66:67] op_sel:[1,0]
	s_nop 0
	v_pk_fma_f32 v[66:67], v[102:103], v[66:67], v[106:107] op_sel:[1,0,0] op_sel_hi:[0,1,1]
	v_pk_add_f32 v[64:65], v[64:65], v[66:67]
	s_waitcnt lgkmcnt(1)
	v_mov_b32_e32 v66, v174
	v_mov_b32_e32 v67, v69
	v_pk_mul_f32 v[66:67], v[108:109], v[66:67]
	v_pk_mov_b32 v[68:69], v[174:175], v[68:69] op_sel:[1,0]
	v_pk_add_f32 v[64:65], v[64:65], 0 op_sel_hi:[1,0]
	v_pk_fma_f32 v[66:67], v[108:109], v[68:69], v[66:67] op_sel:[1,0,0] op_sel_hi:[0,1,1]
	v_mov_b32_e32 v68, v176
	v_mov_b32_e32 v69, v71
	v_pk_mul_f32 v[68:69], v[104:105], v[68:69]
	v_pk_mov_b32 v[70:71], v[176:177], v[70:71] op_sel:[1,0]
	s_waitcnt lgkmcnt(0)
	v_pk_mov_b32 v[102:103], v[178:179], v[152:153] op_sel:[1,0]
	v_pk_fma_f32 v[68:69], v[104:105], v[70:71], v[68:69] op_sel:[1,0,0] op_sel_hi:[0,1,1]
	v_pk_add_f32 v[66:67], v[66:67], v[68:69]
	v_mov_b32_e32 v70, v178
	v_mov_b32_e32 v71, v153
	v_pk_add_f32 v[64:65], v[64:65], v[66:67]
	ds_read_b128 v[66:69], v1 offset:60416
	v_pk_mul_f32 v[70:71], v[100:101], v[70:71]
	v_mov_b32_e32 v105, v63
	v_pk_fma_f32 v[70:71], v[100:101], v[102:103], v[70:71] op_sel:[1,0,0] op_sel_hi:[0,1,1]
	v_mov_b32_e32 v100, v180
	v_mov_b32_e32 v101, v155
	v_pk_mul_f32 v[100:101], v[96:97], v[100:101]
	v_pk_mov_b32 v[102:103], v[180:181], v[154:155] op_sel:[1,0]
	s_nop 0
	v_pk_fma_f32 v[96:97], v[96:97], v[102:103], v[100:101] op_sel:[1,0,0] op_sel_hi:[0,1,1]
	v_pk_add_f32 v[70:71], v[70:71], v[96:97]
	v_mov_b32_e32 v103, v61
	v_pk_add_f32 v[64:65], v[64:65], v[70:71]
	s_waitcnt lgkmcnt(0)
	v_mov_b32_e32 v70, v66
	v_mov_b32_e32 v71, v157
	v_pk_mul_f32 v[70:71], v[94:95], v[70:71]
	v_pk_mov_b32 v[66:67], v[66:67], v[156:157] op_sel:[1,0]
	s_nop 0
	v_pk_fma_f32 v[66:67], v[94:95], v[66:67], v[70:71] op_sel:[1,0,0] op_sel_hi:[0,1,1]
	ds_read_b128 v[94:97], v1 offset:61440
	v_mov_b32_e32 v70, v68
	v_mov_b32_e32 v71, v159
	v_pk_mul_f32 v[70:71], v[92:93], v[70:71]
	v_pk_mov_b32 v[68:69], v[68:69], v[158:159] op_sel:[1,0]
	s_nop 0
	v_pk_fma_f32 v[68:69], v[92:93], v[68:69], v[70:71] op_sel:[1,0,0] op_sel_hi:[0,1,1]
	v_pk_add_f32 v[70:71], v[66:67], v[68:69]
	ds_read_b128 v[66:69], v1 offset:62464
	s_waitcnt lgkmcnt(1)
	v_mov_b32_e32 v92, v94
	v_mov_b32_e32 v93, v161
	v_pk_mul_f32 v[92:93], v[90:91], v[92:93]
	v_pk_mov_b32 v[94:95], v[94:95], v[160:161] op_sel:[1,0]
	s_waitcnt lgkmcnt(0)
	v_mov_b32_e32 v102, v66
	v_pk_fma_f32 v[100:101], v[90:91], v[94:95], v[92:93] op_sel:[1,0,0] op_sel_hi:[0,1,1]
	v_mov_b32_e32 v90, v96
	v_mov_b32_e32 v91, v163
	v_pk_mul_f32 v[90:91], v[88:89], v[90:91]
	v_pk_mov_b32 v[92:93], v[96:97], v[162:163] op_sel:[1,0]
	v_mov_b32_e32 v104, v68
	v_pk_fma_f32 v[96:97], v[88:89], v[92:93], v[90:91] op_sel:[1,0,0] op_sel_hi:[0,1,1]
	ds_read_b128 v[88:91], v1 offset:63488
	ds_read_b128 v[92:95], v1 offset:64512
	v_pk_mov_b32 v[10:11], v[32:33], v[10:11] op_sel:[1,0]
	v_pk_mov_b32 v[12:13], v[34:35], v[12:13] op_sel:[1,0]
	v_pk_mul_f32 v[10:11], v[86:87], v[10:11] op_sel:[1,0] op_sel_hi:[0,1]
	v_pk_mul_f32 v[12:13], v[84:85], v[12:13] op_sel:[1,0] op_sel_hi:[0,1]
	v_pk_fma_f32 v[10:11], v[86:87], v[132:133], v[10:11]
	v_pk_fma_f32 v[12:13], v[84:85], v[130:131], v[12:13]
	v_pk_add_f32 v[72:73], v[98:99], v[72:73]
	v_pk_add_f32 v[10:11], v[10:11], v[12:13]
	v_mov_b32_e32 v13, v7
	v_pk_mov_b32 v[6:7], v[36:37], v[6:7] op_sel:[1,0]
	v_mov_b32_e32 v12, v36
	v_pk_mul_f32 v[6:7], v[78:79], v[6:7] op_sel:[1,0] op_sel_hi:[0,1]
	v_pk_fma_f32 v[6:7], v[78:79], v[12:13], v[6:7]
	v_mov_b32_e32 v13, v9
	v_pk_mov_b32 v[8:9], v[38:39], v[8:9] op_sel:[1,0]
	v_pk_add_f32 v[74:75], v[74:75], v[110:111]
	v_mov_b32_e32 v12, v38
	v_pk_mul_f32 v[8:9], v[76:77], v[8:9] op_sel:[1,0] op_sel_hi:[0,1]
	v_pk_add_f32 v[72:73], v[72:73], v[74:75]
	v_pk_fma_f32 v[8:9], v[76:77], v[12:13], v[8:9]
	v_pk_add_f32 v[10:11], v[72:73], v[10:11]
	v_pk_add_f32 v[6:7], v[6:7], v[8:9]
	v_mov_b32_e32 v9, v3
	v_pk_mov_b32 v[2:3], v[28:29], v[2:3] op_sel:[1,0]
	ds_bpermute_b32 v107, v18, v183
	ds_bpermute_b32 v106, v18, v182
	v_pk_add_f32 v[6:7], v[10:11], v[6:7]
	v_mov_b32_e32 v8, v28
	v_pk_mul_f32 v[2:3], v[82:83], v[2:3] op_sel:[1,0] op_sel_hi:[0,1]
	v_pk_add_f32 v[10:11], v[134:135], v[136:137]
	v_pk_add_f32 v[12:13], v[138:139], v[140:141]
	v_pk_fma_f32 v[2:3], v[82:83], v[8:9], v[2:3]
	v_mov_b32_e32 v9, v5
	v_pk_mov_b32 v[4:5], v[30:31], v[4:5] op_sel:[1,0]
	v_pk_add_f32 v[10:11], v[10:11], v[12:13]
	v_pk_mov_b32 v[12:13], v[44:45], v[24:25] op_sel:[1,0]
	v_pk_mov_b32 v[24:25], v[46:47], v[26:27] op_sel:[1,0]
	v_mov_b32_e32 v8, v30
	v_pk_mul_f32 v[4:5], v[80:81], v[4:5] op_sel:[1,0] op_sel_hi:[0,1]
	v_pk_mul_f32 v[12:13], v[86:87], v[12:13] op_sel:[1,0] op_sel_hi:[0,1]
	v_pk_mul_f32 v[24:25], v[84:85], v[24:25] op_sel:[1,0] op_sel_hi:[0,1]
	v_pk_fma_f32 v[4:5], v[80:81], v[8:9], v[4:5]
	v_pk_fma_f32 v[12:13], v[86:87], v[144:145], v[12:13]
	v_pk_fma_f32 v[24:25], v[84:85], v[142:143], v[24:25]
	v_pk_add_f32 v[2:3], v[2:3], v[4:5]
	v_pk_add_f32 v[12:13], v[12:13], v[24:25]
	s_waitcnt lgkmcnt(0)
	v_pk_add_f32 v[98:99], v[182:183], v[106:107]
	v_pk_add_f32 v[2:3], v[6:7], v[2:3]
	v_pk_add_f32 v[10:11], v[10:11], v[12:13]
	v_mov_b32_e32 v13, v21
	v_pk_mov_b32 v[20:21], v[48:49], v[20:21] op_sel:[1,0]
	ds_bpermute_b32 v107, v146, v99
	ds_bpermute_b32 v106, v146, v98
	ds_bpermute_b32 v5, v18, v3
	ds_bpermute_b32 v4, v18, v2
	v_mov_b32_e32 v12, v48
	v_pk_mul_f32 v[20:21], v[78:79], v[20:21] op_sel:[1,0] op_sel_hi:[0,1]
	v_pk_fma_f32 v[12:13], v[78:79], v[12:13], v[20:21]
	v_mov_b32_e32 v21, v23
	v_pk_mov_b32 v[22:23], v[50:51], v[22:23] op_sel:[1,0]
	v_mov_b32_e32 v20, v50
	v_pk_mul_f32 v[22:23], v[76:77], v[22:23] op_sel:[1,0] op_sel_hi:[0,1]
	v_pk_fma_f32 v[20:21], v[76:77], v[20:21], v[22:23]
	s_waitcnt lgkmcnt(2)
	v_pk_add_f32 v[6:7], v[98:99], v[106:107]
	v_pk_add_f32 v[12:13], v[12:13], v[20:21]
	s_waitcnt lgkmcnt(0)
	v_pk_add_f32 v[2:3], v[2:3], v[4:5]
	v_pk_add_f32 v[10:11], v[10:11], v[12:13]
	v_mov_b32_e32 v13, v15
	v_pk_mov_b32 v[14:15], v[40:41], v[14:15] op_sel:[1,0]
	ds_bpermute_b32 v9, v147, v7
	ds_bpermute_b32 v8, v147, v6
	ds_bpermute_b32 v5, v146, v3
	ds_bpermute_b32 v4, v146, v2
	v_mov_b32_e32 v12, v40
	v_pk_mul_f32 v[14:15], v[82:83], v[14:15] op_sel:[1,0] op_sel_hi:[0,1]
	v_pk_fma_f32 v[12:13], v[82:83], v[12:13], v[14:15]
	v_mov_b32_e32 v15, v17
	v_pk_mov_b32 v[16:17], v[42:43], v[16:17] op_sel:[1,0]
	v_mov_b32_e32 v14, v42
	v_pk_mul_f32 v[16:17], v[80:81], v[16:17] op_sel:[1,0] op_sel_hi:[0,1]
	v_pk_fma_f32 v[14:15], v[80:81], v[14:15], v[16:17]
	s_waitcnt lgkmcnt(2)
	v_pk_add_f32 v[6:7], v[6:7], v[8:9]
	v_pk_add_f32 v[12:13], v[12:13], v[14:15]
	s_waitcnt lgkmcnt(0)
	v_pk_add_f32 v[2:3], v[2:3], v[4:5]
	v_pk_add_f32 v[10:11], v[10:11], v[12:13]
	ds_bpermute_b32 v9, v148, v7
	ds_bpermute_b32 v8, v148, v6
	ds_bpermute_b32 v5, v147, v3
	ds_bpermute_b32 v4, v147, v2
	ds_bpermute_b32 v13, v18, v11
	ds_bpermute_b32 v12, v18, v10
	s_waitcnt lgkmcnt(4)
	v_pk_add_f32 v[14:15], v[6:7], v[8:9]
	v_pk_add_f32 v[8:9], v[64:65], v[70:71]
	s_waitcnt lgkmcnt(2)
	v_pk_add_f32 v[2:3], v[2:3], v[4:5]
	v_pk_mov_b32 v[16:17], v[90:91], v[58:59] op_sel:[1,0]
	s_waitcnt lgkmcnt(0)
	v_pk_add_f32 v[4:5], v[10:11], v[12:13]
	v_pk_add_f32 v[10:11], v[100:101], v[96:97]
	v_pk_mov_b32 v[12:13], v[68:69], v[62:63] op_sel:[1,0]
	v_pk_add_f32 v[8:9], v[8:9], v[10:11]
	v_pk_mov_b32 v[10:11], v[66:67], v[60:61] op_sel:[1,0]
	v_pk_mul_f32 v[12:13], v[84:85], v[12:13] op_sel:[1,0] op_sel_hi:[0,1]
	v_pk_mul_f32 v[10:11], v[86:87], v[10:11] op_sel:[1,0] op_sel_hi:[0,1]
	v_pk_fma_f32 v[10:11], v[86:87], v[102:103], v[10:11]
	v_pk_fma_f32 v[12:13], v[84:85], v[104:105], v[12:13]
	v_pk_mul_f32 v[16:17], v[76:77], v[16:17] op_sel:[1,0] op_sel_hi:[0,1]
	v_pk_add_f32 v[10:11], v[10:11], v[12:13]
	v_pk_mov_b32 v[12:13], v[88:89], v[56:57] op_sel:[1,0]
	v_pk_add_f32 v[8:9], v[8:9], v[10:11]
	v_mov_b32_e32 v10, v88
	v_mov_b32_e32 v11, v57
	v_pk_mul_f32 v[12:13], v[78:79], v[12:13] op_sel:[1,0] op_sel_hi:[0,1]
	v_pk_fma_f32 v[10:11], v[78:79], v[10:11], v[12:13]
	v_mov_b32_e32 v12, v90
	v_mov_b32_e32 v13, v59
	v_pk_fma_f32 v[12:13], v[76:77], v[12:13], v[16:17]
	v_pk_mov_b32 v[16:17], v[94:95], v[54:55] op_sel:[1,0]
	v_pk_add_f32 v[10:11], v[10:11], v[12:13]
	v_pk_mov_b32 v[12:13], v[92:93], v[52:53] op_sel:[1,0]
	v_pk_add_f32 v[8:9], v[8:9], v[10:11]
	v_mov_b32_e32 v10, v92
	v_mov_b32_e32 v11, v53
	v_pk_mul_f32 v[12:13], v[82:83], v[12:13] op_sel:[1,0] op_sel_hi:[0,1]
	v_pk_fma_f32 v[10:11], v[82:83], v[10:11], v[12:13]
	v_mov_b32_e32 v12, v94
	v_mov_b32_e32 v13, v55
	v_pk_mul_f32 v[16:17], v[80:81], v[16:17] op_sel:[1,0] op_sel_hi:[0,1]
	v_pk_fma_f32 v[12:13], v[80:81], v[12:13], v[16:17]
	ds_bpermute_b32 v7, v146, v5
	v_pk_add_f32 v[10:11], v[10:11], v[12:13]
	ds_bpermute_b32 v6, v146, v4
	v_pk_add_f32 v[8:9], v[8:9], v[10:11]
	ds_bpermute_b32 v11, v18, v9
	ds_bpermute_b32 v10, v18, v8
	ds_bpermute_b32 v13, v148, v3
	s_waitcnt lgkmcnt(3)
	v_pk_add_f32 v[4:5], v[4:5], v[6:7]
	ds_bpermute_b32 v7, v147, v5
	ds_bpermute_b32 v6, v147, v4
	s_waitcnt lgkmcnt(3)
	v_pk_add_f32 v[8:9], v[8:9], v[10:11]
	ds_bpermute_b32 v11, v146, v9
	ds_bpermute_b32 v10, v146, v8
	ds_bpermute_b32 v12, v148, v2
	s_waitcnt lgkmcnt(3)
	v_pk_add_f32 v[4:5], v[4:5], v[6:7]
	ds_bpermute_b32 v7, v148, v5
	ds_bpermute_b32 v6, v148, v4
	s_waitcnt lgkmcnt(3)
	v_pk_add_f32 v[8:9], v[8:9], v[10:11]
	ds_bpermute_b32 v11, v147, v9
	ds_bpermute_b32 v10, v147, v8
	s_waitcnt lgkmcnt(4)
	v_pk_add_f32 v[2:3], v[2:3], v[12:13]
	s_waitcnt lgkmcnt(2)
	v_pk_add_f32 v[4:5], v[4:5], v[6:7]
	ds_bpermute_b32 v13, v149, v3
	ds_bpermute_b32 v12, v149, v2
	s_waitcnt lgkmcnt(2)
	v_pk_add_f32 v[6:7], v[8:9], v[10:11]
	ds_bpermute_b32 v9, v148, v7
	ds_bpermute_b32 v8, v148, v6
	ds_bpermute_b32 v11, v149, v5
	ds_bpermute_b32 v10, v149, v4
	ds_bpermute_b32 v17, v149, v15
	ds_bpermute_b32 v16, v149, v14
	s_waitcnt lgkmcnt(4)
	v_pk_add_f32 v[20:21], v[6:7], v[8:9]
	ds_bpermute_b32 v23, v149, v21
	ds_bpermute_b32 v22, v149, v20
	v_pk_add_f32 v[8:9], v[2:3], v[12:13]
	s_waitcnt lgkmcnt(4)
	v_pk_add_f32 v[6:7], v[4:5], v[10:11]
	s_waitcnt lgkmcnt(2)
	v_pk_add_f32 v[2:3], v[14:15], v[16:17]
	ds_bpermute_b32 v17, v150, v9
	s_waitcnt lgkmcnt(1)
	v_pk_add_f32 v[4:5], v[20:21], v[22:23]
	ds_bpermute_b32 v16, v150, v8
	ds_bpermute_b32 v15, v150, v7
	ds_bpermute_b32 v14, v150, v6
	ds_bpermute_b32 v11, v150, v3
	ds_bpermute_b32 v10, v150, v2
	ds_bpermute_b32 v13, v150, v5
	ds_bpermute_b32 v12, v150, v4
	s_and_saveexec_b64 s[18:19], s[0:1]
	s_cbranch_execz .LBB0_195
	s_lshl_b64 s[20:21], s[8:9], 5
	s_waitcnt lgkmcnt(6)
	v_pk_add_f32 v[8:9], v[8:9], v[16:17]
	s_waitcnt lgkmcnt(4)
	v_pk_add_f32 v[6:7], v[6:7], v[14:15]
	s_add_u32 s20, s40, s20
	s_waitcnt lgkmcnt(2)
	v_pk_add_f32 v[10:11], v[2:3], v[10:11]
	s_waitcnt lgkmcnt(0)
	v_pk_add_f32 v[12:13], v[4:5], v[12:13]
	s_addc_u32 s21, s41, s21
	v_mov_b32_e32 v2, v9
	v_mov_b32_e32 v3, v8
	v_mov_b32_e32 v4, v7
	v_mov_b32_e32 v5, v6
	global_store_dwordx4 v19, v[2:5], s[20:21]
	s_nop 1
	v_mov_b32_e32 v2, v11
	v_mov_b32_e32 v3, v10
	v_mov_b32_e32 v4, v13
	v_mov_b32_e32 v5, v12
	global_store_dwordx4 v19, v[2:5], s[20:21] offset:16

.LBB0_215:
	v_readlane_b32 s18, v254, 20
	s_ashr_i32 s9, s18, 31
	s_add_u32 s18, s43, s18
	s_addc_u32 s9, s42, s9
	s_mul_i32 s9, s9, 0xc000
	s_mul_hi_u32 s19, s18, 0xc000
	s_add_i32 s19, s19, s9
	s_mul_i32 s18, s18, 0xc000
	s_add_u32 s18, s38, s18
	s_addc_u32 s19, s39, s19
	v_lshl_add_u64 v[98:99], v[112:113], 4, s[18:19]
	v_add_co_u32_e32 v92, vcc, s78, v98
	global_load_dwordx4 v[48:51], v[118:119], off
	s_nop 0
	v_addc_co_u32_e32 v93, vcc, 0, v99, vcc
	global_load_dwordx4 v[52:55], v[92:93], off offset:-4096
	global_load_dwordx4 v[40:43], v[98:99], off
	s_mov_b64 s[18:19], 0x2000
	v_lshl_add_u64 v[88:89], v[98:99], 0, s[18:19]
	v_add_co_u32_e32 v130, vcc, s3, v98
	s_waitcnt vmcnt(10)
	v_mul_f32_e32 v18, v56, v56
	v_addc_co_u32_e32 v131, vcc, 0, v99, vcc
	s_ashr_i32 s9, s8, 31
	s_lshl_b64 s[18:19], s[8:9], 12
	v_lshl_add_u64 v[192:193], v[128:129], 0, s[18:19]
	s_lshl_b64 s[18:19], s[16:17], 12
	v_lshl_add_u64 v[190:191], v[128:129], 0, s[18:19]
	s_waitcnt vmcnt(1)
	v_pk_add_f32 v[54:55], v[54:55], 1.0 op_sel_hi:[1,0]
	v_pk_add_f32 v[52:53], v[52:53], 1.0 op_sel_hi:[1,0]
	v_pk_mul_f32 v[160:161], v[50:51], v[54:55]
	v_pk_mul_f32 v[162:163], v[48:49], v[52:53]
	global_load_dwordx4 v[52:55], v[118:119], off offset:1024
	global_load_dwordx4 v[64:67], v[88:89], off offset:1024
	global_load_dwordx4 v[48:51], v[98:99], off offset:1024
	s_waitcnt vmcnt(1)
	v_pk_add_f32 v[66:67], v[66:67], 1.0 op_sel_hi:[1,0]
	v_pk_add_f32 v[64:65], v[64:65], 1.0 op_sel_hi:[1,0]
	v_pk_mul_f32 v[170:171], v[54:55], v[66:67]
	v_pk_mul_f32 v[172:173], v[52:53], v[64:65]
	global_load_dwordx4 v[64:67], v[118:119], off offset:2048
	global_load_dwordx4 v[84:87], v[88:89], off offset:2048
	global_load_dwordx4 v[52:55], v[98:99], off offset:2048
	s_waitcnt vmcnt(1)
	v_pk_add_f32 v[86:87], v[86:87], 1.0 op_sel_hi:[1,0]
	v_pk_add_f32 v[84:85], v[84:85], 1.0 op_sel_hi:[1,0]
	v_pk_mul_f32 v[174:175], v[66:67], v[86:87]
	v_pk_mul_f32 v[176:177], v[64:65], v[84:85]
	global_load_dwordx4 v[84:87], v[118:119], off offset:3072
	s_nop 0
	global_load_dwordx4 v[88:91], v[88:89], off offset:3072
	s_nop 0
	global_load_dwordx4 v[64:67], v[98:99], off offset:3072
	s_waitcnt vmcnt(1)
	v_pk_add_f32 v[90:91], v[90:91], 1.0 op_sel_hi:[1,0]
	v_pk_add_f32 v[88:89], v[88:89], 1.0 op_sel_hi:[1,0]
	v_pk_mul_f32 v[178:179], v[86:87], v[90:91]
	v_pk_mul_f32 v[180:181], v[84:85], v[88:89]
	global_load_dwordx4 v[88:91], v[120:121], off
	global_load_dwordx4 v[94:97], v[92:93], off
	global_load_dwordx4 v[84:87], v[130:131], off
	s_waitcnt vmcnt(1)
	v_pk_add_f32 v[96:97], v[96:97], 1.0 op_sel_hi:[1,0]
	v_pk_add_f32 v[94:95], v[94:95], 1.0 op_sel_hi:[1,0]
	v_pk_mul_f32 v[184:185], v[90:91], v[96:97]
	v_pk_mul_f32 v[182:183], v[88:89], v[94:95]
	global_load_dwordx4 v[94:97], v[122:123], off
	global_load_dwordx4 v[98:101], v[92:93], off offset:1024
	global_load_dwordx4 v[88:91], v[130:131], off offset:1024
	s_waitcnt vmcnt(1)
	v_pk_add_f32 v[100:101], v[100:101], 1.0 op_sel_hi:[1,0]
	v_pk_add_f32 v[98:99], v[98:99], 1.0 op_sel_hi:[1,0]
	v_pk_mul_f32 v[188:189], v[96:97], v[100:101]
	v_pk_mul_f32 v[186:187], v[94:95], v[98:99]
	global_load_dwordx4 v[102:105], v[124:125], off
	global_load_dwordx4 v[106:109], v[92:93], off offset:2048
	global_load_dwordx4 v[96:99], v[130:131], off offset:2048
	s_waitcnt vmcnt(1)
	v_pk_add_f32 v[94:95], v[108:109], 1.0 op_sel_hi:[1,0]
	v_pk_add_f32 v[106:107], v[106:107], 1.0 op_sel_hi:[1,0]
	v_pk_mul_f32 v[100:101], v[104:105], v[94:95]
	v_pk_mul_f32 v[102:103], v[102:103], v[106:107]
	global_load_dwordx4 v[104:107], v[126:127], off
	global_load_dwordx4 v[108:111], v[92:93], off offset:3072
	s_nop 0
	global_load_dwordx4 v[92:95], v[130:131], off offset:3072
	s_waitcnt vmcnt(1)
	v_pk_add_f32 v[110:111], v[110:111], 1.0 op_sel_hi:[1,0]
	v_pk_add_f32 v[108:109], v[108:109], 1.0 op_sel_hi:[1,0]
	v_pk_mul_f32 v[144:145], v[106:107], v[110:111]
	v_mov_b32_e32 v106, v37
	v_mov_b32_e32 v107, v33
	v_pk_mul_f32 v[134:135], v[104:105], v[108:109]
	v_mov_b32_e32 v104, v36
	v_mov_b32_e32 v105, v32
	v_pk_mul_f32 v[106:107], v[106:107], v[106:107]
	v_mov_b32_e32 v108, v39
	v_mov_b32_e32 v109, v35
	v_pk_fma_f32 v[104:105], v[104:105], v[104:105], v[106:107]
	v_mov_b32_e32 v106, v38
	v_mov_b32_e32 v107, v34
	v_pk_mul_f32 v[108:109], v[108:109], v[108:109]
	s_nop 0
	v_pk_fma_f32 v[106:107], v[106:107], v[106:107], v[108:109]
	v_pk_mul_f32 v[108:109], v[28:29], v[28:29]
	v_pk_add_f32 v[104:105], v[104:105], v[106:107]
	v_pk_mul_f32 v[106:107], v[30:31], v[30:31]
	v_pk_add_f32 v[104:105], v[104:105], v[104:105] op_sel:[0,1] op_sel_hi:[1,0]
	v_pk_mov_b32 v[110:111], v[108:109], v[106:107] op_sel:[1,0]
	v_mov_b32_e32 v109, v107
	v_pk_add_f32 v[106:107], v[110:111], v[108:109]
	v_mul_f32_e32 v108, v57, v57
	v_pk_add_f32 v[106:107], v[106:107], v[106:107] op_sel:[0,1] op_sel_hi:[1,0]
	v_mov_b32_e32 v105, v18
	v_mov_b32_e32 v107, v108
	v_mul_f32_e32 v18, v45, v45
	v_mul_f32_e32 v109, v58, v58
	v_pk_add_f32 v[104:105], v[104:105], v[106:107]
	v_pk_fma_f32 v[106:107], v[44:45], v[44:45], v[18:19] op_sel_hi:[1,1,0]
	v_mul_f32_e32 v18, v47, v47
	v_mul_f32_e32 v110, v59, v59
	v_mov_b32_e32 v107, v109
	v_pk_fma_f32 v[108:109], v[46:47], v[46:47], v[18:19] op_sel_hi:[1,1,0]
	v_mul_f32_e32 v18, v76, v76
	v_mov_b32_e32 v109, v110
	v_pk_add_f32 v[106:107], v[106:107], v[108:109]
	v_pk_mul_f32 v[108:109], v[60:61], v[60:61]
	v_pk_add_f32 v[104:105], v[104:105], v[106:107]
	v_pk_mul_f32 v[106:107], v[62:63], v[62:63]
	v_pk_add_f32 v[104:105], v[104:105], v[104:105] op_sel:[0,1] op_sel_hi:[1,0]
	v_pk_mov_b32 v[110:111], v[108:109], v[106:107] op_sel:[1,0]
	v_mov_b32_e32 v109, v107
	v_pk_add_f32 v[106:107], v[110:111], v[108:109]
	v_mul_f32_e32 v108, v77, v77
	v_pk_add_f32 v[106:107], v[106:107], v[106:107] op_sel:[0,1] op_sel_hi:[1,0]
	v_mov_b32_e32 v105, v18
	v_mov_b32_e32 v107, v108
	v_mul_f32_e32 v18, v81, v81
	v_mul_f32_e32 v109, v78, v78
	v_pk_add_f32 v[104:105], v[104:105], v[106:107]
	v_pk_fma_f32 v[106:107], v[80:81], v[80:81], v[18:19] op_sel_hi:[1,1,0]
	v_mul_f32_e32 v18, v83, v83
	v_mul_f32_e32 v110, v79, v79
	v_mov_b32_e32 v107, v109
	v_pk_fma_f32 v[108:109], v[82:83], v[82:83], v[18:19] op_sel_hi:[1,1,0]
	v_mul_f32_e32 v18, v20, v20
	v_mov_b32_e32 v109, v110
	v_pk_add_f32 v[106:107], v[106:107], v[108:109]
	v_mov_b32_e32 v108, v13
	v_pk_add_f32 v[104:105], v[104:105], v[106:107]
	v_mov_b32_e32 v106, v11
	v_mov_b32_e32 v107, v7
	v_add_f32_e32 v130, v104, v105
	v_mov_b32_e32 v104, v10
	v_mov_b32_e32 v105, v6
	v_pk_mul_f32 v[106:107], v[106:107], v[106:107]
	v_mov_b32_e32 v109, v9
	v_pk_fma_f32 v[104:105], v[104:105], v[104:105], v[106:107]
	v_mov_b32_e32 v106, v12
	v_mov_b32_e32 v107, v8
	v_pk_mul_f32 v[108:109], v[108:109], v[108:109]
	s_nop 0
	v_pk_fma_f32 v[106:107], v[106:107], v[106:107], v[108:109]
	v_pk_mul_f32 v[108:109], v[2:3], v[2:3]
	v_pk_add_f32 v[104:105], v[104:105], v[106:107]
	v_pk_mul_f32 v[106:107], v[4:5], v[4:5]
	v_pk_add_f32 v[104:105], v[104:105], v[104:105] op_sel:[0,1] op_sel_hi:[1,0]
	v_pk_mov_b32 v[110:111], v[108:109], v[106:107] op_sel:[1,0]
	v_mov_b32_e32 v109, v107
	v_pk_add_f32 v[106:107], v[110:111], v[108:109]
	v_mul_f32_e32 v108, v21, v21
	v_pk_add_f32 v[106:107], v[106:107], v[106:107] op_sel:[0,1] op_sel_hi:[1,0]
	v_mov_b32_e32 v105, v18
	v_mov_b32_e32 v107, v108
	v_mul_f32_e32 v18, v15, v15
	v_mul_f32_e32 v109, v22, v22
	v_pk_add_f32 v[104:105], v[104:105], v[106:107]
	v_pk_fma_f32 v[106:107], v[14:15], v[14:15], v[18:19] op_sel_hi:[1,1,0]
	v_mul_f32_e32 v18, v17, v17
	v_mul_f32_e32 v110, v23, v23
	v_mov_b32_e32 v107, v109
	v_pk_fma_f32 v[108:109], v[16:17], v[16:17], v[18:19] op_sel_hi:[1,1,0]
	v_mul_f32_e32 v18, v68, v68
	v_mov_b32_e32 v109, v110
	v_pk_add_f32 v[106:107], v[106:107], v[108:109]
	v_pk_mul_f32 v[108:109], v[24:25], v[24:25]
	v_pk_add_f32 v[104:105], v[104:105], v[106:107]
	v_pk_mul_f32 v[106:107], v[26:27], v[26:27]
	v_pk_add_f32 v[104:105], v[104:105], v[104:105] op_sel:[0,1] op_sel_hi:[1,0]
	v_pk_mov_b32 v[110:111], v[108:109], v[106:107] op_sel:[1,0]
	v_mov_b32_e32 v109, v107
	v_pk_add_f32 v[106:107], v[110:111], v[108:109]
	v_mul_f32_e32 v108, v69, v69
	v_pk_add_f32 v[106:107], v[106:107], v[106:107] op_sel:[0,1] op_sel_hi:[1,0]
	v_mov_b32_e32 v105, v18
	v_mov_b32_e32 v107, v108
	v_mul_f32_e32 v18, v73, v73
	v_mul_f32_e32 v109, v70, v70
	v_pk_add_f32 v[104:105], v[104:105], v[106:107]
	v_pk_fma_f32 v[106:107], v[72:73], v[72:73], v[18:19] op_sel_hi:[1,1,0]
	v_mul_f32_e32 v18, v75, v75
	v_mul_f32_e32 v110, v71, v71
	v_mov_b32_e32 v107, v109
	v_pk_fma_f32 v[108:109], v[74:75], v[74:75], v[18:19] op_sel_hi:[1,1,0]
	s_nop 0
	v_mov_b32_e32 v109, v110
	v_pk_add_f32 v[106:107], v[106:107], v[108:109]
	s_nop 0
	v_pk_add_f32 v[104:105], v[104:105], v[106:107]
	s_nop 0
	v_add_f32_e32 v18, v104, v105
	v_and_b32_e32 v104, 64, v213
	v_add_u32_e32 v104, 64, v104
	v_xor_b32_e32 v105, 1, v213
	v_cmp_lt_i32_e32 vcc, v105, v104
	s_nop 1
	v_cndmask_b32_e32 v105, v213, v105, vcc
	v_lshlrev_b32_e32 v167, 2, v105
	ds_bpermute_b32 v106, v167, v18
	ds_bpermute_b32 v105, v167, v130
	s_waitcnt lgkmcnt(1)
	v_add_f32_e32 v18, v18, v106
	v_xor_b32_e32 v106, 2, v213
	v_cmp_lt_i32_e32 vcc, v106, v104
	s_waitcnt lgkmcnt(0)
	v_add_f32_e32 v105, v130, v105
	v_cndmask_b32_e32 v106, v213, v106, vcc
	v_lshlrev_b32_e32 v194, 2, v106
	ds_bpermute_b32 v106, v194, v105
	s_waitcnt lgkmcnt(0)
	v_add_f32_e32 v105, v105, v106
	ds_bpermute_b32 v106, v194, v18
	s_waitcnt lgkmcnt(0)
	v_add_f32_e32 v18, v18, v106
	v_xor_b32_e32 v106, 4, v213
	v_cmp_lt_i32_e32 vcc, v106, v104
	s_nop 1
	v_cndmask_b32_e32 v106, v213, v106, vcc
	v_lshlrev_b32_e32 v195, 2, v106
	ds_bpermute_b32 v106, v195, v105
	s_waitcnt lgkmcnt(0)
	v_add_f32_e32 v105, v105, v106
	ds_bpermute_b32 v106, v195, v18
	s_waitcnt lgkmcnt(0)
	v_add_f32_e32 v18, v18, v106
	v_xor_b32_e32 v106, 8, v213
	v_cmp_lt_i32_e32 vcc, v106, v104
	s_nop 1
	v_cndmask_b32_e32 v106, v213, v106, vcc
	v_lshlrev_b32_e32 v196, 2, v106
	ds_bpermute_b32 v106, v196, v105
	s_waitcnt lgkmcnt(0)
	v_add_f32_e32 v105, v105, v106
	ds_bpermute_b32 v106, v196, v18
	s_waitcnt lgkmcnt(0)
	v_add_f32_e32 v18, v18, v106
	v_xor_b32_e32 v106, 16, v213
	v_cmp_lt_i32_e32 vcc, v106, v104
	s_nop 1
	v_cndmask_b32_e32 v106, v213, v106, vcc
	v_lshlrev_b32_e32 v198, 2, v106
	ds_bpermute_b32 v106, v198, v105
	s_waitcnt lgkmcnt(0)
	v_add_f32_e32 v105, v105, v106
	ds_bpermute_b32 v106, v198, v18
	s_waitcnt lgkmcnt(0)
	v_add_f32_e32 v18, v18, v106
	v_xor_b32_e32 v106, 32, v213
	v_cmp_lt_i32_e32 vcc, v106, v104
	s_nop 1
	v_cndmask_b32_e32 v104, v213, v106, vcc
	v_lshlrev_b32_e32 v197, 2, v104
	ds_bpermute_b32 v104, v197, v105
	s_waitcnt lgkmcnt(0)
	v_add_f32_e32 v104, v105, v104
	ds_bpermute_b32 v105, v197, v18
	v_fmamk_f32 v104, v104, 0x3a000000, v165
	v_rsq_f32_e32 v148, v104
	s_waitcnt lgkmcnt(0)
	v_add_f32_e32 v18, v18, v105
	v_fmamk_f32 v18, v18, 0x3a000000, v165
	v_rsq_f32_e32 v18, v18
	v_pk_mul_f32 v[80:81], v[80:81], v[148:149] op_sel_hi:[1,0]
	v_pk_mul_f32 v[140:141], v[76:77], v[148:149] op_sel_hi:[1,0]
	v_pk_fma_f32 v[138:139], v[102:103], v[80:81], v[96:97]
	v_pk_mul_f32 v[72:73], v[72:73], v[18:19] op_sel_hi:[1,0]
	v_pk_mul_f32 v[80:81], v[82:83], v[148:149] op_sel_hi:[1,0]
	v_pk_fma_f32 v[130:131], v[102:103], v[72:73], v[96:97]
	v_pk_mul_f32 v[72:73], v[74:75], v[18:19] op_sel_hi:[1,0]
	v_pk_mul_f32 v[150:151], v[68:69], v[18:19] op_sel_hi:[1,0]
	v_pk_fma_f32 v[136:137], v[100:101], v[80:81], v[98:99]
	v_bfe_u32 v80, v138, 16, 1
	v_pk_mul_f32 v[146:147], v[78:79], v[148:149] op_sel_hi:[1,0]
	v_pk_fma_f32 v[132:133], v[100:101], v[72:73], v[98:99]
	v_bfe_u32 v72, v130, 16, 1
	v_pk_mul_f32 v[152:153], v[70:71], v[18:19] op_sel_hi:[1,0]
	s_waitcnt vmcnt(0)
	v_pk_fma_f32 v[142:143], v[134:135], v[140:141], v[92:93]
	v_pk_fma_f32 v[134:135], v[134:135], v[150:151], v[92:93]
	v_add3_u32 v80, v138, v80, s79
	v_bfe_u32 v81, v139, 16, 1
	v_add3_u32 v72, v130, v72, s79
	v_bfe_u32 v73, v131, 16, 1
	v_pk_fma_f32 v[140:141], v[144:145], v[146:147], v[94:95]
	v_bfe_u32 v146, v142, 16, 1
	v_pk_fma_f32 v[92:93], v[144:145], v[152:153], v[94:95]
	v_bfe_u32 v94, v134, 16, 1
	v_lshrrev_b32_e32 v80, 16, v80
	v_add3_u32 v81, v139, v81, s79
	v_lshrrev_b32_e32 v72, 16, v72
	v_add3_u32 v73, v131, v73, s79
	v_add3_u32 v146, v142, v146, s79
	v_bfe_u32 v147, v143, 16, 1
	v_add3_u32 v94, v134, v94, s79
	v_bfe_u32 v95, v135, 16, 1
	v_and_or_b32 v80, v81, s80, v80
	v_bfe_u32 v81, v136, 16, 1
	v_and_or_b32 v72, v73, s80, v72
	v_bfe_u32 v73, v132, 16, 1
	v_lshrrev_b32_e32 v146, 16, v146
	v_add3_u32 v147, v143, v147, s79
	v_lshrrev_b32_e32 v94, 16, v94
	v_add3_u32 v95, v135, v95, s79
	v_add3_u32 v81, v136, v81, s79
	v_bfe_u32 v82, v137, 16, 1
	v_add3_u32 v73, v132, v73, s79
	v_bfe_u32 v74, v133, 16, 1
	v_and_or_b32 v146, v147, s80, v146
	v_bfe_u32 v147, v140, 16, 1
	v_bfe_u32 v149, v141, 16, 1
	v_and_or_b32 v94, v95, s80, v94
	v_bfe_u32 v95, v92, 16, 1
	v_lshrrev_b32_e32 v81, 16, v81
	v_add3_u32 v82, v137, v82, s79
	v_lshrrev_b32_e32 v73, 16, v73
	v_add3_u32 v74, v133, v74, s79
	v_add3_u32 v147, v140, v147, s79
	v_add3_u32 v149, v141, v149, s79
	v_add3_u32 v95, v92, v95, s79
	v_bfe_u32 v144, v93, 16, 1
	v_and_or_b32 v81, v82, s80, v81
	v_and_or_b32 v73, v74, s80, v73
	v_lshrrev_b32_e32 v147, 16, v147
	v_lshrrev_b32_e32 v95, 16, v95
	v_add3_u32 v144, v93, v144, s79
	v_pk_mul_f32 v[62:63], v[62:63], v[148:149] op_sel_hi:[1,0]
	v_subrev_u32_e32 v248, s30, v192
	v_add_u32_e32 v248, 0xe8400000, v248
	v_and_b32_e32 v249, 0xfff00000, v248
	v_lshrrev_b32_e32 v218, 5, v248
	v_and_b32_e32 v218, 0x7800, v218
	v_or_b32_e32 v249, v249, v218
	v_lshrrev_b32_e32 v218, 6, v248
	v_and_b32_e32 v218, 0x3c0, v218
	v_or_b32_e32 v249, v249, v218
	v_and_b32_e32 v218, 0x180, v248
	v_lshlrev_b32_e32 v218, 8, v218
	v_or_b32_e32 v249, v249, v218
	v_and_b32_e32 v218, 64, v248
	v_lshlrev_b32_e32 v218, 4, v218
	v_or_b32_e32 v249, v249, v218
	v_and_b32_e32 v218, 56, v248
	v_or_b32_e32 v249, v249, v218
	v_lshrrev_b32_e32 v218, 10, v248
	v_and_b32_e32 v218, 32, v218
	v_xor_b32_e32 v249, v249, v218
	v_sub_u32_e32 v218, v249, v248
	v_ashrrev_i32_e32 v219, 31, v218
	v_lshl_add_u64 v[192:193], v[192:193], 0, v[218:219]
	s_mov_b64 s[100:101], 0xc0000
	v_lshl_add_u64 v[248:249], v[192:193], 0, s[100:101]
	global_store_dwordx2 v[248:249], v[80:81], off
	v_subrev_u32_e32 v248, s30, v190
	v_add_u32_e32 v248, 0xe8400000, v248
	v_and_b32_e32 v249, 0xfff00000, v248
	v_lshrrev_b32_e32 v218, 5, v248
	v_and_b32_e32 v218, 0x7800, v218
	v_or_b32_e32 v249, v249, v218
	v_lshrrev_b32_e32 v218, 6, v248
	v_and_b32_e32 v218, 0x3c0, v218
	v_or_b32_e32 v249, v249, v218
	v_and_b32_e32 v218, 0x180, v248
	v_lshlrev_b32_e32 v218, 8, v218
	v_or_b32_e32 v249, v249, v218
	v_and_b32_e32 v218, 64, v248
	v_lshlrev_b32_e32 v218, 4, v218
	v_or_b32_e32 v249, v249, v218
	v_and_b32_e32 v218, 56, v248
	v_or_b32_e32 v249, v249, v218
	v_lshrrev_b32_e32 v218, 10, v248
	v_and_b32_e32 v218, 32, v218
	v_xor_b32_e32 v249, v249, v218
	v_sub_u32_e32 v218, v249, v248
	v_ashrrev_i32_e32 v219, 31, v218
	v_lshl_add_u64 v[190:191], v[190:191], 0, v[218:219]
	s_mov_b64 s[100:101], 0xc0000
	v_lshl_add_u64 v[248:249], v[190:191], 0, s[100:101]
	global_store_dwordx2 v[248:249], v[72:73], off
	v_and_or_b32 v147, v149, s80, v147
	v_and_or_b32 v95, v144, s80, v95
	v_pk_fma_f32 v[62:63], v[188:189], v[62:63], v[90:91]
	ds_read_b128 v[108:111], v1
	ds_read_b128 v[104:107], v1 offset:1024
	ds_read_b128 v[100:103], v1 offset:2048
	ds_read_b128 v[96:99], v1 offset:3072
	ds_read_b128 v[80:83], v1 offset:4096
	ds_read_b128 v[76:79], v1 offset:5120
	ds_read_b128 v[72:75], v1 offset:6144
	ds_read_b128 v[68:71], v1 offset:7168
	s_mov_b64 s[100:101], 0xe0000
	v_lshl_add_u64 v[248:249], v[192:193], 0, s[100:101]
	global_store_dwordx2 v[248:249], v[146:147], off
	s_mov_b64 s[100:101], 0xe0000
	v_lshl_add_u64 v[248:249], v[190:191], 0, s[100:101]
	global_store_dwordx2 v[248:249], v[94:95], off
	v_bfe_u32 v94, v62, 16, 1
	v_add3_u32 v94, v62, v94, s79
	v_bfe_u32 v95, v63, 16, 1
	v_pk_mul_f32 v[60:61], v[60:61], v[148:149] op_sel_hi:[1,0]
	v_lshrrev_b32_e32 v94, 16, v94
	v_add3_u32 v95, v63, v95, s79
	v_pk_fma_f32 v[60:61], v[186:187], v[60:61], v[88:89]
	v_and_or_b32 v95, v95, s80, v94
	v_bfe_u32 v94, v60, 16, 1
	v_add3_u32 v94, v60, v94, s79
	v_bfe_u32 v144, v61, 16, 1
	v_lshrrev_b32_e32 v94, 16, v94
	v_add3_u32 v144, v61, v144, s79
	v_pk_mul_f32 v[44:45], v[44:45], v[148:149] op_sel_hi:[1,0]
	v_and_or_b32 v94, v144, s80, v94
	v_pk_mul_f32 v[58:59], v[58:59], v[148:149] op_sel_hi:[1,0]
	v_pk_mul_f32 v[56:57], v[56:57], v[148:149] op_sel_hi:[1,0]
	v_pk_fma_f32 v[146:147], v[180:181], v[44:45], v[64:65]
	s_mov_b64 s[100:101], 0xa0000
	v_lshl_add_u64 v[248:249], v[192:193], 0, s[100:101]
	global_store_dwordx2 v[248:249], v[94:95], off
	v_pk_fma_f32 v[94:95], v[184:185], v[58:59], v[86:87]
	v_pk_fma_f32 v[144:145], v[182:183], v[56:57], v[84:85]
	v_pk_mul_f32 v[44:45], v[46:47], v[148:149] op_sel_hi:[1,0]
	v_bfe_u32 v46, v146, 16, 1
	v_bfe_u32 v58, v94, 16, 1
	v_bfe_u32 v56, v144, 16, 1
	v_add3_u32 v46, v146, v46, s79
	v_bfe_u32 v47, v147, 16, 1
	v_add3_u32 v58, v94, v58, s79
	v_bfe_u32 v59, v95, 16, 1
	v_add3_u32 v56, v144, v56, s79
	v_bfe_u32 v57, v145, 16, 1
	v_pk_fma_f32 v[44:45], v[178:179], v[44:45], v[66:67]
	v_lshrrev_b32_e32 v46, 16, v46
	v_add3_u32 v47, v147, v47, s79
	v_lshrrev_b32_e32 v58, 16, v58
	v_add3_u32 v59, v95, v59, s79
	v_lshrrev_b32_e32 v56, 16, v56
	v_add3_u32 v57, v145, v57, s79
	v_and_or_b32 v46, v47, s80, v46
	v_bfe_u32 v47, v44, 16, 1
	v_and_or_b32 v59, v59, s80, v58
	v_and_or_b32 v58, v57, s80, v56
	v_add3_u32 v47, v44, v47, s79
	v_bfe_u32 v56, v45, 16, 1
	v_lshrrev_b32_e32 v47, 16, v47
	v_add3_u32 v56, v45, v56, s79
	v_and_or_b32 v47, v56, s80, v47
	v_pk_mul_f32 v[22:23], v[22:23], v[18:19] op_sel_hi:[1,0]
	v_pk_mul_f32 v[14:15], v[14:15], v[18:19] op_sel_hi:[1,0]
	s_mov_b64 s[100:101], 0x60000
	v_lshl_add_u64 v[248:249], v[192:193], 0, s[100:101]
	global_store_dwordx2 v[248:249], v[46:47], off
	v_pk_mul_f32 v[36:37], v[36:37], v[148:149] op_sel_hi:[1,0]
	v_pk_mul_f32 v[32:33], v[32:33], v[148:149] op_sel_hi:[1,0]
	v_pk_mul_f32 v[28:29], v[28:29], v[148:149] op_sel_hi:[1,0]
	v_pk_mul_f32 v[26:27], v[26:27], v[18:19] op_sel_hi:[1,0]
	v_pk_fma_f32 v[46:47], v[184:185], v[22:23], v[86:87]
	v_pk_fma_f32 v[86:87], v[180:181], v[14:15], v[64:65]
	v_pk_mul_f32 v[14:15], v[16:17], v[18:19] op_sel_hi:[1,0]
	v_pk_mul_f32 v[10:11], v[10:11], v[18:19] op_sel_hi:[1,0]
	v_pk_mul_f32 v[6:7], v[6:7], v[18:19] op_sel_hi:[1,0]
	v_pk_mul_f32 v[2:3], v[2:3], v[18:19] op_sel_hi:[1,0]
	v_pk_fma_f32 v[154:155], v[162:163], v[36:37], v[40:41]
	v_pk_mul_f32 v[36:37], v[38:39], v[148:149] op_sel_hi:[1,0]
	v_pk_fma_f32 v[158:159], v[172:173], v[32:33], v[48:49]
	v_pk_mul_f32 v[32:33], v[34:35], v[148:149] op_sel_hi:[1,0]
	v_pk_fma_f32 v[150:151], v[176:177], v[28:29], v[52:53]
	v_pk_mul_f32 v[28:29], v[30:31], v[148:149] op_sel_hi:[1,0]
	v_pk_fma_f32 v[56:57], v[188:189], v[26:27], v[90:91]
	v_pk_mul_f32 v[24:25], v[24:25], v[18:19] op_sel_hi:[1,0]
	v_pk_fma_f32 v[64:65], v[178:179], v[14:15], v[66:67]
	v_pk_fma_f32 v[66:67], v[162:163], v[10:11], v[40:41]
	v_pk_mul_f32 v[10:11], v[12:13], v[18:19] op_sel_hi:[1,0]
	v_pk_fma_f32 v[48:49], v[172:173], v[6:7], v[48:49]
	v_pk_mul_f32 v[6:7], v[8:9], v[18:19] op_sel_hi:[1,0]
	v_pk_fma_f32 v[90:91], v[176:177], v[2:3], v[52:53]
	v_pk_mul_f32 v[2:3], v[4:5], v[18:19] op_sel_hi:[1,0]
	s_mov_b64 s[100:101], 0x80000
	v_lshl_add_u64 v[248:249], v[192:193], 0, s[100:101]
	global_store_dwordx2 v[248:249], v[58:59], off
	v_pk_fma_f32 v[152:153], v[160:161], v[36:37], v[42:43]
	v_bfe_u32 v36, v154, 16, 1
	v_pk_fma_f32 v[156:157], v[170:171], v[32:33], v[50:51]
	v_bfe_u32 v32, v158, 16, 1
	v_pk_fma_f32 v[148:149], v[174:175], v[28:29], v[54:55]
	v_bfe_u32 v28, v150, 16, 1
	v_pk_fma_f32 v[58:59], v[186:187], v[24:25], v[88:89]
	v_bfe_u32 v14, v86, 16, 1
	v_pk_fma_f32 v[88:89], v[160:161], v[10:11], v[42:43]
	v_bfe_u32 v10, v66, 16, 1
	v_pk_fma_f32 v[50:51], v[170:171], v[6:7], v[50:51]
	v_bfe_u32 v6, v48, 16, 1
	v_pk_fma_f32 v[54:55], v[174:175], v[2:3], v[54:55]
	v_bfe_u32 v2, v90, 16, 1
	v_add3_u32 v36, v154, v36, s79
	v_bfe_u32 v37, v155, 16, 1
	v_add3_u32 v32, v158, v32, s79
	v_bfe_u32 v33, v159, 16, 1
	v_add3_u32 v28, v150, v28, s79
	v_bfe_u32 v29, v151, 16, 1
	v_pk_mul_f32 v[20:21], v[20:21], v[18:19] op_sel_hi:[1,0]
	v_add3_u32 v14, v86, v14, s79
	v_bfe_u32 v15, v87, 16, 1
	v_add3_u32 v10, v66, v10, s79
	v_bfe_u32 v11, v67, 16, 1
	v_add3_u32 v6, v48, v6, s79
	v_bfe_u32 v7, v49, 16, 1
	v_add3_u32 v2, v90, v2, s79
	v_bfe_u32 v3, v91, 16, 1
	v_lshrrev_b32_e32 v36, 16, v36
	v_add3_u32 v37, v155, v37, s79
	v_lshrrev_b32_e32 v32, 16, v32
	v_add3_u32 v33, v159, v33, s79
	v_lshrrev_b32_e32 v28, 16, v28
	v_add3_u32 v29, v151, v29, s79
	v_pk_fma_f32 v[84:85], v[182:183], v[20:21], v[84:85]
	v_lshrrev_b32_e32 v14, 16, v14
	v_add3_u32 v15, v87, v15, s79
	v_lshrrev_b32_e32 v10, 16, v10
	v_add3_u32 v11, v67, v11, s79
	v_lshrrev_b32_e32 v6, 16, v6
	v_add3_u32 v7, v49, v7, s79
	v_lshrrev_b32_e32 v2, 16, v2
	v_add3_u32 v3, v91, v3, s79
	v_and_or_b32 v36, v37, s80, v36
	v_bfe_u32 v37, v152, 16, 1
	v_and_or_b32 v32, v33, s80, v32
	v_bfe_u32 v33, v156, 16, 1
	v_and_or_b32 v28, v29, s80, v28
	v_bfe_u32 v29, v148, 16, 1
	v_bfe_u32 v26, v56, 16, 1
	v_bfe_u32 v24, v58, 16, 1
	v_bfe_u32 v22, v46, 16, 1
	v_bfe_u32 v20, v84, 16, 1
	v_and_or_b32 v14, v15, s80, v14
	v_bfe_u32 v15, v64, 16, 1
	v_and_or_b32 v10, v11, s80, v10
	v_bfe_u32 v11, v88, 16, 1
	v_and_or_b32 v6, v7, s80, v6
	v_bfe_u32 v7, v50, 16, 1
	v_and_or_b32 v2, v3, s80, v2
	v_bfe_u32 v3, v54, 16, 1
	v_add3_u32 v37, v152, v37, s79
	v_bfe_u32 v38, v153, 16, 1
	v_add3_u32 v33, v156, v33, s79
	v_bfe_u32 v34, v157, 16, 1
	v_add3_u32 v29, v148, v29, s79
	v_bfe_u32 v30, v149, 16, 1
	v_add3_u32 v26, v56, v26, s79
	v_bfe_u32 v27, v57, 16, 1
	v_add3_u32 v24, v58, v24, s79
	v_bfe_u32 v25, v59, 16, 1
	v_add3_u32 v22, v46, v22, s79
	v_bfe_u32 v23, v47, 16, 1
	v_add3_u32 v20, v84, v20, s79
	v_bfe_u32 v21, v85, 16, 1
	v_add3_u32 v15, v64, v15, s79
	v_bfe_u32 v16, v65, 16, 1
	v_add3_u32 v11, v88, v11, s79
	v_bfe_u32 v12, v89, 16, 1
	v_add3_u32 v7, v50, v7, s79
	v_bfe_u32 v8, v51, 16, 1
	v_add3_u32 v3, v54, v3, s79
	v_bfe_u32 v4, v55, 16, 1
	v_lshrrev_b32_e32 v37, 16, v37
	v_add3_u32 v38, v153, v38, s79
	v_lshrrev_b32_e32 v33, 16, v33
	v_add3_u32 v34, v157, v34, s79
	v_lshrrev_b32_e32 v29, 16, v29
	v_add3_u32 v30, v149, v30, s79
	v_lshrrev_b32_e32 v26, 16, v26
	v_add3_u32 v27, v57, v27, s79
	v_lshrrev_b32_e32 v24, 16, v24
	v_add3_u32 v25, v59, v25, s79
	v_lshrrev_b32_e32 v22, 16, v22
	v_add3_u32 v23, v47, v23, s79
	v_lshrrev_b32_e32 v20, 16, v20
	v_add3_u32 v21, v85, v21, s79
	v_lshrrev_b32_e32 v15, 16, v15
	v_add3_u32 v16, v65, v16, s79
	v_lshrrev_b32_e32 v11, 16, v11
	v_add3_u32 v12, v89, v12, s79
	v_lshrrev_b32_e32 v7, 16, v7
	v_add3_u32 v8, v51, v8, s79
	v_lshrrev_b32_e32 v3, 16, v3
	v_add3_u32 v4, v55, v4, s79
	v_and_or_b32 v37, v38, s80, v37
	v_and_or_b32 v33, v34, s80, v33
	v_and_or_b32 v29, v30, s80, v29
	v_and_or_b32 v27, v27, s80, v26
	v_and_or_b32 v26, v25, s80, v24
	v_and_or_b32 v23, v23, s80, v22
	v_and_or_b32 v22, v21, s80, v20
	v_and_or_b32 v15, v16, s80, v15
	v_and_or_b32 v11, v12, s80, v11
	v_and_or_b32 v7, v8, s80, v7
	v_and_or_b32 v3, v4, s80, v3
	global_store_dwordx2 v[192:193], v[36:37], off
	s_mov_b64 s[100:101], 0x20000
	v_lshl_add_u64 v[248:249], v[192:193], 0, s[100:101]
	global_store_dwordx2 v[248:249], v[32:33], off
	s_mov_b64 s[100:101], 0x40000
	v_lshl_add_u64 v[248:249], v[192:193], 0, s[100:101]
	global_store_dwordx2 v[248:249], v[28:29], off
	s_mov_b64 s[100:101], 0xa0000
	v_lshl_add_u64 v[248:249], v[190:191], 0, s[100:101]
	global_store_dwordx2 v[248:249], v[26:27], off
	s_mov_b64 s[100:101], 0x80000
	v_lshl_add_u64 v[248:249], v[190:191], 0, s[100:101]
	global_store_dwordx2 v[248:249], v[22:23], off
	s_mov_b64 s[100:101], 0x60000
	v_lshl_add_u64 v[248:249], v[190:191], 0, s[100:101]
	global_store_dwordx2 v[248:249], v[14:15], off
	global_store_dwordx2 v[190:191], v[10:11], off
	s_mov_b64 s[100:101], 0x20000
	v_lshl_add_u64 v[248:249], v[190:191], 0, s[100:101]
	global_store_dwordx2 v[248:249], v[6:7], off
	s_mov_b64 s[100:101], 0x40000
	v_lshl_add_u64 v[248:249], v[190:191], 0, s[100:101]
	global_store_dwordx2 v[248:249], v[2:3], off
	ds_read_b128 v[2:5], v1 offset:8192
	ds_read_b128 v[6:9], v1 offset:9216
	s_waitcnt lgkmcnt(9)
	v_mov_b32_e32 v11, v109
	v_mov_b32_e32 v13, v111
	s_waitcnt lgkmcnt(8)
	v_mov_b32_e32 v17, v105
	s_waitcnt lgkmcnt(1)
	v_mov_b32_e32 v10, v2
	v_mov_b32_e32 v12, v4
	v_mov_b32_e32 v109, v3
	v_pk_mul_f32 v[2:3], v[66:67], v[10:11]
	v_pk_mul_f32 v[14:15], v[88:89], v[12:13]
	v_mov_b32_e32 v111, v5
	v_pk_fma_f32 v[2:3], v[66:67], v[108:109], v[2:3] op_sel:[0,0,1] op_sel_hi:[1,1,0]
	v_pk_fma_f32 v[4:5], v[88:89], v[110:111], v[14:15] op_sel:[0,0,1] op_sel_hi:[1,1,0]
	s_waitcnt lgkmcnt(0)
	v_mov_b32_e32 v16, v6
	v_pk_add_f32 v[2:3], v[2:3], v[4:5]
	v_mov_b32_e32 v105, v7
	v_pk_add_f32 v[14:15], v[2:3], 0 op_sel_hi:[1,0]
	v_pk_mul_f32 v[2:3], v[48:49], v[16:17]
	v_mov_b32_e32 v20, v8
	v_pk_fma_f32 v[6:7], v[48:49], v[104:105], v[2:3] op_sel:[0,0,1] op_sel_hi:[1,1,0]
	ds_read_b128 v[2:5], v1 offset:10240
	v_mov_b32_e32 v21, v107
	v_pk_mul_f32 v[22:23], v[50:51], v[20:21]
	v_mov_b32_e32 v107, v9
	v_pk_fma_f32 v[8:9], v[50:51], v[106:107], v[22:23] op_sel:[0,0,1] op_sel_hi:[1,1,0]
	v_mov_b32_e32 v23, v101
	v_pk_add_f32 v[6:7], v[6:7], v[8:9]
	v_mov_b32_e32 v29, v99
	v_pk_add_f32 v[14:15], v[14:15], v[6:7]
	ds_read_b128 v[6:9], v1 offset:11264
	s_waitcnt lgkmcnt(1)
	v_mov_b32_e32 v22, v2
	v_pk_mul_f32 v[24:25], v[90:91], v[22:23]
	v_mov_b32_e32 v101, v3
	v_pk_fma_f32 v[2:3], v[90:91], v[100:101], v[24:25] op_sel:[0,0,1] op_sel_hi:[1,1,0]
	v_mov_b32_e32 v24, v4
	v_mov_b32_e32 v25, v103
	v_pk_mul_f32 v[26:27], v[54:55], v[24:25]
	v_mov_b32_e32 v103, v5
	v_pk_fma_f32 v[4:5], v[54:55], v[102:103], v[26:27] op_sel:[0,0,1] op_sel_hi:[1,1,0]
	s_waitcnt lgkmcnt(0)
	v_mov_b32_e32 v26, v6
	v_pk_add_f32 v[2:3], v[2:3], v[4:5]
	v_mov_b32_e32 v27, v97
	v_pk_add_f32 v[14:15], v[14:15], v[2:3]
	v_pk_mul_f32 v[2:3], v[86:87], v[26:27]
	v_mov_b32_e32 v97, v7
	v_mov_b32_e32 v28, v8
	v_pk_fma_f32 v[6:7], v[86:87], v[96:97], v[2:3] op_sel:[0,0,1] op_sel_hi:[1,1,0]
	v_pk_mul_f32 v[30:31], v[64:65], v[28:29]
	v_mov_b32_e32 v99, v9
	ds_read_b128 v[2:5], v1 offset:12288
	v_pk_fma_f32 v[8:9], v[64:65], v[98:99], v[30:31] op_sel:[0,0,1] op_sel_hi:[1,1,0]
	v_mov_b32_e32 v31, v81
	v_pk_add_f32 v[6:7], v[6:7], v[8:9]
	v_mov_b32_e32 v33, v83
	v_pk_add_f32 v[14:15], v[14:15], v[6:7]
	ds_read_b128 v[6:9], v1 offset:13312
	s_waitcnt lgkmcnt(1)
	v_mov_b32_e32 v81, v3
	v_mov_b32_e32 v83, v5
	v_mov_b32_e32 v30, v2
	v_pk_mul_f32 v[2:3], v[84:85], v[80:81]
	v_mov_b32_e32 v32, v4
	v_pk_mul_f32 v[4:5], v[46:47], v[82:83]
	v_pk_fma_f32 v[2:3], v[84:85], v[30:31], v[2:3] op_sel:[0,0,1] op_sel_hi:[1,1,0]
	v_pk_fma_f32 v[4:5], v[46:47], v[32:33], v[4:5] op_sel:[0,0,1] op_sel_hi:[1,1,0]
	v_mov_b32_e32 v35, v77
	v_pk_add_f32 v[2:3], v[2:3], v[4:5]
	s_waitcnt lgkmcnt(0)
	v_mov_b32_e32 v77, v7
	v_pk_add_f32 v[14:15], v[14:15], v[2:3] op_sel:[1,0] op_sel_hi:[0,1]
	v_mov_b32_e32 v34, v6
	v_pk_mul_f32 v[2:3], v[58:59], v[76:77]
	v_mov_b32_e32 v37, v79
	v_pk_fma_f32 v[6:7], v[58:59], v[34:35], v[2:3] op_sel:[0,0,1] op_sel_hi:[1,1,0]
	v_mov_b32_e32 v79, v9
	ds_read_b128 v[2:5], v1 offset:14336
	v_mov_b32_e32 v36, v8
	v_pk_mul_f32 v[8:9], v[56:57], v[78:79]
	v_mov_b32_e32 v39, v73
	v_pk_fma_f32 v[8:9], v[56:57], v[36:37], v[8:9] op_sel:[0,0,1] op_sel_hi:[1,1,0]
	v_mov_b32_e32 v41, v75
	v_pk_add_f32 v[6:7], v[6:7], v[8:9]
	s_nop 0
	v_pk_add_f32 v[14:15], v[14:15], v[6:7]
	ds_read_b128 v[6:9], v1 offset:15360
	s_waitcnt lgkmcnt(1)
	v_mov_b32_e32 v73, v3
	v_mov_b32_e32 v75, v5
	v_mov_b32_e32 v38, v2
	v_pk_mul_f32 v[2:3], v[130:131], v[72:73]
	v_mov_b32_e32 v40, v4
	v_pk_mul_f32 v[4:5], v[132:133], v[74:75]
	v_pk_fma_f32 v[2:3], v[130:131], v[38:39], v[2:3] op_sel:[0,0,1] op_sel_hi:[1,1,0]
	v_pk_fma_f32 v[4:5], v[132:133], v[40:41], v[4:5] op_sel:[0,0,1] op_sel_hi:[1,1,0]
	s_nop 0
	v_pk_add_f32 v[2:3], v[2:3], v[4:5]
	v_mov_b32_e32 v5, v69
	v_pk_add_f32 v[2:3], v[14:15], v[2:3]
	s_waitcnt lgkmcnt(0)
	v_mov_b32_e32 v69, v7
	v_mov_b32_e32 v15, v71
	v_mov_b32_e32 v71, v9
	v_mov_b32_e32 v4, v6
	v_pk_mul_f32 v[6:7], v[134:135], v[68:69]
	v_mov_b32_e32 v14, v8
	v_pk_mul_f32 v[8:9], v[92:93], v[70:71]
	v_pk_fma_f32 v[6:7], v[134:135], v[4:5], v[6:7] op_sel:[0,0,1] op_sel_hi:[1,1,0]
	v_pk_fma_f32 v[8:9], v[92:93], v[14:15], v[8:9] op_sel:[0,0,1] op_sel_hi:[1,1,0]
	s_nop 0
	v_pk_add_f32 v[6:7], v[6:7], v[8:9]
	v_pk_mul_f32 v[8:9], v[156:157], v[20:21]
	v_pk_add_f32 v[2:3], v[2:3], v[6:7]
	ds_bpermute_b32 v7, v167, v3
	ds_bpermute_b32 v6, v167, v2
	v_pk_fma_f32 v[8:9], v[156:157], v[106:107], v[8:9] op_sel:[0,0,1] op_sel_hi:[1,1,0]
	s_waitcnt lgkmcnt(0)
	v_pk_add_f32 v[2:3], v[2:3], v[6:7]
	ds_bpermute_b32 v7, v194, v3
	ds_bpermute_b32 v6, v194, v2
	s_waitcnt lgkmcnt(0)
	v_pk_add_f32 v[2:3], v[2:3], v[6:7]
	ds_bpermute_b32 v7, v195, v3
	ds_bpermute_b32 v6, v195, v2
	s_waitcnt lgkmcnt(0)
	v_pk_add_f32 v[160:161], v[2:3], v[6:7]
	v_pk_mul_f32 v[2:3], v[154:155], v[10:11]
	v_pk_mul_f32 v[6:7], v[152:153], v[12:13]
	v_pk_fma_f32 v[2:3], v[154:155], v[108:109], v[2:3] op_sel:[0,0,1] op_sel_hi:[1,1,0]
	v_pk_fma_f32 v[6:7], v[152:153], v[110:111], v[6:7] op_sel:[0,0,1] op_sel_hi:[1,1,0]
	ds_bpermute_b32 v163, v196, v161
	v_pk_add_f32 v[2:3], v[2:3], v[6:7]
	v_pk_mul_f32 v[6:7], v[158:159], v[16:17]
	v_pk_add_f32 v[2:3], v[2:3], 0 op_sel_hi:[1,0]
	v_pk_fma_f32 v[6:7], v[158:159], v[104:105], v[6:7] op_sel:[0,0,1] op_sel_hi:[1,1,0]
	s_nop 0
	v_pk_add_f32 v[6:7], v[6:7], v[8:9]
	v_pk_mul_f32 v[8:9], v[148:149], v[24:25]
	v_pk_add_f32 v[2:3], v[2:3], v[6:7]
	v_pk_mul_f32 v[6:7], v[150:151], v[22:23]
	v_pk_fma_f32 v[8:9], v[148:149], v[102:103], v[8:9] op_sel:[0,0,1] op_sel_hi:[1,1,0]
	v_pk_fma_f32 v[6:7], v[150:151], v[100:101], v[6:7] op_sel:[0,0,1] op_sel_hi:[1,1,0]
	s_nop 0
	v_pk_add_f32 v[6:7], v[6:7], v[8:9]
	v_pk_mul_f32 v[8:9], v[44:45], v[28:29]
	v_pk_add_f32 v[2:3], v[2:3], v[6:7]
	v_pk_mul_f32 v[6:7], v[146:147], v[26:27]
	v_pk_fma_f32 v[8:9], v[44:45], v[98:99], v[8:9] op_sel:[0,0,1] op_sel_hi:[1,1,0]
	v_pk_fma_f32 v[6:7], v[146:147], v[96:97], v[6:7] op_sel:[0,0,1] op_sel_hi:[1,1,0]
	s_nop 0
	v_pk_add_f32 v[6:7], v[6:7], v[8:9]
	v_pk_mul_f32 v[8:9], v[94:95], v[82:83]
	v_pk_add_f32 v[2:3], v[2:3], v[6:7]
	v_pk_mul_f32 v[6:7], v[144:145], v[80:81]
	v_pk_fma_f32 v[8:9], v[94:95], v[32:33], v[8:9] op_sel:[0,0,1] op_sel_hi:[1,1,0]
	v_pk_fma_f32 v[6:7], v[144:145], v[30:31], v[6:7] op_sel:[0,0,1] op_sel_hi:[1,1,0]
	s_nop 0
	v_pk_add_f32 v[6:7], v[6:7], v[8:9]
	v_pk_mul_f32 v[8:9], v[62:63], v[78:79]
	v_pk_add_f32 v[2:3], v[2:3], v[6:7] op_sel:[1,0] op_sel_hi:[0,1]
	v_pk_mul_f32 v[6:7], v[60:61], v[76:77]
	v_pk_fma_f32 v[8:9], v[62:63], v[36:37], v[8:9] op_sel:[0,0,1] op_sel_hi:[1,1,0]
	v_pk_fma_f32 v[6:7], v[60:61], v[34:35], v[6:7] op_sel:[0,0,1] op_sel_hi:[1,1,0]
	s_nop 0
	v_pk_add_f32 v[6:7], v[6:7], v[8:9]
	v_pk_mul_f32 v[8:9], v[136:137], v[74:75]
	v_pk_add_f32 v[2:3], v[2:3], v[6:7]
	v_pk_mul_f32 v[6:7], v[138:139], v[72:73]
	v_pk_fma_f32 v[8:9], v[136:137], v[40:41], v[8:9] op_sel:[0,0,1] op_sel_hi:[1,1,0]
	v_pk_fma_f32 v[6:7], v[138:139], v[38:39], v[6:7] op_sel:[0,0,1] op_sel_hi:[1,1,0]
	s_nop 0
	v_pk_add_f32 v[6:7], v[6:7], v[8:9]
	s_nop 0
	v_pk_add_f32 v[2:3], v[2:3], v[6:7]
	v_pk_mul_f32 v[6:7], v[142:143], v[68:69]
	s_nop 0
	v_pk_fma_f32 v[4:5], v[142:143], v[4:5], v[6:7] op_sel:[0,0,1] op_sel_hi:[1,1,0]
	v_pk_mul_f32 v[6:7], v[140:141], v[70:71]
	s_nop 0
	v_pk_fma_f32 v[6:7], v[140:141], v[14:15], v[6:7] op_sel:[0,0,1] op_sel_hi:[1,1,0]
	s_nop 0
	v_pk_add_f32 v[4:5], v[4:5], v[6:7]
	s_nop 0
	v_pk_add_f32 v[98:99], v[2:3], v[4:5]
	ds_read_b128 v[24:27], v1 offset:16384
	ds_read_b128 v[28:31], v1 offset:17408
	ds_read_b128 v[32:35], v1 offset:18432
	ds_read_b128 v[20:23], v1 offset:19456
	ds_read_b128 v[14:17], v1 offset:20480
	ds_read_b128 v[10:13], v1 offset:21504
	ds_read_b128 v[6:9], v1 offset:22528
	ds_read_b128 v[2:5], v1 offset:23552
	ds_read_b128 v[36:39], v1 offset:24576
	ds_read_b128 v[40:43], v1 offset:25600
	ds_read_b128 v[68:71], v1 offset:26624
	s_waitcnt lgkmcnt(10)
	v_mov_b32_e32 v53, v25
	v_mov_b32_e32 v73, v27
	s_waitcnt lgkmcnt(2)
	v_mov_b32_e32 v25, v37
	v_mov_b32_e32 v27, v39
	v_mov_b32_e32 v52, v36
	v_pk_mul_f32 v[36:37], v[154:155], v[24:25]
	v_mov_b32_e32 v72, v38
	v_pk_mul_f32 v[38:39], v[152:153], v[26:27]
	v_pk_fma_f32 v[36:37], v[154:155], v[52:53], v[36:37] op_sel:[0,0,1] op_sel_hi:[1,1,0]
	v_pk_fma_f32 v[38:39], v[152:153], v[72:73], v[38:39] op_sel:[0,0,1] op_sel_hi:[1,1,0]
	v_mov_b32_e32 v75, v31
	v_pk_add_f32 v[36:37], v[36:37], v[38:39]
	v_mov_b32_e32 v39, v29
	s_waitcnt lgkmcnt(1)
	v_mov_b32_e32 v29, v41
	v_mov_b32_e32 v31, v43
	v_pk_mul_f32 v[24:25], v[66:67], v[24:25]
	v_pk_mul_f32 v[26:27], v[88:89], v[26:27]
	v_mov_b32_e32 v38, v40
	v_pk_mul_f32 v[40:41], v[158:159], v[28:29]
	v_mov_b32_e32 v74, v42
	v_pk_mul_f32 v[42:43], v[156:157], v[30:31]
	v_pk_fma_f32 v[24:25], v[66:67], v[52:53], v[24:25] op_sel:[0,0,1] op_sel_hi:[1,1,0]
	v_pk_fma_f32 v[26:27], v[88:89], v[72:73], v[26:27] op_sel:[0,0,1] op_sel_hi:[1,1,0]
	v_pk_fma_f32 v[40:41], v[158:159], v[38:39], v[40:41] op_sel:[0,0,1] op_sel_hi:[1,1,0]
	v_pk_fma_f32 v[42:43], v[156:157], v[74:75], v[42:43] op_sel:[0,0,1] op_sel_hi:[1,1,0]
	v_pk_add_f32 v[24:25], v[24:25], v[26:27]
	v_pk_mul_f32 v[26:27], v[48:49], v[28:29]
	v_pk_mul_f32 v[28:29], v[50:51], v[30:31]
	v_pk_add_f32 v[36:37], v[36:37], 0 op_sel_hi:[1,0]
	v_pk_add_f32 v[40:41], v[40:41], v[42:43]
	v_pk_fma_f32 v[26:27], v[48:49], v[38:39], v[26:27] op_sel:[0,0,1] op_sel_hi:[1,1,0]
	v_pk_fma_f32 v[28:29], v[50:51], v[74:75], v[28:29] op_sel:[0,0,1] op_sel_hi:[1,1,0]
	v_pk_add_f32 v[36:37], v[36:37], v[40:41]
	v_mov_b32_e32 v41, v33
	s_waitcnt lgkmcnt(0)
	v_mov_b32_e32 v33, v69
	v_mov_b32_e32 v69, v35
	v_mov_b32_e32 v35, v71
	v_pk_add_f32 v[24:25], v[24:25], 0 op_sel_hi:[1,0]
	v_pk_add_f32 v[26:27], v[26:27], v[28:29]
	v_mov_b32_e32 v40, v68
	v_mov_b32_e32 v68, v70
	v_pk_add_f32 v[24:25], v[24:25], v[26:27]
	v_pk_mul_f32 v[26:27], v[90:91], v[32:33]
	v_pk_mul_f32 v[28:29], v[54:55], v[34:35]
	v_pk_fma_f32 v[26:27], v[90:91], v[40:41], v[26:27] op_sel:[0,0,1] op_sel_hi:[1,1,0]
	v_pk_fma_f32 v[28:29], v[54:55], v[68:69], v[28:29] op_sel:[0,0,1] op_sel_hi:[1,1,0]
	v_mov_b32_e32 v31, v23
	v_pk_add_f32 v[26:27], v[26:27], v[28:29]
	v_mov_b32_e32 v29, v21
	v_pk_add_f32 v[52:53], v[24:25], v[26:27]
	ds_read_b128 v[24:27], v1 offset:27648
	v_pk_mul_f32 v[70:71], v[148:149], v[34:35]
	v_pk_mul_f32 v[42:43], v[150:151], v[32:33]
	v_pk_fma_f32 v[70:71], v[148:149], v[68:69], v[70:71] op_sel:[0,0,1] op_sel_hi:[1,1,0]
	v_pk_fma_f32 v[42:43], v[150:151], v[40:41], v[42:43] op_sel:[0,0,1] op_sel_hi:[1,1,0]
	s_waitcnt lgkmcnt(0)
	v_mov_b32_e32 v21, v25
	v_mov_b32_e32 v23, v27
	v_mov_b32_e32 v28, v24
	v_pk_mul_f32 v[24:25], v[146:147], v[20:21]
	v_mov_b32_e32 v30, v26
	v_pk_mul_f32 v[26:27], v[44:45], v[22:23]
	v_pk_mul_f32 v[20:21], v[86:87], v[20:21]
	v_pk_mul_f32 v[22:23], v[64:65], v[22:23]
	v_pk_fma_f32 v[20:21], v[86:87], v[28:29], v[20:21] op_sel:[0,0,1] op_sel_hi:[1,1,0]
	v_pk_fma_f32 v[22:23], v[64:65], v[30:31], v[22:23] op_sel:[0,0,1] op_sel_hi:[1,1,0]
	v_pk_fma_f32 v[24:25], v[146:147], v[28:29], v[24:25] op_sel:[0,0,1] op_sel_hi:[1,1,0]
	v_pk_add_f32 v[68:69], v[20:21], v[22:23]
	ds_read_b128 v[20:23], v1 offset:28672
	v_pk_fma_f32 v[26:27], v[44:45], v[30:31], v[26:27] op_sel:[0,0,1] op_sel_hi:[1,1,0]
	v_pk_add_f32 v[42:43], v[42:43], v[70:71]
	v_pk_add_f32 v[106:107], v[24:25], v[26:27]
	v_mov_b32_e32 v25, v15
	s_waitcnt lgkmcnt(0)
	v_mov_b32_e32 v15, v21
	v_mov_b32_e32 v24, v20
	v_pk_mul_f32 v[20:21], v[144:145], v[14:15]
	v_pk_mul_f32 v[14:15], v[84:85], v[14:15]
	v_pk_fma_f32 v[108:109], v[144:145], v[24:25], v[20:21] op_sel:[0,0,1] op_sel_hi:[1,1,0]
	v_mov_b32_e32 v21, v17
	v_mov_b32_e32 v17, v23
	v_mov_b32_e32 v20, v22
	v_pk_fma_f32 v[70:71], v[84:85], v[24:25], v[14:15] op_sel:[0,0,1] op_sel_hi:[1,1,0]
	v_pk_mul_f32 v[14:15], v[46:47], v[16:17]
	v_pk_mul_f32 v[22:23], v[94:95], v[16:17]
	v_pk_fma_f32 v[72:73], v[46:47], v[20:21], v[14:15] op_sel:[0,0,1] op_sel_hi:[1,1,0]
	ds_read_b128 v[14:17], v1 offset:29696
	ds_read_b128 v[32:35], v1 offset:30720
	ds_read_b128 v[28:31], v1 offset:31744
	v_mov_b32_e32 v75, v11
	v_mov_b32_e32 v77, v13
	v_pk_add_f32 v[96:97], v[36:37], v[42:43]
	s_waitcnt lgkmcnt(2)
	v_mov_b32_e32 v11, v15
	v_mov_b32_e32 v13, v17
	v_pk_fma_f32 v[110:111], v[94:95], v[20:21], v[22:23] op_sel:[0,0,1] op_sel_hi:[1,1,0]
	v_mov_b32_e32 v74, v14
	v_pk_mul_f32 v[182:183], v[60:61], v[10:11]
	v_mov_b32_e32 v76, v16
	v_pk_mul_f32 v[180:181], v[62:63], v[12:13]
	v_pk_mul_f32 v[78:79], v[58:59], v[10:11]
	v_pk_mul_f32 v[80:81], v[56:57], v[12:13]
	ds_read_b128 v[40:43], v1 offset:32768
	ds_read_b128 v[100:103], v1 offset:33792
	ds_read_b128 v[170:173], v1 offset:34816
	ds_read_b128 v[36:39], v1 offset:35840
	ds_read_b128 v[24:27], v1 offset:36864
	ds_read_b128 v[20:23], v1 offset:37888
	ds_read_b128 v[14:17], v1 offset:38912
	ds_read_b128 v[10:13], v1 offset:39936
	ds_read_b128 v[174:177], v1 offset:40960
	ds_read_b128 v[184:187], v1 offset:41984
	ds_read_b128 v[188:191], v1 offset:43008
	s_waitcnt lgkmcnt(10)
	v_mov_b32_e32 v83, v41
	v_mov_b32_e32 v179, v43
	s_waitcnt lgkmcnt(2)
	v_mov_b32_e32 v41, v175
	v_mov_b32_e32 v43, v177
	v_mov_b32_e32 v82, v174
	v_pk_mul_f32 v[104:105], v[154:155], v[40:41]
	v_mov_b32_e32 v178, v176
	v_pk_mul_f32 v[174:175], v[152:153], v[42:43]
	v_pk_mul_f32 v[40:41], v[66:67], v[40:41]
	v_pk_mul_f32 v[42:43], v[88:89], v[42:43]
	v_pk_fma_f32 v[104:105], v[154:155], v[82:83], v[104:105] op_sel:[0,0,1] op_sel_hi:[1,1,0]
	v_pk_fma_f32 v[174:175], v[152:153], v[178:179], v[174:175] op_sel:[0,0,1] op_sel_hi:[1,1,0]
	v_mov_b32_e32 v177, v101
	s_waitcnt lgkmcnt(1)
	v_mov_b32_e32 v101, v185
	v_mov_b32_e32 v185, v103
	v_mov_b32_e32 v103, v187
	v_pk_fma_f32 v[40:41], v[66:67], v[82:83], v[40:41] op_sel:[0,0,1] op_sel_hi:[1,1,0]
	v_pk_fma_f32 v[42:43], v[88:89], v[178:179], v[42:43] op_sel:[0,0,1] op_sel_hi:[1,1,0]
	v_pk_add_f32 v[104:105], v[104:105], v[174:175]
	v_mov_b32_e32 v176, v184
	v_pk_mul_f32 v[174:175], v[158:159], v[100:101]
	v_mov_b32_e32 v184, v186
	v_pk_mul_f32 v[186:187], v[156:157], v[102:103]
	v_pk_add_f32 v[40:41], v[40:41], v[42:43]
	v_pk_mul_f32 v[42:43], v[48:49], v[100:101]
	v_pk_mul_f32 v[82:83], v[50:51], v[102:103]
	v_pk_fma_f32 v[174:175], v[158:159], v[176:177], v[174:175] op_sel:[0,0,1] op_sel_hi:[1,1,0]
	v_pk_fma_f32 v[186:187], v[156:157], v[184:185], v[186:187] op_sel:[0,0,1] op_sel_hi:[1,1,0]
	v_pk_fma_f32 v[42:43], v[48:49], v[176:177], v[42:43] op_sel:[0,0,1] op_sel_hi:[1,1,0]
	v_pk_fma_f32 v[82:83], v[50:51], v[184:185], v[82:83] op_sel:[0,0,1] op_sel_hi:[1,1,0]
	v_pk_add_f32 v[174:175], v[174:175], v[186:187]
	v_mov_b32_e32 v187, v171
	s_waitcnt lgkmcnt(0)
	v_mov_b32_e32 v171, v189
	v_mov_b32_e32 v189, v173
	v_mov_b32_e32 v173, v191
	v_pk_add_f32 v[40:41], v[40:41], 0 op_sel_hi:[1,0]
	v_pk_add_f32 v[42:43], v[42:43], v[82:83]
	v_mov_b32_e32 v186, v188
	v_mov_b32_e32 v188, v190
	v_pk_add_f32 v[40:41], v[40:41], v[42:43]
	v_pk_mul_f32 v[42:43], v[90:91], v[170:171]
	v_pk_mul_f32 v[82:83], v[54:55], v[172:173]
	v_pk_fma_f32 v[42:43], v[90:91], v[186:187], v[42:43] op_sel:[0,0,1] op_sel_hi:[1,1,0]
	v_pk_fma_f32 v[82:83], v[54:55], v[188:189], v[82:83] op_sel:[0,0,1] op_sel_hi:[1,1,0]
	v_mov_b32_e32 v101, v37
	v_pk_add_f32 v[42:43], v[42:43], v[82:83]
	v_mov_b32_e32 v103, v39
	v_pk_add_f32 v[82:83], v[40:41], v[42:43]
	ds_read_b128 v[40:43], v1 offset:44032
	v_pk_add_f32 v[104:105], v[104:105], 0 op_sel_hi:[1,0]
	v_pk_mul_f32 v[190:191], v[148:149], v[172:173]
	v_pk_add_f32 v[104:105], v[104:105], v[174:175]
	v_pk_mul_f32 v[174:175], v[150:151], v[170:171]
	s_waitcnt lgkmcnt(0)
	v_mov_b32_e32 v37, v41
	v_mov_b32_e32 v39, v43
	v_mov_b32_e32 v100, v40
	v_pk_mul_f32 v[40:41], v[146:147], v[36:37]
	v_mov_b32_e32 v102, v42
	v_pk_mul_f32 v[42:43], v[44:45], v[38:39]
	v_pk_mul_f32 v[36:37], v[86:87], v[36:37]
	v_pk_mul_f32 v[38:39], v[64:65], v[38:39]
	v_pk_fma_f32 v[36:37], v[86:87], v[100:101], v[36:37] op_sel:[0,0,1] op_sel_hi:[1,1,0]
	v_pk_fma_f32 v[38:39], v[64:65], v[102:103], v[38:39] op_sel:[0,0,1] op_sel_hi:[1,1,0]
	v_pk_fma_f32 v[40:41], v[146:147], v[100:101], v[40:41] op_sel:[0,0,1] op_sel_hi:[1,1,0]
	v_pk_add_f32 v[100:101], v[36:37], v[38:39]
	ds_read_b128 v[36:39], v1 offset:45056
	v_pk_fma_f32 v[42:43], v[44:45], v[102:103], v[42:43] op_sel:[0,0,1] op_sel_hi:[1,1,0]
	v_pk_fma_f32 v[174:175], v[150:151], v[186:187], v[174:175] op_sel:[0,0,1] op_sel_hi:[1,1,0]
	v_pk_add_f32 v[184:185], v[40:41], v[42:43]
	v_mov_b32_e32 v41, v25
	s_waitcnt lgkmcnt(0)
	v_mov_b32_e32 v25, v37
	v_mov_b32_e32 v40, v36
	v_pk_mul_f32 v[36:37], v[144:145], v[24:25]
	v_pk_fma_f32 v[190:191], v[148:149], v[188:189], v[190:191] op_sel:[0,0,1] op_sel_hi:[1,1,0]
	v_pk_fma_f32 v[186:187], v[144:145], v[40:41], v[36:37] op_sel:[0,0,1] op_sel_hi:[1,1,0]
	v_mov_b32_e32 v37, v27
	v_mov_b32_e32 v27, v39
	v_pk_mul_f32 v[24:25], v[84:85], v[24:25]
	v_pk_add_f32 v[174:175], v[174:175], v[190:191]
	v_mov_b32_e32 v36, v38
	v_pk_fma_f32 v[102:103], v[84:85], v[40:41], v[24:25] op_sel:[0,0,1] op_sel_hi:[1,1,0]
	v_pk_mul_f32 v[24:25], v[46:47], v[26:27]
	v_pk_add_f32 v[174:175], v[104:105], v[174:175]
	v_pk_mul_f32 v[38:39], v[94:95], v[26:27]
	v_pk_fma_f32 v[104:105], v[46:47], v[36:37], v[24:25] op_sel:[0,0,1] op_sel_hi:[1,1,0]
	ds_read_b128 v[24:27], v1 offset:46080
	v_pk_fma_f32 v[188:189], v[94:95], v[36:37], v[38:39] op_sel:[0,0,1] op_sel_hi:[1,1,0]
	ds_read_b128 v[40:43], v1 offset:47104
	ds_read_b128 v[36:39], v1 offset:48128
	v_mov_b32_e32 v171, v21
	v_mov_b32_e32 v173, v23
	s_waitcnt lgkmcnt(2)
	v_mov_b32_e32 v21, v25
	v_mov_b32_e32 v23, v27
	v_mov_b32_e32 v170, v24
	v_pk_mul_f32 v[190:191], v[60:61], v[20:21]
	v_mov_b32_e32 v172, v26
	v_pk_mul_f32 v[192:193], v[62:63], v[22:23]
	v_pk_mul_f32 v[176:177], v[58:59], v[20:21]
	v_pk_mul_f32 v[178:179], v[56:57], v[22:23]
	ds_read_b128 v[200:203], v1 offset:49152
	ds_read_b128 v[204:207], v1 offset:50176
	ds_read_b128 v[220:223], v1 offset:51200
	ds_read_b128 v[224:227], v1 offset:52224
	ds_read_b128 v[228:231], v1 offset:53248
	ds_read_b128 v[232:235], v1 offset:54272
	ds_read_b128 v[24:27], v1 offset:55296
	ds_read_b128 v[20:23], v1 offset:56320
	ds_read_b128 v[236:239], v1 offset:57344
	ds_read_b128 v[240:243], v1 offset:58368
	ds_read_b128 v[244:247], v1 offset:59392
	s_waitcnt lgkmcnt(10)
	v_mov_b32_e32 v209, v201
	s_waitcnt lgkmcnt(2)
	v_mov_b32_e32 v201, v237
	v_mov_b32_e32 v208, v236
	v_pk_mul_f32 v[236:237], v[154:155], v[200:201]
	s_nop 0
	v_pk_fma_f32 v[154:155], v[154:155], v[208:209], v[236:237] op_sel:[0,0,1] op_sel_hi:[1,1,0]
	v_mov_b32_e32 v237, v203
	v_mov_b32_e32 v203, v239
	v_mov_b32_e32 v236, v238
	v_pk_mul_f32 v[238:239], v[152:153], v[202:203]
	s_nop 0
	v_pk_fma_f32 v[152:153], v[152:153], v[236:237], v[238:239] op_sel:[0,0,1] op_sel_hi:[1,1,0]
	v_mov_b32_e32 v239, v205
	s_waitcnt lgkmcnt(1)
	v_mov_b32_e32 v205, v241
	v_pk_add_f32 v[152:153], v[154:155], v[152:153]
	v_mov_b32_e32 v238, v240
	v_pk_mul_f32 v[154:155], v[158:159], v[204:205]
	v_pk_add_f32 v[152:153], v[152:153], 0 op_sel_hi:[1,0]
	v_pk_fma_f32 v[154:155], v[158:159], v[238:239], v[154:155] op_sel:[0,0,1] op_sel_hi:[1,1,0]
	v_mov_b32_e32 v159, v207
	v_mov_b32_e32 v207, v243
	v_mov_b32_e32 v158, v242
	v_pk_mul_f32 v[240:241], v[156:157], v[206:207]
	s_nop 0
	v_pk_fma_f32 v[156:157], v[156:157], v[158:159], v[240:241] op_sel:[0,0,1] op_sel_hi:[1,1,0]
	v_mov_b32_e32 v241, v221
	s_waitcnt lgkmcnt(0)
	v_mov_b32_e32 v221, v245
	v_mov_b32_e32 v240, v244
	v_pk_mul_f32 v[242:243], v[150:151], v[220:221]
	v_pk_add_f32 v[154:155], v[154:155], v[156:157]
	v_pk_fma_f32 v[150:151], v[150:151], v[240:241], v[242:243] op_sel:[0,0,1] op_sel_hi:[1,1,0]
	v_mov_b32_e32 v243, v223
	v_mov_b32_e32 v223, v247
	v_mov_b32_e32 v242, v246
	v_pk_mul_f32 v[244:245], v[148:149], v[222:223]
	v_pk_add_f32 v[156:157], v[152:153], v[154:155]
	v_pk_fma_f32 v[148:149], v[148:149], v[242:243], v[244:245] op_sel:[0,0,1] op_sel_hi:[1,1,0]
	ds_read_b128 v[152:155], v1 offset:60416
	v_pk_add_f32 v[148:149], v[150:151], v[148:149]
	v_pk_mul_f32 v[150:151], v[66:67], v[200:201]
	v_pk_add_f32 v[148:149], v[156:157], v[148:149]
	v_pk_fma_f32 v[66:67], v[66:67], v[208:209], v[150:151] op_sel:[0,0,1] op_sel_hi:[1,1,0]
	v_pk_mul_f32 v[150:151], v[88:89], v[202:203]
	s_nop 0
	v_pk_fma_f32 v[88:89], v[88:89], v[236:237], v[150:151] op_sel:[0,0,1] op_sel_hi:[1,1,0]
	s_nop 0
	v_pk_add_f32 v[66:67], v[66:67], v[88:89]
	v_pk_mul_f32 v[88:89], v[48:49], v[204:205]
	v_pk_add_f32 v[66:67], v[66:67], 0 op_sel_hi:[1,0]
	v_pk_fma_f32 v[48:49], v[48:49], v[238:239], v[88:89] op_sel:[0,0,1] op_sel_hi:[1,1,0]
	v_pk_mul_f32 v[88:89], v[50:51], v[206:207]
	s_nop 0
	v_pk_fma_f32 v[50:51], v[50:51], v[158:159], v[88:89] op_sel:[0,0,1] op_sel_hi:[1,1,0]
	ds_read_b128 v[156:159], v1 offset:62464
	v_pk_add_f32 v[48:49], v[48:49], v[50:51]
	v_pk_mul_f32 v[50:51], v[90:91], v[220:221]
	v_pk_add_f32 v[48:49], v[66:67], v[48:49]
	v_pk_mul_f32 v[66:67], v[54:55], v[222:223]
	v_pk_fma_f32 v[50:51], v[90:91], v[240:241], v[50:51] op_sel:[0,0,1] op_sel_hi:[1,1,0]
	v_pk_fma_f32 v[54:55], v[54:55], v[242:243], v[66:67] op_sel:[0,0,1] op_sel_hi:[1,1,0]
	v_mov_b32_e32 v91, v235
	v_pk_add_f32 v[50:51], v[50:51], v[54:55]
	v_mov_b32_e32 v55, v227
	v_pk_add_f32 v[66:67], v[48:49], v[50:51]
	v_mov_b32_e32 v49, v225
	s_waitcnt lgkmcnt(1)
	v_mov_b32_e32 v225, v153
	v_mov_b32_e32 v227, v155
	v_mov_b32_e32 v48, v152
	v_pk_mul_f32 v[50:51], v[146:147], v[224:225]
	v_mov_b32_e32 v54, v154
	v_pk_mul_f32 v[88:89], v[44:45], v[226:227]
	v_pk_fma_f32 v[50:51], v[146:147], v[48:49], v[50:51] op_sel:[0,0,1] op_sel_hi:[1,1,0]
	v_pk_fma_f32 v[44:45], v[44:45], v[54:55], v[88:89] op_sel:[0,0,1] op_sel_hi:[1,1,0]
	s_waitcnt lgkmcnt(0)
	v_mov_b32_e32 v235, v159
	v_pk_add_f32 v[146:147], v[50:51], v[44:45]
	v_pk_mul_f32 v[44:45], v[86:87], v[224:225]
	v_mov_b32_e32 v90, v158
	v_pk_fma_f32 v[44:45], v[86:87], v[48:49], v[44:45] op_sel:[0,0,1] op_sel_hi:[1,1,0]
	ds_read_b128 v[48:51], v1 offset:61440
	v_pk_mul_f32 v[86:87], v[64:65], v[226:227]
	v_pk_mul_f32 v[158:159], v[62:63], v[234:235]
	v_pk_fma_f32 v[54:55], v[64:65], v[54:55], v[86:87] op_sel:[0,0,1] op_sel_hi:[1,1,0]
	v_mov_b32_e32 v87, v233
	v_pk_add_f32 v[64:65], v[44:45], v[54:55]
	v_mov_b32_e32 v45, v229
	s_waitcnt lgkmcnt(0)
	v_mov_b32_e32 v229, v49
	v_mov_b32_e32 v44, v48
	v_pk_mul_f32 v[48:49], v[144:145], v[228:229]
	v_mov_b32_e32 v233, v157
	v_pk_fma_f32 v[150:151], v[144:145], v[44:45], v[48:49] op_sel:[0,0,1] op_sel_hi:[1,1,0]
	v_mov_b32_e32 v49, v231
	v_mov_b32_e32 v231, v51
	v_mov_b32_e32 v48, v50
	v_pk_mul_f32 v[50:51], v[94:95], v[230:231]
	v_mov_b32_e32 v86, v156
	v_pk_fma_f32 v[152:153], v[94:95], v[48:49], v[50:51] op_sel:[0,0,1] op_sel_hi:[1,1,0]
	v_pk_mul_f32 v[50:51], v[84:85], v[228:229]
	v_pk_mul_f32 v[156:157], v[60:61], v[232:233]
	v_pk_fma_f32 v[84:85], v[84:85], v[44:45], v[50:51] op_sel:[0,0,1] op_sel_hi:[1,1,0]
	v_pk_mul_f32 v[44:45], v[46:47], v[230:231]
	v_pk_mul_f32 v[94:95], v[58:59], v[232:233]
	v_pk_fma_f32 v[88:89], v[46:47], v[48:49], v[44:45] op_sel:[0,0,1] op_sel_hi:[1,1,0]
	ds_read_b128 v[48:51], v1 offset:63488
	ds_read_b128 v[44:47], v1 offset:64512
	v_pk_mul_f32 v[144:145], v[56:57], v[234:235]
	ds_bpermute_b32 v55, v167, v99
	ds_bpermute_b32 v54, v167, v98
	v_pk_add_f32 v[96:97], v[96:97], v[106:107]
	v_pk_add_f32 v[106:107], v[108:109], v[110:111]
	v_pk_fma_f32 v[108:109], v[62:63], v[76:77], v[180:181] op_sel:[0,0,1] op_sel_hi:[1,1,0]
	v_pk_add_f32 v[96:97], v[96:97], v[106:107]
	s_waitcnt lgkmcnt(0)
	v_pk_add_f32 v[54:55], v[98:99], v[54:55]
	ds_bpermute_b32 v99, v194, v55
	ds_bpermute_b32 v98, v194, v54
	v_pk_fma_f32 v[106:107], v[60:61], v[74:75], v[182:183] op_sel:[0,0,1] op_sel_hi:[1,1,0]
	v_mov_b32_e32 v111, v3
	v_pk_add_f32 v[106:107], v[106:107], v[108:109]
	v_mov_b32_e32 v109, v9
	s_waitcnt lgkmcnt(0)
	v_pk_add_f32 v[54:55], v[54:55], v[98:99]
	ds_bpermute_b32 v99, v195, v55
	ds_bpermute_b32 v98, v195, v54
	v_pk_add_f32 v[96:97], v[96:97], v[106:107]
	v_mov_b32_e32 v107, v7
	v_mov_b32_e32 v7, v33
	v_mov_b32_e32 v9, v35
	s_waitcnt lgkmcnt(0)
	v_pk_add_f32 v[54:55], v[54:55], v[98:99]
	ds_bpermute_b32 v99, v196, v55
	ds_bpermute_b32 v98, v196, v54
	v_mov_b32_e32 v106, v32
	v_pk_mul_f32 v[32:33], v[138:139], v[6:7]
	v_mov_b32_e32 v108, v34
	v_pk_mul_f32 v[34:35], v[136:137], v[8:9]
	s_waitcnt lgkmcnt(0)
	v_pk_add_f32 v[54:55], v[54:55], v[98:99]
	ds_bpermute_b32 v155, v198, v55
	ds_bpermute_b32 v154, v198, v54
	v_mov_b32_e32 v3, v29
	v_pk_fma_f32 v[32:33], v[138:139], v[106:107], v[32:33] op_sel:[0,0,1] op_sel_hi:[1,1,0]
	v_pk_fma_f32 v[34:35], v[136:137], v[108:109], v[34:35] op_sel:[0,0,1] op_sel_hi:[1,1,0]
	v_mov_b32_e32 v110, v28
	s_waitcnt lgkmcnt(0)
	v_pk_add_f32 v[54:55], v[54:55], v[154:155]
	v_mov_b32_e32 v155, v5
	v_mov_b32_e32 v5, v31
	v_pk_mul_f32 v[28:29], v[142:143], v[2:3]
	v_mov_b32_e32 v154, v30
	v_pk_mul_f32 v[30:31], v[140:141], v[4:5]
	v_pk_add_f32 v[32:33], v[32:33], v[34:35]
	v_pk_fma_f32 v[28:29], v[142:143], v[110:111], v[28:29] op_sel:[0,0,1] op_sel_hi:[1,1,0]
	v_pk_fma_f32 v[30:31], v[140:141], v[154:155], v[30:31] op_sel:[0,0,1] op_sel_hi:[1,1,0]
	v_pk_add_f32 v[32:33], v[96:97], v[32:33]
	v_pk_add_f32 v[28:29], v[28:29], v[30:31]
	v_pk_fma_f32 v[34:35], v[62:63], v[172:173], v[192:193] op_sel:[0,0,1] op_sel_hi:[1,1,0]
	v_pk_add_f32 v[28:29], v[32:33], v[28:29]
	ds_bpermute_b32 v31, v167, v29
	ds_bpermute_b32 v30, v167, v28
	v_pk_add_f32 v[32:33], v[186:187], v[188:189]
	v_mov_b32_e32 v97, v15
	v_mov_b32_e32 v15, v41
	v_mov_b32_e32 v41, v17
	s_waitcnt lgkmcnt(0)
	v_pk_add_f32 v[28:29], v[28:29], v[30:31]
	ds_bpermute_b32 v31, v194, v29
	ds_bpermute_b32 v30, v194, v28
	v_mov_b32_e32 v17, v43
	v_mov_b32_e32 v96, v40
	v_mov_b32_e32 v40, v42
	v_mov_b32_e32 v43, v11
	s_waitcnt lgkmcnt(0)
	v_pk_add_f32 v[28:29], v[28:29], v[30:31]
	ds_bpermute_b32 v31, v195, v29
	ds_bpermute_b32 v30, v195, v28
	v_mov_b32_e32 v11, v37
	v_mov_b32_e32 v37, v13
	v_mov_b32_e32 v13, v39
	v_mov_b32_e32 v42, v36
	s_waitcnt lgkmcnt(0)
	v_pk_add_f32 v[28:29], v[28:29], v[30:31]
	ds_bpermute_b32 v31, v196, v29
	ds_bpermute_b32 v30, v196, v28
	v_mov_b32_e32 v36, v38
	v_pk_fma_f32 v[38:39], v[62:63], v[90:91], v[158:159] op_sel:[0,0,1] op_sel_hi:[1,1,0]
	v_pk_mul_f32 v[6:7], v[130:131], v[6:7]
	v_pk_mul_f32 v[8:9], v[132:133], v[8:9]
	s_waitcnt lgkmcnt(0)
	v_pk_add_f32 v[28:29], v[28:29], v[30:31]
	ds_bpermute_b32 v31, v198, v29
	ds_bpermute_b32 v30, v198, v28
	v_pk_fma_f32 v[6:7], v[130:131], v[106:107], v[6:7] op_sel:[0,0,1] op_sel_hi:[1,1,0]
	v_pk_fma_f32 v[8:9], v[132:133], v[108:109], v[8:9] op_sel:[0,0,1] op_sel_hi:[1,1,0]
	v_pk_mul_f32 v[2:3], v[134:135], v[2:3]
	v_pk_mul_f32 v[4:5], v[92:93], v[4:5]
	s_waitcnt lgkmcnt(0)
	v_pk_add_f32 v[28:29], v[28:29], v[30:31]
	v_pk_add_f32 v[30:31], v[174:175], v[184:185]
	v_pk_add_f32 v[6:7], v[6:7], v[8:9]
	v_pk_add_f32 v[30:31], v[30:31], v[32:33]
	v_pk_fma_f32 v[32:33], v[60:61], v[170:171], v[190:191] op_sel:[0,0,1] op_sel_hi:[1,1,0]
	v_pk_fma_f32 v[2:3], v[134:135], v[110:111], v[2:3] op_sel:[0,0,1] op_sel_hi:[1,1,0]
	v_pk_add_f32 v[32:33], v[32:33], v[34:35]
	v_pk_mul_f32 v[34:35], v[136:137], v[16:17]
	v_pk_add_f32 v[30:31], v[30:31], v[32:33]
	v_pk_mul_f32 v[32:33], v[138:139], v[14:15]
	v_pk_fma_f32 v[34:35], v[136:137], v[40:41], v[34:35] op_sel:[0,0,1] op_sel_hi:[1,1,0]
	v_pk_fma_f32 v[32:33], v[138:139], v[96:97], v[32:33] op_sel:[0,0,1] op_sel_hi:[1,1,0]
	v_pk_fma_f32 v[4:5], v[92:93], v[154:155], v[4:5] op_sel:[0,0,1] op_sel_hi:[1,1,0]
	v_pk_add_f32 v[32:33], v[32:33], v[34:35]
	v_pk_mul_f32 v[34:35], v[140:141], v[12:13]
	v_pk_add_f32 v[30:31], v[30:31], v[32:33]
	v_pk_mul_f32 v[32:33], v[142:143], v[10:11]
	v_pk_fma_f32 v[34:35], v[140:141], v[36:37], v[34:35] op_sel:[0,0,1] op_sel_hi:[1,1,0]
	v_pk_fma_f32 v[32:33], v[142:143], v[42:43], v[32:33] op_sel:[0,0,1] op_sel_hi:[1,1,0]
	v_pk_add_f32 v[2:3], v[2:3], v[4:5]
	v_pk_add_f32 v[32:33], v[32:33], v[34:35]
	v_pk_add_f32 v[34:35], v[150:151], v[152:153]
	v_pk_add_f32 v[30:31], v[30:31], v[32:33]
	ds_bpermute_b32 v33, v167, v31
	ds_bpermute_b32 v32, v167, v30
	v_pk_fma_f32 v[8:9], v[56:57], v[172:173], v[178:179] op_sel:[0,0,1] op_sel_hi:[1,1,0]
	ds_bpermute_b32 v162, v196, v160
	s_waitcnt lgkmcnt(1)
	v_pk_add_f32 v[30:31], v[30:31], v[32:33]
	ds_bpermute_b32 v33, v194, v31
	ds_bpermute_b32 v32, v194, v30
	s_waitcnt lgkmcnt(2)
	v_pk_add_f32 v[98:99], v[160:161], v[162:163]
	s_waitcnt lgkmcnt(0)
	v_pk_add_f32 v[30:31], v[30:31], v[32:33]
	ds_bpermute_b32 v33, v195, v31
	ds_bpermute_b32 v32, v195, v30
	s_waitcnt lgkmcnt(0)
	v_pk_add_f32 v[30:31], v[30:31], v[32:33]
	ds_bpermute_b32 v33, v196, v31
	ds_bpermute_b32 v32, v196, v30
	s_waitcnt lgkmcnt(0)
	v_pk_add_f32 v[30:31], v[30:31], v[32:33]
	ds_bpermute_b32 v33, v198, v31
	ds_bpermute_b32 v32, v198, v30
	s_waitcnt lgkmcnt(0)
	v_pk_add_f32 v[30:31], v[30:31], v[32:33]
	v_pk_add_f32 v[32:33], v[148:149], v[146:147]
	s_nop 0
	v_pk_add_f32 v[32:33], v[32:33], v[34:35]
	v_pk_fma_f32 v[34:35], v[60:61], v[86:87], v[156:157] op_sel:[0,0,1] op_sel_hi:[1,1,0]
	v_pk_fma_f32 v[60:61], v[56:57], v[76:77], v[80:81] op_sel:[0,0,1] op_sel_hi:[1,1,0]
	v_pk_add_f32 v[34:35], v[34:35], v[38:39]
	v_mov_b32_e32 v39, v25
	v_mov_b32_e32 v25, v49
	v_mov_b32_e32 v49, v27
	v_mov_b32_e32 v27, v51
	v_pk_add_f32 v[32:33], v[32:33], v[34:35]
	v_mov_b32_e32 v38, v48
	v_pk_mul_f32 v[34:35], v[138:139], v[24:25]
	v_mov_b32_e32 v48, v50
	v_pk_mul_f32 v[50:51], v[136:137], v[26:27]
	v_pk_fma_f32 v[34:35], v[138:139], v[38:39], v[34:35] op_sel:[0,0,1] op_sel_hi:[1,1,0]
	v_pk_fma_f32 v[50:51], v[136:137], v[48:49], v[50:51] op_sel:[0,0,1] op_sel_hi:[1,1,0]
	s_nop 0
	v_pk_add_f32 v[34:35], v[34:35], v[50:51]
	v_mov_b32_e32 v51, v21
	v_mov_b32_e32 v21, v45
	v_mov_b32_e32 v45, v23
	v_mov_b32_e32 v23, v47
	v_pk_add_f32 v[32:33], v[32:33], v[34:35]
	v_mov_b32_e32 v50, v44
	v_pk_mul_f32 v[34:35], v[142:143], v[20:21]
	v_mov_b32_e32 v44, v46
	v_pk_mul_f32 v[46:47], v[140:141], v[22:23]
	v_pk_fma_f32 v[34:35], v[142:143], v[50:51], v[34:35] op_sel:[0,0,1] op_sel_hi:[1,1,0]
	v_pk_fma_f32 v[46:47], v[140:141], v[44:45], v[46:47] op_sel:[0,0,1] op_sel_hi:[1,1,0]
	s_nop 0
	v_pk_add_f32 v[34:35], v[34:35], v[46:47]
	v_pk_add_f32 v[46:47], v[52:53], v[68:69]
	v_pk_add_f32 v[52:53], v[70:71], v[72:73]
	v_pk_add_f32 v[32:33], v[32:33], v[34:35]
	v_pk_add_f32 v[46:47], v[46:47], v[52:53]
	v_pk_fma_f32 v[52:53], v[58:59], v[74:75], v[78:79] op_sel:[0,0,1] op_sel_hi:[1,1,0]
	ds_bpermute_b32 v35, v167, v33
	v_pk_add_f32 v[52:53], v[52:53], v[60:61]
	ds_bpermute_b32 v34, v167, v32
	v_pk_add_f32 v[46:47], v[46:47], v[52:53]
	s_waitcnt lgkmcnt(0)
	v_pk_add_f32 v[32:33], v[32:33], v[34:35]
	v_pk_add_f32 v[6:7], v[46:47], v[6:7]
	ds_bpermute_b32 v35, v194, v33
	v_pk_add_f32 v[2:3], v[6:7], v[2:3]
	ds_bpermute_b32 v5, v167, v3
	ds_bpermute_b32 v4, v167, v2
	v_pk_add_f32 v[6:7], v[102:103], v[104:105]
	ds_bpermute_b32 v34, v194, v32
	s_waitcnt lgkmcnt(1)
	v_pk_add_f32 v[2:3], v[2:3], v[4:5]
	ds_bpermute_b32 v5, v194, v3
	ds_bpermute_b32 v4, v194, v2
	s_waitcnt lgkmcnt(2)
	v_pk_add_f32 v[32:33], v[32:33], v[34:35]
	ds_bpermute_b32 v35, v195, v33
	ds_bpermute_b32 v34, v195, v32
	s_waitcnt lgkmcnt(2)
	v_pk_add_f32 v[2:3], v[2:3], v[4:5]
	ds_bpermute_b32 v5, v195, v3
	ds_bpermute_b32 v4, v195, v2
	s_waitcnt lgkmcnt(2)
	v_pk_add_f32 v[32:33], v[32:33], v[34:35]
	ds_bpermute_b32 v35, v196, v33
	ds_bpermute_b32 v34, v196, v32
	s_waitcnt lgkmcnt(2)
	v_pk_add_f32 v[2:3], v[2:3], v[4:5]
	ds_bpermute_b32 v5, v196, v3
	ds_bpermute_b32 v4, v196, v2
	s_waitcnt lgkmcnt(2)
	v_pk_add_f32 v[32:33], v[32:33], v[34:35]
	ds_bpermute_b32 v35, v198, v33
	ds_bpermute_b32 v34, v198, v32
	s_waitcnt lgkmcnt(2)
	v_pk_add_f32 v[2:3], v[2:3], v[4:5]
	ds_bpermute_b32 v5, v198, v3
	ds_bpermute_b32 v4, v198, v2
	s_waitcnt lgkmcnt(2)
	v_pk_add_f32 v[32:33], v[32:33], v[34:35]
	ds_bpermute_b32 v35, v198, v99
	ds_bpermute_b32 v34, v198, v98
	s_waitcnt lgkmcnt(2)
	v_pk_add_f32 v[2:3], v[2:3], v[4:5]
	v_pk_add_f32 v[4:5], v[82:83], v[100:101]
	s_waitcnt lgkmcnt(0)
	v_pk_add_f32 v[34:35], v[98:99], v[34:35]
	v_pk_add_f32 v[4:5], v[4:5], v[6:7]
	v_pk_fma_f32 v[6:7], v[58:59], v[170:171], v[176:177] op_sel:[0,0,1] op_sel_hi:[1,1,0]
	s_nop 0
	v_pk_add_f32 v[6:7], v[6:7], v[8:9]
	v_pk_mul_f32 v[8:9], v[132:133], v[16:17]
	v_pk_add_f32 v[4:5], v[4:5], v[6:7]
	v_pk_mul_f32 v[6:7], v[130:131], v[14:15]
	v_pk_fma_f32 v[8:9], v[132:133], v[40:41], v[8:9] op_sel:[0,0,1] op_sel_hi:[1,1,0]
	v_pk_fma_f32 v[6:7], v[130:131], v[96:97], v[6:7] op_sel:[0,0,1] op_sel_hi:[1,1,0]
	ds_bpermute_b32 v17, v197, v35
	v_pk_add_f32 v[6:7], v[6:7], v[8:9]
	v_pk_mul_f32 v[8:9], v[92:93], v[12:13]
	v_pk_add_f32 v[4:5], v[4:5], v[6:7]
	v_pk_mul_f32 v[6:7], v[134:135], v[10:11]
	v_pk_fma_f32 v[8:9], v[92:93], v[36:37], v[8:9] op_sel:[0,0,1] op_sel_hi:[1,1,0]
	v_pk_fma_f32 v[6:7], v[134:135], v[42:43], v[6:7] op_sel:[0,0,1] op_sel_hi:[1,1,0]
	v_pk_fma_f32 v[10:11], v[56:57], v[90:91], v[144:145] op_sel:[0,0,1] op_sel_hi:[1,1,0]
	v_pk_add_f32 v[6:7], v[6:7], v[8:9]
	v_pk_add_f32 v[8:9], v[84:85], v[88:89]
	v_pk_add_f32 v[4:5], v[4:5], v[6:7]
	ds_bpermute_b32 v7, v167, v5
	ds_bpermute_b32 v6, v167, v4
	ds_bpermute_b32 v13, v197, v33
	ds_bpermute_b32 v12, v197, v32
	ds_bpermute_b32 v16, v197, v34
	s_waitcnt lgkmcnt(3)
	v_pk_add_f32 v[4:5], v[4:5], v[6:7]
	ds_bpermute_b32 v7, v194, v5
	ds_bpermute_b32 v6, v194, v4
	s_waitcnt lgkmcnt(0)
	v_pk_add_f32 v[4:5], v[4:5], v[6:7]
	ds_bpermute_b32 v7, v195, v5
	ds_bpermute_b32 v6, v195, v4
	s_waitcnt lgkmcnt(0)
	v_pk_add_f32 v[4:5], v[4:5], v[6:7]
	ds_bpermute_b32 v7, v196, v5
	ds_bpermute_b32 v6, v196, v4
	s_waitcnt lgkmcnt(0)
	v_pk_add_f32 v[4:5], v[4:5], v[6:7]
	ds_bpermute_b32 v7, v198, v5
	ds_bpermute_b32 v6, v198, v4
	s_waitcnt lgkmcnt(0)
	v_pk_add_f32 v[4:5], v[4:5], v[6:7]
	v_pk_add_f32 v[6:7], v[66:67], v[64:65]
	s_nop 0
	v_pk_add_f32 v[6:7], v[6:7], v[8:9]
	v_pk_fma_f32 v[8:9], v[58:59], v[86:87], v[94:95] op_sel:[0,0,1] op_sel_hi:[1,1,0]
	s_nop 0
	v_pk_add_f32 v[8:9], v[8:9], v[10:11]
	v_pk_mul_f32 v[10:11], v[132:133], v[26:27]
	v_pk_add_f32 v[6:7], v[6:7], v[8:9]
	v_pk_mul_f32 v[8:9], v[130:131], v[24:25]
	v_pk_fma_f32 v[10:11], v[132:133], v[48:49], v[10:11] op_sel:[0,0,1] op_sel_hi:[1,1,0]
	v_pk_fma_f32 v[8:9], v[130:131], v[38:39], v[8:9] op_sel:[0,0,1] op_sel_hi:[1,1,0]
	s_nop 0
	v_pk_add_f32 v[8:9], v[8:9], v[10:11]
	v_pk_mul_f32 v[10:11], v[92:93], v[22:23]
	v_pk_add_f32 v[6:7], v[6:7], v[8:9]
	v_pk_mul_f32 v[8:9], v[134:135], v[20:21]
	v_pk_fma_f32 v[10:11], v[92:93], v[44:45], v[10:11] op_sel:[0,0,1] op_sel_hi:[1,1,0]
	v_pk_fma_f32 v[8:9], v[134:135], v[50:51], v[8:9] op_sel:[0,0,1] op_sel_hi:[1,1,0]
	ds_bpermute_b32 v21, v197, v3
	v_pk_add_f32 v[8:9], v[8:9], v[10:11]
	ds_bpermute_b32 v11, v197, v31
	v_pk_add_f32 v[6:7], v[6:7], v[8:9]
	ds_bpermute_b32 v9, v167, v7
	ds_bpermute_b32 v8, v167, v6
	ds_bpermute_b32 v10, v197, v30
	ds_bpermute_b32 v20, v197, v2
	ds_bpermute_b32 v23, v197, v5
	ds_bpermute_b32 v22, v197, v4
	s_waitcnt lgkmcnt(4)
	v_pk_add_f32 v[6:7], v[6:7], v[8:9]
	ds_bpermute_b32 v9, v194, v7
	ds_bpermute_b32 v8, v194, v6
	s_waitcnt lgkmcnt(0)
	v_pk_add_f32 v[6:7], v[6:7], v[8:9]
	ds_bpermute_b32 v9, v195, v7
	ds_bpermute_b32 v8, v195, v6
	s_waitcnt lgkmcnt(0)
	v_pk_add_f32 v[6:7], v[6:7], v[8:9]
	ds_bpermute_b32 v9, v196, v7
	ds_bpermute_b32 v8, v196, v6
	s_waitcnt lgkmcnt(0)
	v_pk_add_f32 v[6:7], v[6:7], v[8:9]
	ds_bpermute_b32 v9, v198, v7
	ds_bpermute_b32 v8, v198, v6
	s_waitcnt lgkmcnt(0)
	v_pk_add_f32 v[14:15], v[6:7], v[8:9]
	ds_bpermute_b32 v7, v197, v55
	ds_bpermute_b32 v6, v197, v54
	ds_bpermute_b32 v9, v197, v29
	ds_bpermute_b32 v8, v197, v28
	ds_bpermute_b32 v25, v197, v15
	ds_bpermute_b32 v24, v197, v14
	s_and_saveexec_b64 s[18:19], s[0:1]
	s_cbranch_execz .LBB0_179
	s_lshl_b64 s[20:21], s[8:9], 5
	v_pk_add_f32 v[22:23], v[4:5], v[22:23]
	s_waitcnt lgkmcnt(2)
	v_pk_add_f32 v[8:9], v[28:29], v[8:9]
	v_pk_add_f32 v[4:5], v[54:55], v[6:7]
	s_add_u32 s20, s40, s20
	v_pk_add_f32 v[20:21], v[2:3], v[20:21]
	v_pk_add_f32 v[12:13], v[32:33], v[12:13]
	v_pk_add_f32 v[10:11], v[30:31], v[10:11]
	s_addc_u32 s21, s41, s21
	v_mov_b32_e32 v2, v5
	v_mov_b32_e32 v3, v4
	v_mov_b32_e32 v4, v9
	v_mov_b32_e32 v5, v8
	s_lshl_b64 s[16:17], s[16:17], 5
	v_pk_add_f32 v[16:17], v[34:35], v[16:17]
	global_store_dwordx4 v19, v[2:5], s[20:21]
	s_add_u32 s16, s40, s16
	s_waitcnt lgkmcnt(0)
	v_pk_add_f32 v[14:15], v[14:15], v[24:25]
	v_mov_b32_e32 v2, v11
	v_mov_b32_e32 v3, v10
	v_mov_b32_e32 v4, v13
	v_mov_b32_e32 v5, v12
	global_store_dwordx4 v19, v[2:5], s[20:21] offset:16
	s_addc_u32 s17, s41, s17
	s_nop 0
	v_mov_b32_e32 v2, v17
	v_mov_b32_e32 v3, v16
	v_mov_b32_e32 v4, v21
	v_mov_b32_e32 v5, v20
	global_store_dwordx4 v19, v[2:5], s[16:17]
	s_nop 1
	v_mov_b32_e32 v2, v23
	v_mov_b32_e32 v3, v22
	v_mov_b32_e32 v4, v15
	v_mov_b32_e32 v5, v14
	global_store_dwordx4 v19, v[2:5], s[16:17] offset:16
	s_branch .LBB0_179

.LBB0_274:
	s_andn2_b64 vcc, exec, s[4:5]
	s_cbranch_vccnz .LBB0_273
	v_mov_b32_e32 v146, v164
	v_readlane_b32 s0, v250, 14
	v_mov_b32_e32 v1, v0
	v_readlane_b32 s49, v250, 6
	s_mov_b64 s[0:1], s[30:31]
	s_mov_b64 s[0:1], s[30:31]
	s_mov_b64 s[0:1], s[30:31]
	s_mov_b64 s[0:1], s[30:31]
	s_mov_b64 s[14:15], s[30:31]
	s_mov_b64 s[0:1], s[30:31]
	s_mov_b64 s[0:1], s[30:31]
	s_mov_b64 s[0:1], s[30:31]
	s_mov_b64 s[16:17], s[30:31]
	s_mov_b64 s[0:1], s[30:31]
	s_mov_b64 s[18:19], s[30:31]
	s_mov_b64 s[18:19], s[30:31]
	s_mov_b64 s[18:19], s[30:31]
	s_mov_b64 s[18:19], s[30:31]
	s_mov_b64 s[18:19], s[30:31]
	s_mov_b64 s[18:19], s[30:31]
	s_mov_b64 s[18:19], s[30:31]
	s_mov_b64 s[18:19], s[30:31]
	s_waitcnt vmcnt(0) lgkmcnt(0)
	v_mov_b32_e32 v10, v0
	v_readlane_b32 s18, v253, 33
	v_readlane_b32 s19, v253, 34
	s_andn2_b64 vcc, exec, s[18:19]
	v_readfirstlane_b32 s18, v10
	s_cbranch_vccnz .LBB0_295
	v_lshlrev_b32_e32 v1, 4, v10
	v_add_u32_e32 v2, 0x2000, v1
	v_ashrrev_i32_e32 v3, 31, v2
	v_lshrrev_b32_e32 v3, 22, v3
	v_add_u32_e32 v3, v2, v3
	v_ashrrev_i32_e32 v11, 10, v3
	v_mul_i32_i24_e32 v3, 0x400, v11
	v_sub_u32_e32 v2, v2, v3
	v_lshrrev_b32_e32 v3, 4, v2
	v_bitop3_b32 v2, v3, v2, 32 bitop3:0x6c
	v_ashrrev_i32_e32 v3, 31, v2
	s_add_u32 s50, s16, 0x17c00000
	v_lshrrev_b32_e32 v3, 26, v3
	s_addc_u32 s51, s17, 0
	v_add_u32_e32 v3, v2, v3
	v_lshlrev_b32_e32 v4, 3, v11
	s_add_u32 s14, s14, s12
	s_waitcnt lgkmcnt(0)
	v_ashrrev_i32_e32 v12, 6, v3
	v_and_b32_e32 v4, -16, v4
	s_addc_u32 s15, s15, s13
	v_add_u32_e32 v4, v12, v4
	s_add_u32 s52, s14, 0x1000000
	v_and_b32_e32 v5, 3, v12
	s_mov_b32 s14, 0xfffe0
	v_lshrrev_b32_e32 v6, 2, v4
	v_lshlrev_b32_e32 v7, 1, v4
	v_and_b32_e32 v3, 0xc0, v3
	v_and_or_b32 v5, v4, s14, v5
	v_and_b32_e32 v6, 4, v6
	v_and_b32_e32 v7, 24, v7
	v_sub_u32_e32 v2, v2, v3
	v_or3_b32 v5, v5, v6, v7
	v_lshlrev_b32_e32 v6, 5, v11
	v_ashrrev_i16_sdwa v2, v210, sext(v2) dst_sel:DWORD dst_unused:UNUSED_PAD src0_sel:DWORD src1_sel:BYTE_0
	v_and_b32_e32 v6, 32, v6
	v_bfe_i32 v13, v2, 0, 16
	v_add_lshl_u32 v2, v6, v13, 1
	v_lshl_add_u32 v132, v5, 12, v2
	v_lshlrev_b32_e32 v134, 4, v10
	v_add_u32_e32 v134, 0x2000, v134
	v_bfe_i32 v2, v10, 27, 1
	v_lshrrev_b32_e32 v2, 22, v2
	v_add_u32_e32 v2, v1, v2
	v_and_b32_e32 v2, 0xfffffc00, v2
	v_sub_u32_e32 v1, v1, v2
	v_lshrrev_b32_e32 v2, 4, v1
	v_ashrrev_i32_e32 v3, 31, v10
	v_bitop3_b32 v1, v2, v1, 32 bitop3:0x6c
	v_lshrrev_b32_e32 v3, 26, v3
	v_ashrrev_i32_e32 v2, 31, v1
	v_add_u32_e32 v3, v10, v3
	v_lshrrev_b32_e32 v2, 26, v2
	v_ashrrev_i32_e32 v15, 6, v3
	v_add_u32_e32 v2, v1, v2
	v_lshlrev_b32_e32 v3, 3, v15
	v_ashrrev_i32_e32 v14, 6, v2
	v_and_b32_e32 v3, -16, v3
	v_add_u32_e32 v3, v14, v3
	v_and_b32_e32 v4, 3, v14
	v_lshrrev_b32_e32 v5, 2, v3
	v_lshlrev_b32_e32 v6, 1, v3
	v_and_b32_e32 v2, 0xc0, v2
	s_addc_u32 s53, s15, 0
	s_ashr_i32 s20, s18, 6
	v_and_or_b32 v4, v3, s14, v4
	v_and_b32_e32 v5, 4, v5
	v_and_b32_e32 v6, 24, v6
	v_sub_u32_e32 v1, v1, v2
	s_ashr_i32 s19, s18, 8
	s_lshl_b32 s54, s20, 10
	v_or3_b32 v4, v4, v5, v6
	v_lshlrev_b32_e32 v5, 5, v15
	v_ashrrev_i16_sdwa v1, v210, sext(v1) dst_sel:DWORD dst_unused:UNUSED_PAD src0_sel:DWORD src1_sel:BYTE_0
	v_readlane_b32 s14, v252, 15
	v_and_b32_e32 v5, 32, v5
	v_bfe_i32 v16, v1, 0, 16
	v_readlane_b32 s15, v252, 16
	s_add_u32 s38, s52, s14
	v_add_lshl_u32 v1, v5, v16, 1
	s_addc_u32 s39, s53, s15
	s_add_i32 s55, s54, 0
	v_lshl_add_u32 v18, v4, 12, v1
	s_lshr_b32 s100, s20, 2
	s_lshl_b32 s100, s100, 17
	v_add_u32_e32 v18, s100, v18
	s_add_i32 s101, s100, 0x40000
	v_add_u32_e32 v132, s101, v132
	s_add_i32 m0, s55, 0x10000
	v_lshlrev_b32_e32 v136, 4, v10
	global_load_lds_dwordx4 v18, s[38:39]
	s_add_i32 m0, s55, 0x12000
	s_add_u32 s14, s38, 0x20000
	global_load_lds_dwordx4 v132, s[38:39]
	s_addc_u32 s15, s39, 0
	s_add_i32 m0, s55, 0x14000
	v_mov_b32_e32 v133, v19
	global_load_lds_dwordx4 v18, s[14:15]
	s_add_i32 m0, s55, 0x16000
	v_mov_b32_e32 v137, v19
	global_load_lds_dwordx4 v132, s[14:15]
	v_readlane_b32 s14, v252, 19
	v_readlane_b32 s15, v252, 20
	s_add_u32 s40, s50, s14
	s_addc_u32 s41, s51, s15
	s_sub_u32 s42, s40, s30
	s_and_b32 s43, s42, 0xf80
	s_lshl_b32 s43, s43, 8
	s_and_b32 s42, s42, 0xfff00000
	s_or_b32 s42, s42, s43
	s_add_u32 s42, s30, s42
	s_addc_u32 s43, s31, 0
	s_add_i32 s56, s55, 0x2000
	s_mov_b32 m0, s55
	s_add_u32 s14, s42, 0x4000
	global_load_lds_dwordx4 v136, s[42:43]
	s_mov_b32 m0, s56
	s_addc_u32 s15, s43, 0
	s_add_i32 s57, s55, 0x4000
	global_load_lds_dwordx4 v134, s[42:43]
	s_mov_b32 m0, s57
	s_add_i32 s58, s55, 0x6000
	global_load_lds_dwordx4 v136, s[14:15]
	s_mov_b32 m0, s58
	v_mov_b32_e32 v135, v19
	global_load_lds_dwordx4 v134, s[14:15]
	s_add_u32 s42, s42, 0x7f80
	s_addc_u32 s43, s43, 0
	s_cmp_eq_u32 s19, 1
	s_mov_b32 s72, s60
	v_lshl_add_u64 v[8:9], s[38:39], 0, v[18:19]
	v_lshl_add_u64 v[6:7], s[38:39], 0, v[132:133]
	v_lshl_add_u64 v[2:3], s[42:43], 0, v[136:137]
	s_cselect_b64 s[14:15], -1, 0
	s_cmp_lg_u32 s19, 1
	v_lshl_add_u64 v[4:5], s[42:43], 0, v[134:135]
	s_cbranch_scc1 .LBB0_278
	s_barrier
.LBB0_278:
	s_add_u32 s16, s0, 0x19d00000
	s_addc_u32 s17, s1, 0
	s_lshl_b32 s0, s20, 5
	s_and_b32 s20, s0, 0x60
	s_mov_b64 s[0:1], 0x80
	s_add_i32 m0, s55, 0x18000
	v_lshl_add_u64 v[8:9], v[8:9], 0, s[0:1]
	s_waitcnt vmcnt(2)
	s_barrier
	global_load_lds_dwordx4 v[8:9], off
	v_lshl_add_u64 v[6:7], v[6:7], 0, s[0:1]
	s_add_i32 m0, s55, 0x1a000
	s_add_i32 s59, s55, 0x8000
	s_lshl_b32 s21, s19, 13
	s_lshl_b32 s22, s20, 7
	global_load_lds_dwordx4 v[6:7], off
	v_lshl_add_u64 v[2:3], v[2:3], 0, s[0:1]
	s_mov_b32 m0, s59
	s_add_i32 s60, s55, 0xa000
	global_load_lds_dwordx4 v[2:3], off
	v_lshl_add_u64 v[2:3], v[4:5], 0, s[0:1]
	s_add_u32 s0, s38, 0x20080
	s_mov_b32 m0, s60
	s_addc_u32 s1, s39, 0
	global_load_lds_dwordx4 v[2:3], off
	s_add_i32 m0, s55, 0x1c000
	v_lshl_add_u64 v[2:3], s[0:1], 0, v[18:19]
	global_load_lds_dwordx4 v[2:3], off
	v_lshl_add_u64 v[2:3], s[0:1], 0, v[132:133]
	s_add_i32 m0, s55, 0x1e000
	s_cmpk_lt_u32 s18, 0x100
	global_load_lds_dwordx4 v[2:3], off
	v_lshrrev_b32_e32 v3, 1, v10
	v_and_b32_e32 v3, 24, v3
	v_and_b32_e32 v2, 15, v10
	v_lshlrev_b32_e32 v4, 1, v3
	v_lshl_or_b32 v1, s19, 6, v2
	v_lshl_or_b32 v2, v2, 6, v4
	v_lshlrev_b32_e32 v4, 2, v10
	v_and_b32_e32 v4, 32, v4
	v_bitop3_b32 v5, v2, s21, v4 bitop3:0xde
	v_bitop3_b32 v147, v2, s22, v4 bitop3:0xde
	v_lshlrev_b32_e32 v2, 15, v11
	v_and_b32_e32 v2, 0xffff0000, v2
	v_lshl_or_b32 v148, s20, 1, v3
	v_lshl_add_u32 v2, v12, 12, v2
	v_and_b32_e32 v3, 1, v11
	v_lshl_or_b32 v2, v3, 6, v2
	v_mov_b32_e32 v138, v134
	v_lshlrev_b32_e32 v2, 15, v15
	v_and_b32_e32 v2, 0xffff0000, v2
	s_waitcnt vmcnt(6)
	v_lshl_add_u32 v2, v14, 12, v2
	v_and_b32_e32 v3, 1, v15
	v_lshl_or_b32 v2, v3, 6, v2
	v_readlane_b32 s0, v252, 17
	s_cselect_b64 s[18:19], -1, 0
	v_mov_b32_e32 v139, v19
	v_mov_b32_e32 v140, v136
	v_mov_b32_e32 v141, v19
	s_mov_b32 s61, 0
	v_add_u32_e32 v149, 0, v5
	v_readlane_b32 s62, v252, 36
	s_mov_b32 s63, s0
	s_barrier
	v_readlane_b32 s1, v252, 18
	s_branch .LBB0_281

.LBB0_288:
	s_add_u32 s40, s38, 0xfff80080
	s_addc_u32 s41, s39, -1
	s_cmp_eq_u32 s68, 28
	s_cselect_b32 s43, s23, s41
	s_cselect_b32 s42, s64, s40
	s_cselect_b32 s41, s21, s67
	s_cselect_b32 s40, s65, s66
	s_sub_u32 s70, s42, s30
	s_and_b32 s71, s70, 0xf80
	s_lshl_b32 s71, s71, 8
	s_and_b32 s70, s70, 0xfff00000
	s_or_b32 s70, s70, s71
	s_add_u32 s42, s30, s70
	s_addc_u32 s43, s31, 0
	s_add_i32 s69, 0, 0x14000
	v_add_u32_e32 v158, s73, v147
	v_add_u32_e32 v162, s69, v147
	ds_read_b128 v[142:145], v158
	ds_read_b128 v[150:153], v158 offset:1024
	ds_read_b128 v[154:157], v158 offset:2048
	ds_read_b128 v[158:161], v158 offset:3072
	ds_read_b128 v[170:173], v162
	ds_read_b128 v[174:177], v162 offset:1024
	ds_read_b128 v[178:181], v162 offset:2048
	ds_read_b128 v[182:185], v162 offset:3072
	s_sub_u32 s100, s38, s30
	s_and_b32 s101, s100, 0xf80
	s_lshl_b32 s101, s101, 8
	s_and_b32 s100, s100, 0xfff00000
	s_or_b32 s100, s100, s101
	s_add_i32 s100, s100, 0x4000
	s_add_u32 s100, s30, s100
	s_addc_u32 s101, s31, 0
	v_lshl_add_u64 v[162:163], s[100:101], 0, v[140:141]
	s_add_i32 m0, s55, 0xc000
	ds_read_b128 v[186:189], v149
	ds_read_b128 v[190:193], v149 offset:1024
	ds_read_b128 v[194:197], v149 offset:2048
	ds_read_b128 v[198:201], v149 offset:3072
	ds_read_b128 v[202:205], v149 offset:4096
	ds_read_b128 v[206:209], v149 offset:5120
	ds_read_b128 v[220:223], v149 offset:6144
	ds_read_b128 v[224:227], v149 offset:7168
	global_load_lds_dwordx4 v[162:163], off
	v_lshl_add_u64 v[162:163], s[100:101], 0, v[138:139]
	s_add_i32 m0, s55, 0xe000
	s_nop 0
	global_load_lds_dwordx4 v[162:163], off
	s_waitcnt vmcnt(8)
	s_waitcnt lgkmcnt(0)
	s_barrier
	s_setprio 1
	s_waitcnt lgkmcnt(0)
	v_mfma_f32_16x16x32_bf16 v[128:131], v[142:145], v[186:189], v[128:131]
	v_mfma_f32_16x16x32_bf16 v[124:127], v[154:157], v[186:189], v[124:127]
	v_mfma_f32_16x16x32_bf16 v[120:123], v[142:145], v[194:197], v[120:123]
	v_mfma_f32_16x16x32_bf16 v[112:115], v[154:157], v[194:197], v[112:115]
	v_mfma_f32_16x16x32_bf16 v[104:107], v[142:145], v[202:205], v[104:107]
	v_mfma_f32_16x16x32_bf16 v[96:99], v[154:157], v[202:205], v[96:99]
	v_mfma_f32_16x16x32_bf16 v[88:91], v[142:145], v[220:223], v[88:91]
	v_mfma_f32_16x16x32_bf16 v[80:83], v[154:157], v[220:223], v[80:83]
	v_mfma_f32_16x16x32_bf16 v[128:131], v[150:153], v[190:193], v[128:131]
	v_mfma_f32_16x16x32_bf16 v[124:127], v[158:161], v[190:193], v[124:127]
	v_mfma_f32_16x16x32_bf16 v[120:123], v[150:153], v[198:201], v[120:123]
	v_mfma_f32_16x16x32_bf16 v[112:115], v[158:161], v[198:201], v[112:115]
	v_mfma_f32_16x16x32_bf16 v[104:107], v[150:153], v[206:209], v[104:107]
	v_mfma_f32_16x16x32_bf16 v[96:99], v[158:161], v[206:209], v[96:99]
	v_mfma_f32_16x16x32_bf16 v[88:91], v[150:153], v[224:227], v[88:91]
	v_mfma_f32_16x16x32_bf16 v[80:83], v[158:161], v[224:227], v[80:83]
	s_setprio 0
	s_setprio 1
	v_mfma_f32_16x16x32_bf16 v[116:119], v[170:173], v[186:189], v[116:119]
	v_mfma_f32_16x16x32_bf16 v[108:111], v[178:181], v[186:189], v[108:111]
	v_mfma_f32_16x16x32_bf16 v[100:103], v[170:173], v[194:197], v[100:103]
	v_mfma_f32_16x16x32_bf16 v[92:95], v[178:181], v[194:197], v[92:95]
	v_mfma_f32_16x16x32_bf16 v[84:87], v[170:173], v[202:205], v[84:87]
	v_mfma_f32_16x16x32_bf16 v[76:79], v[178:181], v[202:205], v[76:79]
	v_mfma_f32_16x16x32_bf16 v[72:75], v[170:173], v[220:223], v[72:75]
	v_mfma_f32_16x16x32_bf16 v[68:71], v[178:181], v[220:223], v[68:71]
	v_mfma_f32_16x16x32_bf16 v[116:119], v[174:177], v[190:193], v[116:119]
	v_mfma_f32_16x16x32_bf16 v[108:111], v[182:185], v[190:193], v[108:111]
	v_mfma_f32_16x16x32_bf16 v[100:103], v[174:177], v[198:201], v[100:103]
	v_mfma_f32_16x16x32_bf16 v[92:95], v[182:185], v[198:201], v[92:95]
	v_mfma_f32_16x16x32_bf16 v[84:87], v[174:177], v[206:209], v[84:87]
	v_mfma_f32_16x16x32_bf16 v[76:79], v[182:185], v[206:209], v[76:79]
	v_mfma_f32_16x16x32_bf16 v[72:75], v[174:177], v[224:227], v[72:75]
	v_mfma_f32_16x16x32_bf16 v[68:71], v[182:185], v[224:227], v[68:71]
	s_setprio 0
	s_barrier
	s_add_i32 s70, s73, s54
	v_lshl_add_u64 v[162:163], s[40:41], 0, v[18:19]
	s_mov_b32 m0, s70
	ds_read_b128 v[186:189], v149 offset:16384
	ds_read_b128 v[190:193], v149 offset:17408
	ds_read_b128 v[194:197], v149 offset:18432
	ds_read_b128 v[198:201], v149 offset:19456
	ds_read_b128 v[202:205], v149 offset:20480
	ds_read_b128 v[206:209], v149 offset:21504
	ds_read_b128 v[220:223], v149 offset:22528
	ds_read_b128 v[224:227], v149 offset:23552
	global_load_lds_dwordx4 v[162:163], off
	s_add_i32 m0, s70, 0x2000
	s_add_u32 s70, s40, 0x20000
	v_lshl_add_u64 v[228:229], s[40:41], 0, v[132:133]
	s_addc_u32 s71, s41, 0
	s_add_i32 s69, s69, s54
	global_load_lds_dwordx4 v[228:229], off
	v_lshl_add_u64 v[230:231], s[70:71], 0, v[18:19]
	s_mov_b32 m0, s69
	v_lshl_add_u64 v[232:233], s[42:43], 0, v[134:135]
	global_load_lds_dwordx4 v[230:231], off
	v_lshl_add_u64 v[230:231], s[70:71], 0, v[132:133]
	s_add_i32 m0, s69, 0x2000
	s_nop 0
	global_load_lds_dwordx4 v[230:231], off
	v_lshl_add_u64 v[230:231], s[42:43], 0, v[136:137]
	s_mov_b32 m0, s55
	s_nop 0
	global_load_lds_dwordx4 v[230:231], off
	s_mov_b32 m0, s56
	s_nop 0
	global_load_lds_dwordx4 v[232:233], off
	s_waitcnt vmcnt(8)
	s_waitcnt lgkmcnt(0)
	s_barrier
	s_setprio 1
	s_waitcnt lgkmcnt(0)
	v_mfma_f32_16x16x32_bf16 v[64:67], v[142:145], v[186:189], v[64:67]
	v_mfma_f32_16x16x32_bf16 v[60:63], v[154:157], v[186:189], v[60:63]
	v_mfma_f32_16x16x32_bf16 v[56:59], v[142:145], v[194:197], v[56:59]
	v_mfma_f32_16x16x32_bf16 v[48:51], v[154:157], v[194:197], v[48:51]
	v_mfma_f32_16x16x32_bf16 v[40:43], v[142:145], v[202:205], v[40:43]
	v_mfma_f32_16x16x32_bf16 v[32:35], v[154:157], v[202:205], v[32:35]
	v_mfma_f32_16x16x32_bf16 v[24:27], v[142:145], v[220:223], v[24:27]
	v_mfma_f32_16x16x32_bf16 v[14:17], v[154:157], v[220:223], v[14:17]
	v_mfma_f32_16x16x32_bf16 v[64:67], v[150:153], v[190:193], v[64:67]
	v_mfma_f32_16x16x32_bf16 v[60:63], v[158:161], v[190:193], v[60:63]
	v_mfma_f32_16x16x32_bf16 v[56:59], v[150:153], v[198:201], v[56:59]
	v_mfma_f32_16x16x32_bf16 v[48:51], v[158:161], v[198:201], v[48:51]
	v_mfma_f32_16x16x32_bf16 v[40:43], v[150:153], v[206:209], v[40:43]
	v_mfma_f32_16x16x32_bf16 v[32:35], v[158:161], v[206:209], v[32:35]
	v_mfma_f32_16x16x32_bf16 v[24:27], v[150:153], v[224:227], v[24:27]
	v_mfma_f32_16x16x32_bf16 v[14:17], v[158:161], v[224:227], v[14:17]
	s_setprio 0
	s_setprio 1
	v_mfma_f32_16x16x32_bf16 v[52:55], v[170:173], v[186:189], v[52:55]
	v_mfma_f32_16x16x32_bf16 v[44:47], v[178:181], v[186:189], v[44:47]
	v_mfma_f32_16x16x32_bf16 v[36:39], v[170:173], v[194:197], v[36:39]
	v_mfma_f32_16x16x32_bf16 v[28:31], v[178:181], v[194:197], v[28:31]
	v_mfma_f32_16x16x32_bf16 v[20:23], v[170:173], v[202:205], v[20:23]
	v_mfma_f32_16x16x32_bf16 v[10:13], v[178:181], v[202:205], v[10:13]
	v_mfma_f32_16x16x32_bf16 v[6:9], v[170:173], v[220:223], v[6:9]
	v_mfma_f32_16x16x32_bf16 v[2:5], v[178:181], v[220:223], v[2:5]
	v_mfma_f32_16x16x32_bf16 v[52:55], v[174:177], v[190:193], v[52:55]
	v_mfma_f32_16x16x32_bf16 v[44:47], v[182:185], v[190:193], v[44:47]
	v_mfma_f32_16x16x32_bf16 v[36:39], v[174:177], v[198:201], v[36:39]
	v_mfma_f32_16x16x32_bf16 v[28:31], v[182:185], v[198:201], v[28:31]
	v_mfma_f32_16x16x32_bf16 v[20:23], v[174:177], v[206:209], v[20:23]
	v_mfma_f32_16x16x32_bf16 v[10:13], v[182:185], v[206:209], v[10:13]
	v_mfma_f32_16x16x32_bf16 v[6:9], v[174:177], v[224:227], v[6:9]
	v_mfma_f32_16x16x32_bf16 v[2:5], v[182:185], v[224:227], v[2:5]
	s_setprio 0
	s_barrier
	s_add_i32 s69, 0, 0x18000
	s_add_i32 s70, 0, 0x1c000
	v_add_u32_e32 v158, s69, v147
	v_add_u32_e32 v167, s70, v147
	ds_read_b128 v[142:145], v158
	ds_read_b128 v[150:153], v158 offset:1024
	ds_read_b128 v[154:157], v158 offset:2048
	ds_read_b128 v[158:161], v158 offset:3072
	ds_read_b128 v[170:173], v167
	ds_read_b128 v[174:177], v167 offset:1024
	ds_read_b128 v[178:181], v167 offset:2048
	ds_read_b128 v[182:185], v167 offset:3072
	s_add_u32 s42, s42, 0x4000
	s_addc_u32 s43, s43, 0
	s_mov_b32 m0, s57
	v_lshl_add_u64 v[234:235], s[42:43], 0, v[136:137]
	ds_read_b128 v[186:189], v149 offset:32768
	ds_read_b128 v[190:193], v149 offset:33792
	ds_read_b128 v[194:197], v149 offset:34816
	ds_read_b128 v[198:201], v149 offset:35840
	ds_read_b128 v[202:205], v149 offset:36864
	ds_read_b128 v[206:209], v149 offset:37888
	ds_read_b128 v[220:223], v149 offset:38912
	ds_read_b128 v[224:227], v149 offset:39936
	global_load_lds_dwordx4 v[234:235], off
	v_lshl_add_u64 v[234:235], s[42:43], 0, v[134:135]
	s_mov_b32 m0, s58
	s_nop 0
	global_load_lds_dwordx4 v[234:235], off
	s_waitcnt vmcnt(8)
	s_waitcnt lgkmcnt(0)
	s_barrier
	s_setprio 1
	s_waitcnt lgkmcnt(0)
	v_mfma_f32_16x16x32_bf16 v[128:131], v[142:145], v[186:189], v[128:131]
	v_mfma_f32_16x16x32_bf16 v[124:127], v[154:157], v[186:189], v[124:127]
	v_mfma_f32_16x16x32_bf16 v[120:123], v[142:145], v[194:197], v[120:123]
	v_mfma_f32_16x16x32_bf16 v[112:115], v[154:157], v[194:197], v[112:115]
	v_mfma_f32_16x16x32_bf16 v[104:107], v[142:145], v[202:205], v[104:107]
	v_mfma_f32_16x16x32_bf16 v[96:99], v[154:157], v[202:205], v[96:99]
	v_mfma_f32_16x16x32_bf16 v[88:91], v[142:145], v[220:223], v[88:91]
	v_mfma_f32_16x16x32_bf16 v[80:83], v[154:157], v[220:223], v[80:83]
	v_mfma_f32_16x16x32_bf16 v[128:131], v[150:153], v[190:193], v[128:131]
	v_mfma_f32_16x16x32_bf16 v[124:127], v[158:161], v[190:193], v[124:127]
	v_mfma_f32_16x16x32_bf16 v[120:123], v[150:153], v[198:201], v[120:123]
	v_mfma_f32_16x16x32_bf16 v[112:115], v[158:161], v[198:201], v[112:115]
	v_mfma_f32_16x16x32_bf16 v[104:107], v[150:153], v[206:209], v[104:107]
	v_mfma_f32_16x16x32_bf16 v[96:99], v[158:161], v[206:209], v[96:99]
	v_mfma_f32_16x16x32_bf16 v[88:91], v[150:153], v[224:227], v[88:91]
	v_mfma_f32_16x16x32_bf16 v[80:83], v[158:161], v[224:227], v[80:83]
	s_setprio 0
	s_setprio 1
	v_mfma_f32_16x16x32_bf16 v[116:119], v[170:173], v[186:189], v[116:119]
	v_mfma_f32_16x16x32_bf16 v[108:111], v[178:181], v[186:189], v[108:111]
	v_mfma_f32_16x16x32_bf16 v[100:103], v[170:173], v[194:197], v[100:103]
	v_mfma_f32_16x16x32_bf16 v[92:95], v[178:181], v[194:197], v[92:95]
	v_mfma_f32_16x16x32_bf16 v[84:87], v[170:173], v[202:205], v[84:87]
	v_mfma_f32_16x16x32_bf16 v[76:79], v[178:181], v[202:205], v[76:79]
	v_mfma_f32_16x16x32_bf16 v[72:75], v[170:173], v[220:223], v[72:75]
	v_mfma_f32_16x16x32_bf16 v[68:71], v[178:181], v[220:223], v[68:71]
	v_mfma_f32_16x16x32_bf16 v[116:119], v[174:177], v[190:193], v[116:119]
	v_mfma_f32_16x16x32_bf16 v[108:111], v[182:185], v[190:193], v[108:111]
	v_mfma_f32_16x16x32_bf16 v[100:103], v[174:177], v[198:201], v[100:103]
	v_mfma_f32_16x16x32_bf16 v[92:95], v[182:185], v[198:201], v[92:95]
	v_mfma_f32_16x16x32_bf16 v[84:87], v[174:177], v[206:209], v[84:87]
	v_mfma_f32_16x16x32_bf16 v[76:79], v[182:185], v[206:209], v[76:79]
	v_mfma_f32_16x16x32_bf16 v[72:75], v[174:177], v[224:227], v[72:75]
	v_mfma_f32_16x16x32_bf16 v[68:71], v[182:185], v[224:227], v[68:71]
	s_setprio 0
	s_barrier
	s_add_i32 s42, s69, s54
	v_lshl_add_u64 v[162:163], v[162:163], 0, s[74:75]
	s_mov_b32 m0, s42
	ds_read_b128 v[186:189], v149 offset:49152
	ds_read_b128 v[190:193], v149 offset:50176
	ds_read_b128 v[194:197], v149 offset:51200
	ds_read_b128 v[198:201], v149 offset:52224
	ds_read_b128 v[202:205], v149 offset:53248
	ds_read_b128 v[206:209], v149 offset:54272
	ds_read_b128 v[220:223], v149 offset:55296
	ds_read_b128 v[224:227], v149 offset:56320
	global_load_lds_dwordx4 v[162:163], off
	s_add_i32 m0, s42, 0x2000
	s_add_u32 s40, s40, 0x20080
	v_lshl_add_u64 v[162:163], v[228:229], 0, s[74:75]
	s_addc_u32 s41, s41, 0
	s_add_i32 s42, s70, s54
	global_load_lds_dwordx4 v[162:163], off
	v_lshl_add_u64 v[162:163], s[40:41], 0, v[18:19]
	s_mov_b32 m0, s42
	s_nop 0
	global_load_lds_dwordx4 v[162:163], off
	v_lshl_add_u64 v[162:163], s[40:41], 0, v[132:133]
	s_add_i32 m0, s42, 0x2000
	s_nop 0
	global_load_lds_dwordx4 v[162:163], off
	s_mov_b64 s[100:101], 0x8000
	v_lshl_add_u64 v[162:163], v[230:231], 0, s[100:101]
	s_mov_b32 m0, s59
	s_nop 0
	global_load_lds_dwordx4 v[162:163], off
	v_lshl_add_u64 v[162:163], v[232:233], 0, s[100:101]
	s_mov_b32 m0, s60
	s_nop 0
	global_load_lds_dwordx4 v[162:163], off
	s_waitcnt vmcnt(8)
	s_waitcnt lgkmcnt(0)
	s_barrier
	s_setprio 1
	s_waitcnt lgkmcnt(0)
	v_mfma_f32_16x16x32_bf16 v[64:67], v[142:145], v[186:189], v[64:67]
	v_mfma_f32_16x16x32_bf16 v[60:63], v[154:157], v[186:189], v[60:63]
	v_mfma_f32_16x16x32_bf16 v[56:59], v[142:145], v[194:197], v[56:59]
	v_mfma_f32_16x16x32_bf16 v[48:51], v[154:157], v[194:197], v[48:51]
	v_mfma_f32_16x16x32_bf16 v[40:43], v[142:145], v[202:205], v[40:43]
	v_mfma_f32_16x16x32_bf16 v[32:35], v[154:157], v[202:205], v[32:35]
	v_mfma_f32_16x16x32_bf16 v[24:27], v[142:145], v[220:223], v[24:27]
	v_mfma_f32_16x16x32_bf16 v[14:17], v[154:157], v[220:223], v[14:17]
	v_mfma_f32_16x16x32_bf16 v[64:67], v[150:153], v[190:193], v[64:67]
	v_mfma_f32_16x16x32_bf16 v[60:63], v[158:161], v[190:193], v[60:63]
	v_mfma_f32_16x16x32_bf16 v[56:59], v[150:153], v[198:201], v[56:59]
	v_mfma_f32_16x16x32_bf16 v[48:51], v[158:161], v[198:201], v[48:51]
	v_mfma_f32_16x16x32_bf16 v[40:43], v[150:153], v[206:209], v[40:43]
	v_mfma_f32_16x16x32_bf16 v[32:35], v[158:161], v[206:209], v[32:35]
	v_mfma_f32_16x16x32_bf16 v[24:27], v[150:153], v[224:227], v[24:27]
	v_mfma_f32_16x16x32_bf16 v[14:17], v[158:161], v[224:227], v[14:17]
	s_setprio 0
	s_setprio 1
	v_mfma_f32_16x16x32_bf16 v[52:55], v[170:173], v[186:189], v[52:55]
	v_mfma_f32_16x16x32_bf16 v[44:47], v[178:181], v[186:189], v[44:47]
	v_mfma_f32_16x16x32_bf16 v[36:39], v[170:173], v[194:197], v[36:39]
	v_mfma_f32_16x16x32_bf16 v[28:31], v[178:181], v[194:197], v[28:31]
	v_mfma_f32_16x16x32_bf16 v[20:23], v[170:173], v[202:205], v[20:23]
	v_mfma_f32_16x16x32_bf16 v[10:13], v[178:181], v[202:205], v[10:13]
	v_mfma_f32_16x16x32_bf16 v[6:9], v[170:173], v[220:223], v[6:9]
	v_mfma_f32_16x16x32_bf16 v[2:5], v[178:181], v[220:223], v[2:5]
	v_mfma_f32_16x16x32_bf16 v[52:55], v[174:177], v[190:193], v[52:55]
	v_mfma_f32_16x16x32_bf16 v[44:47], v[182:185], v[190:193], v[44:47]
	v_mfma_f32_16x16x32_bf16 v[36:39], v[174:177], v[198:201], v[36:39]
	v_mfma_f32_16x16x32_bf16 v[28:31], v[182:185], v[198:201], v[28:31]
	v_mfma_f32_16x16x32_bf16 v[20:23], v[174:177], v[206:209], v[20:23]
	v_mfma_f32_16x16x32_bf16 v[10:13], v[182:185], v[206:209], v[10:13]
	v_mfma_f32_16x16x32_bf16 v[6:9], v[174:177], v[224:227], v[6:9]
	v_mfma_f32_16x16x32_bf16 v[2:5], v[182:185], v[224:227], v[2:5]
	s_setprio 0
	s_barrier
	s_add_i32 s68, s68, 2
	s_add_u32 s66, s66, 0x100
	s_addc_u32 s67, s67, 0
	s_add_u32 s38, s38, 0x100
	s_addc_u32 s39, s39, 0
	s_cmp_gt_u32 s68, 29
	s_cbranch_scc0 .LBB0_288
	s_and_b64 vcc, exec, s[18:19]
	s_cbranch_vccz .LBB0_291
	s_barrier

.LBB0_1669:
	v_add_u32_e32 v18, s0, v124
	v_add_u32_e32 v20, 0x10000, v18
	ds_read_b128 v[38:41], v20
	v_add_u32_e32 v20, 0x10400, v18
	s_addk_i32 s0, 0x2000
	s_cmpk_lg_u32 s0, 0xe000
	s_waitcnt vmcnt(0) lgkmcnt(0)
	v_pk_add_f32 v[36:37], v[36:37], v[40:41]
	v_pk_add_f32 v[34:35], v[34:35], v[38:39]
	ds_read_b128 v[38:41], v20
	v_add_u32_e32 v20, 0x10800, v18
	s_waitcnt lgkmcnt(0)
	v_pk_add_f32 v[32:33], v[32:33], v[40:41]
	v_pk_add_f32 v[30:31], v[30:31], v[38:39]
	ds_read_b128 v[38:41], v20
	v_add_u32_e32 v20, 0x10c00, v18
	s_waitcnt lgkmcnt(0)
	v_pk_add_f32 v[28:29], v[28:29], v[40:41]
	v_pk_add_f32 v[26:27], v[26:27], v[38:39]
	ds_read_b128 v[38:41], v20
	v_add_u32_e32 v20, 0x11000, v18
	s_waitcnt lgkmcnt(0)
	v_pk_add_f32 v[24:25], v[24:25], v[40:41]
	v_pk_add_f32 v[22:23], v[22:23], v[38:39]
	ds_read_b128 v[38:41], v20
	v_add_u32_e32 v20, 0x11400, v18
	s_waitcnt lgkmcnt(0)
	v_pk_add_f32 v[16:17], v[16:17], v[40:41]
	v_pk_add_f32 v[14:15], v[14:15], v[38:39]
	ds_read_b128 v[38:41], v20
	v_add_u32_e32 v20, 0x11800, v18
	v_add_u32_e32 v18, 0x11c00, v18
	s_waitcnt lgkmcnt(0)
	v_pk_add_f32 v[12:13], v[12:13], v[40:41]
	v_pk_add_f32 v[10:11], v[10:11], v[38:39]
	ds_read_b128 v[38:41], v20
	s_waitcnt lgkmcnt(0)
	v_pk_add_f32 v[8:9], v[8:9], v[40:41]
	v_pk_add_f32 v[6:7], v[6:7], v[38:39]
	ds_read_b128 v[38:41], v18
	s_waitcnt lgkmcnt(0)
	v_pk_add_f32 v[4:5], v[4:5], v[40:41]
	v_pk_add_f32 v[2:3], v[2:3], v[38:39]
	s_cbranch_scc1 .LBB0_1669
	s_lshr_b32 s1, s26, 3
	s_ashr_i32 s0, s18, 12
	s_add_i32 s1, s1, 2
	s_cmp_lt_i32 s26, 0
	s_cselect_b32 s0, s0, s1
	s_ashr_i32 s1, s0, 31
	s_add_u32 s0, s0, s24
	s_addc_u32 s1, s1, 0
	v_lshl_add_u64 v[20:21], s[20:21], 0, v[70:71]
	s_mul_i32 s1, s1, 0xc000
	s_mul_hi_u32 s20, s0, 0xc000
	s_add_i32 s20, s20, s1
	s_mul_i32 s0, s0, 0xc000
	global_store_dwordx4 v[20:21], v[34:37], off
	global_store_dwordx4 v[20:21], v[30:33], off offset:1024
	global_store_dwordx4 v[20:21], v[26:29], off offset:2048
	global_store_dwordx4 v[20:21], v[22:25], off offset:3072
	v_add_co_u32_e32 v20, vcc, 0x1000, v20
	s_add_u32 s0, s5, s0
	s_nop 0
	v_addc_co_u32_e32 v21, vcc, 0, v21, vcc
	s_addc_u32 s1, s25, s20
	global_store_dwordx4 v[20:21], v[14:17], off
	global_store_dwordx4 v[20:21], v[10:13], off offset:1024
	global_store_dwordx4 v[20:21], v[6:9], off offset:2048
	global_store_dwordx4 v[20:21], v[2:5], off offset:3072
	v_lshl_add_u64 v[20:21], s[0:1], 0, v[70:71]
	v_add_co_u32_e32 v130, vcc, s78, v20
	global_load_dwordx4 v[38:41], v[72:73], off
	s_nop 0
	v_addc_co_u32_e32 v131, vcc, 0, v21, vcc
	global_load_dwordx4 v[42:45], v[130:131], off offset:-4096
	global_load_dwordx4 v[54:57], v[20:21], off
	s_mov_b64 s[0:1], 0x2000
	v_lshl_add_u64 v[46:47], v[20:21], 0, s[0:1]
	v_mul_f32_e32 v18, v35, v35
	v_mul_f32_e32 v125, v37, v37
	v_fmac_f32_e32 v18, v34, v34
	v_fmac_f32_e32 v125, v36, v36
	v_add_f32_e32 v18, v18, v125
	v_mul_f32_e32 v125, v31, v31
	v_fmac_f32_e32 v125, v30, v30
	s_lshl_b64 s[0:1], s[18:19], 12
	s_waitcnt vmcnt(1)
	v_pk_add_f32 v[44:45], v[44:45], 1.0 op_sel_hi:[1,0]
	v_pk_add_f32 v[42:43], v[42:43], 1.0 op_sel_hi:[1,0]
	v_pk_mul_f32 v[98:99], v[40:41], v[44:45]
	v_pk_mul_f32 v[102:103], v[38:39], v[42:43]
	global_load_dwordx4 v[38:41], v[72:73], off offset:1024
	global_load_dwordx4 v[42:45], v[46:47], off offset:1024
	global_load_dwordx4 v[62:65], v[20:21], off offset:1024
	s_waitcnt vmcnt(1)
	v_pk_add_f32 v[44:45], v[44:45], 1.0 op_sel_hi:[1,0]
	v_pk_add_f32 v[42:43], v[42:43], 1.0 op_sel_hi:[1,0]
	v_pk_mul_f32 v[106:107], v[40:41], v[44:45]
	v_pk_mul_f32 v[110:111], v[38:39], v[42:43]
	global_load_dwordx4 v[38:41], v[72:73], off offset:2048
	global_load_dwordx4 v[42:45], v[46:47], off offset:2048
	global_load_dwordx4 v[66:69], v[20:21], off offset:2048
	s_waitcnt vmcnt(1)
	v_pk_add_f32 v[44:45], v[44:45], 1.0 op_sel_hi:[1,0]
	v_pk_add_f32 v[42:43], v[42:43], 1.0 op_sel_hi:[1,0]
	v_pk_mul_f32 v[112:113], v[40:41], v[44:45]
	v_pk_mul_f32 v[114:115], v[38:39], v[42:43]
	global_load_dwordx4 v[38:41], v[72:73], off offset:3072
	global_load_dwordx4 v[42:45], v[46:47], off offset:3072
	global_load_dwordx4 v[58:61], v[20:21], off offset:3072
	v_add_co_u32_e32 v20, vcc, s3, v20
	s_waitcnt vmcnt(1)
	v_pk_add_f32 v[44:45], v[44:45], 1.0 op_sel_hi:[1,0]
	v_pk_add_f32 v[42:43], v[42:43], 1.0 op_sel_hi:[1,0]
	v_pk_mul_f32 v[104:105], v[40:41], v[44:45]
	v_pk_mul_f32 v[108:109], v[38:39], v[42:43]
	global_load_dwordx4 v[38:41], v[74:75], off
	global_load_dwordx4 v[42:45], v[130:131], off
	v_addc_co_u32_e32 v21, vcc, 0, v21, vcc
	global_load_dwordx4 v[50:53], v[20:21], off
	s_waitcnt vmcnt(1)
	v_pk_add_f32 v[44:45], v[44:45], 1.0 op_sel_hi:[1,0]
	v_pk_add_f32 v[42:43], v[42:43], 1.0 op_sel_hi:[1,0]
	v_pk_mul_f32 v[96:97], v[40:41], v[44:45]
	v_pk_mul_f32 v[100:101], v[38:39], v[42:43]
	global_load_dwordx4 v[38:41], v[76:77], off
	global_load_dwordx4 v[42:45], v[130:131], off offset:1024
	global_load_dwordx4 v[46:49], v[20:21], off offset:1024
	s_waitcnt vmcnt(1)
	v_pk_add_f32 v[44:45], v[44:45], 1.0 op_sel_hi:[1,0]
	v_pk_add_f32 v[42:43], v[42:43], 1.0 op_sel_hi:[1,0]
	v_pk_mul_f32 v[92:93], v[40:41], v[44:45]
	v_pk_mul_f32 v[94:95], v[38:39], v[42:43]
	global_load_dwordx4 v[38:41], v[78:79], off
	global_load_dwordx4 v[86:89], v[130:131], off offset:2048
	global_load_dwordx4 v[42:45], v[20:21], off offset:2048
	s_waitcnt vmcnt(1)
	v_pk_add_f32 v[88:89], v[88:89], 1.0 op_sel_hi:[1,0]
	v_pk_add_f32 v[86:87], v[86:87], 1.0 op_sel_hi:[1,0]
	v_pk_mul_f32 v[88:89], v[40:41], v[88:89]
	v_pk_mul_f32 v[90:91], v[38:39], v[86:87]
	global_load_dwordx4 v[126:129], v[80:81], off
	s_nop 0
	global_load_dwordx4 v[130:133], v[130:131], off offset:3072
	s_nop 0
	global_load_dwordx4 v[38:41], v[20:21], off offset:3072
	s_waitcnt vmcnt(1)
	v_pk_add_f32 v[86:87], v[130:131], 1.0 op_sel_hi:[1,0]
	s_nop 0
	v_pk_mul_f32 v[86:87], v[126:127], v[86:87]
	v_mul_f32_e32 v126, v33, v33
	v_fmac_f32_e32 v126, v32, v32
	v_add_f32_e32 v125, v125, v126
	v_add_f32_e32 v18, v18, v125
	v_mul_f32_e32 v125, v27, v27
	v_mul_f32_e32 v126, v29, v29
	v_fmac_f32_e32 v125, v26, v26
	v_fmac_f32_e32 v126, v28, v28
	v_add_f32_e32 v125, v125, v126
	v_add_f32_e32 v18, v18, v125
	v_mul_f32_e32 v125, v23, v23
	v_mul_f32_e32 v126, v25, v25
	v_fmac_f32_e32 v125, v22, v22
	v_fmac_f32_e32 v126, v24, v24
	v_add_f32_e32 v125, v125, v126
	v_add_f32_e32 v18, v18, v125
	v_mul_f32_e32 v125, v15, v15
	v_mul_f32_e32 v126, v17, v17
	v_fmac_f32_e32 v125, v14, v14
	v_fmac_f32_e32 v126, v16, v16
	v_add_f32_e32 v125, v125, v126
	v_add_f32_e32 v18, v18, v125
	v_mul_f32_e32 v125, v11, v11
	v_mul_f32_e32 v126, v13, v13
	v_fmac_f32_e32 v125, v10, v10
	v_fmac_f32_e32 v126, v12, v12
	v_add_f32_e32 v125, v125, v126
	v_add_f32_e32 v18, v18, v125
	v_mul_f32_e32 v125, v7, v7
	v_mul_f32_e32 v126, v9, v9
	v_fmac_f32_e32 v125, v6, v6
	v_fmac_f32_e32 v126, v8, v8
	v_add_f32_e32 v125, v125, v126
	v_add_f32_e32 v18, v18, v125
	v_mul_f32_e32 v125, v3, v3
	v_mul_f32_e32 v126, v5, v5
	v_fmac_f32_e32 v125, v2, v2
	v_fmac_f32_e32 v126, v4, v4
	v_add_f32_e32 v125, v125, v126
	v_add_f32_e32 v18, v18, v125
	v_and_b32_e32 v125, 64, v213
	v_add_u32_e32 v125, 64, v125
	v_xor_b32_e32 v126, 1, v213
	v_cmp_lt_i32_e32 vcc, v126, v125
	v_pk_add_f32 v[20:21], v[132:133], 1.0 op_sel_hi:[1,0]
	s_nop 0
	v_cndmask_b32_e32 v126, v213, v126, vcc
	v_lshlrev_b32_e32 v126, 2, v126
	ds_bpermute_b32 v126, v126, v18
	v_pk_mul_f32 v[20:21], v[128:129], v[20:21]
	s_waitcnt lgkmcnt(0)
	v_add_f32_e32 v18, v18, v126
	v_xor_b32_e32 v126, 2, v213
	v_cmp_lt_i32_e32 vcc, v126, v125
	s_nop 1
	v_cndmask_b32_e32 v126, v213, v126, vcc
	v_lshlrev_b32_e32 v126, 2, v126
	ds_bpermute_b32 v126, v126, v18
	s_waitcnt lgkmcnt(0)
	v_add_f32_e32 v18, v18, v126
	v_xor_b32_e32 v126, 4, v213
	v_cmp_lt_i32_e32 vcc, v126, v125
	s_nop 1
	v_cndmask_b32_e32 v126, v213, v126, vcc
	v_lshlrev_b32_e32 v126, 2, v126
	ds_bpermute_b32 v126, v126, v18
	s_waitcnt lgkmcnt(0)
	v_add_f32_e32 v18, v18, v126
	v_xor_b32_e32 v126, 8, v213
	v_cmp_lt_i32_e32 vcc, v126, v125
	s_nop 1
	v_cndmask_b32_e32 v126, v213, v126, vcc
	v_lshlrev_b32_e32 v126, 2, v126
	ds_bpermute_b32 v126, v126, v18
	s_waitcnt lgkmcnt(0)
	v_add_f32_e32 v18, v18, v126
	v_xor_b32_e32 v126, 16, v213
	v_cmp_lt_i32_e32 vcc, v126, v125
	s_nop 1
	v_cndmask_b32_e32 v126, v213, v126, vcc
	v_lshlrev_b32_e32 v126, 2, v126
	ds_bpermute_b32 v126, v126, v18
	s_waitcnt lgkmcnt(0)
	v_add_f32_e32 v18, v18, v126
	v_xor_b32_e32 v126, 32, v213
	v_cmp_lt_i32_e32 vcc, v126, v125
	s_nop 1
	v_cndmask_b32_e32 v125, v213, v126, vcc
	v_lshlrev_b32_e32 v125, 2, v125
	ds_bpermute_b32 v125, v125, v18
	s_waitcnt lgkmcnt(0)
	v_add_f32_e32 v18, v18, v125
	v_fmamk_f32 v18, v18, 0x3a000000, v165
	v_rsq_f32_e32 v18, v18
	s_nop 0
	v_mul_f32_e32 v34, v34, v18
	v_mul_f32_e32 v30, v30, v18
	v_mul_f32_e32 v26, v26, v18
	v_mul_f32_e32 v22, v22, v18
	v_mul_f32_e32 v14, v14, v18
	v_mul_f32_e32 v10, v10, v18
	v_mul_f32_e32 v6, v6, v18
	v_mul_f32_e32 v2, v2, v18
	v_fma_f32 v34, v102, v34, v54
	v_mul_f32_e32 v35, v35, v18
	v_mul_f32_e32 v37, v37, v18
	v_fma_f32 v30, v110, v30, v62
	v_mul_f32_e32 v31, v31, v18
	v_mul_f32_e32 v33, v33, v18
	v_fma_f32 v26, v114, v26, v66
	v_mul_f32_e32 v27, v27, v18
	v_mul_f32_e32 v29, v29, v18
	v_fma_f32 v22, v108, v22, v58
	v_mul_f32_e32 v23, v23, v18
	v_mul_f32_e32 v25, v25, v18
	v_fma_f32 v14, v100, v14, v50
	v_mul_f32_e32 v15, v15, v18
	v_mul_f32_e32 v17, v17, v18
	v_fma_f32 v10, v94, v10, v46
	v_mul_f32_e32 v11, v11, v18
	v_mul_f32_e32 v13, v13, v18
	v_fma_f32 v6, v90, v6, v42
	v_mul_f32_e32 v7, v7, v18
	v_mul_f32_e32 v9, v9, v18
	s_waitcnt vmcnt(0)
	v_fma_f32 v2, v86, v2, v38
	v_mul_f32_e32 v3, v3, v18
	v_mul_f32_e32 v5, v5, v18
	v_fma_f32 v35, v103, v35, v55
	v_fmac_f32_e32 v57, v99, v37
	v_bfe_u32 v37, v34, 16, 1
	v_fma_f32 v31, v111, v31, v63
	v_fmac_f32_e32 v65, v107, v33
	v_bfe_u32 v33, v30, 16, 1
	v_fma_f32 v27, v115, v27, v67
	v_fmac_f32_e32 v69, v113, v29
	v_bfe_u32 v29, v26, 16, 1
	v_fma_f32 v23, v109, v23, v59
	v_fmac_f32_e32 v61, v105, v25
	v_bfe_u32 v25, v22, 16, 1
	v_fma_f32 v15, v101, v15, v51
	v_fmac_f32_e32 v53, v97, v17
	v_bfe_u32 v17, v14, 16, 1
	v_fma_f32 v11, v95, v11, v47
	v_fmac_f32_e32 v49, v93, v13
	v_bfe_u32 v13, v10, 16, 1
	v_fma_f32 v7, v91, v7, v43
	v_fmac_f32_e32 v45, v89, v9
	v_bfe_u32 v9, v6, 16, 1
	v_fma_f32 v3, v87, v3, v39
	v_fmac_f32_e32 v41, v21, v5
	v_bfe_u32 v5, v2, 16, 1
	v_mul_f32_e32 v36, v36, v18
	v_add3_u32 v34, v34, v37, s79
	v_bfe_u32 v37, v35, 16, 1
	v_mul_f32_e32 v32, v32, v18
	v_add3_u32 v30, v30, v33, s79
	v_bfe_u32 v33, v31, 16, 1
	v_mul_f32_e32 v28, v28, v18
	v_add3_u32 v26, v26, v29, s79
	v_bfe_u32 v29, v27, 16, 1
	v_mul_f32_e32 v24, v24, v18
	v_add3_u32 v22, v22, v25, s79
	v_bfe_u32 v25, v23, 16, 1
	v_mul_f32_e32 v16, v16, v18
	v_add3_u32 v14, v14, v17, s79
	v_bfe_u32 v17, v15, 16, 1
	v_mul_f32_e32 v12, v12, v18
	v_add3_u32 v10, v10, v13, s79
	v_bfe_u32 v13, v11, 16, 1
	v_mul_f32_e32 v8, v8, v18
	v_add3_u32 v6, v6, v9, s79
	v_bfe_u32 v9, v7, 16, 1
	v_mul_f32_e32 v4, v4, v18
	v_add3_u32 v2, v2, v5, s79
	v_bfe_u32 v5, v3, 16, 1
	v_fma_f32 v36, v98, v36, v56
	v_lshrrev_b32_e32 v34, 16, v34
	v_add3_u32 v35, v35, v37, s79
	v_fma_f32 v32, v106, v32, v64
	v_lshrrev_b32_e32 v30, 16, v30
	v_add3_u32 v31, v31, v33, s79
	v_fma_f32 v28, v112, v28, v68
	v_lshrrev_b32_e32 v26, 16, v26
	v_add3_u32 v27, v27, v29, s79
	v_fma_f32 v24, v104, v24, v60
	v_lshrrev_b32_e32 v22, 16, v22
	v_add3_u32 v23, v23, v25, s79
	v_fma_f32 v16, v96, v16, v52
	v_lshrrev_b32_e32 v14, 16, v14
	v_add3_u32 v15, v15, v17, s79
	v_fma_f32 v12, v92, v12, v48
	v_lshrrev_b32_e32 v10, 16, v10
	v_add3_u32 v11, v11, v13, s79
	v_fma_f32 v8, v88, v8, v44
	v_lshrrev_b32_e32 v6, 16, v6
	v_add3_u32 v7, v7, v9, s79
	v_fma_f32 v4, v20, v4, v40
	v_lshrrev_b32_e32 v2, 16, v2
	v_add3_u32 v3, v3, v5, s79
	v_and_or_b32 v34, v35, s80, v34
	v_bfe_u32 v35, v36, 16, 1
	v_and_or_b32 v30, v31, s80, v30
	v_bfe_u32 v31, v32, 16, 1
	v_and_or_b32 v26, v27, s80, v26
	v_bfe_u32 v27, v28, 16, 1
	v_and_or_b32 v22, v23, s80, v22
	v_bfe_u32 v23, v24, 16, 1
	v_and_or_b32 v14, v15, s80, v14
	v_bfe_u32 v15, v16, 16, 1
	v_and_or_b32 v10, v11, s80, v10
	v_bfe_u32 v11, v12, 16, 1
	v_and_or_b32 v6, v7, s80, v6
	v_bfe_u32 v7, v8, 16, 1
	v_and_or_b32 v2, v3, s80, v2
	v_bfe_u32 v3, v4, 16, 1
	v_add3_u32 v35, v36, v35, s79
	v_bfe_u32 v36, v57, 16, 1
	v_add3_u32 v31, v32, v31, s79
	v_bfe_u32 v32, v65, 16, 1
	v_add3_u32 v27, v28, v27, s79
	v_bfe_u32 v28, v69, 16, 1
	v_add3_u32 v23, v24, v23, s79
	v_bfe_u32 v24, v61, 16, 1
	v_add3_u32 v15, v16, v15, s79
	v_bfe_u32 v16, v53, 16, 1
	v_add3_u32 v11, v12, v11, s79
	v_bfe_u32 v12, v49, 16, 1
	v_add3_u32 v7, v8, v7, s79
	v_bfe_u32 v8, v45, 16, 1
	v_add3_u32 v3, v4, v3, s79
	v_bfe_u32 v4, v41, 16, 1
	v_lshrrev_b32_e32 v35, 16, v35
	v_add3_u32 v36, v57, v36, s79
	v_lshrrev_b32_e32 v31, 16, v31
	v_add3_u32 v32, v65, v32, s79
	v_lshrrev_b32_e32 v27, 16, v27
	v_add3_u32 v28, v69, v28, s79
	v_lshrrev_b32_e32 v23, 16, v23
	v_add3_u32 v24, v61, v24, s79
	v_lshrrev_b32_e32 v15, 16, v15
	v_add3_u32 v16, v53, v16, s79
	v_lshrrev_b32_e32 v11, 16, v11
	v_add3_u32 v12, v49, v12, s79
	v_lshrrev_b32_e32 v7, 16, v7
	v_add3_u32 v8, v45, v8, s79
	v_lshrrev_b32_e32 v3, 16, v3
	v_add3_u32 v4, v41, v4, s79
	v_and_or_b32 v35, v36, s80, v35
	v_lshl_add_u64 v[36:37], v[82:83], 0, s[0:1]
	v_and_or_b32 v31, v32, s80, v31
	v_and_or_b32 v27, v28, s80, v27
	v_and_or_b32 v23, v24, s80, v23
	v_and_or_b32 v15, v16, s80, v15
	v_and_or_b32 v11, v12, s80, v11
	v_and_or_b32 v7, v8, s80, v7
	v_and_or_b32 v3, v4, s80, v3
	v_subrev_u32_e32 v248, s30, v36
	v_add_u32_e32 v248, 0xe8400000, v248
	v_and_b32_e32 v249, 0xfff00000, v248
	v_lshrrev_b32_e32 v246, 5, v248
	v_and_b32_e32 v246, 0x7800, v246
	v_or_b32_e32 v249, v249, v246
	v_lshrrev_b32_e32 v246, 6, v248
	v_and_b32_e32 v246, 0x3c0, v246
	v_or_b32_e32 v249, v249, v246
	v_and_b32_e32 v246, 0x180, v248
	v_lshlrev_b32_e32 v246, 8, v246
	v_or_b32_e32 v249, v249, v246
	v_and_b32_e32 v246, 64, v248
	v_lshlrev_b32_e32 v246, 4, v246
	v_or_b32_e32 v249, v249, v246
	v_and_b32_e32 v246, 56, v248
	v_or_b32_e32 v249, v249, v246
	v_lshrrev_b32_e32 v246, 10, v248
	v_and_b32_e32 v246, 32, v246
	v_xor_b32_e32 v249, v249, v246
	v_sub_u32_e32 v246, v249, v248
	v_ashrrev_i32_e32 v247, 31, v246
	v_lshl_add_u64 v[36:37], v[36:37], 0, v[246:247]
	global_store_dwordx2 v[36:37], v[34:35], off
	s_mov_b64 s[100:101], 0x20000
	v_lshl_add_u64 v[248:249], v[36:37], 0, s[100:101]
	global_store_dwordx2 v[248:249], v[30:31], off
	s_mov_b64 s[100:101], 0x40000
	v_lshl_add_u64 v[248:249], v[36:37], 0, s[100:101]
	global_store_dwordx2 v[248:249], v[26:27], off
	s_mov_b64 s[100:101], 0x60000
	v_lshl_add_u64 v[248:249], v[36:37], 0, s[100:101]
	global_store_dwordx2 v[248:249], v[22:23], off
	s_mov_b64 s[100:101], 0x80000
	v_lshl_add_u64 v[248:249], v[36:37], 0, s[100:101]
	global_store_dwordx2 v[248:249], v[14:15], off
	s_mov_b64 s[100:101], 0xa0000
	v_lshl_add_u64 v[248:249], v[36:37], 0, s[100:101]
	global_store_dwordx2 v[248:249], v[10:11], off
	s_mov_b64 s[100:101], 0xc0000
	v_lshl_add_u64 v[248:249], v[36:37], 0, s[100:101]
	global_store_dwordx2 v[248:249], v[6:7], off
	s_mov_b64 s[100:101], 0xe0000
	v_lshl_add_u64 v[248:249], v[36:37], 0, s[100:101]
	global_store_dwordx2 v[248:249], v[2:3], off
	s_branch .LBB0_1656

.LBB0_1683:
	s_mov_b32 s0, 0x20400
	s_mov_b32 s0, 0x20408
	s_nop 0
	v_readlane_b32 s0, v250, 56
	s_mul_i32 s0, s0, 24
	v_readlane_b32 s1, v250, 57
	v_mov_b32_e32 v1, s0
	v_add_u32_e32 v1, s4, v1
	s_movk_i32 s0, 0x1fff
	v_cmp_lt_i32_e32 vcc, s0, v1
	s_and_b64 s[0:1], vcc, exec
	v_readfirstlane_b32 s0, v1
	s_cbranch_scc1 .LBB0_1687
	s_add_i32 s5, s4, 0xffffe000
	s_lshr_b32 s5, s5, 3
	s_ashr_i32 s1, s4, 12
	s_add_i32 s5, s5, 2
	s_cmpk_lt_i32 s4, 0x2000
	s_cselect_b32 s23, s1, s5
	v_readlane_b32 s1, v251, 24
	s_sub_i32 s14, s0, s1
	s_add_i32 s5, s14, 0xffffe000
	s_lshr_b32 s5, s5, 3
	s_ashr_i32 s1, s14, 12
	s_add_i32 s5, s5, 2
	s_cmpk_lt_i32 s14, 0x2000
	s_cselect_b32 s1, s1, s5
	s_cmp_lg_u32 s23, s1
	s_cbranch_scc1 .LBB0_1687
	v_readlane_b32 s1, v254, 12
	s_add_i32 s12, s14, s1
	s_add_i32 s5, s12, 0xffffe000
	s_lshr_b32 s5, s5, 3
	s_ashr_i32 s1, s12, 12
	s_add_i32 s5, s5, 2
	s_cmpk_lt_i32 s12, 0x2000
	s_cselect_b32 s20, s1, s5
	s_ashr_i32 s1, s0, 12
	s_cmp_lg_u32 s20, s1
	s_cbranch_scc1 .LBB0_1687
	s_add_u32 s21, s6, 0x100000
	s_addc_u32 s22, s7, 0
	s_ashr_i32 s5, s4, 31
	s_lshl_b64 s[16:17], s[4:5], 13
	s_add_u32 s26, s28, s16
	s_addc_u32 s27, s29, s17
	s_ashr_i32 s15, s14, 31
	s_lshl_b64 s[16:17], s[14:15], 13
	s_add_u32 s38, s28, s16
	s_addc_u32 s39, s29, s17
	v_lshlrev_b64 v[172:173], 4, v[170:171]
	s_ashr_i32 s13, s12, 31
	s_ashr_i32 s1, s0, 31
	s_waitcnt vmcnt(0)
	v_lshl_add_u64 v[2:3], s[26:27], 0, v[172:173]
	v_lshl_add_u64 v[4:5], s[38:39], 0, v[172:173]
	s_lshl_b64 s[16:17], s[12:13], 13
	s_lshl_b64 s[18:19], s[0:1], 13
	global_load_dwordx4 v[128:131], v[2:3], off
	global_load_dwordx4 v[96:99], v[4:5], off
	global_load_dwordx4 v[124:127], v[2:3], off offset:1024
	global_load_dwordx4 v[92:95], v[4:5], off offset:1024
	global_load_dwordx4 v[120:123], v[2:3], off offset:2048
	global_load_dwordx4 v[88:91], v[4:5], off offset:2048
	global_load_dwordx4 v[116:119], v[2:3], off offset:3072
	global_load_dwordx4 v[84:87], v[4:5], off offset:3072
	v_add_co_u32_e32 v2, vcc, s3, v2
	s_add_u32 s16, s28, s16
	s_nop 0
	v_addc_co_u32_e32 v3, vcc, 0, v3, vcc
	v_add_co_u32_e32 v4, vcc, s3, v4
	s_addc_u32 s17, s29, s17
	s_nop 0
	v_addc_co_u32_e32 v5, vcc, 0, v5, vcc
	s_add_u32 s18, s28, s18
	global_load_dwordx4 v[112:115], v[2:3], off
	global_load_dwordx4 v[80:83], v[4:5], off
	global_load_dwordx4 v[108:111], v[2:3], off offset:1024
	global_load_dwordx4 v[76:79], v[4:5], off offset:1024
	global_load_dwordx4 v[104:107], v[2:3], off offset:2048
	global_load_dwordx4 v[72:75], v[4:5], off offset:2048
	global_load_dwordx4 v[100:103], v[2:3], off offset:3072
	global_load_dwordx4 v[68:71], v[4:5], off offset:3072
	s_addc_u32 s19, s29, s19
	v_lshl_add_u64 v[2:3], s[16:17], 0, v[172:173]
	s_ashr_i32 s16, s23, 31
	s_add_u32 s17, s23, s24
	s_addc_u32 s16, s16, 0
	v_lshl_add_u64 v[4:5], s[18:19], 0, v[172:173]
	s_mul_i32 s16, s16, 0xc000
	s_mul_hi_u32 s18, s17, 0xc000
	global_load_dwordx4 v[64:67], v[2:3], off
	global_load_dwordx4 v[32:35], v[4:5], off
	global_load_dwordx4 v[60:63], v[2:3], off offset:1024
	global_load_dwordx4 v[28:31], v[4:5], off offset:1024
	global_load_dwordx4 v[56:59], v[2:3], off offset:2048
	global_load_dwordx4 v[24:27], v[4:5], off offset:2048
	global_load_dwordx4 v[52:55], v[2:3], off offset:3072
	global_load_dwordx4 v[20:23], v[4:5], off offset:3072
	v_add_co_u32_e32 v2, vcc, s3, v2
	s_add_i32 s18, s18, s16
	s_mul_i32 s17, s17, 0xc000
	v_addc_co_u32_e32 v3, vcc, 0, v3, vcc
	s_add_u32 s16, s21, s17
	v_add_co_u32_e32 v4, vcc, s3, v4
	s_addc_u32 s17, s22, s18
	s_nop 0
	v_addc_co_u32_e32 v5, vcc, 0, v5, vcc
	v_lshl_add_u64 v[132:133], s[16:17], 0, v[172:173]
	s_mov_b32 s19, 0x9000
	v_add_co_u32_e32 v160, vcc, s19, v132
	global_load_dwordx4 v[48:51], v[2:3], off
	s_nop 0
	v_addc_co_u32_e32 v161, vcc, 0, v133, vcc
	global_load_dwordx4 v[14:17], v[4:5], off
	global_load_dwordx4 v[44:47], v[2:3], off offset:1024
	global_load_dwordx4 v[10:13], v[4:5], off offset:1024
	global_load_dwordx4 v[40:43], v[2:3], off offset:2048
	global_load_dwordx4 v[6:9], v[4:5], off offset:2048
	global_load_dwordx4 v[36:39], v[2:3], off offset:3072
	s_nop 0
	global_load_dwordx4 v[2:5], v[4:5], off offset:3072
	v_lshl_add_u64 v[176:177], s[10:11], 0, v[172:173]
	global_load_dwordx4 v[140:143], v[160:161], off offset:-4096
	global_load_dwordx4 v[136:139], v[176:177], off
	s_movk_i32 s18, 0x7000
	v_add_co_u32_e32 v162, vcc, s18, v132
	s_mov_b64 s[26:27], 0x8000
	s_mov_b64 s[38:39], 0x6000
	v_addc_co_u32_e32 v163, vcc, 0, v133, vcc
	v_lshl_add_u64 v[152:153], v[132:133], 0, s[26:27]
	v_lshl_add_u64 v[156:157], v[132:133], 0, s[38:39]
	global_load_dwordx4 v[132:135], v[162:163], off offset:-4096
	v_add_co_u32_e32 v174, vcc, s3, v176
	s_lshl_b64 s[16:17], s[4:5], 12
	s_nop 0
	v_addc_co_u32_e32 v175, vcc, 0, v177, vcc
	s_add_u32 s16, s8, s16
	s_addc_u32 s17, s9, s17
	s_lshl_b64 s[14:15], s[14:15], 12
	s_add_u32 s14, s8, s14
	s_addc_u32 s15, s9, s15
	s_ashr_i32 s5, s20, 31
	s_mov_b64 s[84:85], 0x8000
	s_waitcnt vmcnt(32)
	v_mul_f32_e32 v167, v127, v127
	v_fmac_f32_e32 v167, v126, v126
	v_mul_f32_e32 v1, v129, v129
	v_mul_f32_e32 v18, v131, v131
	v_fmac_f32_e32 v1, v128, v128
	v_fmac_f32_e32 v18, v130, v130
	v_add_f32_e32 v1, v1, v18
	v_mul_f32_e32 v18, v125, v125
	v_fmac_f32_e32 v18, v124, v124
	v_add_f32_e32 v18, v18, v167
	v_add_f32_e32 v1, v1, v18
	s_waitcnt vmcnt(30)
	v_mul_f32_e32 v18, v121, v121
	v_mul_f32_e32 v167, v123, v123
	v_fmac_f32_e32 v18, v120, v120
	v_fmac_f32_e32 v167, v122, v122
	v_add_f32_e32 v18, v18, v167
	v_add_f32_e32 v1, v1, v18
	s_waitcnt vmcnt(28)
	v_mul_f32_e32 v18, v117, v117
	v_mul_f32_e32 v167, v119, v119
	v_fmac_f32_e32 v18, v116, v116
	v_fmac_f32_e32 v167, v118, v118
	v_add_f32_e32 v18, v18, v167
	v_add_f32_e32 v1, v1, v18
	s_waitcnt vmcnt(26)
	v_mul_f32_e32 v18, v113, v113
	v_mul_f32_e32 v167, v115, v115
	v_fmac_f32_e32 v18, v112, v112
	v_fmac_f32_e32 v167, v114, v114
	v_add_f32_e32 v18, v18, v167
	v_add_f32_e32 v1, v1, v18
	s_waitcnt vmcnt(24)
	v_mul_f32_e32 v18, v109, v109
	v_mul_f32_e32 v167, v111, v111
	v_fmac_f32_e32 v18, v108, v108
	v_fmac_f32_e32 v167, v110, v110
	v_add_f32_e32 v18, v18, v167
	v_add_f32_e32 v1, v1, v18
	s_waitcnt vmcnt(22)
	v_mul_f32_e32 v18, v105, v105
	v_mul_f32_e32 v167, v107, v107
	v_fmac_f32_e32 v18, v104, v104
	v_fmac_f32_e32 v167, v106, v106
	v_add_f32_e32 v18, v18, v167
	v_add_f32_e32 v1, v1, v18
	s_waitcnt vmcnt(20)
	v_mul_f32_e32 v18, v101, v101
	v_mul_f32_e32 v167, v103, v103
	v_fmac_f32_e32 v18, v100, v100
	v_fmac_f32_e32 v167, v102, v102
	v_add_f32_e32 v18, v18, v167
	v_add_f32_e32 v18, v1, v18
	v_mul_f32_e32 v1, v97, v97
	s_waitcnt vmcnt(2)
	v_pk_add_f32 v[142:143], v[142:143], 1.0 op_sel_hi:[1,0]
	v_pk_add_f32 v[140:141], v[140:141], 1.0 op_sel_hi:[1,0]
	s_waitcnt vmcnt(1)
	v_pk_mul_f32 v[178:179], v[138:139], v[142:143]
	v_pk_mul_f32 v[180:181], v[136:137], v[140:141]
	global_load_dwordx4 v[140:143], v[176:177], off offset:1024
	global_load_dwordx4 v[144:147], v[152:153], off offset:1024
	global_load_dwordx4 v[136:139], v[156:157], off offset:1024
	v_mul_f32_e32 v167, v99, v99
	v_fmac_f32_e32 v1, v96, v96
	v_fmac_f32_e32 v167, v98, v98
	v_add_f32_e32 v1, v1, v167
	v_mul_f32_e32 v167, v93, v93
	v_fmac_f32_e32 v167, v92, v92
	s_waitcnt vmcnt(1)
	v_pk_add_f32 v[146:147], v[146:147], 1.0 op_sel_hi:[1,0]
	v_pk_add_f32 v[144:145], v[144:145], 1.0 op_sel_hi:[1,0]
	v_pk_mul_f32 v[182:183], v[142:143], v[146:147]
	v_pk_mul_f32 v[184:185], v[140:141], v[144:145]
	global_load_dwordx4 v[144:147], v[176:177], off offset:2048
	global_load_dwordx4 v[148:151], v[152:153], off offset:2048
	global_load_dwordx4 v[140:143], v[156:157], off offset:2048
	s_waitcnt vmcnt(1)
	v_pk_add_f32 v[150:151], v[150:151], 1.0 op_sel_hi:[1,0]
	v_pk_add_f32 v[148:149], v[148:149], 1.0 op_sel_hi:[1,0]
	v_pk_mul_f32 v[186:187], v[146:147], v[150:151]
	v_pk_mul_f32 v[188:189], v[144:145], v[148:149]
	global_load_dwordx4 v[148:151], v[176:177], off offset:3072
	s_nop 0
	global_load_dwordx4 v[152:155], v[152:153], off offset:3072
	s_nop 0
	global_load_dwordx4 v[144:147], v[156:157], off offset:3072
	s_waitcnt vmcnt(1)
	v_pk_add_f32 v[154:155], v[154:155], 1.0 op_sel_hi:[1,0]
	v_pk_add_f32 v[152:153], v[152:153], 1.0 op_sel_hi:[1,0]
	v_pk_mul_f32 v[190:191], v[150:151], v[154:155]
	v_pk_mul_f32 v[192:193], v[148:149], v[152:153]
	global_load_dwordx4 v[152:155], v[174:175], off
	global_load_dwordx4 v[156:159], v[160:161], off
	global_load_dwordx4 v[148:151], v[162:163], off
	s_waitcnt vmcnt(1)
	v_pk_add_f32 v[158:159], v[158:159], 1.0 op_sel_hi:[1,0]
	v_pk_add_f32 v[156:157], v[156:157], 1.0 op_sel_hi:[1,0]
	v_pk_mul_f32 v[194:195], v[154:155], v[158:159]
	v_pk_mul_f32 v[198:199], v[152:153], v[156:157]
	global_load_dwordx4 v[156:159], v[174:175], off offset:1024
	global_load_dwordx4 v[200:203], v[160:161], off offset:1024
	global_load_dwordx4 v[152:155], v[162:163], off offset:1024
	s_waitcnt vmcnt(1)
	v_pk_add_f32 v[168:169], v[202:203], 1.0 op_sel_hi:[1,0]
	v_pk_add_f32 v[200:201], v[200:201], 1.0 op_sel_hi:[1,0]
	v_pk_mul_f32 v[196:197], v[158:159], v[168:169]
	v_pk_mul_f32 v[200:201], v[156:157], v[200:201]
	global_load_dwordx4 v[204:207], v[174:175], off offset:2048
	global_load_dwordx4 v[220:223], v[160:161], off offset:2048
	global_load_dwordx4 v[156:159], v[162:163], off offset:2048
	s_waitcnt vmcnt(1)
	v_pk_add_f32 v[168:169], v[222:223], 1.0 op_sel_hi:[1,0]
	v_pk_add_f32 v[208:209], v[220:221], 1.0 op_sel_hi:[1,0]
	v_pk_mul_f32 v[202:203], v[206:207], v[168:169]
	v_pk_mul_f32 v[204:205], v[204:205], v[208:209]
	global_load_dwordx4 v[220:223], v[174:175], off offset:3072
	global_load_dwordx4 v[206:209], v[160:161], off offset:3072
	s_nop 0
	global_load_dwordx4 v[160:163], v[162:163], off offset:3072
	s_waitcnt vmcnt(1)
	v_pk_add_f32 v[168:169], v[208:209], 1.0 op_sel_hi:[1,0]
	v_pk_add_f32 v[208:209], v[206:207], 1.0 op_sel_hi:[1,0]
	v_pk_mul_f32 v[206:207], v[222:223], v[168:169]
	v_mul_f32_e32 v168, v95, v95
	v_fmac_f32_e32 v168, v94, v94
	v_add_f32_e32 v167, v167, v168
	v_add_f32_e32 v1, v1, v167
	v_mul_f32_e32 v167, v89, v89
	v_mul_f32_e32 v168, v91, v91
	v_fmac_f32_e32 v167, v88, v88
	v_fmac_f32_e32 v168, v90, v90
	v_add_f32_e32 v167, v167, v168
	v_add_f32_e32 v1, v1, v167
	v_mul_f32_e32 v167, v85, v85
	v_mul_f32_e32 v168, v87, v87
	v_fmac_f32_e32 v167, v84, v84
	v_fmac_f32_e32 v168, v86, v86
	v_add_f32_e32 v167, v167, v168
	v_add_f32_e32 v1, v1, v167
	v_mul_f32_e32 v167, v81, v81
	v_mul_f32_e32 v168, v83, v83
	v_fmac_f32_e32 v167, v80, v80
	v_fmac_f32_e32 v168, v82, v82
	v_add_f32_e32 v167, v167, v168
	v_add_f32_e32 v1, v1, v167
	v_mul_f32_e32 v167, v77, v77
	v_mul_f32_e32 v168, v79, v79
	v_fmac_f32_e32 v167, v76, v76
	v_fmac_f32_e32 v168, v78, v78
	v_add_f32_e32 v167, v167, v168
	v_add_f32_e32 v1, v1, v167
	v_mul_f32_e32 v167, v73, v73
	v_mul_f32_e32 v168, v75, v75
	v_fmac_f32_e32 v167, v72, v72
	v_fmac_f32_e32 v168, v74, v74
	v_add_f32_e32 v167, v167, v168
	v_add_f32_e32 v1, v1, v167
	v_mul_f32_e32 v167, v69, v69
	v_mul_f32_e32 v168, v71, v71
	v_fmac_f32_e32 v167, v68, v68
	v_fmac_f32_e32 v168, v70, v70
	v_add_f32_e32 v167, v167, v168
	v_add_f32_e32 v167, v1, v167
	v_and_b32_e32 v1, 64, v213
	v_add_u32_e32 v168, 64, v1
	v_xor_b32_e32 v1, 1, v213
	v_cmp_lt_i32_e32 vcc, v1, v168
	v_pk_mul_f32 v[208:209], v[220:221], v[208:209]
	s_nop 0
	v_cndmask_b32_e32 v1, v213, v1, vcc
	v_lshlrev_b32_e32 v1, 2, v1
	ds_bpermute_b32 v169, v1, v18
	s_waitcnt lgkmcnt(0)
	v_add_f32_e32 v169, v18, v169
	ds_bpermute_b32 v18, v1, v167
	s_waitcnt lgkmcnt(0)
	v_add_f32_e32 v167, v167, v18
	v_xor_b32_e32 v18, 2, v213
	v_cmp_lt_i32_e32 vcc, v18, v168
	s_nop 1
	v_cndmask_b32_e32 v18, v213, v18, vcc
	v_lshlrev_b32_e32 v18, 2, v18
	ds_bpermute_b32 v218, v18, v169
	s_waitcnt lgkmcnt(0)
	v_add_f32_e32 v169, v169, v218
	ds_bpermute_b32 v218, v18, v167
	s_waitcnt lgkmcnt(0)
	v_add_f32_e32 v218, v167, v218
	v_xor_b32_e32 v167, 4, v213
	v_cmp_lt_i32_e32 vcc, v167, v168
	s_nop 1
	v_cndmask_b32_e32 v167, v213, v167, vcc
	v_lshlrev_b32_e32 v167, 2, v167
	ds_bpermute_b32 v219, v167, v169
	s_waitcnt lgkmcnt(0)
	v_add_f32_e32 v169, v169, v219
	ds_bpermute_b32 v219, v167, v218
	s_waitcnt lgkmcnt(0)
	v_add_f32_e32 v218, v218, v219
	v_xor_b32_e32 v219, 8, v213
	v_cmp_lt_i32_e32 vcc, v219, v168
	s_nop 1
	v_cndmask_b32_e32 v219, v213, v219, vcc
	v_lshlrev_b32_e32 v220, 2, v219
	ds_bpermute_b32 v219, v220, v169
	s_waitcnt lgkmcnt(0)
	v_add_f32_e32 v169, v169, v219
	ds_bpermute_b32 v219, v220, v218
	s_waitcnt lgkmcnt(0)
	v_add_f32_e32 v218, v218, v219
	v_xor_b32_e32 v219, 16, v213
	v_cmp_lt_i32_e32 vcc, v219, v168
	s_nop 1
	v_cndmask_b32_e32 v219, v213, v219, vcc
	v_lshlrev_b32_e32 v221, 2, v219
	ds_bpermute_b32 v219, v221, v169
	s_waitcnt lgkmcnt(0)
	v_add_f32_e32 v169, v169, v219
	ds_bpermute_b32 v219, v221, v218
	s_waitcnt lgkmcnt(0)
	v_add_f32_e32 v218, v218, v219
	v_xor_b32_e32 v219, 32, v213
	v_cmp_lt_i32_e32 vcc, v219, v168
	s_nop 1
	v_cndmask_b32_e32 v168, v213, v219, vcc
	v_lshlrev_b32_e32 v222, 2, v168
	ds_bpermute_b32 v168, v222, v169
	s_waitcnt lgkmcnt(0)
	v_add_f32_e32 v168, v169, v168
	v_fmamk_f32 v168, v168, 0x3a000000, v165
	v_rsq_f32_e32 v219, v168
	ds_bpermute_b32 v169, v222, v218
	v_mul_f32_e32 v128, v128, v219
	v_mul_f32_e32 v130, v130, v219
	v_fma_f32 v128, v180, v128, v132
	v_mul_f32_e32 v129, v129, v219
	v_fma_f32 v168, v178, v130, v134
	v_mul_f32_e32 v130, v131, v219
	v_fma_f32 v129, v181, v129, v133
	v_fma_f32 v131, v179, v130, v135
	v_bfe_u32 v130, v128, 16, 1
	v_add3_u32 v128, v128, v130, s79
	v_bfe_u32 v130, v129, 16, 1
	v_lshrrev_b32_e32 v128, 16, v128
	v_add3_u32 v129, v129, v130, s79
	v_and_or_b32 v130, v129, s80, v128
	v_bfe_u32 v128, v168, 16, 1
	v_add3_u32 v128, v168, v128, s79
	v_bfe_u32 v129, v131, 16, 1
	v_lshrrev_b32_e32 v128, 16, v128
	v_add3_u32 v129, v131, v129, s79
	v_and_or_b32 v131, v129, s80, v128
	v_lshlrev_b64 v[128:129], 3, v[170:171]
	v_mul_f32_e32 v124, v124, v219
	s_waitcnt lgkmcnt(0)
	v_add_f32_e32 v218, v218, v169
	v_lshl_add_u64 v[168:169], s[16:17], 0, v[128:129]
	v_fma_f32 v124, v184, v124, v136
	v_mul_f32_e32 v125, v125, v219
	v_subrev_u32_e32 v248, s30, v168
	v_add_u32_e32 v248, 0xe8400000, v248
	v_and_b32_e32 v249, 0xfff00000, v248
	v_lshrrev_b32_e32 v246, 5, v248
	v_and_b32_e32 v246, 0x7800, v246
	v_or_b32_e32 v249, v249, v246
	v_lshrrev_b32_e32 v246, 6, v248
	v_and_b32_e32 v246, 0x3c0, v246
	v_or_b32_e32 v249, v249, v246
	v_and_b32_e32 v246, 0x180, v248
	v_lshlrev_b32_e32 v246, 8, v246
	v_or_b32_e32 v249, v249, v246
	v_and_b32_e32 v246, 64, v248
	v_lshlrev_b32_e32 v246, 4, v246
	v_or_b32_e32 v249, v249, v246
	v_and_b32_e32 v246, 56, v248
	v_or_b32_e32 v249, v249, v246
	v_lshrrev_b32_e32 v246, 10, v248
	v_and_b32_e32 v246, 32, v246
	v_xor_b32_e32 v249, v249, v246
	v_sub_u32_e32 v246, v249, v248
	v_ashrrev_i32_e32 v247, 31, v246
	v_lshl_add_u64 v[168:169], v[168:169], 0, v[246:247]
	global_store_dwordx2 v[168:169], v[130:131], off
	v_fma_f32 v125, v185, v125, v137
	v_bfe_u32 v130, v124, 16, 1
	v_mul_f32_e32 v126, v126, v219
	v_add3_u32 v124, v124, v130, s79
	v_bfe_u32 v130, v125, 16, 1
	v_fma_f32 v126, v182, v126, v138
	v_mul_f32_e32 v127, v127, v219
	v_lshrrev_b32_e32 v124, 16, v124
	v_add3_u32 v125, v125, v130, s79
	v_fma_f32 v127, v183, v127, v139
	v_and_or_b32 v124, v125, s80, v124
	v_bfe_u32 v125, v126, 16, 1
	v_add3_u32 v125, v126, v125, s79
	v_bfe_u32 v126, v127, 16, 1
	v_lshrrev_b32_e32 v125, 16, v125
	v_add3_u32 v126, v127, v126, s79
	v_mul_f32_e32 v120, v120, v219
	v_and_or_b32 v125, v126, s80, v125
	v_fma_f32 v120, v188, v120, v140
	v_mul_f32_e32 v121, v121, v219
	s_mov_b64 s[100:101], 0x20000
	v_lshl_add_u64 v[248:249], v[168:169], 0, s[100:101]
	global_store_dwordx2 v[248:249], v[124:125], off
	v_fma_f32 v121, v189, v121, v141
	v_bfe_u32 v124, v120, 16, 1
	v_mul_f32_e32 v122, v122, v219
	v_add3_u32 v120, v120, v124, s79
	v_bfe_u32 v124, v121, 16, 1
	v_fma_f32 v122, v186, v122, v142
	v_mul_f32_e32 v123, v123, v219
	v_lshrrev_b32_e32 v120, 16, v120
	v_add3_u32 v121, v121, v124, s79
	v_fma_f32 v123, v187, v123, v143
	v_and_or_b32 v120, v121, s80, v120
	v_bfe_u32 v121, v122, 16, 1
	v_add3_u32 v121, v122, v121, s79
	v_bfe_u32 v122, v123, 16, 1
	v_lshrrev_b32_e32 v121, 16, v121
	v_add3_u32 v122, v123, v122, s79
	v_mul_f32_e32 v116, v116, v219
	v_and_or_b32 v121, v122, s80, v121
	v_fma_f32 v116, v192, v116, v144
	v_mul_f32_e32 v117, v117, v219
	s_mov_b64 s[100:101], 0x40000
	v_lshl_add_u64 v[248:249], v[168:169], 0, s[100:101]
	global_store_dwordx2 v[248:249], v[120:121], off
	v_fma_f32 v117, v193, v117, v145
	v_bfe_u32 v120, v116, 16, 1
	v_mul_f32_e32 v118, v118, v219
	v_add3_u32 v116, v116, v120, s79
	v_bfe_u32 v120, v117, 16, 1
	v_fma_f32 v118, v190, v118, v146
	v_mul_f32_e32 v119, v119, v219
	v_lshrrev_b32_e32 v116, 16, v116
	v_add3_u32 v117, v117, v120, s79
	v_fma_f32 v119, v191, v119, v147
	v_and_or_b32 v116, v117, s80, v116
	v_bfe_u32 v117, v118, 16, 1
	v_add3_u32 v117, v118, v117, s79
	v_bfe_u32 v118, v119, 16, 1
	v_lshrrev_b32_e32 v117, 16, v117
	v_add3_u32 v118, v119, v118, s79
	v_mul_f32_e32 v112, v112, v219
	v_and_or_b32 v117, v118, s80, v117
	v_fma_f32 v112, v198, v112, v148
	v_mul_f32_e32 v113, v113, v219
	s_mov_b64 s[100:101], 0x60000
	v_lshl_add_u64 v[248:249], v[168:169], 0, s[100:101]
	global_store_dwordx2 v[248:249], v[116:117], off
	v_fma_f32 v113, v199, v113, v149
	v_bfe_u32 v116, v112, 16, 1
	v_mul_f32_e32 v114, v114, v219
	v_add3_u32 v112, v112, v116, s79
	v_bfe_u32 v116, v113, 16, 1
	v_fma_f32 v114, v194, v114, v150
	v_mul_f32_e32 v115, v115, v219
	v_lshrrev_b32_e32 v112, 16, v112
	v_add3_u32 v113, v113, v116, s79
	v_fma_f32 v115, v195, v115, v151
	v_and_or_b32 v112, v113, s80, v112
	v_bfe_u32 v113, v114, 16, 1
	v_add3_u32 v113, v114, v113, s79
	v_bfe_u32 v114, v115, 16, 1
	v_lshrrev_b32_e32 v113, 16, v113
	v_add3_u32 v114, v115, v114, s79
	v_mul_f32_e32 v108, v108, v219
	v_and_or_b32 v113, v114, s80, v113
	v_fma_f32 v108, v200, v108, v152
	v_mul_f32_e32 v109, v109, v219
	s_mov_b64 s[100:101], 0x80000
	v_lshl_add_u64 v[248:249], v[168:169], 0, s[100:101]
	global_store_dwordx2 v[248:249], v[112:113], off
	v_fma_f32 v109, v201, v109, v153
	v_bfe_u32 v112, v108, 16, 1
	v_mul_f32_e32 v110, v110, v219
	v_add3_u32 v108, v108, v112, s79
	v_bfe_u32 v112, v109, 16, 1
	v_fma_f32 v110, v196, v110, v154
	v_mul_f32_e32 v111, v111, v219
	v_lshrrev_b32_e32 v108, 16, v108
	v_add3_u32 v109, v109, v112, s79
	v_fma_f32 v111, v197, v111, v155
	v_and_or_b32 v108, v109, s80, v108
	v_bfe_u32 v109, v110, 16, 1
	v_add3_u32 v109, v110, v109, s79
	v_bfe_u32 v110, v111, 16, 1
	v_lshrrev_b32_e32 v109, 16, v109
	v_add3_u32 v110, v111, v110, s79
	v_mul_f32_e32 v104, v104, v219
	v_and_or_b32 v109, v110, s80, v109
	v_fma_f32 v104, v204, v104, v156
	v_mul_f32_e32 v105, v105, v219
	s_mov_b64 s[100:101], 0xa0000
	v_lshl_add_u64 v[248:249], v[168:169], 0, s[100:101]
	global_store_dwordx2 v[248:249], v[108:109], off
	v_fma_f32 v105, v205, v105, v157
	v_bfe_u32 v108, v104, 16, 1
	v_mul_f32_e32 v106, v106, v219
	v_add3_u32 v104, v104, v108, s79
	v_bfe_u32 v108, v105, 16, 1
	v_fma_f32 v106, v202, v106, v158
	v_mul_f32_e32 v107, v107, v219
	v_lshrrev_b32_e32 v104, 16, v104
	v_add3_u32 v105, v105, v108, s79
	v_fma_f32 v107, v203, v107, v159
	v_and_or_b32 v104, v105, s80, v104
	v_bfe_u32 v105, v106, 16, 1
	v_add3_u32 v105, v106, v105, s79
	v_bfe_u32 v106, v107, 16, 1
	v_lshrrev_b32_e32 v105, 16, v105
	v_add3_u32 v106, v107, v106, s79
	v_mul_f32_e32 v100, v100, v219
	v_and_or_b32 v105, v106, s80, v105
	s_waitcnt vmcnt(6)
	v_fma_f32 v100, v208, v100, v160
	v_mul_f32_e32 v101, v101, v219
	s_mov_b64 s[100:101], 0xc0000
	v_lshl_add_u64 v[248:249], v[168:169], 0, s[100:101]
	global_store_dwordx2 v[248:249], v[104:105], off
	v_fma_f32 v101, v209, v101, v161
	v_bfe_u32 v104, v100, 16, 1
	v_mul_f32_e32 v102, v102, v219
	v_add3_u32 v100, v100, v104, s79
	v_bfe_u32 v104, v101, 16, 1
	v_fma_f32 v102, v206, v102, v162
	v_mul_f32_e32 v103, v103, v219
	v_lshrrev_b32_e32 v100, 16, v100
	v_add3_u32 v101, v101, v104, s79
	v_fma_f32 v103, v207, v103, v163
	v_and_or_b32 v100, v101, s80, v100
	v_bfe_u32 v101, v102, 16, 1
	v_add3_u32 v101, v102, v101, s79
	v_bfe_u32 v102, v103, 16, 1
	v_lshrrev_b32_e32 v101, 16, v101
	v_add3_u32 v102, v103, v102, s79
	v_and_or_b32 v101, v102, s80, v101
	s_mov_b64 s[100:101], 0xe0000
	v_lshl_add_u64 v[248:249], v[168:169], 0, s[100:101]
	global_store_dwordx2 v[248:249], v[100:101], off
	v_fmamk_f32 v100, v218, 0x3a000000, v165
	v_rsq_f32_e32 v100, v100
	s_nop 0
	v_mul_f32_e32 v96, v96, v100
	v_fma_f32 v96, v180, v96, v132
	v_mul_f32_e32 v97, v97, v100
	v_mul_f32_e32 v99, v99, v100
	v_fma_f32 v97, v181, v97, v133
	v_fmac_f32_e32 v135, v179, v99
	v_bfe_u32 v99, v96, 16, 1
	v_mul_f32_e32 v98, v98, v100
	v_add3_u32 v96, v96, v99, s79
	v_bfe_u32 v99, v97, 16, 1
	v_fma_f32 v98, v178, v98, v134
	v_lshrrev_b32_e32 v96, 16, v96
	v_add3_u32 v97, v97, v99, s79
	v_and_or_b32 v96, v97, s80, v96
	v_bfe_u32 v97, v98, 16, 1
	v_mul_f32_e32 v68, v68, v100
	v_add3_u32 v97, v98, v97, s79
	v_bfe_u32 v98, v135, 16, 1
	v_fma_f32 v68, v208, v68, v160
	v_mul_f32_e32 v69, v69, v100
	v_mul_f32_e32 v71, v71, v100
	v_lshrrev_b32_e32 v97, 16, v97
	v_add3_u32 v98, v135, v98, s79
	v_mul_f32_e32 v92, v92, v100
	v_mul_f32_e32 v88, v88, v100
	v_mul_f32_e32 v84, v84, v100
	v_mul_f32_e32 v80, v80, v100
	v_mul_f32_e32 v76, v76, v100
	v_mul_f32_e32 v72, v72, v100
	v_fma_f32 v69, v209, v69, v161
	v_fmac_f32_e32 v163, v207, v71
	v_bfe_u32 v71, v68, 16, 1
	v_and_or_b32 v97, v98, s80, v97
	v_lshl_add_u64 v[98:99], s[14:15], 0, v[128:129]
	v_fma_f32 v92, v184, v92, v136
	v_mul_f32_e32 v93, v93, v100
	v_mul_f32_e32 v95, v95, v100
	v_fma_f32 v88, v188, v88, v140
	v_mul_f32_e32 v89, v89, v100
	v_mul_f32_e32 v91, v91, v100
	v_fma_f32 v84, v192, v84, v144
	v_mul_f32_e32 v85, v85, v100
	v_mul_f32_e32 v87, v87, v100
	v_fma_f32 v80, v198, v80, v148
	v_mul_f32_e32 v81, v81, v100
	v_mul_f32_e32 v83, v83, v100
	v_fma_f32 v76, v200, v76, v152
	v_mul_f32_e32 v77, v77, v100
	v_mul_f32_e32 v79, v79, v100
	v_fma_f32 v72, v204, v72, v156
	v_mul_f32_e32 v73, v73, v100
	v_mul_f32_e32 v75, v75, v100
	v_mul_f32_e32 v70, v70, v100
	v_add3_u32 v68, v68, v71, s79
	v_bfe_u32 v71, v69, 16, 1
	s_add_u32 s14, s20, s24
	v_fma_f32 v93, v185, v93, v137
	v_fmac_f32_e32 v139, v183, v95
	v_bfe_u32 v95, v92, 16, 1
	v_fma_f32 v89, v189, v89, v141
	v_fmac_f32_e32 v143, v187, v91
	v_bfe_u32 v91, v88, 16, 1
	v_fma_f32 v85, v193, v85, v145
	v_fmac_f32_e32 v147, v191, v87
	v_bfe_u32 v87, v84, 16, 1
	v_fma_f32 v81, v199, v81, v149
	v_fmac_f32_e32 v151, v195, v83
	v_bfe_u32 v83, v80, 16, 1
	v_fma_f32 v77, v201, v77, v153
	v_fmac_f32_e32 v155, v197, v79
	v_bfe_u32 v79, v76, 16, 1
	v_fma_f32 v73, v205, v73, v157
	v_fmac_f32_e32 v159, v203, v75
	v_bfe_u32 v75, v72, 16, 1
	v_fma_f32 v70, v206, v70, v162
	v_lshrrev_b32_e32 v68, 16, v68
	v_add3_u32 v69, v69, v71, s79
	s_addc_u32 s5, s5, 0
	v_mul_f32_e32 v94, v94, v100
	v_add3_u32 v92, v92, v95, s79
	v_bfe_u32 v95, v93, 16, 1
	v_mul_f32_e32 v90, v90, v100
	v_add3_u32 v88, v88, v91, s79
	v_bfe_u32 v91, v89, 16, 1
	v_mul_f32_e32 v86, v86, v100
	v_add3_u32 v84, v84, v87, s79
	v_bfe_u32 v87, v85, 16, 1
	v_mul_f32_e32 v82, v82, v100
	v_add3_u32 v80, v80, v83, s79
	v_bfe_u32 v83, v81, 16, 1
	v_mul_f32_e32 v78, v78, v100
	v_add3_u32 v76, v76, v79, s79
	v_bfe_u32 v79, v77, 16, 1
	v_mul_f32_e32 v74, v74, v100
	v_add3_u32 v72, v72, v75, s79
	v_bfe_u32 v75, v73, 16, 1
	v_and_or_b32 v68, v69, s80, v68
	v_bfe_u32 v69, v70, 16, 1
	s_mul_i32 s5, s5, 0xc000
	s_mul_hi_u32 s15, s14, 0xc000
	v_fma_f32 v94, v182, v94, v138
	v_lshrrev_b32_e32 v92, 16, v92
	v_add3_u32 v93, v93, v95, s79
	v_fma_f32 v90, v186, v90, v142
	v_lshrrev_b32_e32 v88, 16, v88
	v_add3_u32 v89, v89, v91, s79
	v_fma_f32 v86, v190, v86, v146
	v_lshrrev_b32_e32 v84, 16, v84
	v_add3_u32 v85, v85, v87, s79
	v_fma_f32 v82, v194, v82, v150
	v_lshrrev_b32_e32 v80, 16, v80
	v_add3_u32 v81, v81, v83, s79
	v_fma_f32 v78, v196, v78, v154
	v_lshrrev_b32_e32 v76, 16, v76
	v_add3_u32 v77, v77, v79, s79
	v_fma_f32 v74, v202, v74, v158
	v_lshrrev_b32_e32 v72, 16, v72
	v_add3_u32 v73, v73, v75, s79
	v_add3_u32 v69, v70, v69, s79
	v_bfe_u32 v70, v163, 16, 1
	s_add_i32 s15, s15, s5
	s_mul_i32 s14, s14, 0xc000
	v_and_or_b32 v92, v93, s80, v92
	v_bfe_u32 v93, v94, 16, 1
	v_and_or_b32 v88, v89, s80, v88
	v_bfe_u32 v89, v90, 16, 1
	v_and_or_b32 v84, v85, s80, v84
	v_bfe_u32 v85, v86, 16, 1
	v_and_or_b32 v80, v81, s80, v80
	v_bfe_u32 v81, v82, 16, 1
	v_and_or_b32 v76, v77, s80, v76
	v_bfe_u32 v77, v78, 16, 1
	v_and_or_b32 v72, v73, s80, v72
	v_bfe_u32 v73, v74, 16, 1
	v_lshrrev_b32_e32 v69, 16, v69
	v_add3_u32 v70, v163, v70, s79
	s_add_u32 s14, s21, s14
	v_add3_u32 v93, v94, v93, s79
	v_bfe_u32 v94, v139, 16, 1
	v_add3_u32 v89, v90, v89, s79
	v_bfe_u32 v90, v143, 16, 1
	v_add3_u32 v85, v86, v85, s79
	v_bfe_u32 v86, v147, 16, 1
	v_add3_u32 v81, v82, v81, s79
	v_bfe_u32 v82, v151, 16, 1
	v_add3_u32 v77, v78, v77, s79
	v_bfe_u32 v78, v155, 16, 1
	v_add3_u32 v73, v74, v73, s79
	v_bfe_u32 v74, v159, 16, 1
	v_and_or_b32 v69, v70, s80, v69
	s_addc_u32 s15, s22, s15
	v_lshrrev_b32_e32 v93, 16, v93
	v_add3_u32 v94, v139, v94, s79
	v_lshrrev_b32_e32 v89, 16, v89
	v_add3_u32 v90, v143, v90, s79
	v_lshrrev_b32_e32 v85, 16, v85
	v_add3_u32 v86, v147, v86, s79
	v_lshrrev_b32_e32 v81, 16, v81
	v_add3_u32 v82, v151, v82, s79
	v_lshrrev_b32_e32 v77, 16, v77
	v_add3_u32 v78, v155, v78, s79
	v_lshrrev_b32_e32 v73, 16, v73
	v_add3_u32 v74, v159, v74, s79
	v_subrev_u32_e32 v248, s30, v98
	v_add_u32_e32 v248, 0xe8400000, v248
	v_and_b32_e32 v249, 0xfff00000, v248
	v_lshrrev_b32_e32 v246, 5, v248
	v_and_b32_e32 v246, 0x7800, v246
	v_or_b32_e32 v249, v249, v246
	v_lshrrev_b32_e32 v246, 6, v248
	v_and_b32_e32 v246, 0x3c0, v246
	v_or_b32_e32 v249, v249, v246
	v_and_b32_e32 v246, 0x180, v248
	v_lshlrev_b32_e32 v246, 8, v246
	v_or_b32_e32 v249, v249, v246
	v_and_b32_e32 v246, 64, v248
	v_lshlrev_b32_e32 v246, 4, v246
	v_or_b32_e32 v249, v249, v246
	v_and_b32_e32 v246, 56, v248
	v_or_b32_e32 v249, v249, v246
	v_lshrrev_b32_e32 v246, 10, v248
	v_and_b32_e32 v246, 32, v246
	v_xor_b32_e32 v249, v249, v246
	v_sub_u32_e32 v246, v249, v248
	v_ashrrev_i32_e32 v247, 31, v246
	v_lshl_add_u64 v[98:99], v[98:99], 0, v[246:247]
	s_mov_b64 s[100:101], 0xe0000
	v_lshl_add_u64 v[248:249], v[98:99], 0, s[100:101]
	global_store_dwordx2 v[248:249], v[68:69], off
	v_lshl_add_u64 v[68:69], s[14:15], 0, v[172:173]
	global_store_dwordx2 v[98:99], v[96:97], off
	v_and_or_b32 v93, v94, s80, v93
	v_and_or_b32 v89, v90, s80, v89
	v_and_or_b32 v85, v86, s80, v85
	v_and_or_b32 v81, v82, s80, v81
	v_and_or_b32 v77, v78, s80, v77
	v_and_or_b32 v73, v74, s80, v73
	v_add_co_u32_e32 v96, vcc, s19, v68
	s_mov_b64 s[100:101], 0x20000
	v_lshl_add_u64 v[248:249], v[98:99], 0, s[100:101]
	global_store_dwordx2 v[248:249], v[92:93], off
	s_mov_b64 s[100:101], 0x40000
	v_lshl_add_u64 v[248:249], v[98:99], 0, s[100:101]
	global_store_dwordx2 v[248:249], v[88:89], off
	s_mov_b64 s[100:101], 0x60000
	v_lshl_add_u64 v[248:249], v[98:99], 0, s[100:101]
	global_store_dwordx2 v[248:249], v[84:85], off
	s_mov_b64 s[100:101], 0x80000
	v_lshl_add_u64 v[248:249], v[98:99], 0, s[100:101]
	global_store_dwordx2 v[248:249], v[80:81], off
	s_mov_b64 s[100:101], 0xa0000
	v_lshl_add_u64 v[248:249], v[98:99], 0, s[100:101]
	global_store_dwordx2 v[248:249], v[76:77], off
	s_mov_b64 s[100:101], 0xc0000
	v_lshl_add_u64 v[248:249], v[98:99], 0, s[100:101]
	global_store_dwordx2 v[248:249], v[72:73], off
	v_addc_co_u32_e32 v97, vcc, 0, v69, vcc
	global_load_dwordx4 v[76:79], v[96:97], off offset:-4096
	global_load_dwordx4 v[72:75], v[176:177], off
	v_add_co_u32_e32 v98, vcc, s18, v68
	v_lshl_add_u64 v[88:89], v[68:69], 0, s[26:27]
	s_nop 0
	v_addc_co_u32_e32 v99, vcc, 0, v69, vcc
	v_lshl_add_u64 v[92:93], v[68:69], 0, s[38:39]
	global_load_dwordx4 v[68:71], v[98:99], off offset:-4096
	s_lshl_b64 s[12:13], s[12:13], 12
	s_add_u32 s12, s8, s12
	s_addc_u32 s13, s9, s13
	s_lshl_b64 s[0:1], s[0:1], 12
	s_add_u32 s0, s8, s0
	s_addc_u32 s1, s9, s1
	s_waitcnt vmcnt(2)
	v_pk_add_f32 v[78:79], v[78:79], 1.0 op_sel_hi:[1,0]
	v_pk_add_f32 v[76:77], v[76:77], 1.0 op_sel_hi:[1,0]
	s_waitcnt vmcnt(1)
	v_pk_mul_f32 v[100:101], v[74:75], v[78:79]
	v_pk_mul_f32 v[102:103], v[72:73], v[76:77]
	global_load_dwordx4 v[76:79], v[176:177], off offset:1024
	global_load_dwordx4 v[80:83], v[88:89], off offset:1024
	global_load_dwordx4 v[72:75], v[92:93], off offset:1024
	s_waitcnt vmcnt(1)
	v_pk_add_f32 v[82:83], v[82:83], 1.0 op_sel_hi:[1,0]
	v_pk_add_f32 v[80:81], v[80:81], 1.0 op_sel_hi:[1,0]
	v_pk_mul_f32 v[104:105], v[78:79], v[82:83]
	v_pk_mul_f32 v[106:107], v[76:77], v[80:81]
	global_load_dwordx4 v[80:83], v[176:177], off offset:2048
	global_load_dwordx4 v[84:87], v[88:89], off offset:2048
	global_load_dwordx4 v[76:79], v[92:93], off offset:2048
	s_waitcnt vmcnt(1)
	v_pk_add_f32 v[86:87], v[86:87], 1.0 op_sel_hi:[1,0]
	v_pk_add_f32 v[84:85], v[84:85], 1.0 op_sel_hi:[1,0]
	v_pk_mul_f32 v[108:109], v[82:83], v[86:87]
	v_pk_mul_f32 v[110:111], v[80:81], v[84:85]
	global_load_dwordx4 v[84:87], v[176:177], off offset:3072
	s_nop 0
	global_load_dwordx4 v[88:91], v[88:89], off offset:3072
	s_nop 0
	global_load_dwordx4 v[80:83], v[92:93], off offset:3072
	s_waitcnt vmcnt(1)
	v_pk_add_f32 v[90:91], v[90:91], 1.0 op_sel_hi:[1,0]
	v_pk_add_f32 v[88:89], v[88:89], 1.0 op_sel_hi:[1,0]
	v_pk_mul_f32 v[112:113], v[86:87], v[90:91]
	v_pk_mul_f32 v[114:115], v[84:85], v[88:89]
	global_load_dwordx4 v[88:91], v[174:175], off
	global_load_dwordx4 v[92:95], v[96:97], off
	global_load_dwordx4 v[84:87], v[98:99], off
	s_waitcnt vmcnt(1)
	v_pk_add_f32 v[94:95], v[94:95], 1.0 op_sel_hi:[1,0]
	v_pk_add_f32 v[92:93], v[92:93], 1.0 op_sel_hi:[1,0]
	v_pk_mul_f32 v[116:117], v[90:91], v[94:95]
	v_pk_mul_f32 v[120:121], v[88:89], v[92:93]
	global_load_dwordx4 v[92:95], v[174:175], off offset:1024
	global_load_dwordx4 v[122:125], v[96:97], off offset:1024
	global_load_dwordx4 v[88:91], v[98:99], off offset:1024
	s_waitcnt vmcnt(1)
	v_pk_add_f32 v[118:119], v[124:125], 1.0 op_sel_hi:[1,0]
	v_pk_add_f32 v[122:123], v[122:123], 1.0 op_sel_hi:[1,0]
	v_pk_mul_f32 v[118:119], v[94:95], v[118:119]
	v_pk_mul_f32 v[122:123], v[92:93], v[122:123]
	global_load_dwordx4 v[130:133], v[174:175], off offset:2048
	global_load_dwordx4 v[124:127], v[96:97], off offset:2048
	global_load_dwordx4 v[92:95], v[98:99], off offset:2048
	s_waitcnt vmcnt(1)
	v_pk_add_f32 v[126:127], v[126:127], 1.0 op_sel_hi:[1,0]
	v_pk_add_f32 v[134:135], v[124:125], 1.0 op_sel_hi:[1,0]
	v_pk_mul_f32 v[124:125], v[132:133], v[126:127]
	v_pk_mul_f32 v[126:127], v[130:131], v[134:135]
	global_load_dwordx4 v[132:135], v[174:175], off offset:3072
	global_load_dwordx4 v[136:139], v[96:97], off offset:3072
	s_nop 0
	global_load_dwordx4 v[96:99], v[98:99], off offset:3072
	s_waitcnt vmcnt(1)
	v_pk_add_f32 v[130:131], v[138:139], 1.0 op_sel_hi:[1,0]
	s_nop 0
	v_pk_mul_f32 v[130:131], v[134:135], v[130:131]
	v_mul_f32_e32 v134, v65, v65
	v_mul_f32_e32 v135, v67, v67
	v_pk_add_f32 v[136:137], v[136:137], 1.0 op_sel_hi:[1,0]
	v_fmac_f32_e32 v134, v64, v64
	v_fmac_f32_e32 v135, v66, v66
	v_pk_mul_f32 v[132:133], v[132:133], v[136:137]
	v_add_f32_e32 v134, v134, v135
	v_mul_f32_e32 v135, v61, v61
	v_mul_f32_e32 v136, v63, v63
	v_fmac_f32_e32 v135, v60, v60
	v_fmac_f32_e32 v136, v62, v62
	v_add_f32_e32 v135, v135, v136
	v_add_f32_e32 v134, v134, v135
	v_mul_f32_e32 v135, v57, v57
	v_mul_f32_e32 v136, v59, v59
	v_fmac_f32_e32 v135, v56, v56
	v_fmac_f32_e32 v136, v58, v58
	v_add_f32_e32 v135, v135, v136
	v_add_f32_e32 v134, v134, v135
	v_mul_f32_e32 v135, v53, v53
	v_mul_f32_e32 v136, v55, v55
	v_fmac_f32_e32 v135, v52, v52
	v_fmac_f32_e32 v136, v54, v54
	v_add_f32_e32 v135, v135, v136
	v_add_f32_e32 v134, v134, v135
	v_mul_f32_e32 v135, v49, v49
	v_mul_f32_e32 v136, v51, v51
	v_fmac_f32_e32 v135, v48, v48
	v_fmac_f32_e32 v136, v50, v50
	v_add_f32_e32 v135, v135, v136
	v_add_f32_e32 v134, v134, v135
	v_mul_f32_e32 v135, v45, v45
	v_mul_f32_e32 v136, v47, v47
	v_fmac_f32_e32 v135, v44, v44
	v_fmac_f32_e32 v136, v46, v46
	v_add_f32_e32 v135, v135, v136
	v_add_f32_e32 v134, v134, v135
	v_mul_f32_e32 v135, v41, v41
	v_mul_f32_e32 v136, v43, v43
	v_fmac_f32_e32 v135, v40, v40
	v_fmac_f32_e32 v136, v42, v42
	v_add_f32_e32 v135, v135, v136
	v_add_f32_e32 v134, v134, v135
	v_mul_f32_e32 v135, v37, v37
	v_mul_f32_e32 v136, v39, v39
	v_fmac_f32_e32 v135, v36, v36
	v_fmac_f32_e32 v136, v38, v38
	v_add_f32_e32 v135, v135, v136
	v_add_f32_e32 v134, v134, v135
	v_mul_f32_e32 v135, v33, v33
	v_mul_f32_e32 v136, v35, v35
	v_fmac_f32_e32 v135, v32, v32
	v_fmac_f32_e32 v136, v34, v34
	v_add_f32_e32 v135, v135, v136
	v_mul_f32_e32 v136, v29, v29
	v_mul_f32_e32 v137, v31, v31
	v_fmac_f32_e32 v136, v28, v28
	v_fmac_f32_e32 v137, v30, v30
	v_add_f32_e32 v136, v136, v137
	v_add_f32_e32 v135, v135, v136
	v_mul_f32_e32 v136, v25, v25
	v_mul_f32_e32 v137, v27, v27
	v_fmac_f32_e32 v136, v24, v24
	v_fmac_f32_e32 v137, v26, v26
	v_add_f32_e32 v136, v136, v137
	v_add_f32_e32 v135, v135, v136
	v_mul_f32_e32 v136, v21, v21
	v_mul_f32_e32 v137, v23, v23
	v_fmac_f32_e32 v136, v20, v20
	v_fmac_f32_e32 v137, v22, v22
	v_add_f32_e32 v136, v136, v137
	v_add_f32_e32 v135, v135, v136
	v_mul_f32_e32 v136, v15, v15
	v_mul_f32_e32 v137, v17, v17
	v_fmac_f32_e32 v136, v14, v14
	v_fmac_f32_e32 v137, v16, v16
	v_add_f32_e32 v136, v136, v137
	v_add_f32_e32 v135, v135, v136
	v_mul_f32_e32 v136, v11, v11
	v_mul_f32_e32 v137, v13, v13
	v_fmac_f32_e32 v136, v10, v10
	v_fmac_f32_e32 v137, v12, v12
	v_add_f32_e32 v136, v136, v137
	v_add_f32_e32 v135, v135, v136
	v_mul_f32_e32 v136, v7, v7
	v_mul_f32_e32 v137, v9, v9
	v_fmac_f32_e32 v136, v6, v6
	v_fmac_f32_e32 v137, v8, v8
	v_add_f32_e32 v136, v136, v137
	v_add_f32_e32 v135, v135, v136
	v_mul_f32_e32 v136, v3, v3
	v_mul_f32_e32 v137, v5, v5
	v_fmac_f32_e32 v136, v2, v2
	v_fmac_f32_e32 v137, v4, v4
	v_add_f32_e32 v136, v136, v137
	v_add_f32_e32 v135, v135, v136
	ds_bpermute_b32 v136, v1, v134
	ds_bpermute_b32 v1, v1, v135
	s_waitcnt lgkmcnt(1)
	v_add_f32_e32 v134, v134, v136
	s_waitcnt lgkmcnt(0)
	v_add_f32_e32 v1, v135, v1
	ds_bpermute_b32 v135, v18, v134
	ds_bpermute_b32 v18, v18, v1
	s_waitcnt lgkmcnt(1)
	v_add_f32_e32 v134, v134, v135
	s_waitcnt lgkmcnt(0)
	v_add_f32_e32 v1, v1, v18
	ds_bpermute_b32 v18, v167, v134
	s_waitcnt lgkmcnt(0)
	v_add_f32_e32 v18, v134, v18
	ds_bpermute_b32 v134, v167, v1
	s_waitcnt lgkmcnt(0)
	v_add_f32_e32 v1, v1, v134
	ds_bpermute_b32 v134, v220, v18
	s_waitcnt lgkmcnt(0)
	v_add_f32_e32 v18, v18, v134
	ds_bpermute_b32 v134, v220, v1
	s_waitcnt lgkmcnt(0)
	v_add_f32_e32 v1, v1, v134
	ds_bpermute_b32 v134, v221, v18
	s_waitcnt lgkmcnt(0)
	v_add_f32_e32 v18, v18, v134
	ds_bpermute_b32 v134, v221, v1
	s_waitcnt lgkmcnt(0)
	v_add_f32_e32 v1, v1, v134
	ds_bpermute_b32 v134, v222, v18
	s_waitcnt lgkmcnt(0)
	v_add_f32_e32 v18, v18, v134
	v_fmamk_f32 v18, v18, 0x3a000000, v165
	v_rsq_f32_e32 v18, v18
	ds_bpermute_b32 v134, v222, v1
	v_mul_f32_e32 v64, v64, v18
	v_fma_f32 v64, v102, v64, v68
	v_mul_f32_e32 v65, v65, v18
	s_waitcnt lgkmcnt(0)
	v_add_f32_e32 v1, v1, v134
	v_fma_f32 v65, v103, v65, v69
	v_bfe_u32 v134, v64, 16, 1
	v_mul_f32_e32 v66, v66, v18
	v_add3_u32 v64, v64, v134, s79
	v_bfe_u32 v134, v65, 16, 1
	v_fma_f32 v66, v100, v66, v70
	v_mul_f32_e32 v67, v67, v18
	v_lshrrev_b32_e32 v64, 16, v64
	v_add3_u32 v65, v65, v134, s79
	v_fma_f32 v67, v101, v67, v71
	v_and_or_b32 v64, v65, s80, v64
	v_bfe_u32 v65, v66, 16, 1
	v_add3_u32 v65, v66, v65, s79
	v_bfe_u32 v66, v67, 16, 1
	v_lshrrev_b32_e32 v65, 16, v65
	v_add3_u32 v66, v67, v66, s79
	v_mul_f32_e32 v60, v60, v18
	v_and_or_b32 v65, v66, s80, v65
	v_lshl_add_u64 v[66:67], s[12:13], 0, v[128:129]
	v_fma_f32 v60, v106, v60, v72
	v_mul_f32_e32 v61, v61, v18
	v_subrev_u32_e32 v248, s30, v66
	v_add_u32_e32 v248, 0xe8400000, v248
	v_and_b32_e32 v249, 0xfff00000, v248
	v_lshrrev_b32_e32 v246, 5, v248
	v_and_b32_e32 v246, 0x7800, v246
	v_or_b32_e32 v249, v249, v246
	v_lshrrev_b32_e32 v246, 6, v248
	v_and_b32_e32 v246, 0x3c0, v246
	v_or_b32_e32 v249, v249, v246
	v_and_b32_e32 v246, 0x180, v248
	v_lshlrev_b32_e32 v246, 8, v246
	v_or_b32_e32 v249, v249, v246
	v_and_b32_e32 v246, 64, v248
	v_lshlrev_b32_e32 v246, 4, v246
	v_or_b32_e32 v249, v249, v246
	v_and_b32_e32 v246, 56, v248
	v_or_b32_e32 v249, v249, v246
	v_lshrrev_b32_e32 v246, 10, v248
	v_and_b32_e32 v246, 32, v246
	v_xor_b32_e32 v249, v249, v246
	v_sub_u32_e32 v246, v249, v248
	v_ashrrev_i32_e32 v247, 31, v246
	v_lshl_add_u64 v[66:67], v[66:67], 0, v[246:247]
	global_store_dwordx2 v[66:67], v[64:65], off
	v_fma_f32 v61, v107, v61, v73
	v_bfe_u32 v64, v60, 16, 1
	v_mul_f32_e32 v62, v62, v18
	v_add3_u32 v60, v60, v64, s79
	v_bfe_u32 v64, v61, 16, 1
	v_mul_f32_e32 v36, v36, v18
	v_fma_f32 v62, v104, v62, v74
	v_mul_f32_e32 v63, v63, v18
	v_lshrrev_b32_e32 v60, 16, v60
	v_add3_u32 v61, v61, v64, s79
	s_waitcnt vmcnt(1)
	v_fma_f32 v36, v132, v36, v96
	v_mul_f32_e32 v37, v37, v18
	v_fma_f32 v63, v105, v63, v75
	v_and_or_b32 v60, v61, s80, v60
	v_bfe_u32 v61, v62, 16, 1
	v_mul_f32_e32 v56, v56, v18
	v_mul_f32_e32 v57, v57, v18
	v_mul_f32_e32 v58, v58, v18
	v_mul_f32_e32 v59, v59, v18
	v_mul_f32_e32 v52, v52, v18
	v_mul_f32_e32 v53, v53, v18
	v_mul_f32_e32 v54, v54, v18
	v_mul_f32_e32 v55, v55, v18
	v_mul_f32_e32 v48, v48, v18
	v_mul_f32_e32 v49, v49, v18
	v_mul_f32_e32 v50, v50, v18
	v_mul_f32_e32 v51, v51, v18
	v_mul_f32_e32 v44, v44, v18
	v_mul_f32_e32 v45, v45, v18
	v_mul_f32_e32 v46, v46, v18
	v_mul_f32_e32 v47, v47, v18
	v_mul_f32_e32 v40, v40, v18
	v_mul_f32_e32 v41, v41, v18
	v_mul_f32_e32 v42, v42, v18
	v_mul_f32_e32 v43, v43, v18
	v_fma_f32 v37, v133, v37, v97
	v_mul_f32_e32 v38, v38, v18
	v_mul_f32_e32 v18, v39, v18
	v_bfe_u32 v39, v36, 16, 1
	v_add3_u32 v61, v62, v61, s79
	v_bfe_u32 v62, v63, 16, 1
	v_add3_u32 v36, v36, v39, s79
	v_bfe_u32 v39, v37, 16, 1
	v_fmamk_f32 v1, v1, 0x3a000000, v165
	v_lshrrev_b32_e32 v61, 16, v61
	v_add3_u32 v62, v63, v62, s79
	v_fma_f32 v38, v130, v38, v98
	v_lshrrev_b32_e32 v36, 16, v36
	v_add3_u32 v37, v37, v39, s79
	v_rsq_f32_e32 v1, v1
	v_and_or_b32 v61, v62, s80, v61
	v_fma_f32 v56, v110, v56, v76
	v_fma_f32 v18, v131, v18, v99
	v_and_or_b32 v36, v37, s80, v36
	v_bfe_u32 v37, v38, 16, 1
	s_mov_b64 s[100:101], 0x20000
	v_lshl_add_u64 v[248:249], v[66:67], 0, s[100:101]
	global_store_dwordx2 v[248:249], v[60:61], off
	v_fma_f32 v57, v111, v57, v77
	v_bfe_u32 v60, v56, 16, 1
	v_add3_u32 v37, v38, v37, s79
	v_bfe_u32 v38, v18, 16, 1
	v_add3_u32 v56, v56, v60, s79
	v_bfe_u32 v60, v57, 16, 1
	v_lshrrev_b32_e32 v37, 16, v37
	v_add3_u32 v18, v18, v38, s79
	v_fma_f32 v58, v108, v58, v78
	v_lshrrev_b32_e32 v56, 16, v56
	v_add3_u32 v57, v57, v60, s79
	v_and_or_b32 v37, v18, s80, v37
	v_mul_f32_e32 v18, v32, v1
	v_fma_f32 v59, v109, v59, v79
	v_and_or_b32 v56, v57, s80, v56
	v_bfe_u32 v57, v58, 16, 1
	v_fma_f32 v18, v102, v18, v68
	v_mul_f32_e32 v32, v33, v1
	v_mul_f32_e32 v33, v34, v1
	v_mul_f32_e32 v34, v35, v1
	v_add3_u32 v57, v58, v57, s79
	v_bfe_u32 v58, v59, 16, 1
	v_fma_f32 v32, v103, v32, v69
	v_fmac_f32_e32 v71, v101, v34
	v_bfe_u32 v34, v18, 16, 1
	v_lshrrev_b32_e32 v57, 16, v57
	v_add3_u32 v58, v59, v58, s79
	v_add3_u32 v18, v18, v34, s79
	v_bfe_u32 v34, v32, 16, 1
	v_and_or_b32 v57, v58, s80, v57
	v_fma_f32 v52, v114, v52, v80
	v_fma_f32 v33, v100, v33, v70
	v_lshrrev_b32_e32 v18, 16, v18
	v_add3_u32 v32, v32, v34, s79
	s_mov_b64 s[100:101], 0x40000
	v_lshl_add_u64 v[248:249], v[66:67], 0, s[100:101]
	global_store_dwordx2 v[248:249], v[56:57], off
	v_fma_f32 v53, v115, v53, v81
	v_bfe_u32 v56, v52, 16, 1
	v_and_or_b32 v32, v32, s80, v18
	v_bfe_u32 v18, v33, 16, 1
	v_add3_u32 v52, v52, v56, s79
	v_bfe_u32 v56, v53, 16, 1
	v_add3_u32 v18, v33, v18, s79
	v_bfe_u32 v33, v71, 16, 1
	v_fma_f32 v54, v112, v54, v82
	v_lshrrev_b32_e32 v52, 16, v52
	v_add3_u32 v53, v53, v56, s79
	v_lshrrev_b32_e32 v18, 16, v18
	v_add3_u32 v33, v71, v33, s79
	v_fma_f32 v55, v113, v55, v83
	v_and_or_b32 v52, v53, s80, v52
	v_bfe_u32 v53, v54, 16, 1
	v_and_or_b32 v33, v33, s80, v18
	v_mul_f32_e32 v18, v28, v1
	v_add3_u32 v53, v54, v53, s79
	v_bfe_u32 v54, v55, 16, 1
	v_fma_f32 v18, v106, v18, v72
	v_mul_f32_e32 v28, v29, v1
	v_mul_f32_e32 v29, v30, v1
	v_mul_f32_e32 v30, v31, v1
	v_lshrrev_b32_e32 v53, 16, v53
	v_add3_u32 v54, v55, v54, s79
	v_fma_f32 v28, v107, v28, v73
	v_fmac_f32_e32 v75, v105, v30
	v_bfe_u32 v30, v18, 16, 1
	v_and_or_b32 v53, v54, s80, v53
	v_fma_f32 v48, v120, v48, v84
	v_add3_u32 v18, v18, v30, s79
	v_bfe_u32 v30, v28, 16, 1
	s_mov_b64 s[100:101], 0x60000
	v_lshl_add_u64 v[248:249], v[66:67], 0, s[100:101]
	global_store_dwordx2 v[248:249], v[52:53], off
	v_fma_f32 v49, v121, v49, v85
	v_bfe_u32 v52, v48, 16, 1
	v_fma_f32 v29, v104, v29, v74
	v_lshrrev_b32_e32 v18, 16, v18
	v_add3_u32 v28, v28, v30, s79
	v_add3_u32 v48, v48, v52, s79
	v_bfe_u32 v52, v49, 16, 1
	v_and_or_b32 v28, v28, s80, v18
	v_bfe_u32 v18, v29, 16, 1
	v_fma_f32 v50, v116, v50, v86
	v_lshrrev_b32_e32 v48, 16, v48
	v_add3_u32 v49, v49, v52, s79
	v_add3_u32 v18, v29, v18, s79
	v_bfe_u32 v29, v75, 16, 1
	v_fma_f32 v51, v117, v51, v87
	v_and_or_b32 v48, v49, s80, v48
	v_bfe_u32 v49, v50, 16, 1
	v_lshrrev_b32_e32 v18, 16, v18
	v_add3_u32 v29, v75, v29, s79
	v_add3_u32 v49, v50, v49, s79
	v_bfe_u32 v50, v51, 16, 1
	v_and_or_b32 v29, v29, s80, v18
	v_mul_f32_e32 v18, v24, v1
	v_lshrrev_b32_e32 v49, 16, v49
	v_add3_u32 v50, v51, v50, s79
	v_fma_f32 v18, v110, v18, v76
	v_mul_f32_e32 v24, v25, v1
	v_mul_f32_e32 v25, v26, v1
	v_mul_f32_e32 v26, v27, v1
	v_and_or_b32 v49, v50, s80, v49
	v_fma_f32 v44, v122, v44, v88
	v_fma_f32 v24, v111, v24, v77
	v_fmac_f32_e32 v79, v109, v26
	v_bfe_u32 v26, v18, 16, 1
	s_mov_b64 s[100:101], 0x80000
	v_lshl_add_u64 v[248:249], v[66:67], 0, s[100:101]
	global_store_dwordx2 v[248:249], v[48:49], off
	v_fma_f32 v45, v123, v45, v89
	v_bfe_u32 v48, v44, 16, 1
	v_add3_u32 v18, v18, v26, s79
	v_bfe_u32 v26, v24, 16, 1
	v_add3_u32 v44, v44, v48, s79
	v_bfe_u32 v48, v45, 16, 1
	v_fma_f32 v25, v108, v25, v78
	v_lshrrev_b32_e32 v18, 16, v18
	v_add3_u32 v24, v24, v26, s79
	v_fma_f32 v46, v118, v46, v90
	v_lshrrev_b32_e32 v44, 16, v44
	v_add3_u32 v45, v45, v48, s79
	v_and_or_b32 v24, v24, s80, v18
	v_bfe_u32 v18, v25, 16, 1
	v_fma_f32 v47, v119, v47, v91
	v_and_or_b32 v44, v45, s80, v44
	v_bfe_u32 v45, v46, 16, 1
	v_add3_u32 v18, v25, v18, s79
	v_bfe_u32 v25, v79, 16, 1
	v_add3_u32 v45, v46, v45, s79
	v_bfe_u32 v46, v47, 16, 1
	v_lshrrev_b32_e32 v18, 16, v18
	v_add3_u32 v25, v79, v25, s79
	v_lshrrev_b32_e32 v45, 16, v45
	v_add3_u32 v46, v47, v46, s79
	v_and_or_b32 v25, v25, s80, v18
	v_mul_f32_e32 v18, v20, v1
	v_mul_f32_e32 v14, v14, v1
	v_mul_f32_e32 v10, v10, v1
	v_mul_f32_e32 v6, v6, v1
	v_mul_f32_e32 v2, v2, v1
	v_and_or_b32 v45, v46, s80, v45
	v_fma_f32 v40, v126, v40, v92
	v_fma_f32 v18, v114, v18, v80
	v_mul_f32_e32 v20, v21, v1
	v_mul_f32_e32 v21, v22, v1
	v_mul_f32_e32 v22, v23, v1
	v_fma_f32 v14, v120, v14, v84
	v_mul_f32_e32 v15, v15, v1
	v_mul_f32_e32 v16, v16, v1
	v_mul_f32_e32 v17, v17, v1
	v_fma_f32 v10, v122, v10, v88
	v_mul_f32_e32 v11, v11, v1
	v_mul_f32_e32 v12, v12, v1
	v_mul_f32_e32 v13, v13, v1
	v_fma_f32 v6, v126, v6, v92
	v_mul_f32_e32 v7, v7, v1
	v_mul_f32_e32 v8, v8, v1
	v_mul_f32_e32 v9, v9, v1
	v_fma_f32 v2, v132, v2, v96
	v_mul_f32_e32 v3, v3, v1
	v_mul_f32_e32 v4, v4, v1
	v_mul_f32_e32 v1, v5, v1
	s_mov_b64 s[100:101], 0xa0000
	v_lshl_add_u64 v[248:249], v[66:67], 0, s[100:101]
	global_store_dwordx2 v[248:249], v[44:45], off
	v_fma_f32 v41, v127, v41, v93
	v_fma_f32 v43, v125, v43, v95
	v_bfe_u32 v44, v40, 16, 1
	v_fma_f32 v20, v115, v20, v81
	v_fmac_f32_e32 v83, v113, v22
	v_bfe_u32 v22, v18, 16, 1
	v_fma_f32 v15, v121, v15, v85
	v_fmac_f32_e32 v87, v117, v17
	v_bfe_u32 v17, v14, 16, 1
	v_fma_f32 v11, v123, v11, v89
	v_fmac_f32_e32 v91, v119, v13
	v_bfe_u32 v13, v10, 16, 1
	v_fma_f32 v7, v127, v7, v93
	v_fmac_f32_e32 v95, v125, v9
	v_bfe_u32 v9, v6, 16, 1
	v_fma_f32 v3, v133, v3, v97
	v_fmac_f32_e32 v99, v131, v1
	v_bfe_u32 v1, v2, 16, 1
	v_add3_u32 v40, v40, v44, s79
	v_bfe_u32 v44, v41, 16, 1
	v_add3_u32 v18, v18, v22, s79
	v_bfe_u32 v22, v20, 16, 1
	v_add3_u32 v14, v14, v17, s79
	v_bfe_u32 v17, v15, 16, 1
	v_add3_u32 v10, v10, v13, s79
	v_bfe_u32 v13, v11, 16, 1
	v_add3_u32 v6, v6, v9, s79
	v_bfe_u32 v9, v7, 16, 1
	v_add3_u32 v1, v2, v1, s79
	v_bfe_u32 v2, v3, 16, 1
	v_fma_f32 v42, v124, v42, v94
	v_lshrrev_b32_e32 v40, 16, v40
	v_add3_u32 v41, v41, v44, s79
	v_fma_f32 v21, v112, v21, v82
	v_lshrrev_b32_e32 v18, 16, v18
	v_add3_u32 v20, v20, v22, s79
	v_fma_f32 v16, v116, v16, v86
	v_lshrrev_b32_e32 v14, 16, v14
	v_add3_u32 v15, v15, v17, s79
	v_fma_f32 v12, v118, v12, v90
	v_lshrrev_b32_e32 v10, 16, v10
	v_add3_u32 v11, v11, v13, s79
	v_fma_f32 v8, v124, v8, v94
	v_lshrrev_b32_e32 v6, 16, v6
	v_add3_u32 v7, v7, v9, s79
	v_fma_f32 v4, v130, v4, v98
	v_lshrrev_b32_e32 v1, 16, v1
	v_add3_u32 v2, v3, v2, s79
	v_and_or_b32 v40, v41, s80, v40
	v_bfe_u32 v41, v42, 16, 1
	v_and_or_b32 v20, v20, s80, v18
	v_bfe_u32 v18, v21, 16, 1
	v_and_or_b32 v14, v15, s80, v14
	v_bfe_u32 v15, v16, 16, 1
	v_and_or_b32 v10, v11, s80, v10
	v_bfe_u32 v11, v12, 16, 1
	v_and_or_b32 v6, v7, s80, v6
	v_bfe_u32 v7, v8, 16, 1
	v_and_or_b32 v2, v2, s80, v1
	v_bfe_u32 v1, v4, 16, 1
	v_add3_u32 v41, v42, v41, s79
	v_bfe_u32 v42, v43, 16, 1
	v_add3_u32 v18, v21, v18, s79
	v_bfe_u32 v21, v83, 16, 1
	v_add3_u32 v15, v16, v15, s79
	v_bfe_u32 v16, v87, 16, 1
	v_add3_u32 v11, v12, v11, s79
	v_bfe_u32 v12, v91, 16, 1
	v_add3_u32 v7, v8, v7, s79
	v_bfe_u32 v8, v95, 16, 1
	v_add3_u32 v1, v4, v1, s79
	v_bfe_u32 v3, v99, 16, 1
	v_lshrrev_b32_e32 v41, 16, v41
	v_add3_u32 v42, v43, v42, s79
	v_lshl_add_u64 v[34:35], s[0:1], 0, v[128:129]
	v_lshrrev_b32_e32 v18, 16, v18
	v_add3_u32 v21, v83, v21, s79
	v_lshrrev_b32_e32 v15, 16, v15
	v_add3_u32 v16, v87, v16, s79
	v_lshrrev_b32_e32 v11, 16, v11
	v_add3_u32 v12, v91, v12, s79
	v_lshrrev_b32_e32 v7, 16, v7
	v_add3_u32 v8, v95, v8, s79
	v_lshrrev_b32_e32 v1, 16, v1
	v_add3_u32 v3, v99, v3, s79
	v_readlane_b32 s0, v251, 8
	v_and_or_b32 v41, v42, s80, v41
	v_and_or_b32 v21, v21, s80, v18
	v_and_or_b32 v15, v16, s80, v15
	v_and_or_b32 v11, v12, s80, v11
	v_and_or_b32 v7, v8, s80, v7
	v_and_or_b32 v3, v3, s80, v1
	s_add_i32 s4, s4, s0
	s_mov_b64 s[100:101], 0xc0000
	v_lshl_add_u64 v[248:249], v[66:67], 0, s[100:101]
	global_store_dwordx2 v[248:249], v[40:41], off
	s_mov_b64 s[100:101], 0xe0000
	v_lshl_add_u64 v[248:249], v[66:67], 0, s[100:101]
	global_store_dwordx2 v[248:249], v[36:37], off
	v_subrev_u32_e32 v248, s30, v34
	v_add_u32_e32 v248, 0xe8400000, v248
	v_and_b32_e32 v249, 0xfff00000, v248
	v_lshrrev_b32_e32 v246, 5, v248
	v_and_b32_e32 v246, 0x7800, v246
	v_or_b32_e32 v249, v249, v246
	v_lshrrev_b32_e32 v246, 6, v248
	v_and_b32_e32 v246, 0x3c0, v246
	v_or_b32_e32 v249, v249, v246
	v_and_b32_e32 v246, 0x180, v248
	v_lshlrev_b32_e32 v246, 8, v246
	v_or_b32_e32 v249, v249, v246
	v_and_b32_e32 v246, 64, v248
	v_lshlrev_b32_e32 v246, 4, v246
	v_or_b32_e32 v249, v249, v246
	v_and_b32_e32 v246, 56, v248
	v_or_b32_e32 v249, v249, v246
	v_lshrrev_b32_e32 v246, 10, v248
	v_and_b32_e32 v246, 32, v246
	v_xor_b32_e32 v249, v249, v246
	v_sub_u32_e32 v246, v249, v248
	v_ashrrev_i32_e32 v247, 31, v246
	v_lshl_add_u64 v[34:35], v[34:35], 0, v[246:247]
	global_store_dwordx2 v[34:35], v[32:33], off
	s_mov_b64 s[100:101], 0x20000
	v_lshl_add_u64 v[248:249], v[34:35], 0, s[100:101]
	global_store_dwordx2 v[248:249], v[28:29], off
	s_mov_b64 s[100:101], 0x40000
	v_lshl_add_u64 v[248:249], v[34:35], 0, s[100:101]
	global_store_dwordx2 v[248:249], v[24:25], off
	s_mov_b64 s[100:101], 0x60000
	v_lshl_add_u64 v[248:249], v[34:35], 0, s[100:101]
	global_store_dwordx2 v[248:249], v[20:21], off
	s_mov_b64 s[100:101], 0x80000
	v_lshl_add_u64 v[248:249], v[34:35], 0, s[100:101]
	global_store_dwordx2 v[248:249], v[14:15], off
	s_mov_b64 s[100:101], 0xa0000
	v_lshl_add_u64 v[248:249], v[34:35], 0, s[100:101]
	global_store_dwordx2 v[248:249], v[10:11], off
	s_mov_b64 s[100:101], 0xc0000
	v_lshl_add_u64 v[248:249], v[34:35], 0, s[100:101]
	global_store_dwordx2 v[248:249], v[6:7], off
	s_mov_b64 s[100:101], 0xe0000
	v_lshl_add_u64 v[248:249], v[34:35], 0, s[100:101]
	global_store_dwordx2 v[248:249], v[2:3], off

.LBB0_1692:
	s_ashr_i32 s1, s8, 31
	s_add_u32 s6, s8, s24
	s_addc_u32 s1, s1, 0
	s_mul_i32 s1, s1, 0xc000
	s_mul_hi_u32 s7, s6, 0xc000
	s_add_i32 s7, s7, s1
	s_mul_i32 s6, s6, 0xc000
	s_add_u32 s6, s12, s6
	s_waitcnt vmcnt(0)
	v_add_co_u32_e32 v2, vcc, 0x1000, v72
	s_addc_u32 s7, s13, s7
	s_nop 0
	v_addc_co_u32_e32 v3, vcc, 0, v73, vcc
	v_lshl_add_u64 v[66:67], s[6:7], 0, v[100:101]
	v_add_co_u32_e32 v64, vcc, s78, v66
	global_load_dwordx4 v[32:35], v[72:73], off
	global_load_dwordx4 v[28:31], v[72:73], off offset:1024
	global_load_dwordx4 v[24:27], v[72:73], off offset:2048
	global_load_dwordx4 v[20:23], v[72:73], off offset:3072
	v_addc_co_u32_e32 v65, vcc, 0, v67, vcc
	global_load_dwordx4 v[14:17], v[2:3], off
	global_load_dwordx4 v[10:13], v[2:3], off offset:1024
	global_load_dwordx4 v[6:9], v[2:3], off offset:2048
	s_nop 0
	global_load_dwordx4 v[2:5], v[2:3], off offset:3072
	s_mov_b64 s[6:7], 0x2000
	global_load_dwordx4 v[40:43], v[102:103], off
	global_load_dwordx4 v[44:47], v[64:65], off offset:-4096
	global_load_dwordx4 v[36:39], v[66:67], off
	v_lshl_add_u64 v[56:57], v[66:67], 0, s[6:7]
	s_lshl_b64 s[6:7], s[4:5], 12
	s_waitcnt vmcnt(10)
	v_mul_f32_e32 v1, v33, v33
	v_mul_f32_e32 v18, v35, v35
	v_fmac_f32_e32 v1, v32, v32
	v_fmac_f32_e32 v18, v34, v34
	v_add_f32_e32 v1, v1, v18
	s_waitcnt vmcnt(9)
	v_mul_f32_e32 v18, v29, v29
	v_fmac_f32_e32 v18, v28, v28
	s_waitcnt vmcnt(1)
	v_pk_add_f32 v[46:47], v[46:47], 1.0 op_sel_hi:[1,0]
	v_pk_add_f32 v[44:45], v[44:45], 1.0 op_sel_hi:[1,0]
	v_pk_mul_f32 v[68:69], v[42:43], v[46:47]
	v_pk_mul_f32 v[70:71], v[40:41], v[44:45]
	global_load_dwordx4 v[44:47], v[102:103], off offset:1024
	global_load_dwordx4 v[48:51], v[56:57], off offset:1024
	global_load_dwordx4 v[40:43], v[66:67], off offset:1024
	s_waitcnt vmcnt(1)
	v_pk_add_f32 v[50:51], v[50:51], 1.0 op_sel_hi:[1,0]
	v_pk_add_f32 v[48:49], v[48:49], 1.0 op_sel_hi:[1,0]
	v_pk_mul_f32 v[74:75], v[46:47], v[50:51]
	v_pk_mul_f32 v[76:77], v[44:45], v[48:49]
	global_load_dwordx4 v[48:51], v[102:103], off offset:2048
	global_load_dwordx4 v[52:55], v[56:57], off offset:2048
	global_load_dwordx4 v[44:47], v[66:67], off offset:2048
	s_waitcnt vmcnt(1)
	v_pk_add_f32 v[54:55], v[54:55], 1.0 op_sel_hi:[1,0]
	v_pk_add_f32 v[52:53], v[52:53], 1.0 op_sel_hi:[1,0]
	v_pk_mul_f32 v[78:79], v[50:51], v[54:55]
	v_pk_mul_f32 v[82:83], v[48:49], v[52:53]
	global_load_dwordx4 v[52:55], v[102:103], off offset:3072
	s_nop 0
	global_load_dwordx4 v[56:59], v[56:57], off offset:3072
	s_nop 0
	global_load_dwordx4 v[48:51], v[66:67], off offset:3072
	v_add_co_u32_e32 v66, vcc, s3, v66
	s_waitcnt vmcnt(1)
	v_pk_add_f32 v[58:59], v[58:59], 1.0 op_sel_hi:[1,0]
	v_pk_add_f32 v[56:57], v[56:57], 1.0 op_sel_hi:[1,0]
	v_pk_mul_f32 v[80:81], v[54:55], v[58:59]
	v_pk_mul_f32 v[84:85], v[52:53], v[56:57]
	global_load_dwordx4 v[56:59], v[104:105], off
	global_load_dwordx4 v[60:63], v[64:65], off
	v_addc_co_u32_e32 v67, vcc, 0, v67, vcc
	global_load_dwordx4 v[52:55], v[66:67], off
	s_waitcnt vmcnt(1)
	v_pk_add_f32 v[62:63], v[62:63], 1.0 op_sel_hi:[1,0]
	v_pk_add_f32 v[60:61], v[60:61], 1.0 op_sel_hi:[1,0]
	v_pk_mul_f32 v[86:87], v[58:59], v[62:63]
	v_pk_mul_f32 v[88:89], v[56:57], v[60:61]
	global_load_dwordx4 v[60:63], v[106:107], off
	global_load_dwordx4 v[90:93], v[64:65], off offset:1024
	global_load_dwordx4 v[56:59], v[66:67], off offset:1024
	s_waitcnt vmcnt(1)
	v_pk_add_f32 v[92:93], v[92:93], 1.0 op_sel_hi:[1,0]
	v_pk_add_f32 v[94:95], v[90:91], 1.0 op_sel_hi:[1,0]
	v_pk_mul_f32 v[90:91], v[62:63], v[92:93]
	v_pk_mul_f32 v[92:93], v[60:61], v[94:95]
	global_load_dwordx4 v[96:99], v[108:109], off
	global_load_dwordx4 v[116:119], v[64:65], off offset:2048
	global_load_dwordx4 v[60:63], v[66:67], off offset:2048
	s_waitcnt vmcnt(1)
	v_pk_add_f32 v[116:117], v[116:117], 1.0 op_sel_hi:[1,0]
	v_pk_add_f32 v[94:95], v[118:119], 1.0 op_sel_hi:[1,0]
	v_pk_mul_f32 v[96:97], v[96:97], v[116:117]
	global_load_dwordx4 v[116:119], v[110:111], off
	global_load_dwordx4 v[120:123], v[64:65], off offset:3072
	s_nop 0
	global_load_dwordx4 v[64:67], v[66:67], off offset:3072
	v_pk_mul_f32 v[94:95], v[98:99], v[94:95]
	s_waitcnt vmcnt(1)
	v_pk_add_f32 v[98:99], v[122:123], 1.0 op_sel_hi:[1,0]
	s_nop 0
	v_pk_mul_f32 v[98:99], v[118:119], v[98:99]
	v_mul_f32_e32 v118, v31, v31
	v_fmac_f32_e32 v118, v30, v30
	v_add_f32_e32 v18, v18, v118
	v_add_f32_e32 v1, v1, v18
	v_mul_f32_e32 v18, v25, v25
	v_mul_f32_e32 v118, v27, v27
	v_fmac_f32_e32 v18, v24, v24
	v_fmac_f32_e32 v118, v26, v26
	v_add_f32_e32 v18, v18, v118
	v_add_f32_e32 v1, v1, v18
	v_mul_f32_e32 v18, v21, v21
	v_mul_f32_e32 v118, v23, v23
	v_fmac_f32_e32 v18, v20, v20
	v_fmac_f32_e32 v118, v22, v22
	v_add_f32_e32 v18, v18, v118
	v_add_f32_e32 v1, v1, v18
	v_mul_f32_e32 v18, v15, v15
	v_mul_f32_e32 v118, v17, v17
	v_fmac_f32_e32 v18, v14, v14
	v_fmac_f32_e32 v118, v16, v16
	v_add_f32_e32 v18, v18, v118
	v_add_f32_e32 v1, v1, v18
	v_mul_f32_e32 v18, v11, v11
	v_mul_f32_e32 v118, v13, v13
	v_fmac_f32_e32 v18, v10, v10
	v_fmac_f32_e32 v118, v12, v12
	v_add_f32_e32 v18, v18, v118
	v_add_f32_e32 v1, v1, v18
	v_mul_f32_e32 v18, v7, v7
	v_mul_f32_e32 v118, v9, v9
	v_fmac_f32_e32 v18, v6, v6
	v_fmac_f32_e32 v118, v8, v8
	v_add_f32_e32 v18, v18, v118
	v_add_f32_e32 v1, v1, v18
	v_mul_f32_e32 v18, v3, v3
	v_mul_f32_e32 v118, v5, v5
	v_fmac_f32_e32 v18, v2, v2
	v_fmac_f32_e32 v118, v4, v4
	v_add_f32_e32 v18, v18, v118
	v_add_f32_e32 v1, v1, v18
	v_and_b32_e32 v18, 64, v213
	v_add_u32_e32 v18, 64, v18
	v_xor_b32_e32 v118, 1, v213
	v_cmp_lt_i32_e32 vcc, v118, v18
	v_pk_add_f32 v[120:121], v[120:121], 1.0 op_sel_hi:[1,0]
	s_nop 0
	v_cndmask_b32_e32 v118, v213, v118, vcc
	v_lshlrev_b32_e32 v118, 2, v118
	ds_bpermute_b32 v118, v118, v1
	v_pk_mul_f32 v[116:117], v[116:117], v[120:121]
	s_waitcnt lgkmcnt(0)
	v_add_f32_e32 v1, v1, v118
	v_xor_b32_e32 v118, 2, v213
	v_cmp_lt_i32_e32 vcc, v118, v18
	s_nop 1
	v_cndmask_b32_e32 v118, v213, v118, vcc
	v_lshlrev_b32_e32 v118, 2, v118
	ds_bpermute_b32 v118, v118, v1
	s_waitcnt lgkmcnt(0)
	v_add_f32_e32 v1, v1, v118
	v_xor_b32_e32 v118, 4, v213
	v_cmp_lt_i32_e32 vcc, v118, v18
	s_nop 1
	v_cndmask_b32_e32 v118, v213, v118, vcc
	v_lshlrev_b32_e32 v118, 2, v118
	ds_bpermute_b32 v118, v118, v1
	s_waitcnt lgkmcnt(0)
	v_add_f32_e32 v1, v1, v118
	v_xor_b32_e32 v118, 8, v213
	v_cmp_lt_i32_e32 vcc, v118, v18
	s_nop 1
	v_cndmask_b32_e32 v118, v213, v118, vcc
	v_lshlrev_b32_e32 v118, 2, v118
	ds_bpermute_b32 v118, v118, v1
	s_waitcnt lgkmcnt(0)
	v_add_f32_e32 v1, v1, v118
	v_xor_b32_e32 v118, 16, v213
	v_cmp_lt_i32_e32 vcc, v118, v18
	s_nop 1
	v_cndmask_b32_e32 v118, v213, v118, vcc
	v_lshlrev_b32_e32 v118, 2, v118
	ds_bpermute_b32 v118, v118, v1
	s_waitcnt lgkmcnt(0)
	v_add_f32_e32 v1, v1, v118
	v_xor_b32_e32 v118, 32, v213
	v_cmp_lt_i32_e32 vcc, v118, v18
	s_nop 1
	v_cndmask_b32_e32 v18, v213, v118, vcc
	v_lshlrev_b32_e32 v18, 2, v18
	ds_bpermute_b32 v18, v18, v1
	s_waitcnt lgkmcnt(0)
	v_add_f32_e32 v1, v1, v18
	v_fmamk_f32 v1, v1, 0x3a000000, v165
	v_rsq_f32_e32 v1, v1
	s_nop 0
	v_mul_f32_e32 v18, v32, v1
	v_fma_f32 v18, v70, v18, v36
	v_mul_f32_e32 v32, v33, v1
	v_mul_f32_e32 v33, v34, v1
	v_mul_f32_e32 v34, v35, v1
	v_fma_f32 v32, v71, v32, v37
	v_fmac_f32_e32 v39, v69, v34
	v_bfe_u32 v34, v18, 16, 1
	v_add3_u32 v18, v18, v34, s79
	v_bfe_u32 v34, v32, 16, 1
	v_fma_f32 v33, v68, v33, v38
	v_lshrrev_b32_e32 v18, 16, v18
	v_add3_u32 v32, v32, v34, s79
	v_and_or_b32 v32, v32, s80, v18
	v_bfe_u32 v18, v33, 16, 1
	v_add3_u32 v18, v33, v18, s79
	v_bfe_u32 v33, v39, 16, 1
	v_lshrrev_b32_e32 v18, 16, v18
	v_add3_u32 v33, v39, v33, s79
	v_and_or_b32 v33, v33, s80, v18
	v_mul_f32_e32 v18, v28, v1
	v_fma_f32 v18, v76, v18, v40
	v_mul_f32_e32 v28, v29, v1
	v_mul_f32_e32 v29, v30, v1
	v_mul_f32_e32 v30, v31, v1
	v_fma_f32 v28, v77, v28, v41
	v_fmac_f32_e32 v43, v75, v30
	v_bfe_u32 v30, v18, 16, 1
	v_add3_u32 v18, v18, v30, s79
	v_bfe_u32 v30, v28, 16, 1
	v_fma_f32 v29, v74, v29, v42
	v_lshrrev_b32_e32 v18, 16, v18
	v_add3_u32 v28, v28, v30, s79
	v_and_or_b32 v28, v28, s80, v18
	v_bfe_u32 v18, v29, 16, 1
	v_add3_u32 v18, v29, v18, s79
	v_bfe_u32 v29, v43, 16, 1
	v_lshrrev_b32_e32 v18, 16, v18
	v_add3_u32 v29, v43, v29, s79
	v_and_or_b32 v29, v29, s80, v18
	v_mul_f32_e32 v18, v24, v1
	v_fma_f32 v18, v82, v18, v44
	v_mul_f32_e32 v24, v25, v1
	v_mul_f32_e32 v25, v26, v1
	v_mul_f32_e32 v26, v27, v1
	v_fma_f32 v24, v83, v24, v45
	v_fmac_f32_e32 v47, v79, v26
	v_bfe_u32 v26, v18, 16, 1
	v_add3_u32 v18, v18, v26, s79
	v_bfe_u32 v26, v24, 16, 1
	v_fma_f32 v25, v78, v25, v46
	v_lshrrev_b32_e32 v18, 16, v18
	v_add3_u32 v24, v24, v26, s79
	v_and_or_b32 v24, v24, s80, v18
	v_bfe_u32 v18, v25, 16, 1
	v_add3_u32 v18, v25, v18, s79
	v_bfe_u32 v25, v47, 16, 1
	v_lshrrev_b32_e32 v18, 16, v18
	v_add3_u32 v25, v47, v25, s79
	v_and_or_b32 v25, v25, s80, v18
	v_mul_f32_e32 v18, v20, v1
	v_mul_f32_e32 v14, v14, v1
	v_mul_f32_e32 v10, v10, v1
	v_mul_f32_e32 v6, v6, v1
	v_mul_f32_e32 v2, v2, v1
	v_fma_f32 v18, v84, v18, v48
	v_mul_f32_e32 v20, v21, v1
	v_mul_f32_e32 v21, v22, v1
	v_mul_f32_e32 v22, v23, v1
	v_fma_f32 v14, v88, v14, v52
	v_mul_f32_e32 v15, v15, v1
	v_mul_f32_e32 v16, v16, v1
	v_mul_f32_e32 v17, v17, v1
	v_fma_f32 v10, v92, v10, v56
	v_mul_f32_e32 v11, v11, v1
	v_mul_f32_e32 v12, v12, v1
	v_mul_f32_e32 v13, v13, v1
	v_fma_f32 v6, v96, v6, v60
	v_mul_f32_e32 v7, v7, v1
	v_mul_f32_e32 v8, v8, v1
	v_mul_f32_e32 v9, v9, v1
	s_waitcnt vmcnt(0)
	v_fma_f32 v2, v116, v2, v64
	v_mul_f32_e32 v3, v3, v1
	v_mul_f32_e32 v4, v4, v1
	v_mul_f32_e32 v1, v5, v1
	v_fma_f32 v20, v85, v20, v49
	v_fmac_f32_e32 v51, v81, v22
	v_bfe_u32 v22, v18, 16, 1
	v_fma_f32 v15, v89, v15, v53
	v_fmac_f32_e32 v55, v87, v17
	v_bfe_u32 v17, v14, 16, 1
	v_fma_f32 v11, v93, v11, v57
	v_fmac_f32_e32 v59, v91, v13
	v_bfe_u32 v13, v10, 16, 1
	v_fma_f32 v7, v97, v7, v61
	v_fmac_f32_e32 v63, v95, v9
	v_bfe_u32 v9, v6, 16, 1
	v_fma_f32 v3, v117, v3, v65
	v_fmac_f32_e32 v67, v99, v1
	v_bfe_u32 v1, v2, 16, 1
	v_add3_u32 v18, v18, v22, s79
	v_bfe_u32 v22, v20, 16, 1
	v_add3_u32 v14, v14, v17, s79
	v_bfe_u32 v17, v15, 16, 1
	v_add3_u32 v10, v10, v13, s79
	v_bfe_u32 v13, v11, 16, 1
	v_add3_u32 v6, v6, v9, s79
	v_bfe_u32 v9, v7, 16, 1
	v_add3_u32 v1, v2, v1, s79
	v_bfe_u32 v2, v3, 16, 1
	v_fma_f32 v21, v80, v21, v50
	v_lshrrev_b32_e32 v18, 16, v18
	v_add3_u32 v20, v20, v22, s79
	v_fma_f32 v16, v86, v16, v54
	v_lshrrev_b32_e32 v14, 16, v14
	v_add3_u32 v15, v15, v17, s79
	v_fma_f32 v12, v90, v12, v58
	v_lshrrev_b32_e32 v10, 16, v10
	v_add3_u32 v11, v11, v13, s79
	v_fma_f32 v8, v94, v8, v62
	v_lshrrev_b32_e32 v6, 16, v6
	v_add3_u32 v7, v7, v9, s79
	v_fma_f32 v4, v98, v4, v66
	v_lshrrev_b32_e32 v1, 16, v1
	v_add3_u32 v2, v3, v2, s79
	v_and_or_b32 v20, v20, s80, v18
	v_bfe_u32 v18, v21, 16, 1
	v_and_or_b32 v14, v15, s80, v14
	v_bfe_u32 v15, v16, 16, 1
	v_and_or_b32 v10, v11, s80, v10
	v_bfe_u32 v11, v12, 16, 1
	v_and_or_b32 v6, v7, s80, v6
	v_bfe_u32 v7, v8, 16, 1
	v_and_or_b32 v2, v2, s80, v1
	v_bfe_u32 v1, v4, 16, 1
	v_add3_u32 v18, v21, v18, s79
	v_bfe_u32 v21, v51, 16, 1
	v_add3_u32 v15, v16, v15, s79
	v_bfe_u32 v16, v55, 16, 1
	v_add3_u32 v11, v12, v11, s79
	v_bfe_u32 v12, v59, 16, 1
	v_add3_u32 v7, v8, v7, s79
	v_bfe_u32 v8, v63, 16, 1
	v_add3_u32 v1, v4, v1, s79
	v_bfe_u32 v3, v67, 16, 1
	v_lshrrev_b32_e32 v18, 16, v18
	v_add3_u32 v21, v51, v21, s79
	v_lshrrev_b32_e32 v15, 16, v15
	v_add3_u32 v16, v55, v16, s79
	v_lshrrev_b32_e32 v11, 16, v11
	v_add3_u32 v12, v59, v12, s79
	v_lshrrev_b32_e32 v7, 16, v7
	v_add3_u32 v8, v63, v8, s79
	v_lshrrev_b32_e32 v1, 16, v1
	v_add3_u32 v3, v67, v3, s79
	v_lshl_add_u64 v[34:35], v[112:113], 0, s[6:7]
	v_and_or_b32 v21, v21, s80, v18
	v_and_or_b32 v15, v16, s80, v15
	v_and_or_b32 v11, v12, s80, v11
	v_and_or_b32 v7, v8, s80, v7
	v_and_or_b32 v3, v3, s80, v1
	v_subrev_u32_e32 v248, s30, v34
	v_add_u32_e32 v248, 0xe8400000, v248
	v_and_b32_e32 v249, 0xfff00000, v248
	v_lshrrev_b32_e32 v246, 5, v248
	v_and_b32_e32 v246, 0x7800, v246
	v_or_b32_e32 v249, v249, v246
	v_lshrrev_b32_e32 v246, 6, v248
	v_and_b32_e32 v246, 0x3c0, v246
	v_or_b32_e32 v249, v249, v246
	v_and_b32_e32 v246, 0x180, v248
	v_lshlrev_b32_e32 v246, 8, v246
	v_or_b32_e32 v249, v249, v246
	v_and_b32_e32 v246, 64, v248
	v_lshlrev_b32_e32 v246, 4, v246
	v_or_b32_e32 v249, v249, v246
	v_and_b32_e32 v246, 56, v248
	v_or_b32_e32 v249, v249, v246
	v_lshrrev_b32_e32 v246, 10, v248
	v_and_b32_e32 v246, 32, v246
	v_xor_b32_e32 v249, v249, v246
	v_sub_u32_e32 v246, v249, v248
	v_ashrrev_i32_e32 v247, 31, v246
	v_lshl_add_u64 v[34:35], v[34:35], 0, v[246:247]
	global_store_dwordx2 v[34:35], v[32:33], off
	s_mov_b64 s[100:101], 0x20000
	v_lshl_add_u64 v[248:249], v[34:35], 0, s[100:101]
	global_store_dwordx2 v[248:249], v[28:29], off
	s_mov_b64 s[100:101], 0x40000
	v_lshl_add_u64 v[248:249], v[34:35], 0, s[100:101]
	global_store_dwordx2 v[248:249], v[24:25], off
	s_mov_b64 s[100:101], 0x60000
	v_lshl_add_u64 v[248:249], v[34:35], 0, s[100:101]
	global_store_dwordx2 v[248:249], v[20:21], off
	s_mov_b64 s[100:101], 0x80000
	v_lshl_add_u64 v[248:249], v[34:35], 0, s[100:101]
	global_store_dwordx2 v[248:249], v[14:15], off
	s_mov_b64 s[100:101], 0xa0000
	v_lshl_add_u64 v[248:249], v[34:35], 0, s[100:101]
	global_store_dwordx2 v[248:249], v[10:11], off
	s_mov_b64 s[100:101], 0xc0000
	v_lshl_add_u64 v[248:249], v[34:35], 0, s[100:101]
	global_store_dwordx2 v[248:249], v[6:7], off
	s_mov_b64 s[100:101], 0xe0000
	v_lshl_add_u64 v[248:249], v[34:35], 0, s[100:101]
	global_store_dwordx2 v[248:249], v[2:3], off
	s_cbranch_execnz .LBB0_1689
.LBB0_1693:
	s_ashr_i32 s1, s0, 31
	s_lshl_b64 s[6:7], s[0:1], 13
	s_waitcnt vmcnt(0)
	v_lshl_add_u64 v[2:3], v[114:115], 0, s[6:7]
	s_ashr_i32 s6, s8, 31
	s_add_u32 s7, s8, s24
	s_addc_u32 s6, s6, 0
	s_mul_i32 s6, s6, 0xc000
	s_mul_hi_u32 s8, s7, 0xc000
	v_add_co_u32_e32 v4, vcc, 0x1000, v72
	s_add_i32 s8, s8, s6
	s_mul_i32 s7, s7, 0xc000
	v_addc_co_u32_e32 v5, vcc, 0, v73, vcc
	s_add_u32 s6, s12, s7
	global_load_dwordx4 v[84:87], v[72:73], off
	global_load_dwordx4 v[32:35], v[2:3], off
	global_load_dwordx4 v[76:79], v[72:73], off offset:1024
	global_load_dwordx4 v[28:31], v[2:3], off offset:1024
	global_load_dwordx4 v[68:71], v[72:73], off offset:2048
	global_load_dwordx4 v[24:27], v[2:3], off offset:2048
	global_load_dwordx4 v[56:59], v[72:73], off offset:3072
	global_load_dwordx4 v[20:23], v[2:3], off offset:3072
	v_add_co_u32_e32 v2, vcc, 0x1000, v2
	s_addc_u32 s7, s13, s8
	s_nop 0
	v_addc_co_u32_e32 v3, vcc, 0, v3, vcc
	v_lshl_add_u64 v[98:99], s[6:7], 0, v[100:101]
	v_add_co_u32_e32 v96, vcc, s78, v98
	global_load_dwordx4 v[48:51], v[4:5], off
	s_nop 0
	v_addc_co_u32_e32 v97, vcc, 0, v99, vcc
	global_load_dwordx4 v[14:17], v[2:3], off
	global_load_dwordx4 v[44:47], v[4:5], off offset:1024
	global_load_dwordx4 v[10:13], v[2:3], off offset:1024
	global_load_dwordx4 v[40:43], v[4:5], off offset:2048
	global_load_dwordx4 v[6:9], v[2:3], off offset:2048
	global_load_dwordx4 v[36:39], v[4:5], off offset:3072
	s_nop 0
	global_load_dwordx4 v[2:5], v[2:3], off offset:3072
	s_mov_b64 s[6:7], 0x2000
	global_load_dwordx4 v[60:63], v[102:103], off
	global_load_dwordx4 v[64:67], v[96:97], off offset:-4096
	global_load_dwordx4 v[52:55], v[98:99], off
	v_lshl_add_u64 v[88:89], v[98:99], 0, s[6:7]
	s_lshl_b64 s[6:7], s[4:5], 12
	s_lshl_b64 s[0:1], s[0:1], 12
	s_waitcnt vmcnt(18)
	v_mul_f32_e32 v1, v85, v85
	v_mul_f32_e32 v18, v87, v87
	v_fmac_f32_e32 v1, v84, v84
	v_fmac_f32_e32 v18, v86, v86
	v_add_f32_e32 v1, v1, v18
	s_waitcnt vmcnt(16)
	v_mul_f32_e32 v18, v77, v77
	v_fmac_f32_e32 v18, v76, v76
	s_waitcnt vmcnt(1)
	v_pk_add_f32 v[66:67], v[66:67], 1.0 op_sel_hi:[1,0]
	v_pk_add_f32 v[64:65], v[64:65], 1.0 op_sel_hi:[1,0]
	v_pk_mul_f32 v[116:117], v[62:63], v[66:67]
	v_pk_mul_f32 v[118:119], v[60:61], v[64:65]
	global_load_dwordx4 v[64:67], v[102:103], off offset:1024
	global_load_dwordx4 v[72:75], v[88:89], off offset:1024
	global_load_dwordx4 v[60:63], v[98:99], off offset:1024
	s_waitcnt vmcnt(1)
	v_pk_add_f32 v[74:75], v[74:75], 1.0 op_sel_hi:[1,0]
	v_pk_add_f32 v[72:73], v[72:73], 1.0 op_sel_hi:[1,0]
	v_pk_mul_f32 v[120:121], v[66:67], v[74:75]
	v_pk_mul_f32 v[122:123], v[64:65], v[72:73]
	global_load_dwordx4 v[72:75], v[102:103], off offset:2048
	global_load_dwordx4 v[80:83], v[88:89], off offset:2048
	global_load_dwordx4 v[64:67], v[98:99], off offset:2048
	s_waitcnt vmcnt(1)
	v_pk_add_f32 v[82:83], v[82:83], 1.0 op_sel_hi:[1,0]
	v_pk_add_f32 v[80:81], v[80:81], 1.0 op_sel_hi:[1,0]
	v_pk_mul_f32 v[124:125], v[74:75], v[82:83]
	v_pk_mul_f32 v[126:127], v[72:73], v[80:81]
	global_load_dwordx4 v[80:83], v[102:103], off offset:3072
	s_nop 0
	global_load_dwordx4 v[88:91], v[88:89], off offset:3072
	s_nop 0
	global_load_dwordx4 v[72:75], v[98:99], off offset:3072
	v_add_co_u32_e32 v98, vcc, s3, v98
	s_waitcnt vmcnt(1)
	v_pk_add_f32 v[90:91], v[90:91], 1.0 op_sel_hi:[1,0]
	v_pk_add_f32 v[88:89], v[88:89], 1.0 op_sel_hi:[1,0]
	v_pk_mul_f32 v[128:129], v[82:83], v[90:91]
	v_pk_mul_f32 v[130:131], v[80:81], v[88:89]
	global_load_dwordx4 v[88:91], v[104:105], off
	global_load_dwordx4 v[92:95], v[96:97], off
	v_addc_co_u32_e32 v99, vcc, 0, v99, vcc
	global_load_dwordx4 v[80:83], v[98:99], off
	s_waitcnt vmcnt(1)
	v_pk_add_f32 v[94:95], v[94:95], 1.0 op_sel_hi:[1,0]
	v_pk_add_f32 v[92:93], v[92:93], 1.0 op_sel_hi:[1,0]
	v_pk_mul_f32 v[132:133], v[90:91], v[94:95]
	v_pk_mul_f32 v[134:135], v[88:89], v[92:93]
	global_load_dwordx4 v[92:95], v[106:107], off
	global_load_dwordx4 v[136:139], v[96:97], off offset:1024
	global_load_dwordx4 v[88:91], v[98:99], off offset:1024
	s_waitcnt vmcnt(1)
	v_pk_add_f32 v[138:139], v[138:139], 1.0 op_sel_hi:[1,0]
	v_pk_add_f32 v[140:141], v[136:137], 1.0 op_sel_hi:[1,0]
	v_pk_mul_f32 v[136:137], v[94:95], v[138:139]
	v_pk_mul_f32 v[138:139], v[92:93], v[140:141]
	global_load_dwordx4 v[142:145], v[108:109], off
	global_load_dwordx4 v[146:149], v[96:97], off offset:2048
	global_load_dwordx4 v[92:95], v[98:99], off offset:2048
	s_waitcnt vmcnt(1)
	v_pk_add_f32 v[146:147], v[146:147], 1.0 op_sel_hi:[1,0]
	v_pk_add_f32 v[140:141], v[148:149], 1.0 op_sel_hi:[1,0]
	v_pk_mul_f32 v[142:143], v[142:143], v[146:147]
	global_load_dwordx4 v[146:149], v[110:111], off
	global_load_dwordx4 v[150:153], v[96:97], off offset:3072
	s_nop 0
	global_load_dwordx4 v[96:99], v[98:99], off offset:3072
	v_pk_mul_f32 v[140:141], v[144:145], v[140:141]
	s_waitcnt vmcnt(1)
	v_pk_add_f32 v[144:145], v[152:153], 1.0 op_sel_hi:[1,0]
	s_nop 0
	v_pk_mul_f32 v[144:145], v[148:149], v[144:145]
	v_mul_f32_e32 v148, v79, v79
	v_fmac_f32_e32 v148, v78, v78
	v_add_f32_e32 v18, v18, v148
	v_add_f32_e32 v1, v1, v18
	v_mul_f32_e32 v18, v69, v69
	v_mul_f32_e32 v148, v71, v71
	v_fmac_f32_e32 v18, v68, v68
	v_fmac_f32_e32 v148, v70, v70
	v_add_f32_e32 v18, v18, v148
	v_add_f32_e32 v1, v1, v18
	v_mul_f32_e32 v18, v57, v57
	v_mul_f32_e32 v148, v59, v59
	v_fmac_f32_e32 v18, v56, v56
	v_fmac_f32_e32 v148, v58, v58
	v_add_f32_e32 v18, v18, v148
	v_add_f32_e32 v1, v1, v18
	v_mul_f32_e32 v18, v49, v49
	v_mul_f32_e32 v148, v51, v51
	v_fmac_f32_e32 v18, v48, v48
	v_fmac_f32_e32 v148, v50, v50
	v_add_f32_e32 v18, v18, v148
	v_add_f32_e32 v1, v1, v18
	v_mul_f32_e32 v18, v45, v45
	v_mul_f32_e32 v148, v47, v47
	v_fmac_f32_e32 v18, v44, v44
	v_fmac_f32_e32 v148, v46, v46
	v_add_f32_e32 v18, v18, v148
	v_add_f32_e32 v1, v1, v18
	v_mul_f32_e32 v18, v41, v41
	v_mul_f32_e32 v148, v43, v43
	v_fmac_f32_e32 v18, v40, v40
	v_fmac_f32_e32 v148, v42, v42
	v_add_f32_e32 v18, v18, v148
	v_add_f32_e32 v1, v1, v18
	v_mul_f32_e32 v18, v37, v37
	v_mul_f32_e32 v148, v39, v39
	v_fmac_f32_e32 v18, v36, v36
	v_fmac_f32_e32 v148, v38, v38
	v_add_f32_e32 v18, v18, v148
	v_add_f32_e32 v1, v1, v18
	v_mul_f32_e32 v18, v33, v33
	v_mul_f32_e32 v148, v35, v35
	v_fmac_f32_e32 v18, v32, v32
	v_fmac_f32_e32 v148, v34, v34
	v_add_f32_e32 v18, v18, v148
	v_mul_f32_e32 v148, v29, v29
	v_mul_f32_e32 v149, v31, v31
	v_fmac_f32_e32 v148, v28, v28
	v_fmac_f32_e32 v149, v30, v30
	v_add_f32_e32 v148, v148, v149
	v_add_f32_e32 v18, v18, v148
	v_mul_f32_e32 v148, v25, v25
	v_mul_f32_e32 v149, v27, v27
	v_fmac_f32_e32 v148, v24, v24
	v_fmac_f32_e32 v149, v26, v26
	v_add_f32_e32 v148, v148, v149
	v_add_f32_e32 v18, v18, v148
	v_mul_f32_e32 v148, v21, v21
	v_mul_f32_e32 v149, v23, v23
	v_fmac_f32_e32 v148, v20, v20
	v_fmac_f32_e32 v149, v22, v22
	v_add_f32_e32 v148, v148, v149
	v_add_f32_e32 v18, v18, v148
	v_mul_f32_e32 v148, v15, v15
	v_mul_f32_e32 v149, v17, v17
	v_fmac_f32_e32 v148, v14, v14
	v_fmac_f32_e32 v149, v16, v16
	v_add_f32_e32 v148, v148, v149
	v_add_f32_e32 v18, v18, v148
	v_mul_f32_e32 v148, v11, v11
	v_mul_f32_e32 v149, v13, v13
	v_fmac_f32_e32 v148, v10, v10
	v_fmac_f32_e32 v149, v12, v12
	v_add_f32_e32 v148, v148, v149
	v_add_f32_e32 v18, v18, v148
	v_mul_f32_e32 v148, v7, v7
	v_mul_f32_e32 v149, v9, v9
	v_fmac_f32_e32 v148, v6, v6
	v_fmac_f32_e32 v149, v8, v8
	v_add_f32_e32 v148, v148, v149
	v_add_f32_e32 v18, v18, v148
	v_mul_f32_e32 v148, v3, v3
	v_mul_f32_e32 v149, v5, v5
	v_fmac_f32_e32 v148, v2, v2
	v_fmac_f32_e32 v149, v4, v4
	v_add_f32_e32 v148, v148, v149
	v_add_f32_e32 v18, v18, v148
	v_and_b32_e32 v148, 64, v213
	v_add_u32_e32 v148, 64, v148
	v_xor_b32_e32 v149, 1, v213
	v_cmp_lt_i32_e32 vcc, v149, v148
	v_pk_add_f32 v[150:151], v[150:151], 1.0 op_sel_hi:[1,0]
	s_nop 0
	v_cndmask_b32_e32 v149, v213, v149, vcc
	v_lshlrev_b32_e32 v149, 2, v149
	v_pk_mul_f32 v[146:147], v[146:147], v[150:151]
	ds_bpermute_b32 v150, v149, v1
	ds_bpermute_b32 v149, v149, v18
	s_waitcnt lgkmcnt(1)
	v_add_f32_e32 v1, v1, v150
	s_waitcnt lgkmcnt(0)
	v_add_f32_e32 v18, v18, v149
	v_xor_b32_e32 v149, 2, v213
	v_cmp_lt_i32_e32 vcc, v149, v148
	s_nop 1
	v_cndmask_b32_e32 v149, v213, v149, vcc
	v_lshlrev_b32_e32 v149, 2, v149
	ds_bpermute_b32 v150, v149, v1
	ds_bpermute_b32 v149, v149, v18
	s_waitcnt lgkmcnt(1)
	v_add_f32_e32 v1, v1, v150
	s_waitcnt lgkmcnt(0)
	v_add_f32_e32 v18, v18, v149
	v_xor_b32_e32 v149, 4, v213
	v_cmp_lt_i32_e32 vcc, v149, v148
	s_nop 1
	v_cndmask_b32_e32 v149, v213, v149, vcc
	v_lshlrev_b32_e32 v149, 2, v149
	ds_bpermute_b32 v150, v149, v1
	ds_bpermute_b32 v149, v149, v18
	s_waitcnt lgkmcnt(1)
	v_add_f32_e32 v1, v1, v150
	s_waitcnt lgkmcnt(0)
	v_add_f32_e32 v18, v18, v149
	v_xor_b32_e32 v149, 8, v213
	v_cmp_lt_i32_e32 vcc, v149, v148
	s_nop 1
	v_cndmask_b32_e32 v149, v213, v149, vcc
	v_lshlrev_b32_e32 v149, 2, v149
	ds_bpermute_b32 v150, v149, v1
	ds_bpermute_b32 v149, v149, v18
	s_waitcnt lgkmcnt(1)
	v_add_f32_e32 v1, v1, v150
	s_waitcnt lgkmcnt(0)
	v_add_f32_e32 v18, v18, v149
	v_xor_b32_e32 v149, 16, v213
	v_cmp_lt_i32_e32 vcc, v149, v148
	s_nop 1
	v_cndmask_b32_e32 v149, v213, v149, vcc
	v_lshlrev_b32_e32 v149, 2, v149
	ds_bpermute_b32 v150, v149, v1
	ds_bpermute_b32 v149, v149, v18
	s_waitcnt lgkmcnt(1)
	v_add_f32_e32 v1, v1, v150
	s_waitcnt lgkmcnt(0)
	v_add_f32_e32 v18, v18, v149
	v_xor_b32_e32 v149, 32, v213
	v_cmp_lt_i32_e32 vcc, v149, v148
	s_nop 1
	v_cndmask_b32_e32 v148, v213, v149, vcc
	v_lshlrev_b32_e32 v148, 2, v148
	ds_bpermute_b32 v149, v148, v1
	ds_bpermute_b32 v148, v148, v18
	s_waitcnt lgkmcnt(1)
	v_add_f32_e32 v1, v1, v149
	v_fmamk_f32 v1, v1, 0x3a000000, v165
	v_rsq_f32_e32 v1, v1
	s_waitcnt lgkmcnt(0)
	v_add_f32_e32 v18, v18, v148
	v_mul_f32_e32 v84, v84, v1
	v_fma_f32 v84, v118, v84, v52
	v_mul_f32_e32 v85, v85, v1
	v_fma_f32 v85, v119, v85, v53
	v_bfe_u32 v148, v84, 16, 1
	v_mul_f32_e32 v86, v86, v1
	v_add3_u32 v84, v84, v148, s79
	v_bfe_u32 v148, v85, 16, 1
	v_fma_f32 v86, v116, v86, v54
	v_mul_f32_e32 v87, v87, v1
	v_lshrrev_b32_e32 v84, 16, v84
	v_add3_u32 v85, v85, v148, s79
	v_fma_f32 v87, v117, v87, v55
	v_and_or_b32 v84, v85, s80, v84
	v_bfe_u32 v85, v86, 16, 1
	v_mul_f32_e32 v36, v36, v1
	v_add3_u32 v85, v86, v85, s79
	v_bfe_u32 v86, v87, 16, 1
	s_waitcnt vmcnt(0)
	v_fma_f32 v36, v146, v36, v96
	v_mul_f32_e32 v37, v37, v1
	v_lshrrev_b32_e32 v85, 16, v85
	v_add3_u32 v86, v87, v86, s79
	v_mul_f32_e32 v76, v76, v1
	v_mul_f32_e32 v77, v77, v1
	v_mul_f32_e32 v78, v78, v1
	v_mul_f32_e32 v79, v79, v1
	v_mul_f32_e32 v68, v68, v1
	v_mul_f32_e32 v69, v69, v1
	v_mul_f32_e32 v70, v70, v1
	v_mul_f32_e32 v71, v71, v1
	v_mul_f32_e32 v56, v56, v1
	v_mul_f32_e32 v57, v57, v1
	v_mul_f32_e32 v58, v58, v1
	v_mul_f32_e32 v59, v59, v1
	v_mul_f32_e32 v48, v48, v1
	v_mul_f32_e32 v49, v49, v1
	v_mul_f32_e32 v50, v50, v1
	v_mul_f32_e32 v51, v51, v1
	v_mul_f32_e32 v44, v44, v1
	v_mul_f32_e32 v45, v45, v1
	v_mul_f32_e32 v46, v46, v1
	v_mul_f32_e32 v47, v47, v1
	v_mul_f32_e32 v40, v40, v1
	v_mul_f32_e32 v41, v41, v1
	v_mul_f32_e32 v42, v42, v1
	v_mul_f32_e32 v43, v43, v1
	v_fma_f32 v37, v147, v37, v97
	v_mul_f32_e32 v38, v38, v1
	v_mul_f32_e32 v1, v39, v1
	v_bfe_u32 v39, v36, 16, 1
	v_and_or_b32 v85, v86, s80, v85
	v_lshl_add_u64 v[86:87], v[112:113], 0, s[6:7]
	v_fma_f32 v76, v122, v76, v60
	v_add3_u32 v36, v36, v39, s79
	v_bfe_u32 v39, v37, 16, 1
	v_subrev_u32_e32 v248, s30, v86
	v_add_u32_e32 v248, 0xe8400000, v248
	v_and_b32_e32 v249, 0xfff00000, v248
	v_lshrrev_b32_e32 v246, 5, v248
	v_and_b32_e32 v246, 0x7800, v246
	v_or_b32_e32 v249, v249, v246
	v_lshrrev_b32_e32 v246, 6, v248
	v_and_b32_e32 v246, 0x3c0, v246
	v_or_b32_e32 v249, v249, v246
	v_and_b32_e32 v246, 0x180, v248
	v_lshlrev_b32_e32 v246, 8, v246
	v_or_b32_e32 v249, v249, v246
	v_and_b32_e32 v246, 64, v248
	v_lshlrev_b32_e32 v246, 4, v246
	v_or_b32_e32 v249, v249, v246
	v_and_b32_e32 v246, 56, v248
	v_or_b32_e32 v249, v249, v246
	v_lshrrev_b32_e32 v246, 10, v248
	v_and_b32_e32 v246, 32, v246
	v_xor_b32_e32 v249, v249, v246
	v_sub_u32_e32 v246, v249, v248
	v_ashrrev_i32_e32 v247, 31, v246
	v_lshl_add_u64 v[86:87], v[86:87], 0, v[246:247]
	global_store_dwordx2 v[86:87], v[84:85], off
	v_fma_f32 v77, v123, v77, v61
	v_bfe_u32 v84, v76, 16, 1
	v_fma_f32 v38, v144, v38, v98
	v_lshrrev_b32_e32 v36, 16, v36
	v_add3_u32 v37, v37, v39, s79
	v_add3_u32 v76, v76, v84, s79
	v_bfe_u32 v84, v77, 16, 1
	v_fma_f32 v1, v145, v1, v99
	v_and_or_b32 v36, v37, s80, v36
	v_bfe_u32 v37, v38, 16, 1
	v_fma_f32 v78, v120, v78, v62
	v_lshrrev_b32_e32 v76, 16, v76
	v_add3_u32 v77, v77, v84, s79
	v_add3_u32 v37, v38, v37, s79
	v_bfe_u32 v38, v1, 16, 1
	v_fma_f32 v79, v121, v79, v63
	v_and_or_b32 v76, v77, s80, v76
	v_bfe_u32 v77, v78, 16, 1
	v_lshrrev_b32_e32 v37, 16, v37
	v_add3_u32 v1, v1, v38, s79
	v_add3_u32 v77, v78, v77, s79
	v_bfe_u32 v78, v79, 16, 1
	v_and_or_b32 v37, v1, s80, v37
	v_fmamk_f32 v1, v18, 0x3a000000, v165
	v_lshrrev_b32_e32 v77, 16, v77
	v_add3_u32 v78, v79, v78, s79
	v_rsq_f32_e32 v1, v1
	v_and_or_b32 v77, v78, s80, v77
	v_fma_f32 v68, v126, v68, v64
	s_mov_b64 s[100:101], 0x20000
	v_lshl_add_u64 v[248:249], v[86:87], 0, s[100:101]
	global_store_dwordx2 v[248:249], v[76:77], off
	v_fma_f32 v69, v127, v69, v65
	v_bfe_u32 v76, v68, 16, 1
	v_add3_u32 v68, v68, v76, s79
	v_bfe_u32 v76, v69, 16, 1
	v_fma_f32 v70, v124, v70, v66
	v_lshrrev_b32_e32 v68, 16, v68
	v_add3_u32 v69, v69, v76, s79
	v_mul_f32_e32 v18, v32, v1
	v_fma_f32 v71, v125, v71, v67
	v_and_or_b32 v68, v69, s80, v68
	v_bfe_u32 v69, v70, 16, 1
	v_fma_f32 v18, v118, v18, v52
	v_mul_f32_e32 v32, v33, v1
	v_mul_f32_e32 v33, v34, v1
	v_mul_f32_e32 v34, v35, v1
	v_add3_u32 v69, v70, v69, s79
	v_bfe_u32 v70, v71, 16, 1
	v_fma_f32 v32, v119, v32, v53
	v_fmac_f32_e32 v55, v117, v34
	v_bfe_u32 v34, v18, 16, 1
	v_lshrrev_b32_e32 v69, 16, v69
	v_add3_u32 v70, v71, v70, s79
	v_add3_u32 v18, v18, v34, s79
	v_bfe_u32 v34, v32, 16, 1
	v_and_or_b32 v69, v70, s80, v69
	v_fma_f32 v56, v130, v56, v72
	v_fma_f32 v33, v116, v33, v54
	v_lshrrev_b32_e32 v18, 16, v18
	v_add3_u32 v32, v32, v34, s79
	s_mov_b64 s[100:101], 0x40000
	v_lshl_add_u64 v[248:249], v[86:87], 0, s[100:101]
	global_store_dwordx2 v[248:249], v[68:69], off
	v_fma_f32 v57, v131, v57, v73
	v_bfe_u32 v68, v56, 16, 1
	v_and_or_b32 v32, v32, s80, v18
	v_bfe_u32 v18, v33, 16, 1
	v_add3_u32 v56, v56, v68, s79
	v_bfe_u32 v68, v57, 16, 1
	v_add3_u32 v18, v33, v18, s79
	v_bfe_u32 v33, v55, 16, 1
	v_fma_f32 v58, v128, v58, v74
	v_lshrrev_b32_e32 v56, 16, v56
	v_add3_u32 v57, v57, v68, s79
	v_lshrrev_b32_e32 v18, 16, v18
	v_add3_u32 v33, v55, v33, s79
	v_fma_f32 v59, v129, v59, v75
	v_and_or_b32 v56, v57, s80, v56
	v_bfe_u32 v57, v58, 16, 1
	v_and_or_b32 v33, v33, s80, v18
	v_mul_f32_e32 v18, v28, v1
	v_add3_u32 v57, v58, v57, s79
	v_bfe_u32 v58, v59, 16, 1
	v_fma_f32 v18, v122, v18, v60
	v_mul_f32_e32 v28, v29, v1
	v_mul_f32_e32 v29, v30, v1
	v_mul_f32_e32 v30, v31, v1
	v_lshrrev_b32_e32 v57, 16, v57
	v_add3_u32 v58, v59, v58, s79
	v_fma_f32 v28, v123, v28, v61
	v_fmac_f32_e32 v63, v121, v30
	v_bfe_u32 v30, v18, 16, 1
	v_and_or_b32 v57, v58, s80, v57
	v_fma_f32 v48, v134, v48, v80
	v_add3_u32 v18, v18, v30, s79
	v_bfe_u32 v30, v28, 16, 1
	s_mov_b64 s[100:101], 0x60000
	v_lshl_add_u64 v[248:249], v[86:87], 0, s[100:101]
	global_store_dwordx2 v[248:249], v[56:57], off
	v_fma_f32 v49, v135, v49, v81
	v_bfe_u32 v56, v48, 16, 1
	v_fma_f32 v29, v120, v29, v62
	v_lshrrev_b32_e32 v18, 16, v18
	v_add3_u32 v28, v28, v30, s79
	v_add3_u32 v48, v48, v56, s79
	v_bfe_u32 v56, v49, 16, 1
	v_and_or_b32 v28, v28, s80, v18
	v_bfe_u32 v18, v29, 16, 1
	v_fma_f32 v50, v132, v50, v82
	v_lshrrev_b32_e32 v48, 16, v48
	v_add3_u32 v49, v49, v56, s79
	v_add3_u32 v18, v29, v18, s79
	v_bfe_u32 v29, v63, 16, 1
	v_fma_f32 v51, v133, v51, v83
	v_and_or_b32 v48, v49, s80, v48
	v_bfe_u32 v49, v50, 16, 1
	v_lshrrev_b32_e32 v18, 16, v18
	v_add3_u32 v29, v63, v29, s79
	v_add3_u32 v49, v50, v49, s79
	v_bfe_u32 v50, v51, 16, 1
	v_and_or_b32 v29, v29, s80, v18
	v_mul_f32_e32 v18, v24, v1
	v_lshrrev_b32_e32 v49, 16, v49
	v_add3_u32 v50, v51, v50, s79
	v_fma_f32 v18, v126, v18, v64
	v_mul_f32_e32 v24, v25, v1
	v_mul_f32_e32 v25, v26, v1
	v_mul_f32_e32 v26, v27, v1
	v_and_or_b32 v49, v50, s80, v49
	v_fma_f32 v44, v138, v44, v88
	v_fma_f32 v24, v127, v24, v65
	v_fmac_f32_e32 v67, v125, v26
	v_bfe_u32 v26, v18, 16, 1
	s_mov_b64 s[100:101], 0x80000
	v_lshl_add_u64 v[248:249], v[86:87], 0, s[100:101]
	global_store_dwordx2 v[248:249], v[48:49], off
	v_fma_f32 v45, v139, v45, v89
	v_bfe_u32 v48, v44, 16, 1
	v_add3_u32 v18, v18, v26, s79
	v_bfe_u32 v26, v24, 16, 1
	v_add3_u32 v44, v44, v48, s79
	v_bfe_u32 v48, v45, 16, 1
	v_fma_f32 v25, v124, v25, v66
	v_lshrrev_b32_e32 v18, 16, v18
	v_add3_u32 v24, v24, v26, s79
	v_fma_f32 v46, v136, v46, v90
	v_lshrrev_b32_e32 v44, 16, v44
	v_add3_u32 v45, v45, v48, s79
	v_and_or_b32 v24, v24, s80, v18
	v_bfe_u32 v18, v25, 16, 1
	v_fma_f32 v47, v137, v47, v91
	v_and_or_b32 v44, v45, s80, v44
	v_bfe_u32 v45, v46, 16, 1
	v_add3_u32 v18, v25, v18, s79
	v_bfe_u32 v25, v67, 16, 1
	v_add3_u32 v45, v46, v45, s79
	v_bfe_u32 v46, v47, 16, 1
	v_lshrrev_b32_e32 v18, 16, v18
	v_add3_u32 v25, v67, v25, s79
	v_lshrrev_b32_e32 v45, 16, v45
	v_add3_u32 v46, v47, v46, s79
	v_and_or_b32 v25, v25, s80, v18
	v_mul_f32_e32 v18, v20, v1
	v_mul_f32_e32 v14, v14, v1
	v_mul_f32_e32 v10, v10, v1
	v_mul_f32_e32 v6, v6, v1
	v_mul_f32_e32 v2, v2, v1
	v_and_or_b32 v45, v46, s80, v45
	v_fma_f32 v40, v142, v40, v92
	v_fma_f32 v18, v130, v18, v72
	v_mul_f32_e32 v20, v21, v1
	v_mul_f32_e32 v21, v22, v1
	v_mul_f32_e32 v22, v23, v1
	v_fma_f32 v14, v134, v14, v80
	v_mul_f32_e32 v15, v15, v1
	v_mul_f32_e32 v16, v16, v1
	v_mul_f32_e32 v17, v17, v1
	v_fma_f32 v10, v138, v10, v88
	v_mul_f32_e32 v11, v11, v1
	v_mul_f32_e32 v12, v12, v1
	v_mul_f32_e32 v13, v13, v1
	v_fma_f32 v6, v142, v6, v92
	v_mul_f32_e32 v7, v7, v1
	v_mul_f32_e32 v8, v8, v1
	v_mul_f32_e32 v9, v9, v1
	v_fma_f32 v2, v146, v2, v96
	v_mul_f32_e32 v3, v3, v1
	v_mul_f32_e32 v4, v4, v1
	v_mul_f32_e32 v1, v5, v1
	s_mov_b64 s[100:101], 0xa0000
	v_lshl_add_u64 v[248:249], v[86:87], 0, s[100:101]
	global_store_dwordx2 v[248:249], v[44:45], off
	v_fma_f32 v41, v143, v41, v93
	v_fma_f32 v43, v141, v43, v95
	v_bfe_u32 v44, v40, 16, 1
	v_fma_f32 v20, v131, v20, v73
	v_fmac_f32_e32 v75, v129, v22
	v_bfe_u32 v22, v18, 16, 1
	v_fma_f32 v15, v135, v15, v81
	v_fmac_f32_e32 v83, v133, v17
	v_bfe_u32 v17, v14, 16, 1
	v_fma_f32 v11, v139, v11, v89
	v_fmac_f32_e32 v91, v137, v13
	v_bfe_u32 v13, v10, 16, 1
	v_fma_f32 v7, v143, v7, v93
	v_fmac_f32_e32 v95, v141, v9
	v_bfe_u32 v9, v6, 16, 1
	v_fma_f32 v3, v147, v3, v97
	v_fmac_f32_e32 v99, v145, v1
	v_bfe_u32 v1, v2, 16, 1
	v_add3_u32 v40, v40, v44, s79
	v_bfe_u32 v44, v41, 16, 1
	v_add3_u32 v18, v18, v22, s79
	v_bfe_u32 v22, v20, 16, 1
	v_add3_u32 v14, v14, v17, s79
	v_bfe_u32 v17, v15, 16, 1
	v_add3_u32 v10, v10, v13, s79
	v_bfe_u32 v13, v11, 16, 1
	v_add3_u32 v6, v6, v9, s79
	v_bfe_u32 v9, v7, 16, 1
	v_add3_u32 v1, v2, v1, s79
	v_bfe_u32 v2, v3, 16, 1
	v_fma_f32 v42, v140, v42, v94
	v_lshrrev_b32_e32 v40, 16, v40
	v_add3_u32 v41, v41, v44, s79
	v_fma_f32 v21, v128, v21, v74
	v_lshrrev_b32_e32 v18, 16, v18
	v_add3_u32 v20, v20, v22, s79
	v_fma_f32 v16, v132, v16, v82
	v_lshrrev_b32_e32 v14, 16, v14
	v_add3_u32 v15, v15, v17, s79
	v_fma_f32 v12, v136, v12, v90
	v_lshrrev_b32_e32 v10, 16, v10
	v_add3_u32 v11, v11, v13, s79
	v_fma_f32 v8, v140, v8, v94
	v_lshrrev_b32_e32 v6, 16, v6
	v_add3_u32 v7, v7, v9, s79
	v_fma_f32 v4, v144, v4, v98
	v_lshrrev_b32_e32 v1, 16, v1
	v_add3_u32 v2, v3, v2, s79
	v_and_or_b32 v40, v41, s80, v40
	v_bfe_u32 v41, v42, 16, 1
	v_and_or_b32 v20, v20, s80, v18
	v_bfe_u32 v18, v21, 16, 1
	v_and_or_b32 v14, v15, s80, v14
	v_bfe_u32 v15, v16, 16, 1
	v_and_or_b32 v10, v11, s80, v10
	v_bfe_u32 v11, v12, 16, 1
	v_and_or_b32 v6, v7, s80, v6
	v_bfe_u32 v7, v8, 16, 1
	v_and_or_b32 v2, v2, s80, v1
	v_bfe_u32 v1, v4, 16, 1
	v_add3_u32 v41, v42, v41, s79
	v_bfe_u32 v42, v43, 16, 1
	v_add3_u32 v18, v21, v18, s79
	v_bfe_u32 v21, v75, 16, 1
	v_add3_u32 v15, v16, v15, s79
	v_bfe_u32 v16, v83, 16, 1
	v_add3_u32 v11, v12, v11, s79
	v_bfe_u32 v12, v91, 16, 1
	v_add3_u32 v7, v8, v7, s79
	v_bfe_u32 v8, v95, 16, 1
	v_add3_u32 v1, v4, v1, s79
	v_bfe_u32 v3, v99, 16, 1
	v_lshrrev_b32_e32 v41, 16, v41
	v_add3_u32 v42, v43, v42, s79
	v_lshl_add_u64 v[34:35], v[112:113], 0, s[0:1]
	v_lshrrev_b32_e32 v18, 16, v18
	v_add3_u32 v21, v75, v21, s79
	v_lshrrev_b32_e32 v15, 16, v15
	v_add3_u32 v16, v83, v16, s79
	v_lshrrev_b32_e32 v11, 16, v11
	v_add3_u32 v12, v91, v12, s79
	v_lshrrev_b32_e32 v7, 16, v7
	v_add3_u32 v8, v95, v8, s79
	v_lshrrev_b32_e32 v1, 16, v1
	v_add3_u32 v3, v99, v3, s79
	v_readlane_b32 s0, v251, 24
	v_and_or_b32 v41, v42, s80, v41
	v_and_or_b32 v21, v21, s80, v18
	v_and_or_b32 v15, v16, s80, v15
	v_and_or_b32 v11, v12, s80, v11
	v_and_or_b32 v7, v8, s80, v7
	v_and_or_b32 v3, v3, s80, v1
	s_add_i32 s0, s0, s4
	s_mov_b64 s[100:101], 0xc0000
	v_lshl_add_u64 v[248:249], v[86:87], 0, s[100:101]
	global_store_dwordx2 v[248:249], v[40:41], off
	s_mov_b64 s[100:101], 0xe0000
	v_lshl_add_u64 v[248:249], v[86:87], 0, s[100:101]
	global_store_dwordx2 v[248:249], v[36:37], off
	v_subrev_u32_e32 v248, s30, v34
	v_add_u32_e32 v248, 0xe8400000, v248
	v_and_b32_e32 v249, 0xfff00000, v248
	v_lshrrev_b32_e32 v246, 5, v248
	v_and_b32_e32 v246, 0x7800, v246
	v_or_b32_e32 v249, v249, v246
	v_lshrrev_b32_e32 v246, 6, v248
	v_and_b32_e32 v246, 0x3c0, v246
	v_or_b32_e32 v249, v249, v246
	v_and_b32_e32 v246, 0x180, v248
	v_lshlrev_b32_e32 v246, 8, v246
	v_or_b32_e32 v249, v249, v246
	v_and_b32_e32 v246, 64, v248
	v_lshlrev_b32_e32 v246, 4, v246
	v_or_b32_e32 v249, v249, v246
	v_and_b32_e32 v246, 56, v248
	v_or_b32_e32 v249, v249, v246
	v_lshrrev_b32_e32 v246, 10, v248
	v_and_b32_e32 v246, 32, v246
	v_xor_b32_e32 v249, v249, v246
	v_sub_u32_e32 v246, v249, v248
	v_ashrrev_i32_e32 v247, 31, v246
	v_lshl_add_u64 v[34:35], v[34:35], 0, v[246:247]
	global_store_dwordx2 v[34:35], v[32:33], off
	s_mov_b64 s[100:101], 0x20000
	v_lshl_add_u64 v[248:249], v[34:35], 0, s[100:101]
	global_store_dwordx2 v[248:249], v[28:29], off
	s_mov_b64 s[100:101], 0x40000
	v_lshl_add_u64 v[248:249], v[34:35], 0, s[100:101]
	global_store_dwordx2 v[248:249], v[24:25], off
	s_mov_b64 s[100:101], 0x60000
	v_lshl_add_u64 v[248:249], v[34:35], 0, s[100:101]
	global_store_dwordx2 v[248:249], v[20:21], off
	s_mov_b64 s[100:101], 0x80000
	v_lshl_add_u64 v[248:249], v[34:35], 0, s[100:101]
	global_store_dwordx2 v[248:249], v[14:15], off
	s_mov_b64 s[100:101], 0xa0000
	v_lshl_add_u64 v[248:249], v[34:35], 0, s[100:101]
	global_store_dwordx2 v[248:249], v[10:11], off
	s_mov_b64 s[100:101], 0xc0000
	v_lshl_add_u64 v[248:249], v[34:35], 0, s[100:101]
	global_store_dwordx2 v[248:249], v[6:7], off
	s_mov_b64 s[100:101], 0xe0000
	v_lshl_add_u64 v[248:249], v[34:35], 0, s[100:101]
	global_store_dwordx2 v[248:249], v[2:3], off
	s_branch .LBB0_1689

.LBB0_1751:
	s_andn2_b64 vcc, exec, s[4:5]
	s_cbranch_vccnz .LBB0_1750
	v_readlane_b32 s42, v250, 6
	v_mov_b32_e32 v146, v164
	v_readlane_b32 s0, v250, 14
	v_mov_b32_e32 v1, v0
	s_mov_b64 s[0:1], s[30:31]
	s_mov_b64 s[0:1], s[30:31]
	s_mov_b64 s[0:1], s[30:31]
	s_mov_b64 s[0:1], s[30:31]
	s_mov_b64 s[0:1], s[30:31]
	s_mov_b64 s[0:1], s[30:31]
	s_mov_b64 s[8:9], s[30:31]
	s_mov_b64 s[0:1], s[30:31]
	s_mov_b64 s[10:11], s[30:31]
	s_mov_b64 s[0:1], s[30:31]
	s_mov_b64 s[0:1], s[30:31]
	s_mov_b64 s[0:1], s[30:31]
	s_mov_b64 s[12:13], s[30:31]
	s_mov_b64 s[12:13], s[30:31]
	s_mov_b64 s[12:13], s[30:31]
	s_mov_b64 s[12:13], s[30:31]
	s_mov_b64 s[12:13], s[30:31]
	s_mov_b64 s[12:13], s[30:31]
	s_waitcnt vmcnt(0) lgkmcnt(0)
	v_mov_b32_e32 v10, v0
	v_readlane_b32 s12, v253, 58
	v_readlane_b32 s13, v253, 59
	s_andn2_b64 vcc, exec, s[12:13]
	v_readfirstlane_b32 s12, v10
	s_cbranch_vccnz .LBB0_1768
	v_lshlrev_b32_e32 v1, 4, v10
	v_add_u32_e32 v2, 0x2000, v1
	v_ashrrev_i32_e32 v3, 31, v2
	v_lshrrev_b32_e32 v3, 22, v3
	v_add_u32_e32 v3, v2, v3
	v_ashrrev_i32_e32 v11, 10, v3
	v_mul_i32_i24_e32 v3, 0x400, v11
	v_sub_u32_e32 v2, v2, v3
	v_lshrrev_b32_e32 v3, 4, v2
	v_bitop3_b32 v2, v3, v2, 32 bitop3:0x6c
	v_ashrrev_i32_e32 v3, 31, v2
	s_add_u32 s43, s10, 0x17c00000
	v_lshrrev_b32_e32 v3, 26, v3
	s_addc_u32 s44, s11, 0
	v_add_u32_e32 v3, v2, v3
	v_lshlrev_b32_e32 v4, 3, v11
	s_add_u32 s8, s8, s41
	v_ashrrev_i32_e32 v12, 6, v3
	v_and_b32_e32 v4, -16, v4
	s_addc_u32 s9, s9, 0
	v_add_u32_e32 v4, v12, v4
	s_add_u32 s45, s8, 0x7c00000
	v_and_b32_e32 v5, 3, v12
	s_mov_b32 s8, 0xfffe0
	v_lshrrev_b32_e32 v6, 2, v4
	v_lshlrev_b32_e32 v7, 1, v4
	v_and_b32_e32 v3, 0xc0, v3
	v_and_or_b32 v5, v4, s8, v5
	v_and_b32_e32 v6, 4, v6
	v_and_b32_e32 v7, 24, v7
	v_sub_u32_e32 v2, v2, v3
	v_or3_b32 v5, v5, v6, v7
	v_lshlrev_b32_e32 v6, 5, v11
	v_ashrrev_i16_sdwa v2, v210, sext(v2) dst_sel:DWORD dst_unused:UNUSED_PAD src0_sel:DWORD src1_sel:BYTE_0
	v_and_b32_e32 v6, 32, v6
	v_bfe_i32 v13, v2, 0, 16
	v_add_lshl_u32 v2, v6, v13, 1
	v_lshlrev_b32_e32 v132, 4, v10
	v_add_u32_e32 v132, 0x2000, v132
	v_lshlrev_b32_e32 v134, 4, v10
	v_add_u32_e32 v134, 0x2000, v134
	v_bfe_i32 v2, v10, 27, 1
	v_lshrrev_b32_e32 v2, 22, v2
	v_add_u32_e32 v2, v1, v2
	v_and_b32_e32 v2, 0xfffffc00, v2
	v_sub_u32_e32 v1, v1, v2
	v_lshrrev_b32_e32 v2, 4, v1
	v_ashrrev_i32_e32 v3, 31, v10
	v_bitop3_b32 v1, v2, v1, 32 bitop3:0x6c
	v_lshrrev_b32_e32 v3, 26, v3
	v_ashrrev_i32_e32 v2, 31, v1
	v_add_u32_e32 v3, v10, v3
	v_lshrrev_b32_e32 v2, 26, v2
	v_ashrrev_i32_e32 v15, 6, v3
	v_add_u32_e32 v2, v1, v2
	v_lshlrev_b32_e32 v3, 3, v15
	v_ashrrev_i32_e32 v14, 6, v2
	v_and_b32_e32 v3, -16, v3
	v_add_u32_e32 v3, v14, v3
	v_and_b32_e32 v4, 3, v14
	v_lshrrev_b32_e32 v5, 2, v3
	v_lshlrev_b32_e32 v6, 1, v3
	v_and_b32_e32 v2, 0xc0, v2
	s_addc_u32 s46, s9, 0
	s_ashr_i32 s13, s12, 6
	v_and_or_b32 v4, v3, s8, v4
	v_and_b32_e32 v5, 4, v5
	v_and_b32_e32 v6, 24, v6
	v_sub_u32_e32 v1, v1, v2
	s_ashr_i32 s14, s12, 8
	s_lshl_b32 s47, s13, 10
	v_or3_b32 v4, v4, v5, v6
	v_lshlrev_b32_e32 v5, 5, v15
	v_ashrrev_i16_sdwa v1, v210, sext(v1) dst_sel:DWORD dst_unused:UNUSED_PAD src0_sel:DWORD src1_sel:BYTE_0
	v_readlane_b32 s8, v252, 39
	v_and_b32_e32 v5, 32, v5
	v_bfe_i32 v16, v1, 0, 16
	v_readlane_b32 s9, v252, 40
	s_add_u32 s22, s45, s8
	v_add_lshl_u32 v1, v5, v16, 1
	s_addc_u32 s23, s46, s9
	s_sub_u32 s100, s22, s30
	s_and_b32 s101, s100, 0xf80
	s_lshl_b32 s101, s101, 8
	s_and_b32 s100, s100, 0xfff00000
	s_or_b32 s100, s100, s101
	s_add_u32 s100, s30, s100
	s_addc_u32 s101, s31, 0
	s_add_i32 s48, s47, 0
	v_lshlrev_b32_e32 v136, 4, v10
	s_add_i32 m0, s48, 0x10000
	v_lshlrev_b32_e32 v138, 4, v10
	global_load_lds_dwordx4 v136, s[100:101]
	s_add_i32 m0, s48, 0x12000
	s_add_u32 s8, s100, 0x4000
	global_load_lds_dwordx4 v132, s[100:101]
	s_addc_u32 s9, s101, 0
	s_add_i32 m0, s48, 0x14000
	v_mov_b32_e32 v137, v19
	global_load_lds_dwordx4 v136, s[8:9]
	s_add_i32 m0, s48, 0x16000
	v_mov_b32_e32 v133, v19
	global_load_lds_dwordx4 v132, s[8:9]
	s_add_u32 s100, s100, 0x7f80
	s_addc_u32 s101, s101, 0
	v_readlane_b32 s8, v252, 43
	v_readlane_b32 s9, v252, 44
	s_add_u32 s24, s43, s8
	s_addc_u32 s25, s44, s9
	s_sub_u32 s26, s24, s30
	s_and_b32 s27, s26, 0xf80
	s_lshl_b32 s27, s27, 8
	s_and_b32 s26, s26, 0xfff00000
	s_or_b32 s26, s26, s27
	s_add_u32 s26, s30, s26
	s_addc_u32 s27, s31, 0
	s_add_i32 s49, s48, 0x2000
	s_mov_b32 m0, s48
	s_add_u32 s8, s26, 0x4000
	global_load_lds_dwordx4 v138, s[26:27]
	s_mov_b32 m0, s49
	s_addc_u32 s9, s27, 0
	s_add_i32 s50, s48, 0x4000
	global_load_lds_dwordx4 v134, s[26:27]
	s_mov_b32 m0, s50
	s_add_i32 s51, s48, 0x6000
	global_load_lds_dwordx4 v138, s[8:9]
	s_mov_b32 m0, s51
	v_mov_b32_e32 v139, v19
	global_load_lds_dwordx4 v134, s[8:9]
	s_add_u32 s26, s26, 0x7f80
	s_addc_u32 s27, s27, 0
	v_mov_b32_e32 v135, v19
	s_cmp_eq_u32 s14, 1
	v_lshl_add_u64 v[8:9], s[100:101], 0, v[136:137]
	v_lshl_add_u64 v[6:7], s[100:101], 0, v[132:133]
	v_lshl_add_u64 v[2:3], s[26:27], 0, v[138:139]
	s_cselect_b64 s[8:9], -1, 0
	s_cmp_lg_u32 s14, 1
	v_lshl_add_u64 v[4:5], s[26:27], 0, v[134:135]
	s_cbranch_scc1 .LBB0_1755
	s_barrier
.LBB0_1755:
	s_add_u32 s10, s0, 0x37300000
	s_addc_u32 s11, s1, 0
	s_mov_b64 s[0:1], 0x80
	s_lshl_b32 s15, s13, 5
	s_add_i32 m0, s48, 0x18000
	v_lshl_add_u64 v[8:9], v[8:9], 0, s[0:1]
	s_and_b32 s53, s15, 0x60
	s_waitcnt vmcnt(2)
	s_barrier
	global_load_lds_dwordx4 v[8:9], off
	v_lshl_add_u64 v[6:7], v[6:7], 0, s[0:1]
	s_add_i32 m0, s48, 0x1a000
	s_add_i32 s54, s48, 0x8000
	s_lshl_b32 s52, s14, 6
	s_lshl_b32 s14, s14, 13
	s_lshl_b32 s13, s53, 7
	global_load_lds_dwordx4 v[6:7], off
	v_lshl_add_u64 v[2:3], v[2:3], 0, s[0:1]
	s_mov_b32 m0, s54
	s_add_i32 s55, s48, 0xa000
	global_load_lds_dwordx4 v[2:3], off
	v_lshl_add_u64 v[2:3], v[4:5], 0, s[0:1]
	s_add_u32 s0, s100, 0x4080
	s_mov_b32 m0, s55
	s_addc_u32 s1, s101, 0
	global_load_lds_dwordx4 v[2:3], off
	s_add_i32 m0, s48, 0x1c000
	v_lshl_add_u64 v[2:3], s[0:1], 0, v[136:137]
	global_load_lds_dwordx4 v[2:3], off
	v_lshl_add_u64 v[2:3], s[0:1], 0, v[132:133]
	s_add_i32 m0, s48, 0x1e000
	v_and_b32_e32 v1, 15, v10
	global_load_lds_dwordx4 v[2:3], off
	v_lshrrev_b32_e32 v2, 1, v10
	v_and_b32_e32 v2, 24, v2
	v_lshlrev_b32_e32 v3, 1, v2
	v_lshlrev_b32_e32 v4, 2, v10
	v_lshl_or_b32 v3, v1, 6, v3
	v_and_b32_e32 v4, 32, v4
	v_bitop3_b32 v5, v3, s14, v4 bitop3:0xde
	v_bitop3_b32 v147, v3, s13, v4 bitop3:0xde
	v_lshlrev_b32_e32 v3, 15, v11
	v_and_b32_e32 v3, 0xffff0000, v3
	v_lshl_add_u32 v3, v12, 12, v3
	v_and_b32_e32 v4, 1, v11
	v_lshl_or_b32 v3, v4, 6, v3
	v_mov_b32_e32 v140, v134
	v_lshlrev_b32_e32 v3, 15, v15
	v_and_b32_e32 v3, 0xffff0000, v3
	s_waitcnt vmcnt(6)
	v_lshl_add_u32 v3, v14, 12, v3
	v_and_b32_e32 v4, 1, v15
	s_cmpk_lt_u32 s12, 0x100
	v_and_or_b32 v2, s15, 32, v2
	v_lshl_or_b32 v3, v4, 6, v3
	v_readlane_b32 s0, v252, 41
	s_cselect_b64 s[12:13], -1, 0
	v_mov_b32_e32 v141, v19
	v_mov_b32_e32 v142, v138
	v_mov_b32_e32 v143, v19
	s_mov_b32 s56, 0
	v_add_u32_e32 v148, 0, v5
	v_lshlrev_b32_e32 v144, 1, v2
	v_readlane_b32 s57, v252, 38
	s_mov_b32 s58, s0
	s_barrier
	v_readlane_b32 s1, v252, 42
	s_branch .LBB0_1758

.LBB0_1761:
	s_add_u32 s24, s22, 0xfff80080
	s_addc_u32 s25, s23, -1
	s_cmp_eq_u32 s63, 28
	s_cselect_b32 s27, s17, s25
	s_cselect_b32 s26, s59, s24
	v_add_u32_e32 v18, s67, v147
	s_cselect_b32 s25, s15, s62
	s_cselect_b32 s24, s60, s61
	s_sub_u32 s66, s24, s30
	s_and_b32 s64, s66, 0xf80
	s_lshl_b32 s64, s64, 8
	s_and_b32 s66, s66, 0xfff00000
	s_or_b32 s66, s66, s64
	s_add_u32 s24, s30, s66
	s_addc_u32 s25, s31, 0
	s_sub_u32 s66, s26, s30
	s_and_b32 s64, s66, 0xf80
	s_lshl_b32 s64, s64, 8
	s_and_b32 s66, s66, 0xfff00000
	s_or_b32 s66, s66, s64
	s_add_u32 s26, s30, s66
	s_addc_u32 s27, s31, 0
	s_sub_u32 s100, s22, s30
	s_and_b32 s101, s100, 0xf80
	s_lshl_b32 s101, s101, 8
	s_and_b32 s100, s100, 0xfff00000
	s_or_b32 s100, s100, s101
	s_add_i32 s100, s100, 0x4000
	s_add_u32 s100, s30, s100
	s_addc_u32 s101, s31, 0
	ds_read_b128 v[150:153], v18
	ds_read_b128 v[154:157], v18 offset:1024
	ds_read_b128 v[158:161], v18 offset:2048
	ds_read_b128 v[170:173], v18 offset:3072
	v_add_u32_e32 v18, 0x14000, v147
	ds_read_b128 v[174:177], v18
	ds_read_b128 v[178:181], v18 offset:1024
	ds_read_b128 v[182:185], v18 offset:2048
	ds_read_b128 v[186:189], v18 offset:3072
	s_add_i32 m0, s48, 0xc000
	ds_read_b128 v[190:193], v148
	ds_read_b128 v[194:197], v148 offset:1024
	ds_read_b128 v[198:201], v148 offset:2048
	ds_read_b128 v[202:205], v148 offset:3072
	ds_read_b128 v[206:209], v148 offset:4096
	ds_read_b128 v[220:223], v148 offset:5120
	ds_read_b128 v[224:227], v148 offset:6144
	ds_read_b128 v[228:231], v148 offset:7168
	global_load_lds_dwordx4 v142, s[100:101]
	s_add_i32 m0, s48, 0xe000
	s_nop 0
	global_load_lds_dwordx4 v140, s[100:101]
	s_waitcnt vmcnt(8)
	s_waitcnt lgkmcnt(0)
	s_barrier
	s_setprio 1
	s_waitcnt lgkmcnt(0)
	v_mfma_f32_16x16x32_bf16 v[128:131], v[150:153], v[190:193], v[128:131]
	v_mfma_f32_16x16x32_bf16 v[124:127], v[158:161], v[190:193], v[124:127]
	v_mfma_f32_16x16x32_bf16 v[112:115], v[150:153], v[198:201], v[112:115]
	v_mfma_f32_16x16x32_bf16 v[108:111], v[158:161], v[198:201], v[108:111]
	v_mfma_f32_16x16x32_bf16 v[96:99], v[150:153], v[206:209], v[96:99]
	v_mfma_f32_16x16x32_bf16 v[92:95], v[158:161], v[206:209], v[92:95]
	v_mfma_f32_16x16x32_bf16 v[80:83], v[150:153], v[224:227], v[80:83]
	v_mfma_f32_16x16x32_bf16 v[76:79], v[158:161], v[224:227], v[76:79]
	v_mfma_f32_16x16x32_bf16 v[128:131], v[154:157], v[194:197], v[128:131]
	v_mfma_f32_16x16x32_bf16 v[124:127], v[170:173], v[194:197], v[124:127]
	v_mfma_f32_16x16x32_bf16 v[112:115], v[154:157], v[202:205], v[112:115]
	v_mfma_f32_16x16x32_bf16 v[108:111], v[170:173], v[202:205], v[108:111]
	v_mfma_f32_16x16x32_bf16 v[96:99], v[154:157], v[220:223], v[96:99]
	v_mfma_f32_16x16x32_bf16 v[92:95], v[170:173], v[220:223], v[92:95]
	v_mfma_f32_16x16x32_bf16 v[80:83], v[154:157], v[228:231], v[80:83]
	v_mfma_f32_16x16x32_bf16 v[76:79], v[170:173], v[228:231], v[76:79]
	s_setprio 0
	s_setprio 1
	v_mfma_f32_16x16x32_bf16 v[120:123], v[174:177], v[190:193], v[120:123]
	v_mfma_f32_16x16x32_bf16 v[116:119], v[182:185], v[190:193], v[116:119]
	v_mfma_f32_16x16x32_bf16 v[104:107], v[174:177], v[198:201], v[104:107]
	v_mfma_f32_16x16x32_bf16 v[100:103], v[182:185], v[198:201], v[100:103]
	v_mfma_f32_16x16x32_bf16 v[88:91], v[174:177], v[206:209], v[88:91]
	v_mfma_f32_16x16x32_bf16 v[84:87], v[182:185], v[206:209], v[84:87]
	v_mfma_f32_16x16x32_bf16 v[72:75], v[174:177], v[224:227], v[72:75]
	v_mfma_f32_16x16x32_bf16 v[68:71], v[182:185], v[224:227], v[68:71]
	v_mfma_f32_16x16x32_bf16 v[120:123], v[178:181], v[194:197], v[120:123]
	v_mfma_f32_16x16x32_bf16 v[116:119], v[186:189], v[194:197], v[116:119]
	v_mfma_f32_16x16x32_bf16 v[104:107], v[178:181], v[202:205], v[104:107]
	v_mfma_f32_16x16x32_bf16 v[100:103], v[186:189], v[202:205], v[100:103]
	v_mfma_f32_16x16x32_bf16 v[88:91], v[178:181], v[220:223], v[88:91]
	v_mfma_f32_16x16x32_bf16 v[84:87], v[186:189], v[220:223], v[84:87]
	v_mfma_f32_16x16x32_bf16 v[72:75], v[178:181], v[228:231], v[72:75]
	v_mfma_f32_16x16x32_bf16 v[68:71], v[186:189], v[228:231], v[68:71]
	s_setprio 0
	s_barrier
	s_add_i32 m0, s67, s47
	ds_read_b128 v[190:193], v148 offset:16384
	ds_read_b128 v[194:197], v148 offset:17408
	ds_read_b128 v[198:201], v148 offset:18432
	ds_read_b128 v[202:205], v148 offset:19456
	ds_read_b128 v[206:209], v148 offset:20480
	ds_read_b128 v[220:223], v148 offset:21504
	ds_read_b128 v[224:227], v148 offset:22528
	ds_read_b128 v[228:231], v148 offset:23552
	global_load_lds_dwordx4 v136, s[24:25]
	s_add_i32 s66, s67, s47
	s_add_i32 m0, s66, 0x2000
	s_add_u32 s64, s24, 0x4000
	s_addc_u32 s65, s25, 0
	global_load_lds_dwordx4 v132, s[24:25]
	s_add_i32 m0, s47, 0x14000
	s_nop 0
	global_load_lds_dwordx4 v136, s[64:65]
	s_add_i32 m0, s47, 0x16000
	s_nop 0
	global_load_lds_dwordx4 v132, s[64:65]
	s_mov_b32 m0, s48
	s_nop 0
	global_load_lds_dwordx4 v138, s[26:27]
	s_mov_b32 m0, s49
	s_nop 0
	global_load_lds_dwordx4 v134, s[26:27]
	s_waitcnt vmcnt(8)
	s_waitcnt lgkmcnt(0)
	s_barrier
	s_setprio 1
	s_waitcnt lgkmcnt(0)
	v_mfma_f32_16x16x32_bf16 v[64:67], v[150:153], v[190:193], v[64:67]
	v_mfma_f32_16x16x32_bf16 v[60:63], v[158:161], v[190:193], v[60:63]
	v_mfma_f32_16x16x32_bf16 v[48:51], v[150:153], v[198:201], v[48:51]
	v_mfma_f32_16x16x32_bf16 v[44:47], v[158:161], v[198:201], v[44:47]
	v_mfma_f32_16x16x32_bf16 v[32:35], v[150:153], v[206:209], v[32:35]
	v_mfma_f32_16x16x32_bf16 v[28:31], v[158:161], v[206:209], v[28:31]
	v_mfma_f32_16x16x32_bf16 v[14:17], v[150:153], v[224:227], v[14:17]
	v_mfma_f32_16x16x32_bf16 v[10:13], v[158:161], v[224:227], v[10:13]
	v_mfma_f32_16x16x32_bf16 v[64:67], v[154:157], v[194:197], v[64:67]
	v_mfma_f32_16x16x32_bf16 v[60:63], v[170:173], v[194:197], v[60:63]
	v_mfma_f32_16x16x32_bf16 v[48:51], v[154:157], v[202:205], v[48:51]
	v_mfma_f32_16x16x32_bf16 v[44:47], v[170:173], v[202:205], v[44:47]
	v_mfma_f32_16x16x32_bf16 v[32:35], v[154:157], v[220:223], v[32:35]
	v_mfma_f32_16x16x32_bf16 v[28:31], v[170:173], v[220:223], v[28:31]
	v_mfma_f32_16x16x32_bf16 v[14:17], v[154:157], v[228:231], v[14:17]
	v_mfma_f32_16x16x32_bf16 v[10:13], v[170:173], v[228:231], v[10:13]
	s_setprio 0
	s_setprio 1
	v_mfma_f32_16x16x32_bf16 v[56:59], v[174:177], v[190:193], v[56:59]
	v_mfma_f32_16x16x32_bf16 v[52:55], v[182:185], v[190:193], v[52:55]
	v_mfma_f32_16x16x32_bf16 v[40:43], v[174:177], v[198:201], v[40:43]
	v_mfma_f32_16x16x32_bf16 v[36:39], v[182:185], v[198:201], v[36:39]
	v_mfma_f32_16x16x32_bf16 v[24:27], v[174:177], v[206:209], v[24:27]
	v_mfma_f32_16x16x32_bf16 v[20:23], v[182:185], v[206:209], v[20:23]
	v_mfma_f32_16x16x32_bf16 v[6:9], v[174:177], v[224:227], v[6:9]
	v_mfma_f32_16x16x32_bf16 v[2:5], v[182:185], v[224:227], v[2:5]
	v_mfma_f32_16x16x32_bf16 v[56:59], v[178:181], v[194:197], v[56:59]
	v_mfma_f32_16x16x32_bf16 v[52:55], v[186:189], v[194:197], v[52:55]
	v_mfma_f32_16x16x32_bf16 v[40:43], v[178:181], v[202:205], v[40:43]
	v_mfma_f32_16x16x32_bf16 v[36:39], v[186:189], v[202:205], v[36:39]
	v_mfma_f32_16x16x32_bf16 v[24:27], v[178:181], v[220:223], v[24:27]
	v_mfma_f32_16x16x32_bf16 v[20:23], v[186:189], v[220:223], v[20:23]
	v_mfma_f32_16x16x32_bf16 v[6:9], v[178:181], v[228:231], v[6:9]
	v_mfma_f32_16x16x32_bf16 v[2:5], v[186:189], v[228:231], v[2:5]
	s_setprio 0
	s_barrier
	v_add_u32_e32 v18, 0x18000, v147
	ds_read_b128 v[150:153], v18
	ds_read_b128 v[154:157], v18 offset:1024
	ds_read_b128 v[158:161], v18 offset:2048
	ds_read_b128 v[170:173], v18 offset:3072
	v_add_u32_e32 v18, 0x1c000, v147
	ds_read_b128 v[174:177], v18
	ds_read_b128 v[178:181], v18 offset:1024
	ds_read_b128 v[182:185], v18 offset:2048
	ds_read_b128 v[186:189], v18 offset:3072
	s_add_u32 s26, s26, 0x4000
	s_addc_u32 s27, s27, 0
	s_mov_b32 m0, s50
	ds_read_b128 v[190:193], v148 offset:32768
	ds_read_b128 v[194:197], v148 offset:33792
	ds_read_b128 v[198:201], v148 offset:34816
	ds_read_b128 v[202:205], v148 offset:35840
	ds_read_b128 v[206:209], v148 offset:36864
	ds_read_b128 v[220:223], v148 offset:37888
	ds_read_b128 v[224:227], v148 offset:38912
	ds_read_b128 v[228:231], v148 offset:39936
	global_load_lds_dwordx4 v138, s[26:27]
	s_mov_b32 m0, s51
	s_nop 0
	global_load_lds_dwordx4 v134, s[26:27]
	s_waitcnt vmcnt(8)
	s_waitcnt lgkmcnt(0)
	s_barrier
	s_setprio 1
	s_waitcnt lgkmcnt(0)
	v_mfma_f32_16x16x32_bf16 v[128:131], v[150:153], v[190:193], v[128:131]
	v_mfma_f32_16x16x32_bf16 v[124:127], v[158:161], v[190:193], v[124:127]
	v_mfma_f32_16x16x32_bf16 v[112:115], v[150:153], v[198:201], v[112:115]
	v_mfma_f32_16x16x32_bf16 v[108:111], v[158:161], v[198:201], v[108:111]
	v_mfma_f32_16x16x32_bf16 v[96:99], v[150:153], v[206:209], v[96:99]
	v_mfma_f32_16x16x32_bf16 v[92:95], v[158:161], v[206:209], v[92:95]
	v_mfma_f32_16x16x32_bf16 v[80:83], v[150:153], v[224:227], v[80:83]
	v_mfma_f32_16x16x32_bf16 v[76:79], v[158:161], v[224:227], v[76:79]
	v_mfma_f32_16x16x32_bf16 v[128:131], v[154:157], v[194:197], v[128:131]
	v_mfma_f32_16x16x32_bf16 v[124:127], v[170:173], v[194:197], v[124:127]
	v_mfma_f32_16x16x32_bf16 v[112:115], v[154:157], v[202:205], v[112:115]
	v_mfma_f32_16x16x32_bf16 v[108:111], v[170:173], v[202:205], v[108:111]
	v_mfma_f32_16x16x32_bf16 v[96:99], v[154:157], v[220:223], v[96:99]
	v_mfma_f32_16x16x32_bf16 v[92:95], v[170:173], v[220:223], v[92:95]
	v_mfma_f32_16x16x32_bf16 v[80:83], v[154:157], v[228:231], v[80:83]
	v_mfma_f32_16x16x32_bf16 v[76:79], v[170:173], v[228:231], v[76:79]
	s_setprio 0
	s_setprio 1
	v_mfma_f32_16x16x32_bf16 v[120:123], v[174:177], v[190:193], v[120:123]
	v_mfma_f32_16x16x32_bf16 v[116:119], v[182:185], v[190:193], v[116:119]
	v_mfma_f32_16x16x32_bf16 v[104:107], v[174:177], v[198:201], v[104:107]
	v_mfma_f32_16x16x32_bf16 v[100:103], v[182:185], v[198:201], v[100:103]
	v_mfma_f32_16x16x32_bf16 v[88:91], v[174:177], v[206:209], v[88:91]
	v_mfma_f32_16x16x32_bf16 v[84:87], v[182:185], v[206:209], v[84:87]
	v_mfma_f32_16x16x32_bf16 v[72:75], v[174:177], v[224:227], v[72:75]
	v_mfma_f32_16x16x32_bf16 v[68:71], v[182:185], v[224:227], v[68:71]
	v_mfma_f32_16x16x32_bf16 v[120:123], v[178:181], v[194:197], v[120:123]
	v_mfma_f32_16x16x32_bf16 v[116:119], v[186:189], v[194:197], v[116:119]
	v_mfma_f32_16x16x32_bf16 v[104:107], v[178:181], v[202:205], v[104:107]
	v_mfma_f32_16x16x32_bf16 v[100:103], v[186:189], v[202:205], v[100:103]
	v_mfma_f32_16x16x32_bf16 v[88:91], v[178:181], v[220:223], v[88:91]
	v_mfma_f32_16x16x32_bf16 v[84:87], v[186:189], v[220:223], v[84:87]
	v_mfma_f32_16x16x32_bf16 v[72:75], v[178:181], v[228:231], v[72:75]
	v_mfma_f32_16x16x32_bf16 v[68:71], v[186:189], v[228:231], v[68:71]
	s_setprio 0
	s_barrier
	s_add_i32 m0, s47, 0x17f80
	ds_read_b128 v[190:193], v148 offset:49152
	ds_read_b128 v[194:197], v148 offset:50176
	ds_read_b128 v[198:201], v148 offset:51200
	ds_read_b128 v[202:205], v148 offset:52224
	ds_read_b128 v[206:209], v148 offset:53248
	ds_read_b128 v[220:223], v148 offset:54272
	ds_read_b128 v[224:227], v148 offset:55296
	ds_read_b128 v[228:231], v148 offset:56320
	s_add_u32 s64, s24, 0x7f80
	s_addc_u32 s65, s25, 0
	s_nop 0
	global_load_lds_dwordx4 v136, s[64:65] offset:128
	s_add_i32 m0, s47, 0x19f80
	s_add_u32 s26, s26, 0x3f80
	s_addc_u32 s27, s27, 0
	global_load_lds_dwordx4 v132, s[64:65] offset:128
	s_add_i32 m0, s47, 0x1bf80
	s_nop 0
	s_add_u32 s64, s24, 0xbf80
	s_addc_u32 s65, s25, 0
	s_nop 0
	global_load_lds_dwordx4 v136, s[64:65] offset:128
	s_add_i32 m0, s47, 0x1df80
	s_nop 0
	global_load_lds_dwordx4 v132, s[64:65] offset:128
	s_add_i32 m0, s54, 0xffffff80
	s_nop 0
	global_load_lds_dwordx4 v138, s[26:27] offset:128
	s_add_i32 m0, s55, 0xffffff80
	s_nop 0
	global_load_lds_dwordx4 v134, s[26:27] offset:128
	s_waitcnt vmcnt(8)
	s_waitcnt lgkmcnt(0)
	s_barrier
	s_setprio 1
	s_waitcnt lgkmcnt(0)
	v_mfma_f32_16x16x32_bf16 v[64:67], v[150:153], v[190:193], v[64:67]
	v_mfma_f32_16x16x32_bf16 v[60:63], v[158:161], v[190:193], v[60:63]
	v_mfma_f32_16x16x32_bf16 v[48:51], v[150:153], v[198:201], v[48:51]
	v_mfma_f32_16x16x32_bf16 v[44:47], v[158:161], v[198:201], v[44:47]
	v_mfma_f32_16x16x32_bf16 v[32:35], v[150:153], v[206:209], v[32:35]
	v_mfma_f32_16x16x32_bf16 v[28:31], v[158:161], v[206:209], v[28:31]
	v_mfma_f32_16x16x32_bf16 v[14:17], v[150:153], v[224:227], v[14:17]
	v_mfma_f32_16x16x32_bf16 v[10:13], v[158:161], v[224:227], v[10:13]
	v_mfma_f32_16x16x32_bf16 v[64:67], v[154:157], v[194:197], v[64:67]
	v_mfma_f32_16x16x32_bf16 v[60:63], v[170:173], v[194:197], v[60:63]
	v_mfma_f32_16x16x32_bf16 v[48:51], v[154:157], v[202:205], v[48:51]
	v_mfma_f32_16x16x32_bf16 v[44:47], v[170:173], v[202:205], v[44:47]
	v_mfma_f32_16x16x32_bf16 v[32:35], v[154:157], v[220:223], v[32:35]
	v_mfma_f32_16x16x32_bf16 v[28:31], v[170:173], v[220:223], v[28:31]
	v_mfma_f32_16x16x32_bf16 v[14:17], v[154:157], v[228:231], v[14:17]
	v_mfma_f32_16x16x32_bf16 v[10:13], v[170:173], v[228:231], v[10:13]
	s_setprio 0
	s_setprio 1
	v_mfma_f32_16x16x32_bf16 v[56:59], v[174:177], v[190:193], v[56:59]
	v_mfma_f32_16x16x32_bf16 v[52:55], v[182:185], v[190:193], v[52:55]
	v_mfma_f32_16x16x32_bf16 v[40:43], v[174:177], v[198:201], v[40:43]
	v_mfma_f32_16x16x32_bf16 v[36:39], v[182:185], v[198:201], v[36:39]
	v_mfma_f32_16x16x32_bf16 v[24:27], v[174:177], v[206:209], v[24:27]
	v_mfma_f32_16x16x32_bf16 v[20:23], v[182:185], v[206:209], v[20:23]
	v_mfma_f32_16x16x32_bf16 v[6:9], v[174:177], v[224:227], v[6:9]
	v_mfma_f32_16x16x32_bf16 v[2:5], v[182:185], v[224:227], v[2:5]
	v_mfma_f32_16x16x32_bf16 v[56:59], v[178:181], v[194:197], v[56:59]
	v_mfma_f32_16x16x32_bf16 v[52:55], v[186:189], v[194:197], v[52:55]
	v_mfma_f32_16x16x32_bf16 v[40:43], v[178:181], v[202:205], v[40:43]
	v_mfma_f32_16x16x32_bf16 v[36:39], v[186:189], v[202:205], v[36:39]
	v_mfma_f32_16x16x32_bf16 v[24:27], v[178:181], v[220:223], v[24:27]
	v_mfma_f32_16x16x32_bf16 v[20:23], v[186:189], v[220:223], v[20:23]
	v_mfma_f32_16x16x32_bf16 v[6:9], v[178:181], v[228:231], v[6:9]
	v_mfma_f32_16x16x32_bf16 v[2:5], v[186:189], v[228:231], v[2:5]
	s_setprio 0
	s_barrier
	s_add_i32 s63, s63, 2
	s_add_u32 s61, s61, 0x100
	s_addc_u32 s62, s62, 0
	s_add_u32 s22, s22, 0x100
	s_addc_u32 s23, s23, 0
	s_cmp_gt_u32 s63, 29
	s_cbranch_scc0 .LBB0_1761
	s_and_b64 vcc, exec, s[12:13]
	s_cbranch_vccz .LBB0_1764
	s_barrier
